# FFT second radix-4 stage: spectrum rows requested one pass / one stage ahead with counted waits
# speedup vs baseline: 1.0097x; 1.0020x over previous
.LBB0_236:
	s_add_u32 s4, s4, s0
	s_addc_u32 s5, s5, s1
	s_lshl_b64 s[4:5], s[4:5], 14
	s_add_u32 s6, s68, s4
	v_lshlrev_b32_e32 v0, 1, v146
	v_ashrrev_i32_e32 v1, 31, v0
	s_addc_u32 s7, s69, s5
	v_lshlrev_b64 v[68:69], 1, v[0:1]
	v_lshl_add_u64 v[50:51], s[6:7], 0, v[68:69]
	global_load_dword v1, v[50:51], off
	v_add_u32_e32 v8, 0x1000, v0
	s_add_u32 s8, s6, 0x1000000
	v_add_u32_e32 v2, 0x400, v0
	v_add_u32_e32 v4, 0x800, v0
	v_add_u32_e32 v6, 0xc00, v0
	v_ashrrev_i32_e32 v9, 31, v8
	v_add_u32_e32 v10, 0x1400, v0
	v_add_u32_e32 v12, 0x1800, v0
	v_add_u32_e32 v14, 0x1c00, v0
	s_addc_u32 s9, s7, 0
	v_ashrrev_i32_e32 v3, 31, v2
	v_ashrrev_i32_e32 v5, 31, v4
	v_ashrrev_i32_e32 v7, 31, v6
	v_lshlrev_b64 v[62:63], 1, v[8:9]
	v_ashrrev_i32_e32 v11, 31, v10
	v_ashrrev_i32_e32 v13, 31, v12
	v_ashrrev_i32_e32 v15, 31, v14
	v_lshl_add_u64 v[54:55], s[8:9], 0, v[68:69]
	v_lshlrev_b64 v[70:71], 1, v[2:3]
	v_lshlrev_b64 v[66:67], 1, v[4:5]
	v_lshlrev_b64 v[64:65], 1, v[6:7]
	v_lshl_add_u64 v[42:43], s[6:7], 0, v[62:63]
	v_lshlrev_b64 v[60:61], 1, v[10:11]
	v_lshlrev_b64 v[58:59], 1, v[12:13]
	v_lshlrev_b64 v[56:57], 1, v[14:15]
	v_lshl_add_u64 v[52:53], s[8:9], 0, v[70:71]
	v_lshl_add_u64 v[46:47], s[6:7], 0, v[66:67]
	v_lshl_add_u64 v[48:49], s[8:9], 0, v[66:67]
	v_lshl_add_u64 v[38:39], s[6:7], 0, v[64:65]
	v_lshl_add_u64 v[40:41], s[8:9], 0, v[64:65]
	global_load_dword v3, v[54:55], off
	global_load_dword v5, v[52:53], off
	global_load_dword v7, v[46:47], off
	global_load_dword v80, v[48:49], off
	global_load_dword v81, v[38:39], off
	global_load_dword v82, v[40:41], off
	global_load_dword v83, v[50:51], off offset:2048
	v_lshl_add_u64 v[44:45], s[8:9], 0, v[62:63]
	v_lshl_add_u64 v[34:35], s[6:7], 0, v[60:61]
	v_lshl_add_u64 v[36:37], s[8:9], 0, v[60:61]
	v_lshl_add_u64 v[30:31], s[6:7], 0, v[58:59]
	v_lshl_add_u64 v[32:33], s[8:9], 0, v[58:59]
	v_lshl_add_u64 v[26:27], s[6:7], 0, v[56:57]
	v_lshl_add_u64 v[28:29], s[8:9], 0, v[56:57]
	global_load_dword v9, v[42:43], off
	global_load_dword v11, v[44:45], off
	global_load_dword v13, v[34:35], off
	global_load_dword v15, v[36:37], off
	global_load_dword v104, v[30:31], off
	global_load_dword v105, v[32:33], off
	global_load_dword v106, v[26:27], off
	global_load_dword v107, v[28:29], off
	s_add_u32 s12, s6, 0x4000000
	s_addc_u32 s13, s7, 0
	s_add_u32 s4, s6, 0x8000000
	s_addc_u32 s5, s7, 0
	s_add_u32 s14, s6, 0x5000000
	s_addc_u32 s15, s7, 0
	v_lshl_add_u64 v[16:17], s[12:13], 0, v[68:69]
	v_lshl_add_u64 v[72:73], s[12:13], 0, v[66:67]
	v_lshl_add_u64 v[74:75], s[14:15], 0, v[66:67]
	v_lshl_add_u64 v[76:77], s[12:13], 0, v[64:65]
	v_lshl_add_u64 v[78:79], s[14:15], 0, v[64:65]
	v_lshl_add_u64 v[18:19], s[14:15], 0, v[68:69]
	v_lshl_add_u64 v[20:21], s[12:13], 0, v[70:71]
	v_lshl_add_u64 v[22:23], s[14:15], 0, v[70:71]
	global_load_dword v186, v[16:17], off
	global_load_dword v185, v[18:19], off
	global_load_dword v184, v[20:21], off
	global_load_dword v183, v[22:23], off
	global_load_dword v182, v[72:73], off
	global_load_dword v181, v[74:75], off
	global_load_dword v180, v[76:77], off
	global_load_dword v178, v[78:79], off
	v_lshl_add_u64 v[16:17], s[12:13], 0, v[62:63]
	v_lshl_add_u64 v[72:73], s[12:13], 0, v[58:59]
	v_lshl_add_u64 v[74:75], s[14:15], 0, v[58:59]
	v_lshl_add_u64 v[76:77], s[12:13], 0, v[56:57]
	v_lshl_add_u64 v[78:79], s[14:15], 0, v[56:57]
	v_lshl_add_u64 v[18:19], s[14:15], 0, v[62:63]
	v_lshl_add_u64 v[20:21], s[12:13], 0, v[60:61]
	v_lshl_add_u64 v[22:23], s[14:15], 0, v[60:61]
	global_load_dword v179, v[16:17], off
	global_load_dword v177, v[18:19], off
	global_load_dword v176, v[20:21], off
	global_load_dword v175, v[22:23], off
	global_load_dword v174, v[72:73], off
	global_load_dword v171, v[74:75], off
	global_load_dword v170, v[76:77], off
	global_load_dword v168, v[78:79], off
	s_add_u32 s6, s6, 0x9000000
	s_addc_u32 s7, s7, 0
	s_waitcnt vmcnt(31)
	v_lshlrev_b32_e32 v100, 16, v1
	v_and_b32_e32 v101, 0xffff0000, v1
	v_bfe_i32 v1, v146, 3, 28
	v_and_b32_e32 v1, 0x3ffffffc, v1
	v_add_lshl_u32 v1, v1, v0, 2
	v_add_u32_e32 v172, 0, v1
	v_add_u32_e32 v173, s91, v1
	v_ashrrev_i32_e32 v1, 4, v2
	v_and_b32_e32 v1, -4, v1
	v_add_u32_e32 v2, v1, v2
	v_add_u32_e32 v1, v1, v0
	v_lshl_add_u32 v160, v1, 2, 0
	v_ashrrev_i32_e32 v1, 4, v4
	v_and_b32_e32 v1, -4, v1
	v_lshl_add_u32 v169, v2, 2, s91
	v_add_u32_e32 v2, v1, v4
	v_add_u32_e32 v1, v1, v0
	v_lshl_add_u32 v158, v1, 2, 0
	v_ashrrev_i32_e32 v1, 4, v6
	v_and_b32_e32 v1, -4, v1
	v_lshl_add_u32 v159, v2, 2, s91
	v_add_u32_e32 v2, v1, v6
	v_add_u32_e32 v1, v1, v0
	v_lshl_add_u32 v156, v1, 2, 0
	v_ashrrev_i32_e32 v1, 4, v8
	v_and_b32_e32 v1, -4, v1
	v_lshl_add_u32 v157, v2, 2, s91
	v_add_u32_e32 v2, v1, v8
	v_add_u32_e32 v1, v1, v0
	v_lshl_add_u32 v154, v1, 2, 0
	v_ashrrev_i32_e32 v1, 4, v10
	v_and_b32_e32 v1, -4, v1
	v_lshl_add_u32 v155, v2, 2, s91
	v_add_u32_e32 v2, v1, v10
	v_add_u32_e32 v1, v1, v0
	v_lshl_add_u32 v152, v1, 2, 0
	v_ashrrev_i32_e32 v1, 4, v12
	v_and_b32_e32 v1, -4, v1
	v_lshl_add_u32 v153, v2, 2, s91
	v_add_u32_e32 v2, v1, v12
	v_add_u32_e32 v1, v1, v0
	v_lshl_add_u32 v150, v1, 2, 0
	v_ashrrev_i32_e32 v1, 4, v14
	v_and_b32_e32 v1, -4, v1
	v_lshl_add_u32 v151, v2, 2, s91
	v_add_u32_e32 v2, v1, v14
	v_add_u32_e32 v0, v1, v0
	s_waitcnt vmcnt(30)
	v_lshlrev_b32_e32 v102, 16, v3
	v_and_b32_e32 v103, 0xffff0000, v3
	s_waitcnt vmcnt(24)
	v_lshlrev_b32_e32 v96, 16, v83
	v_and_b32_e32 v97, 0xffff0000, v83
	v_lshlrev_b32_e32 v98, 16, v5
	v_and_b32_e32 v99, 0xffff0000, v5
	v_lshlrev_b32_e32 v92, 16, v7
	v_and_b32_e32 v93, 0xffff0000, v7
	v_lshlrev_b32_e32 v94, 16, v80
	v_and_b32_e32 v95, 0xffff0000, v80
	v_lshlrev_b32_e32 v88, 16, v81
	v_and_b32_e32 v89, 0xffff0000, v81
	v_lshlrev_b32_e32 v90, 16, v82
	v_and_b32_e32 v91, 0xffff0000, v82
	s_waitcnt vmcnt(23)
	v_lshlrev_b32_e32 v84, 16, v9
	v_and_b32_e32 v85, 0xffff0000, v9
	s_waitcnt vmcnt(22)
	v_lshlrev_b32_e32 v86, 16, v11
	v_and_b32_e32 v87, 0xffff0000, v11
	s_waitcnt vmcnt(21)
	v_lshlrev_b32_e32 v80, 16, v13
	v_and_b32_e32 v81, 0xffff0000, v13
	s_waitcnt vmcnt(20)
	v_lshlrev_b32_e32 v82, 16, v15
	v_and_b32_e32 v83, 0xffff0000, v15
	s_waitcnt vmcnt(19)
	v_lshlrev_b32_e32 v76, 16, v104
	v_and_b32_e32 v77, 0xffff0000, v104
	s_waitcnt vmcnt(18)
	v_lshlrev_b32_e32 v78, 16, v105
	v_and_b32_e32 v79, 0xffff0000, v105
	s_waitcnt vmcnt(17)
	v_lshlrev_b32_e32 v72, 16, v106
	v_and_b32_e32 v73, 0xffff0000, v106
	v_lshl_add_u32 v148, v0, 2, 0
	s_waitcnt vmcnt(16)
	v_lshlrev_b32_e32 v74, 16, v107
	v_and_b32_e32 v75, 0xffff0000, v107
	v_lshl_add_u32 v149, v2, 2, s91
	v_mov_b32_e32 v0, v163
	ds_write_b64 v172, v[100:101]
	ds_write_b64 v173, v[102:103]
	ds_write_b64 v160, v[96:97] offset:4096
	ds_write_b64 v169, v[98:99]
	ds_write_b64 v158, v[92:93] offset:8192
	ds_write_b64 v159, v[94:95]
	ds_write_b64 v156, v[88:89] offset:12288
	ds_write_b64 v157, v[90:91]
	ds_write_b64 v154, v[84:85] offset:16384
	ds_write_b64 v155, v[86:87]
	ds_write_b64 v152, v[80:81] offset:20480
	ds_write_b64 v153, v[82:83]
	ds_write_b64 v150, v[76:77] offset:24576
	ds_write_b64 v151, v[78:79]
	ds_write_b64 v148, v[72:73] offset:28672
	ds_write_b64 v149, v[74:75]
	s_waitcnt lgkmcnt(0)
	s_barrier
	s_nop 0
	s_nop 0
	v_ashrrev_i32_e32 v2, 31, v0
	v_lshlrev_b32_e32 v1, 1, v0
	v_lshrrev_b32_e32 v2, 23, v2
	v_and_b32_e32 v1, 0x3fe, v1
	v_add_lshl_u32 v0, v0, v2, 5
	v_and_or_b32 v0, v0, s85, v1
	v_cvt_f32_u32_e32 v3, v1
	v_or_b32_e32 v1, 1, v1
	v_ashrrev_i32_e32 v2, 4, v0
	v_cvt_f32_u32_e32 v1, v1
	v_and_b32_e32 v2, 0x3ffffc3c, v2
	v_add_lshl_u32 v136, v2, v0, 2
	v_add_u32_e32 v164, 0, v136
	v_mul_f32_e32 v3, 0x38800000, v3
	v_mul_f32_e32 v1, 0x38800000, v1
	v_add_u32_e32 v165, s91, v136
	ds_read_b64 v[136:137], v164
	ds_read_b64 v[138:139], v164 offset:4352
	ds_read_b64 v[140:141], v164 offset:8704
	ds_read_b64 v[142:143], v164 offset:13056
	ds_read_b64 v[144:145], v165
	ds_read_b64 v[188:189], v165 offset:4352
	ds_read_b64 v[190:191], v165 offset:8704
	ds_read_b64 v[192:193], v165 offset:13056
	ds_read_b64 v[194:195], v164 offset:17408
	ds_read_b64 v[196:197], v164 offset:21760
	ds_read_b64 v[198:199], v164 offset:26112
	ds_read_b64 v[200:201], v164 offset:30464
	ds_read_b64 v[202:203], v165 offset:17408
	ds_read_b64 v[204:205], v165 offset:21760
	ds_read_b64 v[206:207], v165 offset:26112
	ds_read_b64 v[208:209], v165 offset:30464
	v_sin_f32_e64 v14, -v3
	v_sin_f32_e64 v15, -v1
	s_waitcnt lgkmcnt(10)
	v_pk_mul_f32 v[218:219], v[188:189], s[80:81] op_sel_hi:[1,0]
	v_cos_f32_e32 v12, v3
	v_cos_f32_e32 v13, v1
	v_pk_add_f32 v[214:215], v[138:139], 0 op_sel_hi:[1,0]
	v_pk_fma_f32 v[218:219], v[138:139], s[72:73], v[218:219] op_sel_hi:[1,0,1]
	v_pk_mul_f32 v[138:139], v[138:139], s[80:81] op_sel_hi:[1,0]
	v_pk_add_f32 v[216:217], v[188:189], 0 op_sel_hi:[1,0]
	v_pk_fma_f32 v[138:139], v[188:189], s[72:73], v[138:139] op_sel_hi:[1,0,1] neg_lo:[0,0,1] neg_hi:[0,0,1]
	v_pk_add_f32 v[188:189], v[140:141], 0 op_sel_hi:[1,0]
	v_pk_mul_f32 v[140:141], v[140:141], s[82:83] op_sel_hi:[1,0]
	s_waitcnt lgkmcnt(8)
	v_pk_mul_f32 v[226:227], v[192:193], s[72:73] op_sel_hi:[1,0]
	v_pk_add_f32 v[220:221], v[190:191], 0 op_sel_hi:[1,0]
	v_pk_fma_f32 v[222:223], v[190:191], s[82:83], v[140:141] op_sel_hi:[1,0,1]
	v_pk_fma_f32 v[140:141], v[190:191], s[82:83], v[140:141] op_sel_hi:[1,0,1] neg_lo:[0,0,1] neg_hi:[0,0,1]
	v_pk_add_f32 v[190:191], v[142:143], 0 op_sel_hi:[1,0]
	v_pk_fma_f32 v[226:227], v[142:143], s[80:81], v[226:227] op_sel_hi:[1,0,1]
	v_pk_mul_f32 v[142:143], v[142:143], s[72:73] op_sel_hi:[1,0]
	s_waitcnt lgkmcnt(6)
	v_pk_mul_f32 v[234:235], v[196:197], s[80:81] op_sel_hi:[1,0]
	s_waitcnt lgkmcnt(4)
	v_pk_mul_f32 v[242:243], v[200:201], s[72:73] op_sel_hi:[1,0]
	v_pk_mul_f32 v[0:1], v[14:15], v[14:15]
	v_pk_add_f32 v[210:211], v[136:137], 0 op_sel_hi:[1,0]
	v_pk_add_f32 v[212:213], v[144:145], 0 op_sel_hi:[1,0]
	v_pk_add_f32 v[224:225], v[192:193], 0 op_sel_hi:[1,0]
	v_pk_fma_f32 v[142:143], v[192:193], s[80:81], v[142:143] op_sel_hi:[1,0,1] neg_lo:[0,0,1] neg_hi:[0,0,1]
	v_pk_add_f32 v[192:193], v[194:195], 0 op_sel_hi:[1,0]
	s_waitcnt lgkmcnt(3)
	v_pk_add_f32 v[228:229], v[202:203], 0 op_sel_hi:[1,0]
	v_pk_add_f32 v[230:231], v[196:197], 0 op_sel_hi:[1,0]
	s_waitcnt lgkmcnt(2)
	v_pk_add_f32 v[232:233], v[204:205], 0 op_sel_hi:[1,0]
	v_pk_fma_f32 v[234:235], v[204:205], s[72:73], v[234:235] op_sel_hi:[1,0,1] neg_lo:[0,0,1] neg_hi:[0,0,1]
	v_pk_mul_f32 v[204:205], v[204:205], s[80:81] op_sel_hi:[1,0]
	s_waitcnt lgkmcnt(1)
	v_pk_add_f32 v[236:237], v[206:207], 0 op_sel_hi:[1,0]
	v_pk_mul_f32 v[206:207], v[206:207], s[54:55] op_sel_hi:[1,0]
	s_waitcnt lgkmcnt(0)
	v_pk_add_f32 v[240:241], v[208:209], 0 op_sel_hi:[1,0]
	v_pk_fma_f32 v[242:243], v[208:209], s[80:81], v[242:243] op_sel_hi:[1,0,1] neg_lo:[0,0,1] neg_hi:[0,0,1]
	v_pk_mul_f32 v[208:209], v[208:209], s[72:73] op_sel_hi:[1,0]
	v_pk_fma_f32 v[106:107], v[12:13], v[12:13], v[0:1] neg_lo:[0,0,1] neg_hi:[0,0,1]
	v_pk_mul_f32 v[0:1], v[12:13], v[14:15]
	v_pk_fma_f32 v[196:197], v[196:197], s[52:53], v[204:205] op_sel_hi:[1,0,1] neg_lo:[0,0,1] neg_hi:[0,0,1]
	v_pk_add_f32 v[204:205], v[198:199], 0 op_sel_hi:[1,0]
	v_pk_fma_f32 v[238:239], v[198:199], s[54:55], v[206:207] op_sel_hi:[1,0,1] neg_lo:[0,0,1] neg_hi:[0,0,1]
	v_pk_fma_f32 v[198:199], v[198:199], s[54:55], v[206:207] op_sel_hi:[1,0,1]
	v_pk_add_f32 v[206:207], v[200:201], 0 op_sel_hi:[1,0]
	v_pk_fma_f32 v[200:201], v[200:201], s[84:85], v[208:209] op_sel_hi:[1,0,1] neg_lo:[0,0,1] neg_hi:[0,0,1]
	v_pk_add_f32 v[208:209], v[210:211], v[192:193]
	v_pk_add_f32 v[244:245], v[212:213], v[228:229]
	v_pk_add_f32 v[192:193], v[210:211], v[192:193] neg_lo:[0,1] neg_hi:[0,1]
	v_pk_add_f32 v[210:211], v[212:213], v[228:229] neg_lo:[0,1] neg_hi:[0,1]
	v_pk_add_f32 v[212:213], v[214:215], v[230:231]
	v_pk_add_f32 v[214:215], v[214:215], v[230:231] neg_lo:[0,1] neg_hi:[0,1]
	v_pk_add_f32 v[108:109], v[0:1], v[0:1]
	v_pk_add_f32 v[228:229], v[216:217], v[232:233]
	v_pk_add_f32 v[216:217], v[216:217], v[232:233] neg_lo:[0,1] neg_hi:[0,1]
	v_pk_mul_f32 v[214:215], v[214:215], s[82:83] op_sel_hi:[1,0]
	v_pk_mul_f32 v[0:1], v[14:15], v[108:109]
	v_pk_fma_f32 v[230:231], v[216:217], s[82:83], v[214:215] op_sel_hi:[1,0,1]
	v_pk_fma_f32 v[214:215], v[216:217], s[82:83], v[214:215] op_sel_hi:[1,0,1] neg_lo:[0,0,1] neg_hi:[0,0,1]
	v_pk_add_f32 v[216:217], v[188:189], v[204:205]
	v_pk_add_f32 v[232:233], v[220:221], v[236:237]
	v_pk_add_f32 v[188:189], v[188:189], v[204:205] neg_lo:[0,1] neg_hi:[0,1]
	v_pk_add_f32 v[204:205], v[220:221], v[236:237] neg_lo:[0,1] neg_hi:[0,1]
	v_pk_add_f32 v[220:221], v[190:191], v[206:207]
	v_pk_add_f32 v[190:191], v[190:191], v[206:207] neg_lo:[0,1] neg_hi:[0,1]
	v_pk_add_f32 v[206:207], v[224:225], v[240:241] neg_lo:[0,1] neg_hi:[0,1]
	v_pk_fma_f32 v[4:5], v[12:13], v[106:107], v[0:1] neg_lo:[0,0,1] neg_hi:[0,0,1]
	v_pk_mul_f32 v[0:1], v[14:15], v[106:107]
	v_pk_add_f32 v[236:237], v[224:225], v[240:241]
	v_pk_mul_f32 v[206:207], v[206:207], s[54:55] op_sel_hi:[1,0]
	v_pk_add_f32 v[240:241], v[144:145], v[194:195] neg_lo:[0,1] neg_hi:[0,1]
	v_pk_add_f32 v[144:145], v[144:145], v[194:195]
	v_pk_add_f32 v[194:195], v[218:219], v[234:235]
	v_pk_add_f32 v[218:219], v[218:219], v[234:235] neg_lo:[0,1] neg_hi:[0,1]
	v_pk_fma_f32 v[10:11], v[12:13], v[108:109], v[0:1]
	v_pk_mul_f32 v[0:1], v[108:109], v[108:109]
	v_pk_fma_f32 v[224:225], v[190:191], s[54:55], v[206:207] op_sel_hi:[1,0,1] neg_lo:[0,0,1] neg_hi:[0,0,1]
	v_pk_fma_f32 v[190:191], v[190:191], s[54:55], v[206:207] op_sel_hi:[1,0,1]
	v_pk_add_f32 v[206:207], v[136:137], v[202:203]
	v_pk_add_f32 v[136:137], v[136:137], v[202:203] neg_lo:[0,1] neg_hi:[0,1]
	v_pk_add_f32 v[202:203], v[138:139], v[196:197]
	v_pk_add_f32 v[138:139], v[138:139], v[196:197] neg_lo:[0,1] neg_hi:[0,1]
	v_pk_mul_f32 v[196:197], v[218:219], s[82:83] op_sel_hi:[1,0]
	v_pk_fma_f32 v[110:111], v[106:107], v[106:107], v[0:1] neg_lo:[0,0,1] neg_hi:[0,0,1]
	v_pk_mul_f32 v[0:1], v[106:107], v[108:109]
	v_pk_fma_f32 v[218:219], v[138:139], s[82:83], v[196:197] op_sel_hi:[1,0,1]
	v_pk_fma_f32 v[138:139], v[138:139], s[82:83], v[196:197] op_sel_hi:[1,0,1] neg_lo:[0,0,1] neg_hi:[0,0,1]
	v_pk_add_f32 v[196:197], v[222:223], v[238:239]
	v_pk_add_f32 v[222:223], v[222:223], v[238:239] neg_lo:[0,1] neg_hi:[0,1]
	v_pk_add_f32 v[238:239], v[142:143], v[200:201]
	v_pk_add_f32 v[142:143], v[142:143], v[200:201] neg_lo:[0,1] neg_hi:[0,1]
	v_pk_add_f32 v[112:113], v[0:1], v[0:1]
	v_pk_add_f32 v[234:235], v[140:141], v[198:199]
	v_pk_add_f32 v[140:141], v[140:141], v[198:199] neg_lo:[0,1] neg_hi:[0,1]
	v_pk_add_f32 v[198:199], v[226:227], v[242:243]
	v_pk_add_f32 v[226:227], v[226:227], v[242:243] neg_lo:[0,1] neg_hi:[0,1]
	v_pk_mul_f32 v[142:143], v[142:143], s[54:55] op_sel_hi:[1,0]
	v_pk_mul_f32 v[0:1], v[14:15], v[112:113]
	v_pk_mul_f32 v[6:7], v[112:113], v[112:113]
	v_pk_mul_f32 v[8:9], v[110:111], v[112:113]
	v_pk_fma_f32 v[200:201], v[226:227], s[54:55], v[142:143] op_sel_hi:[1,0,1] neg_lo:[0,0,1] neg_hi:[0,0,1]
	v_pk_fma_f32 v[142:143], v[226:227], s[54:55], v[142:143] op_sel_hi:[1,0,1]
	v_pk_add_f32 v[226:227], v[208:209], v[216:217]
	v_pk_add_f32 v[242:243], v[244:245], v[232:233]
	v_pk_add_f32 v[208:209], v[208:209], v[216:217] neg_lo:[0,1] neg_hi:[0,1]
	v_pk_add_f32 v[216:217], v[244:245], v[232:233] neg_lo:[0,1] neg_hi:[0,1]
	v_pk_add_f32 v[232:233], v[212:213], v[220:221]
	v_pk_add_f32 v[244:245], v[228:229], v[236:237]
	v_pk_fma_f32 v[16:17], v[12:13], v[110:111], v[0:1] neg_lo:[0,0,1] neg_hi:[0,0,1]
	v_pk_mul_f32 v[0:1], v[14:15], v[110:111]
	v_pk_fma_f32 v[6:7], v[110:111], v[110:111], v[6:7] neg_lo:[0,0,1] neg_hi:[0,0,1]
	v_pk_add_f32 v[8:9], v[8:9], v[8:9]
	v_pk_add_f32 v[212:213], v[212:213], v[220:221] neg_lo:[0,1] neg_hi:[0,1]
	v_pk_add_f32 v[220:221], v[228:229], v[236:237] neg_lo:[0,1] neg_hi:[0,1]
	v_pk_add_f32 v[228:229], v[192:193], v[204:205]
	v_pk_add_f32 v[236:237], v[210:211], v[188:189] neg_lo:[0,1] neg_hi:[0,1]
	v_pk_add_f32 v[192:193], v[192:193], v[204:205] neg_lo:[0,1] neg_hi:[0,1]
	v_pk_add_f32 v[188:189], v[210:211], v[188:189]
	v_pk_add_f32 v[204:205], v[230:231], v[224:225]
	v_pk_add_f32 v[210:211], v[214:215], v[190:191]
	v_pk_add_f32 v[224:225], v[230:231], v[224:225] neg_lo:[0,1] neg_hi:[0,1]
	v_pk_add_f32 v[190:191], v[214:215], v[190:191] neg_lo:[0,1] neg_hi:[0,1]
	v_pk_add_f32 v[214:215], v[206:207], v[196:197]
	v_pk_add_f32 v[230:231], v[240:241], v[234:235]
	v_pk_add_f32 v[196:197], v[206:207], v[196:197] neg_lo:[0,1] neg_hi:[0,1]
	v_pk_add_f32 v[206:207], v[240:241], v[234:235] neg_lo:[0,1] neg_hi:[0,1]
	v_pk_add_f32 v[234:235], v[194:195], v[198:199]
	v_pk_add_f32 v[240:241], v[202:203], v[238:239]
	v_pk_add_f32 v[194:195], v[194:195], v[198:199] neg_lo:[0,1] neg_hi:[0,1]
	v_pk_add_f32 v[198:199], v[202:203], v[238:239] neg_lo:[0,1] neg_hi:[0,1]
	v_pk_add_f32 v[202:203], v[136:137], v[140:141]
	v_pk_add_f32 v[238:239], v[144:145], v[222:223] neg_lo:[0,1] neg_hi:[0,1]
	v_pk_add_f32 v[136:137], v[136:137], v[140:141] neg_lo:[0,1] neg_hi:[0,1]
	v_pk_add_f32 v[140:141], v[144:145], v[222:223]
	v_pk_add_f32 v[144:145], v[218:219], v[200:201]
	v_pk_add_f32 v[222:223], v[138:139], v[142:143]
	v_pk_add_f32 v[200:201], v[218:219], v[200:201] neg_lo:[0,1] neg_hi:[0,1]
	v_pk_add_f32 v[138:139], v[138:139], v[142:143] neg_lo:[0,1] neg_hi:[0,1]
	v_pk_add_f32 v[142:143], v[226:227], v[232:233]
	v_pk_add_f32 v[218:219], v[242:243], v[244:245]
	v_pk_add_f32 v[226:227], v[226:227], v[232:233] neg_lo:[0,1] neg_hi:[0,1]
	v_pk_add_f32 v[232:233], v[242:243], v[244:245] neg_lo:[0,1] neg_hi:[0,1]
	v_pk_fma_f32 v[18:19], v[12:13], v[112:113], v[0:1]
	v_pk_mul_f32 v[0:1], v[108:109], v[112:113]
	ds_write_b64 v164, v[142:143]
	ds_write_b64 v165, v[218:219]
	v_pk_mul_f32 v[142:143], v[6:7], v[232:233]
	v_pk_mul_f32 v[218:219], v[8:9], v[232:233]
	v_pk_fma_f32 v[114:115], v[106:107], v[110:111], v[0:1] neg_lo:[0,0,1] neg_hi:[0,0,1]
	v_pk_mul_f32 v[0:1], v[108:109], v[110:111]
	v_pk_mul_f32 v[2:3], v[110:111], v[10:11]
	v_pk_add_f32 v[242:243], v[208:209], v[220:221]
	v_pk_add_f32 v[244:245], v[216:217], v[212:213] neg_lo:[0,1] neg_hi:[0,1]
	v_pk_fma_f32 v[142:143], v[8:9], v[226:227], v[142:143]
	v_pk_fma_f32 v[218:219], v[6:7], v[226:227], v[218:219] neg_lo:[0,0,1] neg_hi:[0,0,1]
	v_pk_fma_f32 v[116:117], v[106:107], v[112:113], v[0:1]
	v_pk_mul_f32 v[0:1], v[112:113], v[10:11]
	v_pk_fma_f32 v[2:3], v[112:113], v[4:5], v[2:3]
	v_pk_mul_f32 v[124:125], v[112:113], v[8:9]
	v_pk_mul_f32 v[126:127], v[112:113], v[6:7]
	ds_write_b64 v164, v[218:219] offset:34816
	ds_write_b64 v165, v[142:143] offset:34816
	v_pk_mul_f32 v[142:143], v[112:113], v[242:243]
	v_pk_mul_f32 v[112:113], v[112:113], v[244:245]
	v_pk_fma_f32 v[0:1], v[110:111], v[4:5], v[0:1] neg_lo:[0,0,1] neg_hi:[0,0,1]
	v_pk_mul_f32 v[20:21], v[14:15], v[8:9]
	v_pk_fma_f32 v[124:125], v[110:111], v[6:7], v[124:125] neg_lo:[0,0,1] neg_hi:[0,0,1]
	v_pk_fma_f32 v[126:127], v[110:111], v[8:9], v[126:127]
	v_pk_add_f32 v[208:209], v[208:209], v[220:221] neg_lo:[0,1] neg_hi:[0,1]
	v_pk_add_f32 v[212:213], v[216:217], v[212:213]
	v_pk_fma_f32 v[142:143], v[110:111], v[244:245], v[142:143]
	v_pk_fma_f32 v[110:111], v[110:111], v[242:243], v[112:113] neg_lo:[0,0,1] neg_hi:[0,0,1]
	v_pk_fma_f32 v[104:105], v[12:13], v[6:7], v[20:21] neg_lo:[0,0,1] neg_hi:[0,0,1]
	v_pk_mul_f32 v[20:21], v[14:15], v[6:7]
	ds_write_b64 v164, v[110:111] offset:17408
	ds_write_b64 v165, v[142:143] offset:17408
	v_pk_mul_f32 v[110:111], v[126:127], v[208:209]
	v_pk_mul_f32 v[112:113], v[126:127], v[212:213]
	v_pk_fma_f32 v[118:119], v[12:13], v[8:9], v[20:21]
	v_pk_mul_f32 v[20:21], v[108:109], v[8:9]
	v_pk_add_f32 v[216:217], v[228:229], v[204:205]
	v_pk_add_f32 v[220:221], v[236:237], v[210:211]
	v_pk_fma_f32 v[110:111], v[124:125], v[212:213], v[110:111]
	v_pk_fma_f32 v[112:113], v[124:125], v[208:209], v[112:113] neg_lo:[0,0,1] neg_hi:[0,0,1]
	v_pk_fma_f32 v[120:121], v[106:107], v[6:7], v[20:21] neg_lo:[0,0,1] neg_hi:[0,0,1]
	v_pk_mul_f32 v[20:21], v[108:109], v[6:7]
	ds_write_b64 v164, v[112:113] offset:52224
	ds_write_b64 v165, v[110:111] offset:52224
	v_pk_mul_f32 v[110:111], v[108:109], v[216:217]
	v_pk_mul_f32 v[108:109], v[108:109], v[220:221]
	v_pk_fma_f32 v[122:123], v[106:107], v[8:9], v[20:21]
	v_pk_add_f32 v[204:205], v[228:229], v[204:205] neg_lo:[0,1] neg_hi:[0,1]
	v_pk_add_f32 v[210:211], v[236:237], v[210:211] neg_lo:[0,1] neg_hi:[0,1]
	v_pk_fma_f32 v[110:111], v[106:107], v[220:221], v[110:111]
	v_pk_fma_f32 v[106:107], v[106:107], v[216:217], v[108:109] neg_lo:[0,0,1] neg_hi:[0,0,1]
	ds_write_b64 v164, v[106:107] offset:8704
	ds_write_b64 v165, v[110:111] offset:8704
	v_pk_mul_f32 v[106:107], v[122:123], v[204:205]
	v_pk_mul_f32 v[108:109], v[122:123], v[210:211]
	v_pk_add_f32 v[228:229], v[192:193], v[190:191]
	v_pk_add_f32 v[236:237], v[188:189], v[224:225] neg_lo:[0,1] neg_hi:[0,1]
	v_pk_fma_f32 v[106:107], v[120:121], v[210:211], v[106:107]
	v_pk_fma_f32 v[108:109], v[120:121], v[204:205], v[108:109] neg_lo:[0,0,1] neg_hi:[0,0,1]
	v_pk_mul_f32 v[134:135], v[6:7], v[116:117]
	ds_write_b64 v164, v[108:109] offset:43520
	ds_write_b64 v165, v[106:107] offset:43520
	v_pk_mul_f32 v[106:107], v[116:117], v[228:229]
	v_pk_mul_f32 v[108:109], v[116:117], v[236:237]
	v_pk_mul_f32 v[132:133], v[8:9], v[116:117]
	v_pk_fma_f32 v[134:135], v[8:9], v[114:115], v[134:135]
	v_pk_add_f32 v[190:191], v[192:193], v[190:191] neg_lo:[0,1] neg_hi:[0,1]
	v_pk_add_f32 v[188:189], v[188:189], v[224:225]
	v_pk_fma_f32 v[106:107], v[114:115], v[236:237], v[106:107]
	v_pk_fma_f32 v[108:109], v[114:115], v[228:229], v[108:109] neg_lo:[0,0,1] neg_hi:[0,0,1]
	v_pk_fma_f32 v[132:133], v[6:7], v[114:115], v[132:133] neg_lo:[0,0,1] neg_hi:[0,0,1]
	ds_write_b64 v164, v[108:109] offset:26112
	ds_write_b64 v165, v[106:107] offset:26112
	v_pk_mul_f32 v[106:107], v[134:135], v[190:191]
	v_pk_mul_f32 v[108:109], v[134:135], v[188:189]
	v_pk_add_f32 v[192:193], v[214:215], v[234:235]
	v_pk_add_f32 v[224:225], v[230:231], v[240:241]
	v_pk_fma_f32 v[106:107], v[132:133], v[188:189], v[106:107]
	v_pk_fma_f32 v[108:109], v[132:133], v[190:191], v[108:109] neg_lo:[0,0,1] neg_hi:[0,0,1]
	ds_write_b64 v164, v[108:109] offset:60928
	ds_write_b64 v165, v[106:107] offset:60928
	v_pk_mul_f32 v[106:107], v[14:15], v[192:193]
	v_pk_mul_f32 v[14:15], v[14:15], v[224:225]
	v_pk_add_f32 v[214:215], v[214:215], v[234:235] neg_lo:[0,1] neg_hi:[0,1]
	v_pk_add_f32 v[230:231], v[230:231], v[240:241] neg_lo:[0,1] neg_hi:[0,1]
	v_pk_fma_f32 v[106:107], v[12:13], v[224:225], v[106:107]
	v_pk_fma_f32 v[12:13], v[12:13], v[192:193], v[14:15] neg_lo:[0,0,1] neg_hi:[0,0,1]
	ds_write_b64 v164, v[12:13] offset:4352
	ds_write_b64 v165, v[106:107] offset:4352
	v_pk_mul_f32 v[12:13], v[118:119], v[214:215]
	v_pk_mul_f32 v[14:15], v[118:119], v[230:231]
	v_pk_add_f32 v[234:235], v[196:197], v[198:199]
	v_pk_add_f32 v[240:241], v[206:207], v[194:195] neg_lo:[0,1] neg_hi:[0,1]
	v_pk_fma_f32 v[12:13], v[104:105], v[230:231], v[12:13]
	v_pk_fma_f32 v[14:15], v[104:105], v[214:215], v[14:15] neg_lo:[0,0,1] neg_hi:[0,0,1]
	v_pk_mul_f32 v[130:131], v[6:7], v[18:19]
	ds_write_b64 v164, v[14:15] offset:39168
	ds_write_b64 v165, v[12:13] offset:39168
	v_pk_mul_f32 v[12:13], v[18:19], v[234:235]
	v_pk_mul_f32 v[14:15], v[18:19], v[240:241]
	v_pk_mul_f32 v[128:129], v[8:9], v[18:19]
	v_pk_fma_f32 v[130:131], v[8:9], v[16:17], v[130:131]
	v_pk_add_f32 v[196:197], v[196:197], v[198:199] neg_lo:[0,1] neg_hi:[0,1]
	v_pk_add_f32 v[194:195], v[206:207], v[194:195]
	v_pk_fma_f32 v[12:13], v[16:17], v[240:241], v[12:13]
	v_pk_fma_f32 v[14:15], v[16:17], v[234:235], v[14:15] neg_lo:[0,0,1] neg_hi:[0,0,1]
	v_pk_fma_f32 v[128:129], v[6:7], v[16:17], v[128:129] neg_lo:[0,0,1] neg_hi:[0,0,1]
	ds_write_b64 v164, v[14:15] offset:21760
	ds_write_b64 v165, v[12:13] offset:21760
	v_pk_mul_f32 v[12:13], v[130:131], v[196:197]
	v_pk_mul_f32 v[14:15], v[130:131], v[194:195]
	v_pk_mul_f32 v[22:23], v[10:11], v[6:7]
	v_pk_add_f32 v[198:199], v[202:203], v[144:145]
	v_pk_add_f32 v[206:207], v[238:239], v[222:223]
	v_pk_fma_f32 v[12:13], v[128:129], v[194:195], v[12:13]
	v_pk_fma_f32 v[14:15], v[128:129], v[196:197], v[14:15] neg_lo:[0,0,1] neg_hi:[0,0,1]
	v_pk_mul_f32 v[20:21], v[10:11], v[8:9]
	v_pk_fma_f32 v[22:23], v[4:5], v[8:9], v[22:23]
	v_pk_add_f32 v[144:145], v[202:203], v[144:145] neg_lo:[0,1] neg_hi:[0,1]
	v_pk_add_f32 v[202:203], v[238:239], v[222:223] neg_lo:[0,1] neg_hi:[0,1]
	ds_write_b64 v164, v[14:15] offset:56576
	ds_write_b64 v165, v[12:13] offset:56576
	v_pk_mul_f32 v[12:13], v[10:11], v[198:199]
	v_pk_mul_f32 v[10:11], v[10:11], v[206:207]
	v_pk_fma_f32 v[20:21], v[4:5], v[6:7], v[20:21] neg_lo:[0,0,1] neg_hi:[0,0,1]
	v_pk_fma_f32 v[12:13], v[4:5], v[206:207], v[12:13]
	v_pk_fma_f32 v[4:5], v[4:5], v[198:199], v[10:11] neg_lo:[0,0,1] neg_hi:[0,0,1]
	v_pk_mul_f32 v[10:11], v[22:23], v[202:203]
	v_pk_add_f32 v[238:239], v[140:141], v[200:201] neg_lo:[0,1] neg_hi:[0,1]
	ds_write_b64 v164, v[4:5] offset:13056
	ds_write_b64 v165, v[12:13] offset:13056
	v_pk_mul_f32 v[4:5], v[22:23], v[144:145]
	v_pk_fma_f32 v[10:11], v[20:21], v[144:145], v[10:11] neg_lo:[0,0,1] neg_hi:[0,0,1]
	v_pk_add_f32 v[222:223], v[136:137], v[138:139]
	v_pk_fma_f32 v[4:5], v[20:21], v[202:203], v[4:5]
	ds_write_b64 v164, v[10:11] offset:47872
	ds_write_b64 v165, v[4:5] offset:47872
	v_pk_mul_f32 v[10:11], v[2:3], v[238:239]
	v_pk_mul_f32 v[4:5], v[2:3], v[222:223]
	v_pk_fma_f32 v[10:11], v[0:1], v[222:223], v[10:11] neg_lo:[0,0,1] neg_hi:[0,0,1]
	v_pk_fma_f32 v[4:5], v[0:1], v[238:239], v[4:5]
	ds_write_b64 v164, v[10:11] offset:30464
	ds_write_b64 v165, v[4:5] offset:30464
	v_pk_mul_f32 v[10:11], v[8:9], v[2:3]
	v_pk_mul_f32 v[2:3], v[6:7], v[2:3]
	v_pk_add_f32 v[4:5], v[140:141], v[200:201]
	v_pk_fma_f32 v[10:11], v[6:7], v[0:1], v[10:11] neg_lo:[0,0,1] neg_hi:[0,0,1]
	v_pk_add_f32 v[12:13], v[136:137], v[138:139] neg_lo:[0,1] neg_hi:[0,1]
	v_pk_fma_f32 v[0:1], v[8:9], v[0:1], v[2:3]
	s_nop 0
	v_pk_mul_f32 v[2:3], v[0:1], v[12:13]
	v_pk_mul_f32 v[0:1], v[0:1], v[4:5]
	v_pk_fma_f32 v[2:3], v[10:11], v[4:5], v[2:3]
	v_pk_fma_f32 v[0:1], v[10:11], v[12:13], v[0:1] neg_lo:[0,0,1] neg_hi:[0,0,1]
	ds_write_b64 v164, v[0:1] offset:65280
	ds_write_b64 v165, v[2:3] offset:65280
	v_mov_b32_e32 v0, v163
	s_waitcnt lgkmcnt(0)
	s_barrier
	s_nop 0
	s_nop 0
	v_ashrrev_i32_e32 v2, 31, v0
	v_lshrrev_b32_e32 v2, 27, v2
	v_lshlrev_b32_e32 v1, 1, v0
	v_add_u32_e32 v0, v0, v2
	v_and_b32_e32 v1, 62, v1
	v_ashrrev_i32_e32 v0, 5, v0
	v_lshl_or_b32 v2, v0, 10, v1
	v_cvt_f32_ubyte0_e32 v3, v1
	v_or_b32_e32 v1, 1, v1
	v_cvt_f32_ubyte0_e32 v1, v1
	v_mul_f32_e32 v3, 0x3a800000, v3
	v_mul_f32_e32 v1, 0x3a800000, v1
	v_sin_f32_e64 v14, -v3
	v_sin_f32_e64 v15, -v1
	v_cos_f32_e32 v12, v3
	v_cos_f32_e32 v13, v1
	v_lshlrev_b32_e32 v0, 6, v0
	v_add_lshl_u32 v118, v2, v0, 2
	v_pk_mul_f32 v[0:1], v[14:15], v[14:15]
	v_add_u32_e32 v164, 0, v118
	v_pk_fma_f32 v[104:105], v[12:13], v[12:13], v[0:1] neg_lo:[0,0,1] neg_hi:[0,0,1]
	v_pk_mul_f32 v[0:1], v[12:13], v[14:15]
	v_add_u32_e32 v166, 0x800, v164
	v_pk_add_f32 v[106:107], v[0:1], v[0:1]
	v_add_u32_e32 v165, s91, v118
	v_pk_mul_f32 v[0:1], v[14:15], v[106:107]
	v_add_u32_e32 v167, 0x800, v165
	v_pk_fma_f32 v[4:5], v[12:13], v[104:105], v[0:1] neg_lo:[0,0,1] neg_hi:[0,0,1]
	v_pk_mul_f32 v[0:1], v[14:15], v[104:105]
	s_nop 0
	v_pk_fma_f32 v[10:11], v[12:13], v[106:107], v[0:1]
	v_pk_mul_f32 v[0:1], v[106:107], v[106:107]
	s_nop 0
	v_pk_fma_f32 v[144:145], v[104:105], v[104:105], v[0:1] neg_lo:[0,0,1] neg_hi:[0,0,1]
	v_pk_mul_f32 v[0:1], v[104:105], v[106:107]
	v_pk_mul_f32 v[2:3], v[144:145], v[10:11]
	v_pk_add_f32 v[224:225], v[0:1], v[0:1]
	s_nop 0
	v_pk_mul_f32 v[0:1], v[14:15], v[224:225]
	v_pk_mul_f32 v[6:7], v[224:225], v[224:225]
	v_pk_fma_f32 v[16:17], v[12:13], v[144:145], v[0:1] neg_lo:[0,0,1] neg_hi:[0,0,1]
	v_pk_mul_f32 v[0:1], v[14:15], v[144:145]
	v_pk_fma_f32 v[6:7], v[144:145], v[144:145], v[6:7] neg_lo:[0,0,1] neg_hi:[0,0,1]
	v_pk_fma_f32 v[18:19], v[12:13], v[224:225], v[0:1]
	v_pk_mul_f32 v[0:1], v[106:107], v[224:225]
	v_pk_mul_f32 v[8:9], v[144:145], v[224:225]
	v_pk_fma_f32 v[110:111], v[104:105], v[144:145], v[0:1] neg_lo:[0,0,1] neg_hi:[0,0,1]
	v_pk_mul_f32 v[0:1], v[106:107], v[144:145]
	v_pk_add_f32 v[8:9], v[8:9], v[8:9]
	v_pk_fma_f32 v[226:227], v[104:105], v[224:225], v[0:1]
	v_pk_mul_f32 v[116:117], v[6:7], v[18:19]
	v_pk_mul_f32 v[114:115], v[224:225], v[8:9]
	v_pk_fma_f32 v[236:237], v[8:9], v[16:17], v[116:117]
	v_pk_mul_f32 v[116:117], v[8:9], v[226:227]
	v_pk_mul_f32 v[20:21], v[14:15], v[8:9]
	v_pk_fma_f32 v[238:239], v[6:7], v[110:111], v[116:117] neg_lo:[0,0,1] neg_hi:[0,0,1]
	v_pk_mul_f32 v[116:117], v[6:7], v[226:227]
	v_pk_fma_f32 v[232:233], v[144:145], v[6:7], v[114:115] neg_lo:[0,0,1] neg_hi:[0,0,1]
	v_pk_fma_f32 v[240:241], v[8:9], v[110:111], v[116:117]
	ds_read2_b64 v[116:119], v164 offset1:34
	ds_read2_b64 v[120:123], v165 offset1:34
	ds_read2_b64 v[124:127], v164 offset0:68 offset1:102
	ds_read2_b64 v[128:131], v165 offset0:68 offset1:102
	ds_read2_b64 v[132:135], v164 offset0:136 offset1:170
	ds_read2_b64 v[136:139], v165 offset0:136 offset1:170
	ds_read2_b64 v[140:143], v164 offset0:204 offset1:238
	ds_read2_b64 v[188:191], v165 offset0:204 offset1:238
	ds_read2_b64 v[192:195], v166 offset0:16 offset1:50
	ds_read2_b64 v[196:199], v167 offset0:16 offset1:50
	ds_read2_b64 v[200:203], v166 offset0:84 offset1:118
	ds_read2_b64 v[204:207], v167 offset0:84 offset1:118
	ds_read2_b64 v[208:211], v166 offset0:152 offset1:186
	ds_read2_b64 v[212:215], v167 offset0:152 offset1:186
	ds_read2_b64 v[216:219], v166 offset0:220 offset1:254
	ds_read2_b64 v[220:223], v167 offset0:220 offset1:254
	s_waitcnt lgkmcnt(6)
	v_pk_add_f32 v[244:245], v[120:121], v[196:197]
	v_pk_add_f32 v[120:121], v[120:121], v[196:197] neg_lo:[0,1] neg_hi:[0,1]
	v_pk_mul_f32 v[114:115], v[224:225], v[6:7]
	v_pk_add_f32 v[242:243], v[116:117], v[192:193]
	v_pk_add_f32 v[116:117], v[116:117], v[192:193] neg_lo:[0,1] neg_hi:[0,1]
	v_pk_add_f32 v[192:193], v[118:119], v[194:195]
	v_pk_add_f32 v[118:119], v[118:119], v[194:195] neg_lo:[0,1] neg_hi:[0,1]
	v_pk_add_f32 v[194:195], v[122:123], v[198:199]
	v_pk_add_f32 v[122:123], v[122:123], v[198:199] neg_lo:[0,1] neg_hi:[0,1]
	s_waitcnt lgkmcnt(4)
	v_pk_add_f32 v[198:199], v[128:129], v[204:205]
	v_pk_mul_f32 v[196:197], v[122:123], s[80:81] op_sel_hi:[1,0]
	v_pk_add_f32 v[128:129], v[128:129], v[204:205] neg_lo:[0,1] neg_hi:[0,1]
	v_pk_fma_f32 v[196:197], v[118:119], s[72:73], v[196:197] op_sel_hi:[1,0,1]
	v_pk_mul_f32 v[118:119], v[118:119], s[80:81] op_sel_hi:[1,0]
	v_pk_mul_f32 v[0:1], v[224:225], v[10:11]
	v_pk_fma_f32 v[118:119], v[122:123], s[72:73], v[118:119] op_sel_hi:[1,0,1] neg_lo:[0,0,1] neg_hi:[0,0,1]
	v_pk_add_f32 v[122:123], v[124:125], v[200:201]
	v_pk_add_f32 v[124:125], v[124:125], v[200:201] neg_lo:[0,1] neg_hi:[0,1]
	v_pk_add_f32 v[200:201], v[126:127], v[202:203]
	v_pk_mul_f32 v[124:125], v[124:125], s[82:83] op_sel_hi:[1,0]
	v_pk_add_f32 v[126:127], v[126:127], v[202:203] neg_lo:[0,1] neg_hi:[0,1]
	v_pk_fma_f32 v[202:203], v[128:129], s[82:83], v[124:125] op_sel_hi:[1,0,1]
	v_pk_fma_f32 v[124:125], v[128:129], s[82:83], v[124:125] op_sel_hi:[1,0,1] neg_lo:[0,0,1] neg_hi:[0,0,1]
	v_pk_add_f32 v[128:129], v[130:131], v[206:207]
	v_pk_add_f32 v[130:131], v[130:131], v[206:207] neg_lo:[0,1] neg_hi:[0,1]
	s_waitcnt lgkmcnt(2)
	v_pk_add_f32 v[206:207], v[136:137], v[212:213]
	v_pk_mul_f32 v[204:205], v[130:131], s[72:73] op_sel_hi:[1,0]
	v_pk_add_f32 v[136:137], v[136:137], v[212:213] neg_lo:[0,1] neg_hi:[0,1]
	v_pk_fma_f32 v[204:205], v[126:127], s[80:81], v[204:205] op_sel_hi:[1,0,1]
	v_pk_mul_f32 v[126:127], v[126:127], s[72:73] op_sel_hi:[1,0]
	v_pk_fma_f32 v[108:109], v[12:13], v[6:7], v[20:21] neg_lo:[0,0,1] neg_hi:[0,0,1]
	v_pk_fma_f32 v[126:127], v[130:131], s[80:81], v[126:127] op_sel_hi:[1,0,1] neg_lo:[0,0,1] neg_hi:[0,0,1]
	v_pk_add_f32 v[130:131], v[132:133], v[208:209]
	v_pk_add_f32 v[132:133], v[132:133], v[208:209] neg_lo:[0,1] neg_hi:[0,1]
	v_pk_add_f32 v[208:209], v[134:135], v[210:211]
	v_pk_add_f32 v[134:135], v[134:135], v[210:211] neg_lo:[0,1] neg_hi:[0,1]
	v_pk_add_f32 v[210:211], v[138:139], v[214:215]
	v_pk_add_f32 v[138:139], v[138:139], v[214:215] neg_lo:[0,1] neg_hi:[0,1]
	v_pk_mul_f32 v[212:213], v[134:135], s[80:81] op_sel_hi:[1,0]
	s_waitcnt lgkmcnt(0)
	v_pk_add_f32 v[214:215], v[188:189], v[220:221]
	v_pk_fma_f32 v[212:213], v[138:139], s[72:73], v[212:213] op_sel_hi:[1,0,1] neg_lo:[0,0,1] neg_hi:[0,0,1]
	v_pk_mul_f32 v[138:139], v[138:139], s[80:81] op_sel_hi:[1,0]
	v_pk_add_f32 v[188:189], v[188:189], v[220:221] neg_lo:[0,1] neg_hi:[0,1]
	v_pk_fma_f32 v[134:135], v[134:135], s[52:53], v[138:139] op_sel_hi:[1,0,1] neg_lo:[0,0,1] neg_hi:[0,0,1]
	v_pk_add_f32 v[138:139], v[140:141], v[216:217]
	v_pk_add_f32 v[140:141], v[140:141], v[216:217] neg_lo:[0,1] neg_hi:[0,1]
	v_pk_add_f32 v[216:217], v[142:143], v[218:219]
	v_pk_add_f32 v[142:143], v[142:143], v[218:219] neg_lo:[0,1] neg_hi:[0,1]
	v_pk_mul_f32 v[188:189], v[188:189], s[54:55] op_sel_hi:[1,0]
	v_pk_mul_f32 v[220:221], v[142:143], s[72:73] op_sel_hi:[1,0]
	v_pk_fma_f32 v[218:219], v[140:141], s[54:55], v[188:189] op_sel_hi:[1,0,1] neg_lo:[0,0,1] neg_hi:[0,0,1]
	v_pk_fma_f32 v[140:141], v[140:141], s[54:55], v[188:189] op_sel_hi:[1,0,1]
	v_pk_add_f32 v[188:189], v[190:191], v[222:223]
	v_pk_add_f32 v[190:191], v[190:191], v[222:223] neg_lo:[0,1] neg_hi:[0,1]
	v_pk_add_f32 v[222:223], v[244:245], v[206:207]
	v_pk_fma_f32 v[220:221], v[190:191], s[80:81], v[220:221] op_sel_hi:[1,0,1] neg_lo:[0,0,1] neg_hi:[0,0,1]
	v_pk_mul_f32 v[190:191], v[190:191], s[72:73] op_sel_hi:[1,0]
	v_pk_add_f32 v[206:207], v[244:245], v[206:207] neg_lo:[0,1] neg_hi:[0,1]
	v_pk_fma_f32 v[142:143], v[142:143], s[84:85], v[190:191] op_sel_hi:[1,0,1] neg_lo:[0,0,1] neg_hi:[0,0,1]
	v_pk_add_f32 v[190:191], v[242:243], v[130:131]
	v_pk_add_f32 v[130:131], v[242:243], v[130:131] neg_lo:[0,1] neg_hi:[0,1]
	v_pk_add_f32 v[242:243], v[192:193], v[208:209]
	v_pk_add_f32 v[192:193], v[192:193], v[208:209] neg_lo:[0,1] neg_hi:[0,1]
	v_pk_add_f32 v[244:245], v[194:195], v[210:211]
	v_pk_add_f32 v[194:195], v[194:195], v[210:211] neg_lo:[0,1] neg_hi:[0,1]
	v_pk_mul_f32 v[192:193], v[192:193], s[82:83] op_sel_hi:[1,0]
	v_pk_add_f32 v[210:211], v[198:199], v[214:215]
	v_pk_fma_f32 v[208:209], v[194:195], s[82:83], v[192:193] op_sel_hi:[1,0,1]
	v_pk_fma_f32 v[192:193], v[194:195], s[82:83], v[192:193] op_sel_hi:[1,0,1] neg_lo:[0,0,1] neg_hi:[0,0,1]
	v_pk_add_f32 v[194:195], v[122:123], v[138:139]
	v_pk_add_f32 v[122:123], v[122:123], v[138:139] neg_lo:[0,1] neg_hi:[0,1]
	v_pk_add_f32 v[138:139], v[198:199], v[214:215] neg_lo:[0,1] neg_hi:[0,1]
	v_pk_add_f32 v[214:215], v[128:129], v[188:189]
	v_pk_add_f32 v[128:129], v[128:129], v[188:189] neg_lo:[0,1] neg_hi:[0,1]
	v_pk_add_f32 v[198:199], v[200:201], v[216:217]
	v_pk_add_f32 v[200:201], v[200:201], v[216:217] neg_lo:[0,1] neg_hi:[0,1]
	v_pk_mul_f32 v[128:129], v[128:129], s[54:55] op_sel_hi:[1,0]
	v_pk_add_f32 v[216:217], v[120:121], v[132:133] neg_lo:[0,1] neg_hi:[0,1]
	v_pk_add_f32 v[120:121], v[120:121], v[132:133]
	v_pk_add_f32 v[132:133], v[196:197], v[212:213]
	v_pk_add_f32 v[196:197], v[196:197], v[212:213] neg_lo:[0,1] neg_hi:[0,1]
	v_pk_fma_f32 v[188:189], v[200:201], s[54:55], v[128:129] op_sel_hi:[1,0,1] neg_lo:[0,0,1] neg_hi:[0,0,1]
	v_pk_fma_f32 v[128:129], v[200:201], s[54:55], v[128:129] op_sel_hi:[1,0,1]
	v_pk_add_f32 v[200:201], v[116:117], v[136:137]
	v_pk_add_f32 v[116:117], v[116:117], v[136:137] neg_lo:[0,1] neg_hi:[0,1]
	v_pk_add_f32 v[136:137], v[118:119], v[134:135]
	v_pk_add_f32 v[118:119], v[118:119], v[134:135] neg_lo:[0,1] neg_hi:[0,1]
	v_pk_mul_f32 v[134:135], v[196:197], s[82:83] op_sel_hi:[1,0]
	v_pk_add_f32 v[212:213], v[124:125], v[140:141]
	v_pk_fma_f32 v[196:197], v[118:119], s[82:83], v[134:135] op_sel_hi:[1,0,1]
	v_pk_fma_f32 v[118:119], v[118:119], s[82:83], v[134:135] op_sel_hi:[1,0,1] neg_lo:[0,0,1] neg_hi:[0,0,1]
	v_pk_add_f32 v[134:135], v[202:203], v[218:219]
	v_pk_add_f32 v[202:203], v[202:203], v[218:219] neg_lo:[0,1] neg_hi:[0,1]
	v_pk_add_f32 v[218:219], v[126:127], v[142:143]
	v_pk_add_f32 v[126:127], v[126:127], v[142:143] neg_lo:[0,1] neg_hi:[0,1]
	v_pk_add_f32 v[124:125], v[124:125], v[140:141] neg_lo:[0,1] neg_hi:[0,1]
	v_pk_add_f32 v[140:141], v[204:205], v[220:221]
	v_pk_add_f32 v[204:205], v[204:205], v[220:221] neg_lo:[0,1] neg_hi:[0,1]
	v_pk_mul_f32 v[126:127], v[126:127], s[54:55] op_sel_hi:[1,0]
	v_pk_add_f32 v[220:221], v[222:223], v[210:211]
	v_pk_fma_f32 v[142:143], v[204:205], s[54:55], v[126:127] op_sel_hi:[1,0,1] neg_lo:[0,0,1] neg_hi:[0,0,1]
	v_pk_fma_f32 v[126:127], v[204:205], s[54:55], v[126:127] op_sel_hi:[1,0,1]
	v_pk_add_f32 v[204:205], v[190:191], v[194:195]
	v_pk_add_f32 v[190:191], v[190:191], v[194:195] neg_lo:[0,1] neg_hi:[0,1]
	v_pk_add_f32 v[194:195], v[222:223], v[210:211] neg_lo:[0,1] neg_hi:[0,1]
	v_pk_add_f32 v[210:211], v[242:243], v[198:199]
	v_pk_add_f32 v[222:223], v[244:245], v[214:215]
	v_pk_add_f32 v[198:199], v[242:243], v[198:199] neg_lo:[0,1] neg_hi:[0,1]
	v_pk_add_f32 v[214:215], v[244:245], v[214:215] neg_lo:[0,1] neg_hi:[0,1]
	v_pk_add_f32 v[242:243], v[130:131], v[138:139]
	v_pk_add_f32 v[244:245], v[206:207], v[122:123] neg_lo:[0,1] neg_hi:[0,1]
	v_pk_add_f32 v[130:131], v[130:131], v[138:139] neg_lo:[0,1] neg_hi:[0,1]
	v_pk_add_f32 v[122:123], v[206:207], v[122:123]
	v_pk_add_f32 v[138:139], v[208:209], v[188:189]
	v_pk_add_f32 v[206:207], v[192:193], v[128:129]
	v_pk_add_f32 v[188:189], v[208:209], v[188:189] neg_lo:[0,1] neg_hi:[0,1]
	v_pk_add_f32 v[128:129], v[192:193], v[128:129] neg_lo:[0,1] neg_hi:[0,1]
	v_pk_add_f32 v[192:193], v[200:201], v[134:135]
	v_pk_add_f32 v[208:209], v[216:217], v[212:213]
	v_pk_add_f32 v[134:135], v[200:201], v[134:135] neg_lo:[0,1] neg_hi:[0,1]
	v_pk_add_f32 v[200:201], v[216:217], v[212:213] neg_lo:[0,1] neg_hi:[0,1]
	v_pk_add_f32 v[216:217], v[136:137], v[218:219]
	v_pk_add_f32 v[136:137], v[136:137], v[218:219] neg_lo:[0,1] neg_hi:[0,1]
	v_pk_add_f32 v[218:219], v[120:121], v[202:203] neg_lo:[0,1] neg_hi:[0,1]
	v_pk_add_f32 v[120:121], v[120:121], v[202:203]
	v_pk_add_f32 v[202:203], v[118:119], v[126:127]
	v_pk_add_f32 v[118:119], v[118:119], v[126:127] neg_lo:[0,1] neg_hi:[0,1]
	v_pk_add_f32 v[126:127], v[204:205], v[210:211]
	v_pk_add_f32 v[204:205], v[204:205], v[210:211] neg_lo:[0,1] neg_hi:[0,1]
	v_pk_add_f32 v[210:211], v[220:221], v[222:223] neg_lo:[0,1] neg_hi:[0,1]
	v_pk_add_f32 v[212:213], v[132:133], v[140:141]
	v_pk_add_f32 v[132:133], v[132:133], v[140:141] neg_lo:[0,1] neg_hi:[0,1]
	v_pk_add_f32 v[140:141], v[116:117], v[124:125]
	v_pk_add_f32 v[116:117], v[116:117], v[124:125] neg_lo:[0,1] neg_hi:[0,1]
	v_pk_add_f32 v[124:125], v[196:197], v[142:143]
	v_pk_add_f32 v[142:143], v[196:197], v[142:143] neg_lo:[0,1] neg_hi:[0,1]
	v_pk_add_f32 v[196:197], v[220:221], v[222:223]
	v_pk_add_f32 v[220:221], v[190:191], v[214:215]
	v_pk_mul_f32 v[246:247], v[6:7], v[210:211]
	v_pk_mul_f32 v[210:211], v[8:9], v[210:211]
	v_pk_add_f32 v[222:223], v[194:195], v[198:199] neg_lo:[0,1] neg_hi:[0,1]
	v_pk_fma_f32 v[246:247], v[8:9], v[204:205], v[246:247]
	v_pk_fma_f32 v[204:205], v[6:7], v[204:205], v[210:211] neg_lo:[0,0,1] neg_hi:[0,0,1]
	v_pk_mul_f32 v[210:211], v[224:225], v[220:221]
	v_pk_mul_f32 v[20:21], v[14:15], v[6:7]
	v_pk_fma_f32 v[234:235], v[144:145], v[8:9], v[114:115]
	v_pk_add_f32 v[190:191], v[190:191], v[214:215] neg_lo:[0,1] neg_hi:[0,1]
	v_pk_fma_f32 v[210:211], v[144:145], v[222:223], v[210:211]
	v_pk_mul_f32 v[222:223], v[224:225], v[222:223]
	v_pk_fma_f32 v[0:1], v[144:145], v[4:5], v[0:1] neg_lo:[0,0,1] neg_hi:[0,0,1]
	v_pk_fma_f32 v[112:113], v[12:13], v[8:9], v[20:21]
	v_pk_mul_f32 v[20:21], v[106:107], v[8:9]
	v_pk_add_f32 v[194:195], v[194:195], v[198:199]
	v_pk_fma_f32 v[144:145], v[144:145], v[220:221], v[222:223] neg_lo:[0,0,1] neg_hi:[0,0,1]
	v_pk_mul_f32 v[220:221], v[234:235], v[190:191]
	v_pk_fma_f32 v[228:229], v[104:105], v[6:7], v[20:21] neg_lo:[0,0,1] neg_hi:[0,0,1]
	v_pk_mul_f32 v[20:21], v[106:107], v[6:7]
	v_pk_add_f32 v[198:199], v[242:243], v[138:139]
	v_pk_add_f32 v[214:215], v[244:245], v[206:207]
	v_pk_fma_f32 v[220:221], v[232:233], v[194:195], v[220:221]
	v_pk_mul_f32 v[194:195], v[234:235], v[194:195]
	v_pk_fma_f32 v[230:231], v[104:105], v[8:9], v[20:21]
	v_pk_add_f32 v[138:139], v[242:243], v[138:139] neg_lo:[0,1] neg_hi:[0,1]
	v_pk_add_f32 v[206:207], v[244:245], v[206:207] neg_lo:[0,1] neg_hi:[0,1]
	v_pk_fma_f32 v[190:191], v[232:233], v[190:191], v[194:195] neg_lo:[0,0,1] neg_hi:[0,0,1]
	v_pk_mul_f32 v[194:195], v[106:107], v[198:199]
	v_pk_mul_f32 v[106:107], v[106:107], v[214:215]
	v_pk_add_f32 v[242:243], v[130:131], v[128:129]
	v_pk_add_f32 v[244:245], v[122:123], v[188:189] neg_lo:[0,1] neg_hi:[0,1]
	v_pk_fma_f32 v[194:195], v[104:105], v[214:215], v[194:195]
	v_pk_fma_f32 v[104:105], v[104:105], v[198:199], v[106:107] neg_lo:[0,0,1] neg_hi:[0,0,1]
	v_pk_mul_f32 v[106:107], v[230:231], v[138:139]
	v_pk_mul_f32 v[198:199], v[230:231], v[206:207]
	v_pk_add_f32 v[128:129], v[130:131], v[128:129] neg_lo:[0,1] neg_hi:[0,1]
	v_pk_fma_f32 v[106:107], v[228:229], v[206:207], v[106:107]
	v_pk_fma_f32 v[138:139], v[228:229], v[138:139], v[198:199] neg_lo:[0,0,1] neg_hi:[0,0,1]
	v_pk_mul_f32 v[198:199], v[226:227], v[242:243]
	v_pk_mul_f32 v[206:207], v[226:227], v[244:245]
	v_pk_add_f32 v[122:123], v[122:123], v[188:189]
	v_pk_fma_f32 v[198:199], v[110:111], v[244:245], v[198:199]
	v_pk_fma_f32 v[110:111], v[110:111], v[242:243], v[206:207] neg_lo:[0,0,1] neg_hi:[0,0,1]
	v_pk_mul_f32 v[206:207], v[240:241], v[128:129]
	v_pk_add_f32 v[130:131], v[192:193], v[212:213]
	v_pk_add_f32 v[188:189], v[208:209], v[216:217]
	v_pk_fma_f32 v[206:207], v[238:239], v[122:123], v[206:207]
	v_pk_mul_f32 v[122:123], v[240:241], v[122:123]
	v_pk_add_f32 v[192:193], v[192:193], v[212:213] neg_lo:[0,1] neg_hi:[0,1]
	v_pk_fma_f32 v[122:123], v[238:239], v[128:129], v[122:123] neg_lo:[0,0,1] neg_hi:[0,0,1]
	v_pk_mul_f32 v[128:129], v[14:15], v[130:131]
	v_pk_mul_f32 v[14:15], v[14:15], v[188:189]
	v_pk_add_f32 v[208:209], v[208:209], v[216:217] neg_lo:[0,1] neg_hi:[0,1]
	v_pk_fma_f32 v[128:129], v[12:13], v[188:189], v[128:129]
	v_pk_fma_f32 v[12:13], v[12:13], v[130:131], v[14:15] neg_lo:[0,0,1] neg_hi:[0,0,1]
	ds_write2_b64 v164, v[126:127], v[12:13] offset1:34
	ds_write2_b64 v165, v[196:197], v[128:129] offset1:34
	v_pk_mul_f32 v[12:13], v[112:113], v[192:193]
	v_pk_mul_f32 v[14:15], v[112:113], v[208:209]
	v_pk_add_f32 v[212:213], v[134:135], v[136:137]
	v_pk_add_f32 v[216:217], v[200:201], v[132:133] neg_lo:[0,1] neg_hi:[0,1]
	v_pk_fma_f32 v[12:13], v[108:109], v[208:209], v[12:13]
	v_pk_fma_f32 v[14:15], v[108:109], v[192:193], v[14:15] neg_lo:[0,0,1] neg_hi:[0,0,1]
	ds_write2_b64 v166, v[204:205], v[14:15] offset0:16 offset1:50
	ds_write2_b64 v167, v[246:247], v[12:13] offset0:16 offset1:50
	v_pk_mul_f32 v[12:13], v[18:19], v[212:213]
	v_pk_mul_f32 v[14:15], v[18:19], v[216:217]
	v_pk_mul_f32 v[114:115], v[8:9], v[18:19]
	v_pk_add_f32 v[134:135], v[134:135], v[136:137] neg_lo:[0,1] neg_hi:[0,1]
	v_pk_add_f32 v[132:133], v[200:201], v[132:133]
	v_pk_fma_f32 v[12:13], v[16:17], v[216:217], v[12:13]
	v_pk_fma_f32 v[14:15], v[16:17], v[212:213], v[14:15] neg_lo:[0,0,1] neg_hi:[0,0,1]
	v_pk_fma_f32 v[114:115], v[6:7], v[16:17], v[114:115] neg_lo:[0,0,1] neg_hi:[0,0,1]
	ds_write2_b64 v164, v[144:145], v[14:15] offset0:136 offset1:170
	ds_write2_b64 v165, v[210:211], v[12:13] offset0:136 offset1:170
	v_pk_mul_f32 v[12:13], v[236:237], v[134:135]
	v_pk_mul_f32 v[14:15], v[236:237], v[132:133]
	v_pk_mul_f32 v[22:23], v[10:11], v[6:7]
	v_pk_add_f32 v[136:137], v[140:141], v[124:125]
	v_pk_add_f32 v[200:201], v[218:219], v[202:203]
	v_pk_fma_f32 v[12:13], v[114:115], v[132:133], v[12:13]
	v_pk_fma_f32 v[14:15], v[114:115], v[134:135], v[14:15] neg_lo:[0,0,1] neg_hi:[0,0,1]
	v_pk_mul_f32 v[20:21], v[10:11], v[8:9]
	v_pk_fma_f32 v[22:23], v[4:5], v[8:9], v[22:23]
	v_pk_add_f32 v[124:125], v[140:141], v[124:125] neg_lo:[0,1] neg_hi:[0,1]
	v_pk_add_f32 v[140:141], v[218:219], v[202:203] neg_lo:[0,1] neg_hi:[0,1]
	ds_write2_b64 v166, v[190:191], v[14:15] offset0:152 offset1:186
	ds_write2_b64 v167, v[220:221], v[12:13] offset0:152 offset1:186
	v_pk_mul_f32 v[12:13], v[10:11], v[136:137]
	v_pk_mul_f32 v[10:11], v[10:11], v[200:201]
	v_pk_fma_f32 v[2:3], v[224:225], v[4:5], v[2:3]
	v_pk_fma_f32 v[20:21], v[4:5], v[6:7], v[20:21] neg_lo:[0,0,1] neg_hi:[0,0,1]
	v_pk_fma_f32 v[12:13], v[4:5], v[200:201], v[12:13]
	v_pk_fma_f32 v[4:5], v[4:5], v[136:137], v[10:11] neg_lo:[0,0,1] neg_hi:[0,0,1]
	v_pk_mul_f32 v[10:11], v[22:23], v[140:141]
	v_pk_add_f32 v[218:219], v[120:121], v[142:143] neg_lo:[0,1] neg_hi:[0,1]
	ds_write2_b64 v164, v[104:105], v[4:5] offset0:68 offset1:102
	ds_write2_b64 v165, v[194:195], v[12:13] offset0:68 offset1:102
	v_pk_mul_f32 v[4:5], v[22:23], v[124:125]
	v_pk_fma_f32 v[10:11], v[20:21], v[124:125], v[10:11] neg_lo:[0,0,1] neg_hi:[0,0,1]
	v_pk_add_f32 v[202:203], v[116:117], v[118:119]
	v_pk_fma_f32 v[4:5], v[20:21], v[140:141], v[4:5]
	ds_write2_b64 v166, v[138:139], v[10:11] offset0:84 offset1:118
	ds_write2_b64 v167, v[106:107], v[4:5] offset0:84 offset1:118
	v_pk_mul_f32 v[10:11], v[2:3], v[218:219]
	v_pk_mul_f32 v[4:5], v[2:3], v[202:203]
	v_pk_fma_f32 v[10:11], v[0:1], v[202:203], v[10:11] neg_lo:[0,0,1] neg_hi:[0,0,1]
	v_pk_fma_f32 v[4:5], v[0:1], v[218:219], v[4:5]
	ds_write2_b64 v164, v[110:111], v[10:11] offset0:204 offset1:238
	ds_write2_b64 v165, v[198:199], v[4:5] offset0:204 offset1:238
	v_pk_mul_f32 v[10:11], v[8:9], v[2:3]
	v_pk_mul_f32 v[2:3], v[6:7], v[2:3]
	v_pk_add_f32 v[4:5], v[120:121], v[142:143]
	v_pk_fma_f32 v[10:11], v[6:7], v[0:1], v[10:11] neg_lo:[0,0,1] neg_hi:[0,0,1]
	v_pk_add_f32 v[12:13], v[116:117], v[118:119] neg_lo:[0,1] neg_hi:[0,1]
	v_pk_fma_f32 v[0:1], v[8:9], v[0:1], v[2:3]
	s_nop 0
	v_pk_mul_f32 v[2:3], v[0:1], v[12:13]
	v_pk_mul_f32 v[0:1], v[0:1], v[4:5]
	v_pk_fma_f32 v[2:3], v[10:11], v[4:5], v[2:3]
	v_pk_fma_f32 v[0:1], v[10:11], v[12:13], v[0:1] neg_lo:[0,0,1] neg_hi:[0,0,1]
	ds_write2_b64 v166, v[122:123], v[0:1] offset0:220 offset1:254
	ds_write2_b64 v167, v[206:207], v[2:3] offset0:220 offset1:254
	v_mov_b32_e32 v0, v163
	s_waitcnt lgkmcnt(0)
	s_barrier
	s_nop 0
	s_nop 0
	v_lshlrev_b32_e32 v1, 1, v0
	v_and_b32_e32 v187, 2, v1
	v_lshrrev_b32_e32 v1, 31, v0
	v_add_u32_e32 v0, v0, v1
	v_ashrrev_i32_e32 v164, 1, v0
	v_lshl_or_b32 v0, v164, 6, v187
	v_lshlrev_b32_e32 v1, 2, v164
	v_add_lshl_u32 v128, v0, v1, 2
	v_add_u32_e32 v165, 0, v128
	v_add_u32_e32 v162, s91, v128
	ds_read2_b64 v[128:131], v165 offset1:2
	ds_read2_b64 v[132:135], v165 offset0:4 offset1:6
	ds_read2_b64 v[136:139], v162 offset1:2
	ds_read2_b64 v[140:143], v162 offset0:4 offset1:6
	ds_read2_b64 v[188:191], v165 offset0:8 offset1:10
	ds_read2_b64 v[192:195], v162 offset0:8 offset1:10
	ds_read2_b64 v[196:199], v165 offset0:12 offset1:14
	ds_read2_b64 v[200:203], v162 offset0:12 offset1:14
	ds_read2_b64 v[204:207], v165 offset0:16 offset1:18
	ds_read2_b64 v[208:211], v162 offset0:16 offset1:18
	ds_read2_b64 v[212:215], v165 offset0:20 offset1:22
	ds_read2_b64 v[216:219], v162 offset0:20 offset1:22
	ds_read2_b64 v[220:223], v165 offset0:24 offset1:26
	ds_read2_b64 v[224:227], v162 offset0:24 offset1:26
	ds_read2_b64 v[228:231], v165 offset0:28 offset1:30
	ds_read2_b64 v[232:235], v162 offset0:28 offset1:30
	s_waitcnt lgkmcnt(6)
	v_pk_add_f32 v[240:241], v[136:137], v[208:209]
	v_pk_add_f32 v[136:137], v[136:137], v[208:209] neg_lo:[0,1] neg_hi:[0,1]
	v_pk_add_f32 v[208:209], v[138:139], v[210:211]
	v_pk_add_f32 v[138:139], v[138:139], v[210:211] neg_lo:[0,1] neg_hi:[0,1]
	v_pk_add_f32 v[238:239], v[128:129], v[204:205]
	v_pk_add_f32 v[128:129], v[128:129], v[204:205] neg_lo:[0,1] neg_hi:[0,1]
	v_pk_add_f32 v[204:205], v[130:131], v[206:207]
	v_pk_add_f32 v[130:131], v[130:131], v[206:207] neg_lo:[0,1] neg_hi:[0,1]
	v_pk_mul_f32 v[206:207], v[138:139], s[80:81] op_sel_hi:[1,0]
	s_waitcnt lgkmcnt(4)
	v_pk_add_f32 v[210:211], v[140:141], v[216:217]
	v_pk_fma_f32 v[206:207], v[130:131], s[72:73], v[206:207] op_sel_hi:[1,0,1]
	v_pk_mul_f32 v[130:131], v[130:131], s[80:81] op_sel_hi:[1,0]
	v_pk_add_f32 v[140:141], v[140:141], v[216:217] neg_lo:[0,1] neg_hi:[0,1]
	v_pk_fma_f32 v[130:131], v[138:139], s[72:73], v[130:131] op_sel_hi:[1,0,1] neg_lo:[0,0,1] neg_hi:[0,0,1]
	v_pk_add_f32 v[138:139], v[132:133], v[212:213]
	v_pk_add_f32 v[132:133], v[132:133], v[212:213] neg_lo:[0,1] neg_hi:[0,1]
	v_pk_add_f32 v[216:217], v[142:143], v[218:219]
	v_pk_mul_f32 v[132:133], v[132:133], s[82:83] op_sel_hi:[1,0]
	v_pk_add_f32 v[142:143], v[142:143], v[218:219] neg_lo:[0,1] neg_hi:[0,1]
	v_pk_fma_f32 v[212:213], v[140:141], s[82:83], v[132:133] op_sel_hi:[1,0,1]
	v_pk_fma_f32 v[132:133], v[140:141], s[82:83], v[132:133] op_sel_hi:[1,0,1] neg_lo:[0,0,1] neg_hi:[0,0,1]
	v_pk_add_f32 v[140:141], v[134:135], v[214:215]
	v_pk_add_f32 v[134:135], v[134:135], v[214:215] neg_lo:[0,1] neg_hi:[0,1]
	v_pk_mul_f32 v[214:215], v[142:143], s[72:73] op_sel_hi:[1,0]
	v_or_b32_e32 v3, 1, v187
	v_pk_fma_f32 v[214:215], v[134:135], s[80:81], v[214:215] op_sel_hi:[1,0,1]
	v_pk_mul_f32 v[134:135], v[134:135], s[72:73] op_sel_hi:[1,0]
	v_cvt_f32_ubyte0_e32 v2, v187
	v_cvt_f32_ubyte0_e32 v3, v3
	v_pk_fma_f32 v[134:135], v[142:143], s[80:81], v[134:135] op_sel_hi:[1,0,1] neg_lo:[0,0,1] neg_hi:[0,0,1]
	s_waitcnt lgkmcnt(3)
	v_pk_add_f32 v[142:143], v[188:189], v[220:221]
	v_pk_add_f32 v[188:189], v[188:189], v[220:221] neg_lo:[0,1] neg_hi:[0,1]
	v_pk_add_f32 v[220:221], v[190:191], v[222:223]
	v_pk_add_f32 v[190:191], v[190:191], v[222:223] neg_lo:[0,1] neg_hi:[0,1]
	v_mul_f32_e32 v2, 0x3c800000, v2
	v_mul_f32_e32 v3, 0x3c800000, v3
	s_waitcnt lgkmcnt(2)
	v_pk_add_f32 v[218:219], v[192:193], v[224:225]
	v_pk_add_f32 v[192:193], v[192:193], v[224:225] neg_lo:[0,1] neg_hi:[0,1]
	v_pk_add_f32 v[224:225], v[194:195], v[226:227]
	v_pk_add_f32 v[194:195], v[194:195], v[226:227] neg_lo:[0,1] neg_hi:[0,1]
	v_pk_mul_f32 v[222:223], v[190:191], s[80:81] op_sel_hi:[1,0]
	v_sin_f32_e64 v236, -v2
	v_sin_f32_e64 v237, -v3
	v_pk_fma_f32 v[222:223], v[194:195], s[72:73], v[222:223] op_sel_hi:[1,0,1] neg_lo:[0,0,1] neg_hi:[0,0,1]
	v_pk_mul_f32 v[194:195], v[194:195], s[80:81] op_sel_hi:[1,0]
	s_waitcnt lgkmcnt(0)
	v_pk_add_f32 v[226:227], v[200:201], v[232:233]
	v_pk_add_f32 v[200:201], v[200:201], v[232:233] neg_lo:[0,1] neg_hi:[0,1]
	v_cos_f32_e32 v144, v2
	v_cos_f32_e32 v145, v3
	v_pk_fma_f32 v[190:191], v[190:191], s[52:53], v[194:195] op_sel_hi:[1,0,1] neg_lo:[0,0,1] neg_hi:[0,0,1]
	v_pk_add_f32 v[194:195], v[196:197], v[228:229]
	v_pk_add_f32 v[196:197], v[196:197], v[228:229] neg_lo:[0,1] neg_hi:[0,1]
	v_pk_mul_f32 v[200:201], v[200:201], s[54:55] op_sel_hi:[1,0]
	v_pk_add_f32 v[232:233], v[202:203], v[234:235]
	v_pk_fma_f32 v[228:229], v[196:197], s[54:55], v[200:201] op_sel_hi:[1,0,1] neg_lo:[0,0,1] neg_hi:[0,0,1]
	v_pk_fma_f32 v[196:197], v[196:197], s[54:55], v[200:201] op_sel_hi:[1,0,1]
	v_pk_add_f32 v[200:201], v[198:199], v[230:231]
	v_pk_add_f32 v[198:199], v[198:199], v[230:231] neg_lo:[0,1] neg_hi:[0,1]
	v_pk_add_f32 v[202:203], v[202:203], v[234:235] neg_lo:[0,1] neg_hi:[0,1]
	v_pk_mul_f32 v[230:231], v[198:199], s[72:73] op_sel_hi:[1,0]
	v_pk_mul_f32 v[0:1], v[236:237], v[236:237]
	v_pk_fma_f32 v[230:231], v[202:203], s[80:81], v[230:231] op_sel_hi:[1,0,1] neg_lo:[0,0,1] neg_hi:[0,0,1]
	v_pk_mul_f32 v[202:203], v[202:203], s[72:73] op_sel_hi:[1,0]
	v_pk_fma_f32 v[120:121], v[144:145], v[144:145], v[0:1] neg_lo:[0,0,1] neg_hi:[0,0,1]
	v_pk_mul_f32 v[0:1], v[144:145], v[236:237]
	v_pk_fma_f32 v[198:199], v[198:199], s[84:85], v[202:203] op_sel_hi:[1,0,1] neg_lo:[0,0,1] neg_hi:[0,0,1]
	v_pk_add_f32 v[202:203], v[238:239], v[142:143]
	v_pk_add_f32 v[142:143], v[238:239], v[142:143] neg_lo:[0,1] neg_hi:[0,1]
	v_pk_add_f32 v[238:239], v[204:205], v[220:221]
	v_pk_add_f32 v[204:205], v[204:205], v[220:221] neg_lo:[0,1] neg_hi:[0,1]
	v_pk_add_f32 v[124:125], v[0:1], v[0:1]
	v_pk_add_f32 v[234:235], v[240:241], v[218:219]
	v_pk_add_f32 v[218:219], v[240:241], v[218:219] neg_lo:[0,1] neg_hi:[0,1]
	v_pk_add_f32 v[240:241], v[208:209], v[224:225]
	v_pk_add_f32 v[208:209], v[208:209], v[224:225] neg_lo:[0,1] neg_hi:[0,1]
	v_pk_mul_f32 v[204:205], v[204:205], s[82:83] op_sel_hi:[1,0]
	v_pk_mul_f32 v[0:1], v[236:237], v[124:125]
	v_pk_fma_f32 v[220:221], v[208:209], s[82:83], v[204:205] op_sel_hi:[1,0,1]
	v_pk_fma_f32 v[204:205], v[208:209], s[82:83], v[204:205] op_sel_hi:[1,0,1] neg_lo:[0,0,1] neg_hi:[0,0,1]
	v_pk_add_f32 v[208:209], v[138:139], v[194:195]
	v_pk_add_f32 v[224:225], v[210:211], v[226:227]
	v_pk_add_f32 v[138:139], v[138:139], v[194:195] neg_lo:[0,1] neg_hi:[0,1]
	v_pk_add_f32 v[194:195], v[210:211], v[226:227] neg_lo:[0,1] neg_hi:[0,1]
	v_pk_add_f32 v[210:211], v[140:141], v[200:201]
	v_pk_add_f32 v[140:141], v[140:141], v[200:201] neg_lo:[0,1] neg_hi:[0,1]
	v_pk_add_f32 v[200:201], v[216:217], v[232:233] neg_lo:[0,1] neg_hi:[0,1]
	v_pk_fma_f32 v[122:123], v[144:145], v[120:121], v[0:1] neg_lo:[0,0,1] neg_hi:[0,0,1]
	v_pk_mul_f32 v[0:1], v[236:237], v[120:121]
	v_pk_add_f32 v[226:227], v[216:217], v[232:233]
	v_pk_mul_f32 v[200:201], v[200:201], s[54:55] op_sel_hi:[1,0]
	v_pk_add_f32 v[232:233], v[136:137], v[188:189] neg_lo:[0,1] neg_hi:[0,1]
	v_pk_add_f32 v[136:137], v[136:137], v[188:189]
	v_pk_add_f32 v[188:189], v[206:207], v[222:223]
	v_pk_add_f32 v[206:207], v[206:207], v[222:223] neg_lo:[0,1] neg_hi:[0,1]
	v_pk_fma_f32 v[126:127], v[144:145], v[124:125], v[0:1]
	v_pk_mul_f32 v[0:1], v[124:125], v[124:125]
	v_pk_fma_f32 v[216:217], v[140:141], s[54:55], v[200:201] op_sel_hi:[1,0,1] neg_lo:[0,0,1] neg_hi:[0,0,1]
	v_pk_fma_f32 v[140:141], v[140:141], s[54:55], v[200:201] op_sel_hi:[1,0,1]
	v_pk_add_f32 v[200:201], v[128:129], v[192:193]
	v_pk_add_f32 v[128:129], v[128:129], v[192:193] neg_lo:[0,1] neg_hi:[0,1]
	v_pk_add_f32 v[192:193], v[130:131], v[190:191]
	v_pk_add_f32 v[130:131], v[130:131], v[190:191] neg_lo:[0,1] neg_hi:[0,1]
	v_pk_mul_f32 v[190:191], v[206:207], s[82:83] op_sel_hi:[1,0]
	v_pk_fma_f32 v[112:113], v[120:121], v[120:121], v[0:1] neg_lo:[0,0,1] neg_hi:[0,0,1]
	v_pk_mul_f32 v[0:1], v[120:121], v[124:125]
	v_pk_fma_f32 v[206:207], v[130:131], s[82:83], v[190:191] op_sel_hi:[1,0,1]
	v_pk_fma_f32 v[130:131], v[130:131], s[82:83], v[190:191] op_sel_hi:[1,0,1] neg_lo:[0,0,1] neg_hi:[0,0,1]
	v_pk_add_f32 v[190:191], v[212:213], v[228:229]
	v_pk_add_f32 v[212:213], v[212:213], v[228:229] neg_lo:[0,1] neg_hi:[0,1]
	v_pk_add_f32 v[228:229], v[134:135], v[198:199]
	v_pk_add_f32 v[134:135], v[134:135], v[198:199] neg_lo:[0,1] neg_hi:[0,1]
	v_pk_add_f32 v[116:117], v[0:1], v[0:1]
	v_pk_add_f32 v[222:223], v[132:133], v[196:197]
	v_pk_add_f32 v[132:133], v[132:133], v[196:197] neg_lo:[0,1] neg_hi:[0,1]
	v_pk_add_f32 v[196:197], v[214:215], v[230:231]
	v_pk_add_f32 v[214:215], v[214:215], v[230:231] neg_lo:[0,1] neg_hi:[0,1]
	v_pk_mul_f32 v[134:135], v[134:135], s[54:55] op_sel_hi:[1,0]
	v_pk_mul_f32 v[8:9], v[112:113], v[116:117]
	v_pk_fma_f32 v[198:199], v[214:215], s[54:55], v[134:135] op_sel_hi:[1,0,1] neg_lo:[0,0,1] neg_hi:[0,0,1]
	v_pk_fma_f32 v[134:135], v[214:215], s[54:55], v[134:135] op_sel_hi:[1,0,1]
	v_pk_add_f32 v[214:215], v[202:203], v[208:209]
	v_pk_add_f32 v[230:231], v[234:235], v[224:225]
	v_pk_add_f32 v[202:203], v[202:203], v[208:209] neg_lo:[0,1] neg_hi:[0,1]
	v_pk_add_f32 v[208:209], v[234:235], v[224:225] neg_lo:[0,1] neg_hi:[0,1]
	v_pk_add_f32 v[224:225], v[238:239], v[210:211]
	v_pk_add_f32 v[234:235], v[240:241], v[226:227]
	v_pk_add_f32 v[210:211], v[238:239], v[210:211] neg_lo:[0,1] neg_hi:[0,1]
	v_pk_add_f32 v[226:227], v[240:241], v[226:227] neg_lo:[0,1] neg_hi:[0,1]
	v_pk_add_f32 v[238:239], v[142:143], v[194:195]
	v_pk_add_f32 v[240:241], v[218:219], v[138:139] neg_lo:[0,1] neg_hi:[0,1]
	v_pk_add_f32 v[142:143], v[142:143], v[194:195] neg_lo:[0,1] neg_hi:[0,1]
	v_pk_add_f32 v[138:139], v[218:219], v[138:139]
	v_pk_add_f32 v[194:195], v[220:221], v[216:217]
	v_pk_add_f32 v[218:219], v[204:205], v[140:141]
	v_pk_add_f32 v[216:217], v[220:221], v[216:217] neg_lo:[0,1] neg_hi:[0,1]
	v_pk_add_f32 v[140:141], v[204:205], v[140:141] neg_lo:[0,1] neg_hi:[0,1]
	v_pk_add_f32 v[204:205], v[200:201], v[190:191]
	v_pk_add_f32 v[220:221], v[232:233], v[222:223]
	v_pk_add_f32 v[190:191], v[200:201], v[190:191] neg_lo:[0,1] neg_hi:[0,1]
	v_pk_add_f32 v[200:201], v[232:233], v[222:223] neg_lo:[0,1] neg_hi:[0,1]
	v_pk_add_f32 v[232:233], v[192:193], v[228:229]
	v_pk_mul_f32 v[4:5], v[116:117], v[116:117]
	v_pk_add_f32 v[8:9], v[8:9], v[8:9]
	v_mul_lo_u32 v248, v164, s49
	v_pk_add_f32 v[222:223], v[188:189], v[196:197]
	v_pk_add_f32 v[164:165], v[220:221], v[232:233] neg_lo:[0,1] neg_hi:[0,1]
	v_pk_add_f32 v[220:221], v[220:221], v[232:233]
	v_pk_mul_f32 v[0:1], v[236:237], v[116:117]
	v_pk_fma_f32 v[4:5], v[112:113], v[112:113], v[4:5] neg_lo:[0,0,1] neg_hi:[0,0,1]
	v_pk_mul_f32 v[12:13], v[236:237], v[8:9]
	v_pk_add_f32 v[188:189], v[188:189], v[196:197] neg_lo:[0,1] neg_hi:[0,1]
	v_pk_add_f32 v[192:193], v[192:193], v[228:229] neg_lo:[0,1] neg_hi:[0,1]
	v_pk_add_f32 v[196:197], v[128:129], v[132:133]
	v_pk_add_f32 v[228:229], v[136:137], v[212:213] neg_lo:[0,1] neg_hi:[0,1]
	v_pk_add_f32 v[128:129], v[128:129], v[132:133] neg_lo:[0,1] neg_hi:[0,1]
	v_pk_add_f32 v[132:133], v[136:137], v[212:213]
	v_pk_add_f32 v[212:213], v[130:131], v[134:135]
	v_pk_add_f32 v[130:131], v[130:131], v[134:135] neg_lo:[0,1] neg_hi:[0,1]
	v_pk_add_f32 v[134:135], v[214:215], v[224:225] neg_lo:[0,1] neg_hi:[0,1]
	v_pk_add_f32 v[246:247], v[204:205], v[222:223] neg_lo:[0,1] neg_hi:[0,1]
	v_or_b32_e32 v187, v248, v187
	v_pk_add_f32 v[204:205], v[204:205], v[222:223]
	v_pk_add_f32 v[214:215], v[214:215], v[224:225]
	v_pk_mul_f32 v[224:225], v[236:237], v[220:221]
	v_pk_fma_f32 v[114:115], v[144:145], v[112:113], v[0:1] neg_lo:[0,0,1] neg_hi:[0,0,1]
	v_pk_mul_f32 v[0:1], v[236:237], v[112:113]
	v_pk_fma_f32 v[108:109], v[144:145], v[4:5], v[12:13] neg_lo:[0,0,1] neg_hi:[0,0,1]
	v_pk_mul_f32 v[12:13], v[236:237], v[4:5]
	v_pk_fma_f32 v[224:225], v[144:145], v[204:205], v[224:225] neg_lo:[0,0,1] neg_hi:[0,0,1]
	v_pk_mul_f32 v[204:205], v[236:237], v[204:205]
	v_lshlrev_b32_e32 v187, 2, v187
	v_pk_fma_f32 v[118:119], v[144:145], v[116:117], v[0:1]
	v_pk_fma_f32 v[110:111], v[144:145], v[8:9], v[12:13]
	v_pk_mul_f32 v[12:13], v[124:125], v[8:9]
	v_pk_add_f32 v[222:223], v[230:231], v[234:235]
	v_pk_fma_f32 v[144:145], v[144:145], v[220:221], v[204:205]
	v_mov_b32_e32 v204, v214
	v_mov_b32_e32 v205, v224
	v_add_u32_e32 v214, 0, v187
	v_mov_b32_e32 v224, v215
	v_pk_mul_f32 v[0:1], v[124:125], v[116:117]
	v_pk_fma_f32 v[20:21], v[120:121], v[4:5], v[12:13] neg_lo:[0,0,1] neg_hi:[0,0,1]
	v_pk_mul_f32 v[12:13], v[124:125], v[4:5]
	v_pk_add_f32 v[136:137], v[206:207], v[198:199]
	v_pk_add_f32 v[242:243], v[202:203], v[226:227]
	v_pk_add_f32 v[244:245], v[208:209], v[210:211] neg_lo:[0,1] neg_hi:[0,1]
	v_pk_add_f32 v[202:203], v[202:203], v[226:227] neg_lo:[0,1] neg_hi:[0,1]
	v_pk_add_f32 v[208:209], v[208:209], v[210:211]
	v_pk_add_f32 v[210:211], v[238:239], v[194:195]
	v_pk_add_f32 v[226:227], v[240:241], v[218:219]
	ds_write2_b64 v214, v[204:205], v[224:225] offset1:2
	v_mov_b32_e32 v204, v222
	v_mov_b32_e32 v205, v144
	v_add_u32_e32 v187, s91, v187
	v_mov_b32_e32 v144, v223
	v_pk_fma_f32 v[6:7], v[120:121], v[112:113], v[0:1] neg_lo:[0,0,1] neg_hi:[0,0,1]
	v_pk_mul_f32 v[0:1], v[124:125], v[112:113]
	v_pk_fma_f32 v[104:105], v[120:121], v[8:9], v[12:13]
	v_pk_mul_f32 v[12:13], v[126:127], v[8:9]
	v_pk_add_f32 v[166:167], v[190:191], v[192:193]
	v_pk_add_f32 v[190:191], v[190:191], v[192:193] neg_lo:[0,1] neg_hi:[0,1]
	v_pk_add_f32 v[192:193], v[200:201], v[188:189] neg_lo:[0,1] neg_hi:[0,1]
	v_pk_add_f32 v[188:189], v[200:201], v[188:189]
	v_pk_add_f32 v[200:201], v[196:197], v[136:137]
	v_pk_add_f32 v[136:137], v[196:197], v[136:137] neg_lo:[0,1] neg_hi:[0,1]
	v_pk_add_f32 v[196:197], v[228:229], v[212:213]
	ds_write2_b64 v187, v[204:205], v[144:145] offset1:2
	v_pk_mul_f32 v[144:145], v[124:125], v[210:211]
	v_pk_mul_f32 v[124:125], v[124:125], v[226:227]
	v_pk_fma_f32 v[10:11], v[120:121], v[116:117], v[0:1]
	v_pk_mul_f32 v[0:1], v[116:117], v[126:127]
	v_pk_mul_f32 v[2:3], v[112:113], v[126:127]
	v_pk_fma_f32 v[22:23], v[122:123], v[4:5], v[12:13] neg_lo:[0,0,1] neg_hi:[0,0,1]
	v_pk_mul_f32 v[12:13], v[126:127], v[4:5]
	v_pk_fma_f32 v[144:145], v[120:121], v[226:227], v[144:145]
	v_pk_fma_f32 v[120:121], v[120:121], v[210:211], v[124:125] neg_lo:[0,0,1] neg_hi:[0,0,1]
	v_pk_mul_f32 v[124:125], v[126:127], v[196:197]
	v_pk_mul_f32 v[126:127], v[126:127], v[200:201]
	v_pk_fma_f32 v[0:1], v[112:113], v[122:123], v[0:1] neg_lo:[0,0,1] neg_hi:[0,0,1]
	v_pk_fma_f32 v[2:3], v[116:117], v[122:123], v[2:3]
	v_pk_fma_f32 v[106:107], v[122:123], v[8:9], v[12:13]
	v_pk_fma_f32 v[124:125], v[122:123], v[200:201], v[124:125] neg_lo:[0,0,1] neg_hi:[0,0,1]
	v_pk_fma_f32 v[122:123], v[122:123], v[196:197], v[126:127]
	v_mov_b32_e32 v126, v120
	v_mov_b32_e32 v127, v124
	v_mov_b32_e32 v124, v121
	v_mov_b32_e32 v120, v144
	v_mov_b32_e32 v121, v122
	v_mov_b32_e32 v122, v145
	v_pk_mul_f32 v[12:13], v[116:117], v[8:9]
	v_pk_mul_f32 v[14:15], v[116:117], v[4:5]
	ds_write2_b64 v187, v[120:121], v[122:123] offset0:4 offset1:6
	v_pk_mul_f32 v[120:121], v[116:117], v[242:243]
	v_pk_mul_f32 v[116:117], v[116:117], v[244:245]
	v_pk_fma_f32 v[12:13], v[112:113], v[4:5], v[12:13] neg_lo:[0,0,1] neg_hi:[0,0,1]
	v_pk_fma_f32 v[16:17], v[112:113], v[8:9], v[14:15]
	v_pk_mul_f32 v[14:15], v[8:9], v[118:119]
	v_pk_mul_f32 v[18:19], v[4:5], v[118:119]
	v_pk_fma_f32 v[120:121], v[112:113], v[244:245], v[120:121]
	v_pk_fma_f32 v[112:113], v[112:113], v[242:243], v[116:117] neg_lo:[0,0,1] neg_hi:[0,0,1]
	v_pk_mul_f32 v[116:117], v[118:119], v[192:193]
	v_pk_mul_f32 v[118:119], v[118:119], v[166:167]
	v_pk_fma_f32 v[14:15], v[4:5], v[114:115], v[14:15] neg_lo:[0,0,1] neg_hi:[0,0,1]
	v_pk_fma_f32 v[18:19], v[8:9], v[114:115], v[18:19]
	v_pk_add_f32 v[198:199], v[206:207], v[198:199] neg_lo:[0,1] neg_hi:[0,1]
	v_pk_fma_f32 v[116:117], v[114:115], v[166:167], v[116:117] neg_lo:[0,0,1] neg_hi:[0,0,1]
	v_pk_fma_f32 v[114:115], v[114:115], v[192:193], v[118:119]
	v_pk_add_f32 v[194:195], v[238:239], v[194:195] neg_lo:[0,1] neg_hi:[0,1]
	v_pk_add_f32 v[218:219], v[240:241], v[218:219] neg_lo:[0,1] neg_hi:[0,1]
	v_pk_add_f32 v[238:239], v[142:143], v[140:141]
	v_pk_add_f32 v[240:241], v[138:139], v[216:217] neg_lo:[0,1] neg_hi:[0,1]
	v_pk_add_f32 v[212:213], v[228:229], v[212:213] neg_lo:[0,1] neg_hi:[0,1]
	v_pk_add_f32 v[228:229], v[128:129], v[130:131]
	v_pk_add_f32 v[232:233], v[132:133], v[198:199] neg_lo:[0,1] neg_hi:[0,1]
	v_mov_b32_e32 v118, v112
	v_mov_b32_e32 v119, v116
	v_mov_b32_e32 v116, v113
	v_mov_b32_e32 v112, v120
	v_mov_b32_e32 v113, v114
	v_mov_b32_e32 v114, v121
	ds_write2_b64 v214, v[126:127], v[124:125] offset0:4 offset1:6
	ds_write2_b64 v214, v[118:119], v[116:117] offset0:8 offset1:10
	ds_write2_b64 v162, v[112:113], v[114:115] offset0:8 offset1:10
	v_pk_mul_f32 v[112:113], v[10:11], v[238:239]
	v_pk_mul_f32 v[114:115], v[10:11], v[240:241]
	v_pk_mul_f32 v[116:117], v[2:3], v[232:233]
	v_pk_mul_f32 v[118:119], v[2:3], v[228:229]
	v_pk_fma_f32 v[112:113], v[6:7], v[240:241], v[112:113]
	v_pk_fma_f32 v[114:115], v[6:7], v[238:239], v[114:115] neg_lo:[0,0,1] neg_hi:[0,0,1]
	v_pk_fma_f32 v[116:117], v[0:1], v[228:229], v[116:117] neg_lo:[0,0,1] neg_hi:[0,0,1]
	v_pk_fma_f32 v[118:119], v[0:1], v[232:233], v[118:119]
	v_pk_add_f32 v[206:207], v[230:231], v[234:235] neg_lo:[0,1] neg_hi:[0,1]
	v_mov_b32_e32 v120, v114
	v_mov_b32_e32 v121, v116
	v_mov_b32_e32 v116, v115
	v_mov_b32_e32 v114, v112
	v_mov_b32_e32 v115, v118
	v_mov_b32_e32 v118, v113
	ds_write2_b64 v214, v[120:121], v[116:117] offset0:12 offset1:14
	ds_write2_b64 v187, v[114:115], v[118:119] offset0:12 offset1:14
	v_pk_mul_f32 v[114:115], v[8:9], v[206:207]
	v_pk_mul_f32 v[116:117], v[110:111], v[164:165]
	v_pk_mul_f32 v[112:113], v[4:5], v[206:207]
	v_pk_fma_f32 v[114:115], v[4:5], v[134:135], v[114:115] neg_lo:[0,0,1] neg_hi:[0,0,1]
	v_pk_fma_f32 v[116:117], v[108:109], v[246:247], v[116:117] neg_lo:[0,0,1] neg_hi:[0,0,1]
	v_pk_mul_f32 v[110:111], v[110:111], v[246:247]
	v_pk_fma_f32 v[112:113], v[8:9], v[134:135], v[112:113]
	v_pk_fma_f32 v[108:109], v[108:109], v[164:165], v[110:111]
	v_mov_b32_e32 v110, v114
	v_mov_b32_e32 v111, v116
	v_mov_b32_e32 v116, v115
	ds_write2_b64 v214, v[110:111], v[116:117] offset0:16 offset1:18
	v_mov_b32_e32 v110, v112
	v_mov_b32_e32 v111, v108
	v_mov_b32_e32 v108, v113
	ds_write2_b64 v162, v[110:111], v[108:109] offset0:16 offset1:18
	v_pk_mul_f32 v[108:109], v[104:105], v[194:195]
	v_pk_mul_f32 v[104:105], v[104:105], v[218:219]
	v_pk_fma_f32 v[108:109], v[20:21], v[218:219], v[108:109]
	v_pk_fma_f32 v[20:21], v[20:21], v[194:195], v[104:105] neg_lo:[0,0,1] neg_hi:[0,0,1]
	v_pk_mul_f32 v[104:105], v[106:107], v[212:213]
	v_pk_mul_f32 v[106:107], v[106:107], v[136:137]
	v_pk_fma_f32 v[104:105], v[22:23], v[136:137], v[104:105] neg_lo:[0,0,1] neg_hi:[0,0,1]
	v_pk_fma_f32 v[22:23], v[22:23], v[212:213], v[106:107]
	v_mov_b32_e32 v106, v20
	v_mov_b32_e32 v107, v104
	v_mov_b32_e32 v104, v21
	v_mov_b32_e32 v20, v108
	v_mov_b32_e32 v21, v22
	v_mov_b32_e32 v22, v109
	ds_write2_b64 v187, v[20:21], v[22:23] offset0:20 offset1:22
	v_pk_mul_f32 v[20:21], v[16:17], v[202:203]
	v_pk_mul_f32 v[16:17], v[16:17], v[208:209]
	v_pk_fma_f32 v[20:21], v[12:13], v[208:209], v[20:21]
	v_pk_fma_f32 v[12:13], v[12:13], v[202:203], v[16:17] neg_lo:[0,0,1] neg_hi:[0,0,1]
	v_pk_mul_f32 v[16:17], v[18:19], v[188:189]
	v_pk_mul_f32 v[18:19], v[18:19], v[190:191]
	v_pk_fma_f32 v[16:17], v[14:15], v[190:191], v[16:17] neg_lo:[0,0,1] neg_hi:[0,0,1]
	v_pk_fma_f32 v[14:15], v[14:15], v[188:189], v[18:19]
	v_mov_b32_e32 v18, v12
	v_mov_b32_e32 v19, v16
	v_mov_b32_e32 v16, v13
	v_mov_b32_e32 v12, v20
	v_mov_b32_e32 v13, v14
	v_mov_b32_e32 v14, v21
	ds_write2_b64 v214, v[106:107], v[104:105] offset0:20 offset1:22
	ds_write2_b64 v214, v[18:19], v[16:17] offset0:24 offset1:26
	ds_write2_b64 v162, v[12:13], v[14:15] offset0:24 offset1:26
	v_pk_mul_f32 v[14:15], v[8:9], v[10:11]
	v_pk_mul_f32 v[10:11], v[4:5], v[10:11]
	v_pk_add_f32 v[12:13], v[138:139], v[216:217]
	v_pk_fma_f32 v[14:15], v[4:5], v[6:7], v[14:15] neg_lo:[0,0,1] neg_hi:[0,0,1]
	v_pk_add_f32 v[16:17], v[142:143], v[140:141] neg_lo:[0,1] neg_hi:[0,1]
	v_pk_fma_f32 v[6:7], v[8:9], v[6:7], v[10:11]
	v_mov_b32_e32 v134, v163
	v_pk_mul_f32 v[10:11], v[6:7], v[16:17]
	v_pk_mul_f32 v[6:7], v[6:7], v[12:13]
	v_pk_fma_f32 v[10:11], v[14:15], v[12:13], v[10:11]
	v_pk_fma_f32 v[6:7], v[14:15], v[16:17], v[6:7] neg_lo:[0,0,1] neg_hi:[0,0,1]
	v_pk_mul_f32 v[16:17], v[4:5], v[2:3]
	v_pk_add_f32 v[12:13], v[132:133], v[198:199]
	v_pk_fma_f32 v[16:17], v[8:9], v[0:1], v[16:17]
	v_pk_mul_f32 v[2:3], v[8:9], v[2:3]
	v_pk_add_f32 v[14:15], v[128:129], v[130:131] neg_lo:[0,1] neg_hi:[0,1]
	v_pk_fma_f32 v[0:1], v[4:5], v[0:1], v[2:3] neg_lo:[0,0,1] neg_hi:[0,0,1]
	v_pk_mul_f32 v[2:3], v[16:17], v[12:13]
	v_pk_mul_f32 v[4:5], v[16:17], v[14:15]
	v_pk_fma_f32 v[2:3], v[0:1], v[14:15], v[2:3] neg_lo:[0,0,1] neg_hi:[0,0,1]
	v_pk_fma_f32 v[0:1], v[0:1], v[12:13], v[4:5]
	v_mov_b32_e32 v4, v6
	v_mov_b32_e32 v5, v2
	v_mov_b32_e32 v2, v7
	ds_write2_b64 v214, v[4:5], v[2:3] offset0:28 offset1:30
	v_mov_b32_e32 v2, v10
	v_mov_b32_e32 v3, v0
	v_mov_b32_e32 v0, v11
	ds_write2_b64 v187, v[2:3], v[0:1] offset0:28 offset1:30
	s_waitcnt lgkmcnt(0)
	s_barrier
	s_nop 0
	s_nop 0
	v_lshlrev_b32_e32 v0, 3, v134
	v_ashrrev_i32_e32 v1, 31, v0
	v_lshlrev_b64 v[2:3], 2, v[0:1]
	v_lshl_add_u64 v[14:15], s[88:89], 0, v[2:3]
	v_lshl_add_u64 v[10:11], s[34:35], 0, v[2:3]
	global_load_dwordx4 v[2:5], v[10:11], off
	global_load_dwordx4 v[6:9], v[14:15], off
	s_nop 0
	global_load_dwordx4 v[10:13], v[10:11], off offset:16
	s_nop 0
	global_load_dwordx4 v[14:17], v[14:15], off offset:16
	v_ashrrev_i32_e32 v1, 3, v134
	v_and_b32_e32 v0, 56, v0
	v_mul_lo_u32 v1, v1, s49
	v_add_lshl_u32 v1, v1, v0, 2
	v_add_u32_e32 v135, 0, v1
	ds_read_b128 v[18:21], v135
	v_add_u32_e32 v1, s91, v1
	ds_read_b128 v[104:107], v1
	ds_read_b128 v[108:111], v135 offset:16
	ds_read_b128 v[112:115], v1 offset:16
	v_add_u32_e32 v136, 0x200, v134
	s_waitcnt lgkmcnt(3)
	v_pk_add_f32 v[22:23], v[18:19], v[20:21]
	v_pk_add_f32 v[118:119], v[18:19], v[20:21] neg_lo:[0,1] neg_hi:[0,1]
	v_lshlrev_b32_e32 v18, 3, v136
	v_ashrrev_i32_e32 v19, 31, v18
	v_lshlrev_b64 v[18:19], 2, v[18:19]
	s_waitcnt lgkmcnt(2)
	v_pk_add_f32 v[116:117], v[104:105], v[106:107]
	v_pk_add_f32 v[120:121], v[104:105], v[106:107] neg_lo:[0,1] neg_hi:[0,1]
	s_waitcnt lgkmcnt(0)
	v_pk_add_f32 v[124:125], v[112:113], v[114:115]
	v_pk_add_f32 v[128:129], v[112:113], v[114:115] neg_lo:[0,1] neg_hi:[0,1]
	v_lshl_add_u64 v[112:113], s[88:89], 0, v[18:19]
	v_lshl_add_u64 v[104:105], s[34:35], 0, v[18:19]
	v_pk_add_f32 v[122:123], v[108:109], v[110:111]
	v_pk_add_f32 v[126:127], v[108:109], v[110:111] neg_lo:[0,1] neg_hi:[0,1]
	global_load_dwordx4 v[18:21], v[104:105], off offset:16
	s_nop 0
	global_load_dwordx4 v[104:107], v[104:105], off
	s_nop 0
	global_load_dwordx4 v[108:111], v[112:113], off offset:16
	s_nop 0
	global_load_dwordx4 v[112:115], v[112:113], off
	v_pk_add_f32 v[130:131], v[22:23], v[122:123]
	v_pk_add_f32 v[132:133], v[116:117], v[124:125]
	v_pk_add_f32 v[22:23], v[22:23], v[122:123] neg_lo:[0,1] neg_hi:[0,1]
	v_pk_add_f32 v[116:117], v[116:117], v[124:125] neg_lo:[0,1] neg_hi:[0,1]
	v_pk_add_f32 v[124:125], v[120:121], v[126:127] neg_lo:[0,1] neg_hi:[0,1]
	v_pk_add_f32 v[120:121], v[126:127], v[120:121]
	v_pk_add_f32 v[122:123], v[118:119], v[128:129]
	v_pk_add_f32 v[118:119], v[118:119], v[128:129] neg_lo:[0,1] neg_hi:[0,1]
	s_waitcnt vmcnt(7)
	v_pk_mul_f32 v[126:127], v[132:133], v[2:3]
	v_pk_mul_f32 v[2:3], v[130:131], v[2:3]
	s_waitcnt vmcnt(6)
	v_pk_fma_f32 v[126:127], v[130:131], v[6:7], v[126:127] neg_lo:[0,0,1] neg_hi:[0,0,1]
	v_pk_fma_f32 v[2:3], v[6:7], v[132:133], v[2:3]
	v_pk_mul_f32 v[6:7], v[116:117], v[4:5]
	v_pk_mul_f32 v[4:5], v[22:23], v[4:5]
	v_pk_fma_f32 v[6:7], v[22:23], v[8:9], v[6:7] neg_lo:[0,0,1] neg_hi:[0,0,1]
	v_pk_fma_f32 v[4:5], v[8:9], v[116:117], v[4:5]
	s_waitcnt vmcnt(5)
	v_pk_mul_f32 v[8:9], v[124:125], v[10:11]
	v_pk_mul_f32 v[10:11], v[122:123], v[10:11]
	s_waitcnt vmcnt(4)
	v_pk_fma_f32 v[8:9], v[122:123], v[14:15], v[8:9] neg_lo:[0,0,1] neg_hi:[0,0,1]
	v_pk_fma_f32 v[10:11], v[124:125], v[14:15], v[10:11]
	v_pk_mul_f32 v[14:15], v[120:121], v[12:13]
	v_pk_mul_f32 v[12:13], v[118:119], v[12:13]
	v_pk_fma_f32 v[14:15], v[118:119], v[16:17], v[14:15] neg_lo:[0,0,1] neg_hi:[0,0,1]
	v_pk_fma_f32 v[12:13], v[120:121], v[16:17], v[12:13]
	v_pk_add_f32 v[16:17], v[126:127], v[6:7]
	v_pk_add_f32 v[22:23], v[2:3], v[4:5]
	v_pk_add_f32 v[118:119], v[2:3], v[4:5] neg_lo:[0,1] neg_hi:[0,1]
	v_pk_add_f32 v[4:5], v[8:9], v[14:15]
	v_pk_add_f32 v[116:117], v[126:127], v[6:7] neg_lo:[0,1] neg_hi:[0,1]
	v_pk_add_f32 v[120:121], v[10:11], v[12:13]
	v_pk_add_f32 v[122:123], v[8:9], v[14:15] neg_lo:[0,1] neg_hi:[0,1]
	v_pk_add_f32 v[12:13], v[10:11], v[12:13] neg_lo:[0,1] neg_hi:[0,1]
	v_pk_add_f32 v[2:3], v[16:17], v[4:5]
	v_pk_add_f32 v[4:5], v[16:17], v[4:5] neg_lo:[0,1] neg_hi:[0,1]
	v_pk_add_f32 v[6:7], v[22:23], v[120:121]
	v_pk_add_f32 v[8:9], v[22:23], v[120:121] neg_lo:[0,1] neg_hi:[0,1]
	v_pk_add_f32 v[10:11], v[116:117], v[12:13] neg_lo:[0,1] neg_hi:[0,1]
	v_pk_add_f32 v[14:15], v[118:119], v[122:123]
	v_pk_add_f32 v[12:13], v[116:117], v[12:13]
	v_pk_add_f32 v[16:17], v[118:119], v[122:123] neg_lo:[0,1] neg_hi:[0,1]
	ds_write_b128 v135, v[2:5]
	ds_write_b128 v135, v[10:13] offset:16
	ds_write_b128 v1, v[6:9]
	ds_write_b128 v1, v[14:17] offset:16
	v_ashrrev_i32_e32 v1, 3, v136
	v_mul_lo_u32 v1, v1, s49
	v_add_lshl_u32 v1, v1, v0, 2
	v_add_u32_e32 v135, 0, v1
	ds_read_b128 v[2:5], v135
	v_add_u32_e32 v1, s91, v1
	ds_read_b128 v[6:9], v1
	ds_read_b128 v[10:13], v135 offset:16
	ds_read_b128 v[14:17], v1 offset:16
	v_add_u32_e32 v136, 0x400, v134
	v_add_u32_e32 v134, 0x600, v134
	s_waitcnt lgkmcnt(3)
	v_pk_add_f32 v[22:23], v[2:3], v[4:5]
	v_pk_add_f32 v[118:119], v[2:3], v[4:5] neg_lo:[0,1] neg_hi:[0,1]
	v_lshlrev_b32_e32 v2, 3, v136
	v_ashrrev_i32_e32 v3, 31, v2
	v_lshlrev_b64 v[2:3], 2, v[2:3]
	s_waitcnt lgkmcnt(2)
	v_pk_add_f32 v[116:117], v[6:7], v[8:9]
	v_pk_add_f32 v[120:121], v[6:7], v[8:9] neg_lo:[0,1] neg_hi:[0,1]
	s_waitcnt lgkmcnt(0)
	v_pk_add_f32 v[124:125], v[14:15], v[16:17]
	v_pk_add_f32 v[128:129], v[14:15], v[16:17] neg_lo:[0,1] neg_hi:[0,1]
	v_lshl_add_u64 v[14:15], s[88:89], 0, v[2:3]
	v_lshl_add_u64 v[6:7], s[34:35], 0, v[2:3]
	v_pk_add_f32 v[122:123], v[10:11], v[12:13]
	v_pk_add_f32 v[126:127], v[10:11], v[12:13] neg_lo:[0,1] neg_hi:[0,1]
	global_load_dwordx4 v[2:5], v[6:7], off offset:16
	s_nop 0
	global_load_dwordx4 v[6:9], v[6:7], off
	s_nop 0
	global_load_dwordx4 v[10:13], v[14:15], off offset:16
	s_nop 0
	global_load_dwordx4 v[14:17], v[14:15], off
	v_pk_add_f32 v[130:131], v[22:23], v[122:123]
	v_pk_add_f32 v[132:133], v[116:117], v[124:125]
	v_pk_add_f32 v[116:117], v[116:117], v[124:125] neg_lo:[0,1] neg_hi:[0,1]
	v_pk_add_f32 v[124:125], v[120:121], v[126:127] neg_lo:[0,1] neg_hi:[0,1]
	v_pk_add_f32 v[120:121], v[126:127], v[120:121]
	s_waitcnt vmcnt(6)
	v_pk_mul_f32 v[126:127], v[132:133], v[104:105]
	v_pk_mul_f32 v[104:105], v[130:131], v[104:105]
	v_pk_add_f32 v[22:23], v[22:23], v[122:123] neg_lo:[0,1] neg_hi:[0,1]
	v_pk_add_f32 v[122:123], v[118:119], v[128:129]
	s_waitcnt vmcnt(4)
	v_pk_fma_f32 v[126:127], v[130:131], v[112:113], v[126:127] neg_lo:[0,0,1] neg_hi:[0,0,1]
	v_pk_fma_f32 v[104:105], v[112:113], v[132:133], v[104:105]
	v_pk_mul_f32 v[112:113], v[116:117], v[106:107]
	v_pk_add_f32 v[118:119], v[118:119], v[128:129] neg_lo:[0,1] neg_hi:[0,1]
	v_pk_fma_f32 v[112:113], v[22:23], v[114:115], v[112:113] neg_lo:[0,0,1] neg_hi:[0,0,1]
	v_pk_mul_f32 v[22:23], v[22:23], v[106:107]
	v_pk_mul_f32 v[106:107], v[124:125], v[18:19]
	v_pk_mul_f32 v[18:19], v[122:123], v[18:19]
	v_pk_fma_f32 v[106:107], v[122:123], v[108:109], v[106:107] neg_lo:[0,0,1] neg_hi:[0,0,1]
	v_pk_fma_f32 v[18:19], v[124:125], v[108:109], v[18:19]
	v_pk_mul_f32 v[108:109], v[120:121], v[20:21]
	v_pk_mul_f32 v[20:21], v[118:119], v[20:21]
	v_pk_fma_f32 v[108:109], v[118:119], v[110:111], v[108:109] neg_lo:[0,0,1] neg_hi:[0,0,1]
	v_pk_fma_f32 v[22:23], v[114:115], v[116:117], v[22:23]
	v_pk_fma_f32 v[20:21], v[120:121], v[110:111], v[20:21]
	v_pk_add_f32 v[110:111], v[126:127], v[112:113]
	v_pk_add_f32 v[116:117], v[126:127], v[112:113] neg_lo:[0,1] neg_hi:[0,1]
	v_pk_add_f32 v[112:113], v[106:107], v[108:109]
	v_pk_add_f32 v[114:115], v[104:105], v[22:23]
	v_pk_add_f32 v[22:23], v[104:105], v[22:23] neg_lo:[0,1] neg_hi:[0,1]
	v_pk_add_f32 v[118:119], v[18:19], v[20:21]
	v_pk_add_f32 v[120:121], v[106:107], v[108:109] neg_lo:[0,1] neg_hi:[0,1]
	v_pk_add_f32 v[122:123], v[18:19], v[20:21] neg_lo:[0,1] neg_hi:[0,1]
	v_pk_add_f32 v[18:19], v[110:111], v[112:113]
	v_pk_add_f32 v[20:21], v[110:111], v[112:113] neg_lo:[0,1] neg_hi:[0,1]
	v_pk_add_f32 v[104:105], v[114:115], v[118:119]
	v_pk_add_f32 v[106:107], v[114:115], v[118:119] neg_lo:[0,1] neg_hi:[0,1]
	v_pk_add_f32 v[108:109], v[116:117], v[122:123] neg_lo:[0,1] neg_hi:[0,1]
	v_pk_add_f32 v[112:113], v[22:23], v[120:121]
	v_pk_add_f32 v[110:111], v[116:117], v[122:123]
	v_pk_add_f32 v[114:115], v[22:23], v[120:121] neg_lo:[0,1] neg_hi:[0,1]
	ds_write_b128 v135, v[18:21]
	ds_write_b128 v135, v[108:111] offset:16
	ds_write_b128 v1, v[104:107]
	ds_write_b128 v1, v[112:115] offset:16
	v_ashrrev_i32_e32 v1, 3, v136
	v_lshlrev_b32_e32 v22, 3, v134
	v_mul_lo_u32 v1, v1, s49
	v_ashrrev_i32_e32 v23, 31, v22
	v_add_lshl_u32 v1, v1, v0, 2
	v_lshlrev_b64 v[22:23], 2, v[22:23]
	v_add_u32_e32 v135, 0, v1
	v_add_u32_e32 v1, s91, v1
	v_lshl_add_u64 v[128:129], s[88:89], 0, v[22:23]
	v_lshl_add_u64 v[22:23], s[34:35], 0, v[22:23]
	ds_read_b128 v[18:21], v135
	ds_read_b128 v[104:107], v135 offset:16
	ds_read_b128 v[108:111], v1
	ds_read_b128 v[112:115], v1 offset:16
	global_load_dwordx4 v[116:119], v[22:23], off offset:16
	global_load_dwordx4 v[120:123], v[22:23], off
	global_load_dwordx4 v[124:127], v[128:129], off offset:16
	s_nop 0
	global_load_dwordx4 v[128:131], v[128:129], off
	s_waitcnt lgkmcnt(3)
	v_pk_add_f32 v[22:23], v[18:19], v[20:21]
	s_waitcnt lgkmcnt(1)
	v_pk_add_f32 v[132:133], v[108:109], v[110:111]
	v_pk_add_f32 v[18:19], v[18:19], v[20:21] neg_lo:[0,1] neg_hi:[0,1]
	v_pk_add_f32 v[20:21], v[108:109], v[110:111] neg_lo:[0,1] neg_hi:[0,1]
	v_pk_add_f32 v[108:109], v[104:105], v[106:107]
	s_waitcnt lgkmcnt(0)
	v_pk_add_f32 v[110:111], v[112:113], v[114:115]
	v_pk_add_f32 v[104:105], v[104:105], v[106:107] neg_lo:[0,1] neg_hi:[0,1]
	v_pk_add_f32 v[106:107], v[112:113], v[114:115] neg_lo:[0,1] neg_hi:[0,1]
	v_pk_add_f32 v[112:113], v[22:23], v[108:109]
	v_pk_add_f32 v[114:115], v[132:133], v[110:111]
	v_pk_add_f32 v[22:23], v[22:23], v[108:109] neg_lo:[0,1] neg_hi:[0,1]
	v_pk_add_f32 v[108:109], v[132:133], v[110:111] neg_lo:[0,1] neg_hi:[0,1]
	v_pk_add_f32 v[132:133], v[20:21], v[104:105] neg_lo:[0,1] neg_hi:[0,1]
	v_pk_add_f32 v[20:21], v[104:105], v[20:21]
	v_pk_add_f32 v[110:111], v[18:19], v[106:107]
	v_pk_add_f32 v[18:19], v[18:19], v[106:107] neg_lo:[0,1] neg_hi:[0,1]
	s_waitcnt vmcnt(6)
	v_pk_mul_f32 v[104:105], v[114:115], v[6:7]
	v_pk_mul_f32 v[6:7], v[112:113], v[6:7]
	s_waitcnt vmcnt(4)
	v_pk_fma_f32 v[104:105], v[112:113], v[14:15], v[104:105] neg_lo:[0,0,1] neg_hi:[0,0,1]
	v_pk_fma_f32 v[6:7], v[14:15], v[114:115], v[6:7]
	v_pk_mul_f32 v[14:15], v[108:109], v[8:9]
	v_pk_mul_f32 v[8:9], v[22:23], v[8:9]
	v_pk_fma_f32 v[14:15], v[22:23], v[16:17], v[14:15] neg_lo:[0,0,1] neg_hi:[0,0,1]
	v_pk_fma_f32 v[8:9], v[16:17], v[108:109], v[8:9]
	v_pk_mul_f32 v[16:17], v[132:133], v[2:3]
	v_pk_mul_f32 v[2:3], v[110:111], v[2:3]
	v_pk_fma_f32 v[16:17], v[110:111], v[10:11], v[16:17] neg_lo:[0,0,1] neg_hi:[0,0,1]
	v_pk_fma_f32 v[2:3], v[132:133], v[10:11], v[2:3]
	v_pk_mul_f32 v[10:11], v[20:21], v[4:5]
	v_pk_mul_f32 v[4:5], v[18:19], v[4:5]
	v_pk_fma_f32 v[10:11], v[18:19], v[12:13], v[10:11] neg_lo:[0,0,1] neg_hi:[0,0,1]
	v_pk_fma_f32 v[4:5], v[20:21], v[12:13], v[4:5]
	v_pk_add_f32 v[12:13], v[104:105], v[14:15]
	v_pk_add_f32 v[18:19], v[6:7], v[8:9]
	v_pk_add_f32 v[22:23], v[6:7], v[8:9] neg_lo:[0,1] neg_hi:[0,1]
	v_pk_add_f32 v[8:9], v[16:17], v[10:11]
	v_pk_add_f32 v[20:21], v[104:105], v[14:15] neg_lo:[0,1] neg_hi:[0,1]
	v_pk_add_f32 v[14:15], v[2:3], v[4:5]
	v_pk_add_f32 v[16:17], v[16:17], v[10:11] neg_lo:[0,1] neg_hi:[0,1]
	v_pk_add_f32 v[104:105], v[2:3], v[4:5] neg_lo:[0,1] neg_hi:[0,1]
	v_pk_add_f32 v[2:3], v[12:13], v[8:9]
	v_pk_add_f32 v[4:5], v[12:13], v[8:9] neg_lo:[0,1] neg_hi:[0,1]
	v_pk_add_f32 v[6:7], v[18:19], v[14:15]
	v_pk_add_f32 v[8:9], v[18:19], v[14:15] neg_lo:[0,1] neg_hi:[0,1]
	v_pk_add_f32 v[10:11], v[20:21], v[104:105] neg_lo:[0,1] neg_hi:[0,1]
	v_pk_add_f32 v[14:15], v[22:23], v[16:17]
	v_pk_add_f32 v[12:13], v[20:21], v[104:105]
	v_pk_add_f32 v[16:17], v[22:23], v[16:17] neg_lo:[0,1] neg_hi:[0,1]
	ds_write_b128 v135, v[2:5]
	ds_write_b128 v135, v[10:13] offset:16
	ds_write_b128 v1, v[6:9]
	ds_write_b128 v1, v[14:17] offset:16
	v_ashrrev_i32_e32 v1, 3, v134
	v_mul_lo_u32 v1, v1, s49
	v_add_lshl_u32 v4, v1, v0, 2
	v_add_u32_e32 v104, 0, v4
	v_add_u32_e32 v105, s91, v4
	ds_read_b128 v[0:3], v104
	ds_read_b128 v[4:7], v105
	ds_read_b128 v[8:11], v104 offset:16
	ds_read_b128 v[12:15], v105 offset:16
	s_waitcnt lgkmcnt(2)
	v_pk_add_f32 v[18:19], v[4:5], v[6:7]
	v_pk_add_f32 v[16:17], v[0:1], v[2:3]
	v_pk_add_f32 v[0:1], v[0:1], v[2:3] neg_lo:[0,1] neg_hi:[0,1]
	v_pk_add_f32 v[2:3], v[4:5], v[6:7] neg_lo:[0,1] neg_hi:[0,1]
	s_waitcnt lgkmcnt(0)
	v_pk_add_f32 v[6:7], v[12:13], v[14:15]
	v_pk_add_f32 v[4:5], v[8:9], v[10:11]
	v_pk_add_f32 v[8:9], v[8:9], v[10:11] neg_lo:[0,1] neg_hi:[0,1]
	v_pk_add_f32 v[10:11], v[12:13], v[14:15] neg_lo:[0,1] neg_hi:[0,1]
	v_pk_add_f32 v[14:15], v[18:19], v[6:7]
	v_pk_add_f32 v[12:13], v[16:17], v[4:5]
	v_pk_add_f32 v[6:7], v[18:19], v[6:7] neg_lo:[0,1] neg_hi:[0,1]
	v_pk_add_f32 v[18:19], v[2:3], v[8:9] neg_lo:[0,1] neg_hi:[0,1]
	v_pk_add_f32 v[2:3], v[8:9], v[2:3]
	s_waitcnt vmcnt(2)
	v_pk_mul_f32 v[8:9], v[14:15], v[120:121]
	v_pk_add_f32 v[4:5], v[16:17], v[4:5] neg_lo:[0,1] neg_hi:[0,1]
	v_pk_add_f32 v[16:17], v[0:1], v[10:11]
	v_pk_add_f32 v[0:1], v[0:1], v[10:11] neg_lo:[0,1] neg_hi:[0,1]
	s_waitcnt vmcnt(0)
	v_pk_fma_f32 v[8:9], v[12:13], v[128:129], v[8:9] neg_lo:[0,0,1] neg_hi:[0,0,1]
	v_pk_mul_f32 v[10:11], v[12:13], v[120:121]
	v_pk_mul_f32 v[12:13], v[6:7], v[122:123]
	v_pk_fma_f32 v[10:11], v[128:129], v[14:15], v[10:11]
	v_pk_fma_f32 v[12:13], v[4:5], v[130:131], v[12:13] neg_lo:[0,0,1] neg_hi:[0,0,1]
	v_pk_mul_f32 v[4:5], v[4:5], v[122:123]
	v_pk_mul_f32 v[14:15], v[16:17], v[116:117]
	v_pk_fma_f32 v[4:5], v[130:131], v[6:7], v[4:5]
	v_pk_mul_f32 v[6:7], v[18:19], v[116:117]
	v_pk_fma_f32 v[14:15], v[18:19], v[124:125], v[14:15]
	v_pk_fma_f32 v[6:7], v[16:17], v[124:125], v[6:7] neg_lo:[0,0,1] neg_hi:[0,0,1]
	v_pk_mul_f32 v[16:17], v[2:3], v[118:119]
	v_pk_add_f32 v[20:21], v[8:9], v[12:13] neg_lo:[0,1] neg_hi:[0,1]
	v_pk_fma_f32 v[16:17], v[0:1], v[126:127], v[16:17] neg_lo:[0,0,1] neg_hi:[0,0,1]
	v_pk_mul_f32 v[0:1], v[0:1], v[118:119]
	v_pk_add_f32 v[18:19], v[10:11], v[4:5]
	v_pk_fma_f32 v[0:1], v[2:3], v[126:127], v[0:1]
	v_pk_add_f32 v[2:3], v[8:9], v[12:13]
	v_pk_add_f32 v[8:9], v[6:7], v[16:17]
	v_pk_add_f32 v[22:23], v[10:11], v[4:5] neg_lo:[0,1] neg_hi:[0,1]
	v_pk_add_f32 v[10:11], v[14:15], v[0:1]
	v_pk_add_f32 v[16:17], v[6:7], v[16:17] neg_lo:[0,1] neg_hi:[0,1]
	v_pk_add_f32 v[14:15], v[14:15], v[0:1] neg_lo:[0,1] neg_hi:[0,1]
	v_pk_add_f32 v[0:1], v[2:3], v[8:9]
	v_pk_add_f32 v[2:3], v[2:3], v[8:9] neg_lo:[0,1] neg_hi:[0,1]
	v_pk_add_f32 v[4:5], v[18:19], v[10:11]
	v_pk_add_f32 v[6:7], v[18:19], v[10:11] neg_lo:[0,1] neg_hi:[0,1]
	v_pk_add_f32 v[8:9], v[20:21], v[14:15] neg_lo:[0,1] neg_hi:[0,1]
	v_pk_add_f32 v[12:13], v[22:23], v[16:17]
	v_pk_add_f32 v[10:11], v[20:21], v[14:15]
	v_pk_add_f32 v[14:15], v[22:23], v[16:17] neg_lo:[0,1] neg_hi:[0,1]
	ds_write_b128 v104, v[0:3]
	ds_write_b128 v104, v[8:11] offset:16
	ds_write_b128 v105, v[4:7]
	ds_write_b128 v105, v[12:15] offset:16
	v_mov_b32_e32 v0, v163
	s_waitcnt lgkmcnt(0)
	s_barrier
	s_nop 0
	s_nop 0
	v_lshlrev_b32_e32 v1, 1, v0
	v_and_b32_e32 v162, 2, v1
	v_lshrrev_b32_e32 v1, 31, v0
	v_add_u32_e32 v0, v0, v1
	v_ashrrev_i32_e32 v187, 1, v0
	v_mul_lo_u32 v0, v187, s49
	v_or_b32_e32 v0, v0, v162
	v_lshlrev_b32_e32 v0, 2, v0
	v_add_u32_e32 v136, 0, v0
	v_add_u32_e32 v140, s91, v0
	ds_read2_b64 v[0:3], v136 offset1:2
	ds_read2_b64 v[8:11], v136 offset0:4 offset1:6
	ds_read2_b64 v[4:7], v140 offset1:2
	ds_read2_b64 v[12:15], v140 offset0:4 offset1:6
	ds_read2_b64 v[16:19], v136 offset0:8 offset1:10
	ds_read2_b64 v[20:23], v140 offset0:8 offset1:10
	ds_read2_b64 v[104:107], v136 offset0:12 offset1:14
	ds_read2_b64 v[108:111], v140 offset0:12 offset1:14
	ds_read2_b64 v[112:115], v136 offset0:16 offset1:18
	ds_read2_b64 v[116:119], v136 offset0:20 offset1:22
	ds_read2_b64 v[120:123], v140 offset0:16 offset1:18
	ds_read2_b64 v[124:127], v140 offset0:20 offset1:22
	ds_read2_b64 v[128:131], v136 offset0:24 offset1:26
	ds_read2_b64 v[132:135], v140 offset0:24 offset1:26
	ds_read2_b64 v[136:139], v136 offset0:28 offset1:30
	ds_read2_b64 v[140:143], v140 offset0:28 offset1:30
	s_waitcnt lgkmcnt(3)
	v_mov_b32_e32 v218, v129
	v_mov_b32_e32 v219, v131
	s_waitcnt lgkmcnt(1)
	v_mov_b32_e32 v210, v137
	s_waitcnt lgkmcnt(0)
	v_mov_b32_e32 v145, v143
	v_or_b32_e32 v143, 1, v162
	v_mov_b32_e32 v144, v141
	v_cvt_f32_ubyte0_e32 v141, v162
	v_cvt_f32_ubyte0_e32 v143, v143
	v_mul_f32_e32 v141, 0x3c800000, v141
	v_mul_f32_e32 v143, 0x3c800000, v143
	v_cos_f32_e32 v164, v141
	v_cos_f32_e32 v165, v143
	v_sin_f32_e64 v166, -v141
	v_sin_f32_e64 v167, -v143
	v_mov_b32_e32 v211, v139
	v_mov_b32_e32 v141, v142
	v_mov_b32_e32 v137, v138
	v_pk_mul_f32 v[188:189], v[166:167], v[166:167]
	v_pk_mul_f32 v[190:191], v[164:165], v[166:167]
	v_pk_fma_f32 v[188:189], v[164:165], v[164:165], v[188:189] neg_lo:[0,0,1] neg_hi:[0,0,1]
	v_pk_add_f32 v[190:191], v[190:191], v[190:191]
	v_pk_mul_f32 v[200:201], v[166:167], v[188:189]
	v_pk_mul_f32 v[192:193], v[190:191], v[190:191]
	v_pk_mul_f32 v[194:195], v[188:189], v[190:191]
	v_pk_fma_f32 v[192:193], v[188:189], v[188:189], v[192:193] neg_lo:[0,0,1] neg_hi:[0,0,1]
	v_pk_add_f32 v[194:195], v[194:195], v[194:195]
	v_pk_mul_f32 v[198:199], v[166:167], v[190:191]
	v_pk_fma_f32 v[200:201], v[164:165], v[190:191], v[200:201]
	v_pk_mul_f32 v[196:197], v[194:195], v[194:195]
	v_pk_fma_f32 v[198:199], v[164:165], v[188:189], v[198:199] neg_lo:[0,0,1] neg_hi:[0,0,1]
	v_pk_mul_f32 v[206:207], v[192:193], v[200:201]
	v_pk_fma_f32 v[196:197], v[192:193], v[192:193], v[196:197] neg_lo:[0,0,1] neg_hi:[0,0,1]
	v_pk_mul_f32 v[202:203], v[194:195], v[200:201]
	v_pk_mul_f32 v[204:205], v[192:193], v[194:195]
	v_pk_fma_f32 v[206:207], v[194:195], v[198:199], v[206:207]
	v_pk_fma_f32 v[202:203], v[192:193], v[198:199], v[202:203] neg_lo:[0,0,1] neg_hi:[0,0,1]
	v_pk_add_f32 v[204:205], v[204:205], v[204:205]
	v_pk_mul_f32 v[212:213], v[196:197], v[206:207]
	v_pk_mul_f32 v[208:209], v[204:205], v[206:207]
	v_pk_fma_f32 v[212:213], v[204:205], v[202:203], v[212:213]
	v_pk_fma_f32 v[208:209], v[196:197], v[202:203], v[208:209] neg_lo:[0,0,1] neg_hi:[0,0,1]
	v_pk_mul_f32 v[214:215], v[212:213], v[210:211]
	v_pk_mul_f32 v[142:143], v[190:191], v[194:195]
	v_pk_fma_f32 v[214:215], v[208:209], v[144:145], v[214:215] neg_lo:[0,0,1] neg_hi:[0,0,1]
	v_pk_mul_f32 v[144:145], v[212:213], v[144:145]
	v_pk_fma_f32 v[142:143], v[188:189], v[192:193], v[142:143] neg_lo:[0,0,1] neg_hi:[0,0,1]
	v_pk_fma_f32 v[144:145], v[208:209], v[210:211], v[144:145]
	v_pk_mul_f32 v[208:209], v[190:191], v[192:193]
	v_mov_b32_e32 v129, v130
	v_pk_fma_f32 v[208:209], v[188:189], v[194:195], v[208:209]
	v_pk_mul_f32 v[130:131], v[194:195], v[196:197]
	v_pk_mul_f32 v[138:139], v[196:197], v[208:209]
	v_pk_mul_f32 v[210:211], v[204:205], v[208:209]
	v_pk_fma_f32 v[138:139], v[204:205], v[142:143], v[138:139]
	v_pk_fma_f32 v[210:211], v[196:197], v[142:143], v[210:211] neg_lo:[0,0,1] neg_hi:[0,0,1]
	v_pk_mul_f32 v[212:213], v[138:139], v[136:137]
	v_pk_mul_f32 v[138:139], v[138:139], v[140:141]
	v_pk_fma_f32 v[212:213], v[210:211], v[140:141], v[212:213] neg_lo:[0,0,1] neg_hi:[0,0,1]
	v_pk_fma_f32 v[136:137], v[210:211], v[136:137], v[138:139]
	v_pk_mul_f32 v[210:211], v[166:167], v[192:193]
	v_pk_mul_f32 v[140:141], v[166:167], v[194:195]
	v_pk_fma_f32 v[210:211], v[164:165], v[194:195], v[210:211]
	v_pk_fma_f32 v[140:141], v[164:165], v[192:193], v[140:141] neg_lo:[0,0,1] neg_hi:[0,0,1]
	v_pk_mul_f32 v[220:221], v[196:197], v[210:211]
	v_pk_mul_f32 v[216:217], v[204:205], v[210:211]
	v_pk_fma_f32 v[220:221], v[204:205], v[140:141], v[220:221]
	v_mov_b32_e32 v138, v133
	v_mov_b32_e32 v139, v135
	v_pk_fma_f32 v[216:217], v[196:197], v[140:141], v[216:217] neg_lo:[0,0,1] neg_hi:[0,0,1]
	v_pk_mul_f32 v[222:223], v[220:221], v[218:219]
	v_mov_b32_e32 v133, v134
	v_pk_fma_f32 v[222:223], v[216:217], v[138:139], v[222:223] neg_lo:[0,0,1] neg_hi:[0,0,1]
	v_pk_mul_f32 v[138:139], v[220:221], v[138:139]
	v_pk_mul_f32 v[134:135], v[194:195], v[204:205]
	v_pk_fma_f32 v[130:131], v[192:193], v[204:205], v[130:131]
	v_pk_fma_f32 v[138:139], v[216:217], v[218:219], v[138:139]
	v_pk_fma_f32 v[134:135], v[192:193], v[196:197], v[134:135] neg_lo:[0,0,1] neg_hi:[0,0,1]
	v_pk_mul_f32 v[216:217], v[130:131], v[128:129]
	v_pk_mul_f32 v[130:131], v[130:131], v[132:133]
	v_pk_mul_f32 v[218:219], v[200:201], v[196:197]
	v_pk_fma_f32 v[216:217], v[134:135], v[132:133], v[216:217] neg_lo:[0,0,1] neg_hi:[0,0,1]
	v_pk_fma_f32 v[128:129], v[134:135], v[128:129], v[130:131]
	v_pk_mul_f32 v[132:133], v[200:201], v[204:205]
	v_mov_b32_e32 v134, v117
	v_mov_b32_e32 v135, v119
	v_pk_fma_f32 v[218:219], v[198:199], v[204:205], v[218:219]
	v_mov_b32_e32 v130, v125
	v_mov_b32_e32 v131, v127
	v_pk_fma_f32 v[132:133], v[198:199], v[196:197], v[132:133] neg_lo:[0,0,1] neg_hi:[0,0,1]
	v_pk_mul_f32 v[220:221], v[218:219], v[134:135]
	v_mov_b32_e32 v117, v118
	v_pk_mul_f32 v[118:119], v[190:191], v[196:197]
	v_pk_fma_f32 v[220:221], v[132:133], v[130:131], v[220:221] neg_lo:[0,0,1] neg_hi:[0,0,1]
	v_pk_mul_f32 v[130:131], v[218:219], v[130:131]
	v_mov_b32_e32 v125, v126
	v_pk_mul_f32 v[126:127], v[190:191], v[204:205]
	v_pk_fma_f32 v[118:119], v[188:189], v[204:205], v[118:119]
	v_pk_fma_f32 v[130:131], v[132:133], v[134:135], v[130:131]
	v_pk_fma_f32 v[126:127], v[188:189], v[196:197], v[126:127] neg_lo:[0,0,1] neg_hi:[0,0,1]
	v_pk_mul_f32 v[132:133], v[118:119], v[116:117]
	v_pk_mul_f32 v[118:119], v[118:119], v[124:125]
	v_pk_mul_f32 v[134:135], v[166:167], v[196:197]
	v_pk_fma_f32 v[132:133], v[126:127], v[124:125], v[132:133] neg_lo:[0,0,1] neg_hi:[0,0,1]
	v_pk_fma_f32 v[116:117], v[126:127], v[116:117], v[118:119]
	v_pk_mul_f32 v[124:125], v[166:167], v[204:205]
	v_mov_b32_e32 v126, v113
	v_mov_b32_e32 v127, v115
	v_pk_fma_f32 v[134:135], v[164:165], v[204:205], v[134:135]
	v_mov_b32_e32 v113, v114
	v_mov_b32_e32 v118, v121
	v_mov_b32_e32 v119, v123
	v_pk_fma_f32 v[124:125], v[164:165], v[196:197], v[124:125] neg_lo:[0,0,1] neg_hi:[0,0,1]
	v_pk_mul_f32 v[218:219], v[134:135], v[126:127]
	v_mov_b32_e32 v121, v122
	v_pk_mul_f32 v[114:115], v[204:205], v[112:113]
	v_pk_fma_f32 v[218:219], v[124:125], v[118:119], v[218:219] neg_lo:[0,0,1] neg_hi:[0,0,1]
	v_pk_mul_f32 v[118:119], v[134:135], v[118:119]
	v_pk_fma_f32 v[114:115], v[196:197], v[120:121], v[114:115] neg_lo:[0,0,1] neg_hi:[0,0,1]
	v_pk_mul_f32 v[120:121], v[204:205], v[120:121]
	v_mov_b32_e32 v122, v105
	v_mov_b32_e32 v123, v107
	v_mov_b32_e32 v105, v106
	v_pk_fma_f32 v[118:119], v[124:125], v[126:127], v[118:119]
	v_pk_fma_f32 v[112:113], v[196:197], v[112:113], v[120:121]
	v_mov_b32_e32 v120, v109
	v_mov_b32_e32 v121, v111
	v_pk_mul_f32 v[124:125], v[206:207], v[122:123]
	v_mov_b32_e32 v109, v110
	v_pk_mul_f32 v[106:107], v[208:209], v[104:105]
	v_pk_fma_f32 v[124:125], v[202:203], v[120:121], v[124:125] neg_lo:[0,0,1] neg_hi:[0,0,1]
	v_pk_mul_f32 v[120:121], v[206:207], v[120:121]
	v_pk_fma_f32 v[106:107], v[142:143], v[108:109], v[106:107] neg_lo:[0,0,1] neg_hi:[0,0,1]
	v_pk_mul_f32 v[108:109], v[208:209], v[108:109]
	v_mov_b32_e32 v110, v17
	v_mov_b32_e32 v111, v19
	v_mov_b32_e32 v17, v18
	v_pk_fma_f32 v[120:121], v[202:203], v[122:123], v[120:121]
	v_pk_fma_f32 v[104:105], v[142:143], v[104:105], v[108:109]
	v_mov_b32_e32 v108, v21
	v_mov_b32_e32 v109, v23
	v_pk_mul_f32 v[122:123], v[110:111], v[210:211]
	v_mov_b32_e32 v21, v22
	v_pk_mul_f32 v[18:19], v[16:17], v[194:195]
	v_pk_fma_f32 v[122:123], v[108:109], v[140:141], v[122:123] neg_lo:[0,0,1] neg_hi:[0,0,1]
	v_pk_mul_f32 v[108:109], v[108:109], v[210:211]
	v_pk_fma_f32 v[18:19], v[192:193], v[20:21], v[18:19] neg_lo:[0,0,1] neg_hi:[0,0,1]
	v_pk_mul_f32 v[20:21], v[194:195], v[20:21]
	v_mov_b32_e32 v22, v9
	v_mov_b32_e32 v23, v11
	v_mov_b32_e32 v9, v10
	v_pk_fma_f32 v[108:109], v[110:111], v[140:141], v[108:109]
	v_pk_fma_f32 v[16:17], v[16:17], v[192:193], v[20:21]
	v_mov_b32_e32 v20, v13
	v_mov_b32_e32 v21, v15
	v_pk_mul_f32 v[110:111], v[22:23], v[200:201]
	v_mov_b32_e32 v13, v14
	v_pk_mul_f32 v[10:11], v[8:9], v[190:191]
	v_pk_fma_f32 v[110:111], v[20:21], v[198:199], v[110:111] neg_lo:[0,0,1] neg_hi:[0,0,1]
	v_pk_mul_f32 v[20:21], v[20:21], v[200:201]
	v_pk_fma_f32 v[10:11], v[12:13], v[188:189], v[10:11] neg_lo:[0,0,1] neg_hi:[0,0,1]
	v_pk_mul_f32 v[12:13], v[12:13], v[190:191]
	v_mov_b32_e32 v14, v1
	v_mov_b32_e32 v15, v3
	v_pk_fma_f32 v[20:21], v[22:23], v[198:199], v[20:21]
	v_pk_fma_f32 v[8:9], v[8:9], v[188:189], v[12:13]
	v_mov_b32_e32 v12, v5
	v_mov_b32_e32 v13, v7
	v_pk_mul_f32 v[22:23], v[14:15], v[166:167]
	v_mov_b32_e32 v1, v2
	v_lshl_or_b32 v2, v187, 6, v162
	v_lshlrev_b32_e32 v3, 2, v187
	v_pk_fma_f32 v[22:23], v[12:13], v[164:165], v[22:23] neg_lo:[0,0,1] neg_hi:[0,0,1]
	v_pk_mul_f32 v[12:13], v[12:13], v[166:167]
	v_mov_b32_e32 v5, v6
	v_add_lshl_u32 v2, v2, v3, 2
	v_pk_fma_f32 v[12:13], v[14:15], v[164:165], v[12:13]
	v_add_u32_e32 v162, 0, v2
	v_add_u32_e32 v166, s91, v2
	v_pk_add_f32 v[2:3], v[0:1], v[112:113]
	v_pk_add_f32 v[6:7], v[4:5], v[114:115]
	v_pk_add_f32 v[0:1], v[0:1], v[112:113] neg_lo:[0,1] neg_hi:[0,1]
	v_pk_add_f32 v[4:5], v[4:5], v[114:115] neg_lo:[0,1] neg_hi:[0,1]
	v_pk_add_f32 v[14:15], v[16:17], v[128:129]
	v_pk_add_f32 v[112:113], v[18:19], v[216:217]
	v_pk_add_f32 v[16:17], v[16:17], v[128:129] neg_lo:[0,1] neg_hi:[0,1]
	v_pk_add_f32 v[18:19], v[18:19], v[216:217] neg_lo:[0,1] neg_hi:[0,1]
	v_pk_add_f32 v[114:115], v[8:9], v[116:117]
	v_pk_add_f32 v[126:127], v[10:11], v[132:133]
	v_pk_add_f32 v[8:9], v[8:9], v[116:117] neg_lo:[0,1] neg_hi:[0,1]
	v_pk_add_f32 v[116:117], v[104:105], v[136:137]
	v_pk_add_f32 v[128:129], v[106:107], v[212:213]
	v_pk_add_f32 v[106:107], v[106:107], v[212:213] neg_lo:[0,1] neg_hi:[0,1]
	v_pk_add_f32 v[10:11], v[10:11], v[132:133] neg_lo:[0,1] neg_hi:[0,1]
	v_pk_add_f32 v[104:105], v[104:105], v[136:137] neg_lo:[0,1] neg_hi:[0,1]
	v_pk_add_f32 v[132:133], v[12:13], v[118:119]
	v_pk_add_f32 v[12:13], v[12:13], v[118:119] neg_lo:[0,1] neg_hi:[0,1]
	v_pk_add_f32 v[118:119], v[108:109], v[138:139]
	v_pk_add_f32 v[108:109], v[108:109], v[138:139] neg_lo:[0,1] neg_hi:[0,1]
	v_pk_add_f32 v[138:139], v[20:21], v[130:131]
	v_pk_add_f32 v[20:21], v[20:21], v[130:131] neg_lo:[0,1] neg_hi:[0,1]
	v_pk_add_f32 v[130:131], v[120:121], v[144:145]
	v_pk_add_f32 v[120:121], v[120:121], v[144:145] neg_lo:[0,1] neg_hi:[0,1]
	v_pk_add_f32 v[144:145], v[2:3], v[14:15]
	v_pk_add_f32 v[164:165], v[6:7], v[112:113]
	v_pk_add_f32 v[2:3], v[2:3], v[14:15] neg_lo:[0,1] neg_hi:[0,1]
	v_pk_add_f32 v[6:7], v[6:7], v[112:113] neg_lo:[0,1] neg_hi:[0,1]
	v_pk_add_f32 v[14:15], v[0:1], v[18:19] neg_lo:[0,1] neg_hi:[0,1]
	v_pk_add_f32 v[112:113], v[4:5], v[16:17]
	v_pk_add_f32 v[0:1], v[0:1], v[18:19]
	v_pk_add_f32 v[4:5], v[4:5], v[16:17] neg_lo:[0,1] neg_hi:[0,1]
	v_pk_add_f32 v[16:17], v[114:115], v[116:117]
	v_pk_add_f32 v[18:19], v[126:127], v[128:129]
	v_pk_add_f32 v[114:115], v[114:115], v[116:117] neg_lo:[0,1] neg_hi:[0,1]
	v_pk_add_f32 v[116:117], v[126:127], v[128:129] neg_lo:[0,1] neg_hi:[0,1]
	v_pk_add_f32 v[126:127], v[8:9], v[106:107] neg_lo:[0,1] neg_hi:[0,1]
	v_pk_add_f32 v[134:135], v[22:23], v[218:219]
	v_pk_add_f32 v[22:23], v[22:23], v[218:219] neg_lo:[0,1] neg_hi:[0,1]
	v_pk_add_f32 v[136:137], v[122:123], v[222:223]
	v_pk_add_f32 v[122:123], v[122:123], v[222:223] neg_lo:[0,1] neg_hi:[0,1]
	v_pk_add_f32 v[140:141], v[110:111], v[220:221]
	v_pk_add_f32 v[110:111], v[110:111], v[220:221] neg_lo:[0,1] neg_hi:[0,1]
	v_pk_add_f32 v[142:143], v[124:125], v[214:215]
	v_pk_add_f32 v[128:129], v[10:11], v[104:105]
	v_pk_add_f32 v[10:11], v[10:11], v[104:105] neg_lo:[0,1] neg_hi:[0,1]
	v_pk_mul_f32 v[126:127], v[126:127], s[82:83] op_sel_hi:[1,0]
	v_pk_add_f32 v[124:125], v[124:125], v[214:215] neg_lo:[0,1] neg_hi:[0,1]
	v_pk_add_f32 v[8:9], v[8:9], v[106:107]
	v_pk_add_f32 v[104:105], v[132:133], v[118:119]
	v_pk_add_f32 v[106:107], v[134:135], v[136:137]
	v_pk_add_f32 v[118:119], v[132:133], v[118:119] neg_lo:[0,1] neg_hi:[0,1]
	v_pk_add_f32 v[132:133], v[134:135], v[136:137] neg_lo:[0,1] neg_hi:[0,1]
	v_pk_add_f32 v[134:135], v[12:13], v[122:123] neg_lo:[0,1] neg_hi:[0,1]
	v_pk_add_f32 v[136:137], v[22:23], v[108:109]
	v_pk_add_f32 v[12:13], v[12:13], v[122:123]
	v_pk_add_f32 v[22:23], v[22:23], v[108:109] neg_lo:[0,1] neg_hi:[0,1]
	v_pk_add_f32 v[108:109], v[138:139], v[130:131]
	v_pk_add_f32 v[122:123], v[140:141], v[142:143]
	v_pk_add_f32 v[130:131], v[138:139], v[130:131] neg_lo:[0,1] neg_hi:[0,1]
	v_pk_add_f32 v[138:139], v[140:141], v[142:143] neg_lo:[0,1] neg_hi:[0,1]
	v_pk_add_f32 v[142:143], v[110:111], v[120:121]
	v_pk_add_f32 v[110:111], v[110:111], v[120:121] neg_lo:[0,1] neg_hi:[0,1]
	v_pk_add_f32 v[120:121], v[144:145], v[16:17]
	v_pk_add_f32 v[16:17], v[144:145], v[16:17] neg_lo:[0,1] neg_hi:[0,1]
	v_pk_fma_f32 v[144:145], v[128:129], s[82:83], v[126:127] op_sel_hi:[1,0,1] neg_lo:[1,0,0] neg_hi:[1,0,0]
	v_pk_mul_f32 v[10:11], v[10:11], s[82:83] op_sel_hi:[1,0]
	v_pk_add_f32 v[140:141], v[20:21], v[124:125] neg_lo:[0,1] neg_hi:[0,1]
	v_pk_fma_f32 v[126:127], v[128:129], s[82:83], v[126:127] op_sel_hi:[1,0,1]
	v_pk_add_f32 v[128:129], v[14:15], v[144:145]
	v_pk_add_f32 v[14:15], v[14:15], v[144:145] neg_lo:[0,1] neg_hi:[0,1]
	v_pk_add_f32 v[144:145], v[6:7], v[114:115]
	v_pk_add_f32 v[6:7], v[6:7], v[114:115] neg_lo:[0,1] neg_hi:[0,1]
	v_pk_fma_f32 v[114:115], v[8:9], s[54:55], v[10:11] op_sel_hi:[1,0,1] neg_lo:[0,0,1] neg_hi:[0,0,1]
	v_pk_fma_f32 v[8:9], v[8:9], s[82:83], v[10:11] op_sel_hi:[1,0,1] neg_lo:[0,0,1] neg_hi:[0,0,1]
	v_pk_add_f32 v[20:21], v[20:21], v[124:125]
	v_pk_add_f32 v[124:125], v[164:165], v[18:19]
	v_pk_add_f32 v[18:19], v[164:165], v[18:19] neg_lo:[0,1] neg_hi:[0,1]
	v_pk_add_f32 v[164:165], v[112:113], v[126:127]
	v_pk_add_f32 v[112:113], v[112:113], v[126:127] neg_lo:[0,1] neg_hi:[0,1]
	v_pk_add_f32 v[126:127], v[2:3], v[116:117] neg_lo:[0,1] neg_hi:[0,1]
	v_pk_add_f32 v[2:3], v[2:3], v[116:117]
	v_pk_add_f32 v[116:117], v[4:5], v[8:9]
	v_pk_add_f32 v[4:5], v[4:5], v[8:9] neg_lo:[0,1] neg_hi:[0,1]
	v_pk_add_f32 v[8:9], v[104:105], v[108:109]
	v_pk_add_f32 v[104:105], v[104:105], v[108:109] neg_lo:[0,1] neg_hi:[0,1]
	v_pk_mul_f32 v[108:109], v[140:141], s[82:83] op_sel_hi:[1,0]
	v_pk_add_f32 v[10:11], v[0:1], v[114:115]
	v_pk_add_f32 v[0:1], v[0:1], v[114:115] neg_lo:[0,1] neg_hi:[0,1]
	v_pk_add_f32 v[114:115], v[106:107], v[122:123]
	v_pk_add_f32 v[106:107], v[106:107], v[122:123] neg_lo:[0,1] neg_hi:[0,1]
	v_pk_fma_f32 v[122:123], v[142:143], s[82:83], v[108:109] op_sel_hi:[1,0,1] neg_lo:[1,0,0] neg_hi:[1,0,0]
	v_pk_fma_f32 v[108:109], v[142:143], s[82:83], v[108:109] op_sel_hi:[1,0,1]
	v_pk_mul_f32 v[110:111], v[110:111], s[82:83] op_sel_hi:[1,0]
	v_pk_add_f32 v[142:143], v[136:137], v[108:109]
	v_pk_add_f32 v[108:109], v[136:137], v[108:109] neg_lo:[0,1] neg_hi:[0,1]
	v_pk_add_f32 v[136:137], v[132:133], v[130:131]
	v_pk_add_f32 v[130:131], v[132:133], v[130:131] neg_lo:[0,1] neg_hi:[0,1]
	v_pk_fma_f32 v[132:133], v[20:21], s[54:55], v[110:111] op_sel_hi:[1,0,1] neg_lo:[0,0,1] neg_hi:[0,0,1]
	v_pk_fma_f32 v[20:21], v[20:21], s[82:83], v[110:111] op_sel_hi:[1,0,1] neg_lo:[0,0,1] neg_hi:[0,0,1]
	v_pk_add_f32 v[140:141], v[134:135], v[122:123]
	v_pk_add_f32 v[122:123], v[134:135], v[122:123] neg_lo:[0,1] neg_hi:[0,1]
	v_pk_add_f32 v[134:135], v[118:119], v[138:139] neg_lo:[0,1] neg_hi:[0,1]
	v_pk_add_f32 v[118:119], v[118:119], v[138:139]
	v_pk_add_f32 v[138:139], v[22:23], v[20:21]
	v_pk_add_f32 v[20:21], v[22:23], v[20:21] neg_lo:[0,1] neg_hi:[0,1]
	v_pk_add_f32 v[22:23], v[120:121], v[8:9]
	v_pk_add_f32 v[8:9], v[120:121], v[8:9] neg_lo:[0,1] neg_hi:[0,1]
	v_pk_mul_f32 v[120:121], v[142:143], s[80:81] op_sel_hi:[1,0]
	v_pk_add_f32 v[110:111], v[12:13], v[132:133]
	v_pk_add_f32 v[12:13], v[12:13], v[132:133] neg_lo:[0,1] neg_hi:[0,1]
	v_pk_add_f32 v[132:133], v[124:125], v[114:115]
	v_pk_add_f32 v[114:115], v[124:125], v[114:115] neg_lo:[0,1] neg_hi:[0,1]
	v_pk_fma_f32 v[120:121], v[140:141], s[72:73], v[120:121] op_sel_hi:[1,0,1] neg_lo:[0,0,1] neg_hi:[0,0,1]
	v_pk_mul_f32 v[124:125], v[142:143], s[72:73] op_sel_hi:[1,0]
	s_nop 0
	v_pk_fma_f32 v[124:125], v[140:141], s[80:81], v[124:125] op_sel_hi:[1,0,1]
	v_pk_add_f32 v[140:141], v[128:129], v[120:121]
	v_pk_add_f32 v[120:121], v[128:129], v[120:121] neg_lo:[0,1] neg_hi:[0,1]
	v_pk_mul_f32 v[128:129], v[134:135], s[82:83] op_sel_hi:[1,0]
	v_pk_add_f32 v[142:143], v[164:165], v[124:125]
	v_pk_fma_f32 v[134:135], v[136:137], s[82:83], v[128:129] op_sel_hi:[1,0,1] neg_lo:[1,0,0] neg_hi:[1,0,0]
	v_pk_fma_f32 v[128:129], v[136:137], s[82:83], v[128:129] op_sel_hi:[1,0,1]
	v_pk_add_f32 v[136:137], v[126:127], v[134:135]
	v_pk_add_f32 v[126:127], v[126:127], v[134:135] neg_lo:[0,1] neg_hi:[0,1]
	v_pk_mul_f32 v[134:135], v[138:139], s[72:73] op_sel_hi:[1,0]
	v_pk_mul_f32 v[138:139], v[138:139], s[80:81] op_sel_hi:[1,0]
	v_pk_fma_f32 v[134:135], v[110:111], s[80:81], v[134:135] op_sel_hi:[1,0,1] neg_lo:[0,0,1] neg_hi:[0,0,1]
	v_pk_fma_f32 v[110:111], v[110:111], s[72:73], v[138:139] op_sel_hi:[1,0,1]
	v_pk_add_f32 v[124:125], v[164:165], v[124:125] neg_lo:[0,1] neg_hi:[0,1]
	v_pk_add_f32 v[164:165], v[144:145], v[128:129]
	v_pk_add_f32 v[128:129], v[144:145], v[128:129] neg_lo:[0,1] neg_hi:[0,1]
	v_pk_add_f32 v[138:139], v[10:11], v[134:135]
	v_pk_add_f32 v[144:145], v[116:117], v[110:111]
	v_pk_add_f32 v[10:11], v[10:11], v[134:135] neg_lo:[0,1] neg_hi:[0,1]
	v_pk_add_f32 v[110:111], v[116:117], v[110:111] neg_lo:[0,1] neg_hi:[0,1]
	v_pk_add_f32 v[116:117], v[16:17], v[106:107] neg_lo:[0,1] neg_hi:[0,1]
	v_pk_add_f32 v[134:135], v[18:19], v[104:105]
	v_pk_add_f32 v[16:17], v[16:17], v[106:107]
	v_pk_add_f32 v[18:19], v[18:19], v[104:105] neg_lo:[0,1] neg_hi:[0,1]
	v_pk_mul_f32 v[104:105], v[108:109], s[72:73] op_sel_hi:[1,0]
	v_pk_mul_f32 v[106:107], v[108:109], s[80:81] op_sel_hi:[1,0]
	v_pk_fma_f32 v[104:105], v[122:123], s[84:85], v[104:105] op_sel_hi:[1,0,1] neg_lo:[0,0,1] neg_hi:[0,0,1]
	v_pk_fma_f32 v[106:107], v[122:123], s[72:73], v[106:107] op_sel_hi:[1,0,1] neg_lo:[0,0,1] neg_hi:[0,0,1]
	v_pk_add_f32 v[108:109], v[14:15], v[104:105]
	v_pk_add_f32 v[122:123], v[112:113], v[106:107]
	v_pk_add_f32 v[14:15], v[14:15], v[104:105] neg_lo:[0,1] neg_hi:[0,1]
	v_pk_add_f32 v[104:105], v[112:113], v[106:107] neg_lo:[0,1] neg_hi:[0,1]
	v_pk_mul_f32 v[106:107], v[130:131], s[82:83] op_sel_hi:[1,0]
	s_nop 0
	v_pk_fma_f32 v[112:113], v[118:119], s[54:55], v[106:107] op_sel_hi:[1,0,1] neg_lo:[0,0,1] neg_hi:[0,0,1]
	v_pk_fma_f32 v[106:107], v[118:119], s[82:83], v[106:107] op_sel_hi:[1,0,1] neg_lo:[0,0,1] neg_hi:[0,0,1]
	v_pk_add_f32 v[118:119], v[2:3], v[112:113]
	v_pk_add_f32 v[130:131], v[6:7], v[106:107]
	v_pk_add_f32 v[6:7], v[6:7], v[106:107] neg_lo:[0,1] neg_hi:[0,1]
	v_pk_mul_f32 v[106:107], v[20:21], s[80:81] op_sel_hi:[1,0]
	v_pk_mul_f32 v[20:21], v[20:21], s[72:73] op_sel_hi:[1,0]
	v_pk_fma_f32 v[106:107], v[12:13], s[52:53], v[106:107] op_sel_hi:[1,0,1] neg_lo:[0,0,1] neg_hi:[0,0,1]
	v_pk_fma_f32 v[12:13], v[12:13], s[80:81], v[20:21] op_sel_hi:[1,0,1] neg_lo:[0,0,1] neg_hi:[0,0,1]
	v_pk_add_f32 v[20:21], v[0:1], v[106:107]
	v_pk_add_f32 v[0:1], v[0:1], v[106:107] neg_lo:[0,1] neg_hi:[0,1]
	v_pk_add_f32 v[2:3], v[2:3], v[112:113] neg_lo:[0,1] neg_hi:[0,1]
	v_pk_add_f32 v[112:113], v[4:5], v[12:13]
	v_pk_add_f32 v[4:5], v[4:5], v[12:13] neg_lo:[0,1] neg_hi:[0,1]
	ds_write2_b64 v162, v[22:23], v[140:141] offset1:2
	ds_write2_b64 v166, v[132:133], v[142:143] offset1:2
	ds_write2_b64 v162, v[136:137], v[138:139] offset0:4 offset1:6
	ds_write2_b64 v166, v[164:165], v[144:145] offset0:4 offset1:6
	ds_write2_b64 v162, v[116:117], v[108:109] offset0:8 offset1:10
	ds_write2_b64 v166, v[134:135], v[122:123] offset0:8 offset1:10
	ds_write2_b64 v162, v[118:119], v[20:21] offset0:12 offset1:14
	ds_write2_b64 v166, v[130:131], v[112:113] offset0:12 offset1:14
	ds_write2_b64 v162, v[8:9], v[120:121] offset0:16 offset1:18
	ds_write2_b64 v166, v[114:115], v[124:125] offset0:16 offset1:18
	ds_write2_b64 v162, v[126:127], v[10:11] offset0:20 offset1:22
	ds_write2_b64 v166, v[128:129], v[110:111] offset0:20 offset1:22
	ds_write2_b64 v162, v[16:17], v[14:15] offset0:24 offset1:26
	ds_write2_b64 v166, v[18:19], v[104:105] offset0:24 offset1:26
	ds_write2_b64 v162, v[2:3], v[0:1] offset0:28 offset1:30
	ds_write2_b64 v166, v[6:7], v[4:5] offset0:28 offset1:30
	v_mov_b32_e32 v0, v163
	s_waitcnt lgkmcnt(0)
	s_barrier
	s_nop 0
	s_nop 0
	v_lshlrev_b32_e32 v1, 1, v0
	v_and_b32_e32 v145, 62, v1
	v_ashrrev_i32_e32 v1, 31, v0
	v_lshrrev_b32_e32 v1, 27, v1
	v_add_u32_e32 v0, v0, v1
	v_ashrrev_i32_e32 v0, 5, v0
	v_lshl_or_b32 v1, v0, 10, v145
	v_cvt_f32_ubyte0_e32 v144, v145
	v_or_b32_e32 v145, 1, v145
	v_cvt_f32_ubyte0_e32 v145, v145
	v_mul_f32_e32 v164, 0x3a800000, v144
	v_mul_f32_e32 v165, 0x3a800000, v145
	v_cos_f32_e32 v144, v164
	v_cos_f32_e32 v145, v165
	v_sin_f32_e64 v164, -v164
	v_sin_f32_e64 v165, -v165
	v_lshlrev_b32_e32 v0, 6, v0
	v_add_lshl_u32 v0, v1, v0, 2
	v_add_u32_e32 v162, 0, v0
	v_pk_mul_f32 v[166:167], v[164:165], v[164:165]
	v_pk_mul_f32 v[188:189], v[144:145], v[164:165]
	v_add_u32_e32 v187, s91, v0
	v_pk_fma_f32 v[166:167], v[144:145], v[144:145], v[166:167] neg_lo:[0,0,1] neg_hi:[0,0,1]
	v_pk_add_f32 v[188:189], v[188:189], v[188:189]
	v_add_u32_e32 v212, 0x800, v187
	v_add_u32_e32 v213, 0x800, v162
	v_pk_mul_f32 v[190:191], v[188:189], v[188:189]
	v_pk_mul_f32 v[192:193], v[166:167], v[188:189]
	v_pk_mul_f32 v[198:199], v[164:165], v[166:167]
	ds_read2_b64 v[0:3], v162 offset1:34
	ds_read2_b64 v[4:7], v187 offset1:34
	ds_read2_b64 v[8:11], v212 offset0:16 offset1:50
	ds_read2_b64 v[12:15], v213 offset0:16 offset1:50
	ds_read2_b64 v[16:19], v187 offset0:136 offset1:170
	ds_read2_b64 v[20:23], v162 offset0:136 offset1:170
	ds_read2_b64 v[104:107], v212 offset0:152 offset1:186
	ds_read2_b64 v[108:111], v213 offset0:152 offset1:186
	ds_read2_b64 v[112:115], v187 offset0:68 offset1:102
	ds_read2_b64 v[116:119], v162 offset0:68 offset1:102
	ds_read2_b64 v[120:123], v212 offset0:84 offset1:118
	ds_read2_b64 v[124:127], v213 offset0:84 offset1:118
	ds_read2_b64 v[128:131], v187 offset0:204 offset1:238
	ds_read2_b64 v[132:135], v162 offset0:204 offset1:238
	ds_read2_b64 v[136:139], v212 offset0:220 offset1:254
	ds_read2_b64 v[140:143], v213 offset0:220 offset1:254
	v_pk_fma_f32 v[190:191], v[166:167], v[166:167], v[190:191] neg_lo:[0,0,1] neg_hi:[0,0,1]
	v_pk_add_f32 v[192:193], v[192:193], v[192:193]
	v_pk_mul_f32 v[196:197], v[164:165], v[188:189]
	v_pk_fma_f32 v[198:199], v[144:145], v[188:189], v[198:199]
	v_pk_mul_f32 v[194:195], v[192:193], v[192:193]
	v_pk_fma_f32 v[196:197], v[144:145], v[166:167], v[196:197] neg_lo:[0,0,1] neg_hi:[0,0,1]
	v_pk_mul_f32 v[202:203], v[190:191], v[192:193]
	v_pk_mul_f32 v[204:205], v[190:191], v[198:199]
	v_pk_fma_f32 v[194:195], v[190:191], v[190:191], v[194:195] neg_lo:[0,0,1] neg_hi:[0,0,1]
	v_pk_mul_f32 v[200:201], v[192:193], v[198:199]
	v_pk_add_f32 v[202:203], v[202:203], v[202:203]
	v_pk_fma_f32 v[204:205], v[192:193], v[196:197], v[204:205]
	v_pk_fma_f32 v[200:201], v[190:191], v[196:197], v[200:201] neg_lo:[0,0,1] neg_hi:[0,0,1]
	v_pk_mul_f32 v[206:207], v[202:203], v[204:205]
	v_pk_mul_f32 v[208:209], v[194:195], v[204:205]
	v_pk_fma_f32 v[206:207], v[194:195], v[200:201], v[206:207] neg_lo:[0,0,1] neg_hi:[0,0,1]
	v_pk_fma_f32 v[208:209], v[202:203], v[200:201], v[208:209]
	s_waitcnt lgkmcnt(0)
	v_pk_mul_f32 v[210:211], v[208:209], v[142:143]
	v_pk_mul_f32 v[142:143], v[206:207], v[142:143]
	v_pk_fma_f32 v[210:211], v[206:207], v[138:139], v[210:211] neg_lo:[0,0,1] neg_hi:[0,0,1]
	v_pk_fma_f32 v[138:139], v[208:209], v[138:139], v[142:143]
	v_pk_mul_f32 v[142:143], v[204:205], v[134:135]
	v_pk_mul_f32 v[134:135], v[200:201], v[134:135]
	v_pk_fma_f32 v[142:143], v[200:201], v[130:131], v[142:143] neg_lo:[0,0,1] neg_hi:[0,0,1]
	v_pk_fma_f32 v[130:131], v[204:205], v[130:131], v[134:135]
	v_pk_mul_f32 v[134:135], v[198:199], v[202:203]
	v_pk_mul_f32 v[200:201], v[198:199], v[194:195]
	v_pk_fma_f32 v[134:135], v[196:197], v[194:195], v[134:135] neg_lo:[0,0,1] neg_hi:[0,0,1]
	v_pk_fma_f32 v[200:201], v[196:197], v[202:203], v[200:201]
	s_nop 0
	v_pk_mul_f32 v[204:205], v[200:201], v[126:127]
	v_pk_mul_f32 v[126:127], v[134:135], v[126:127]
	v_pk_fma_f32 v[204:205], v[134:135], v[122:123], v[204:205] neg_lo:[0,0,1] neg_hi:[0,0,1]
	v_pk_fma_f32 v[122:123], v[200:201], v[122:123], v[126:127]
	v_pk_mul_f32 v[126:127], v[198:199], v[118:119]
	v_pk_mul_f32 v[118:119], v[196:197], v[118:119]
	v_pk_mul_f32 v[134:135], v[164:165], v[190:191]
	v_pk_fma_f32 v[126:127], v[196:197], v[114:115], v[126:127] neg_lo:[0,0,1] neg_hi:[0,0,1]
	v_pk_fma_f32 v[114:115], v[198:199], v[114:115], v[118:119]
	v_pk_mul_f32 v[118:119], v[164:165], v[192:193]
	v_pk_fma_f32 v[134:135], v[144:145], v[192:193], v[134:135]
	v_pk_fma_f32 v[118:119], v[144:145], v[190:191], v[118:119] neg_lo:[0,0,1] neg_hi:[0,0,1]
	v_pk_mul_f32 v[196:197], v[202:203], v[134:135]
	v_pk_mul_f32 v[198:199], v[194:195], v[134:135]
	v_pk_fma_f32 v[196:197], v[194:195], v[118:119], v[196:197] neg_lo:[0,0,1] neg_hi:[0,0,1]
	v_pk_fma_f32 v[198:199], v[202:203], v[118:119], v[198:199]
	s_nop 0
	v_pk_mul_f32 v[200:201], v[198:199], v[110:111]
	v_pk_mul_f32 v[110:111], v[196:197], v[110:111]
	v_pk_fma_f32 v[200:201], v[196:197], v[106:107], v[200:201] neg_lo:[0,0,1] neg_hi:[0,0,1]
	v_pk_fma_f32 v[106:107], v[198:199], v[106:107], v[110:111]
	v_pk_mul_f32 v[110:111], v[134:135], v[22:23]
	v_pk_mul_f32 v[22:23], v[118:119], v[22:23]
	v_pk_fma_f32 v[110:111], v[118:119], v[18:19], v[110:111] neg_lo:[0,0,1] neg_hi:[0,0,1]
	v_pk_fma_f32 v[18:19], v[134:135], v[18:19], v[22:23]
	v_pk_mul_f32 v[22:23], v[164:165], v[202:203]
	v_pk_mul_f32 v[118:119], v[164:165], v[194:195]
	v_pk_fma_f32 v[22:23], v[144:145], v[194:195], v[22:23] neg_lo:[0,0,1] neg_hi:[0,0,1]
	v_pk_fma_f32 v[118:119], v[144:145], v[202:203], v[118:119]
	s_nop 0
	v_pk_mul_f32 v[134:135], v[118:119], v[14:15]
	v_pk_mul_f32 v[14:15], v[22:23], v[14:15]
	v_pk_fma_f32 v[134:135], v[22:23], v[10:11], v[134:135] neg_lo:[0,0,1] neg_hi:[0,0,1]
	v_pk_fma_f32 v[10:11], v[118:119], v[10:11], v[14:15]
	v_pk_mul_f32 v[14:15], v[164:165], v[2:3]
	v_pk_mul_f32 v[2:3], v[144:145], v[2:3]
	v_pk_mul_f32 v[22:23], v[188:189], v[190:191]
	v_pk_fma_f32 v[14:15], v[144:145], v[6:7], v[14:15] neg_lo:[0,0,1] neg_hi:[0,0,1]
	v_pk_fma_f32 v[2:3], v[164:165], v[6:7], v[2:3]
	v_pk_mul_f32 v[6:7], v[188:189], v[192:193]
	v_pk_fma_f32 v[22:23], v[166:167], v[192:193], v[22:23]
	v_pk_fma_f32 v[6:7], v[166:167], v[190:191], v[6:7] neg_lo:[0,0,1] neg_hi:[0,0,1]
	v_pk_mul_f32 v[144:145], v[194:195], v[22:23]
	v_pk_mul_f32 v[118:119], v[202:203], v[22:23]
	v_pk_fma_f32 v[144:145], v[202:203], v[6:7], v[144:145]
	v_pk_fma_f32 v[118:119], v[194:195], v[6:7], v[118:119] neg_lo:[0,0,1] neg_hi:[0,0,1]
	v_pk_mul_f32 v[164:165], v[144:145], v[140:141]
	s_nop 0
	v_pk_fma_f32 v[164:165], v[136:137], v[118:119], v[164:165] neg_lo:[0,0,1] neg_hi:[0,0,1]
	v_pk_mul_f32 v[118:119], v[118:119], v[140:141]
	v_pk_add_f32 v[140:141], v[126:127], v[204:205]
	v_pk_fma_f32 v[118:119], v[136:137], v[144:145], v[118:119]
	v_pk_mul_f32 v[136:137], v[22:23], v[132:133]
	v_pk_add_f32 v[144:145], v[142:143], v[210:211]
	v_pk_fma_f32 v[136:137], v[128:129], v[6:7], v[136:137] neg_lo:[0,0,1] neg_hi:[0,0,1]
	v_pk_mul_f32 v[6:7], v[6:7], v[132:133]
	s_nop 0
	v_pk_fma_f32 v[6:7], v[128:129], v[22:23], v[6:7]
	v_pk_mul_f32 v[128:129], v[188:189], v[194:195]
	v_pk_mul_f32 v[22:23], v[188:189], v[202:203]
	v_pk_fma_f32 v[128:129], v[166:167], v[202:203], v[128:129]
	v_pk_fma_f32 v[22:23], v[166:167], v[194:195], v[22:23] neg_lo:[0,0,1] neg_hi:[0,0,1]
	v_pk_mul_f32 v[132:133], v[124:125], v[128:129]
	s_nop 0
	v_pk_fma_f32 v[132:133], v[120:121], v[22:23], v[132:133] neg_lo:[0,0,1] neg_hi:[0,0,1]
	v_pk_mul_f32 v[120:121], v[120:121], v[128:129]
	s_nop 0
	v_pk_fma_f32 v[22:23], v[124:125], v[22:23], v[120:121]
	v_pk_mul_f32 v[120:121], v[188:189], v[116:117]
	v_pk_mul_f32 v[116:117], v[166:167], v[116:117]
	v_pk_mul_f32 v[124:125], v[192:193], v[194:195]
	v_pk_fma_f32 v[120:121], v[112:113], v[166:167], v[120:121] neg_lo:[0,0,1] neg_hi:[0,0,1]
	v_pk_fma_f32 v[112:113], v[112:113], v[188:189], v[116:117]
	v_pk_mul_f32 v[116:117], v[192:193], v[202:203]
	v_pk_fma_f32 v[124:125], v[190:191], v[202:203], v[124:125]
	v_pk_fma_f32 v[116:117], v[190:191], v[194:195], v[116:117] neg_lo:[0,0,1] neg_hi:[0,0,1]
	v_pk_mul_f32 v[128:129], v[108:109], v[124:125]
	s_nop 0
	v_pk_fma_f32 v[128:129], v[104:105], v[116:117], v[128:129] neg_lo:[0,0,1] neg_hi:[0,0,1]
	v_pk_mul_f32 v[104:105], v[104:105], v[124:125]
	v_pk_add_f32 v[124:125], v[120:121], v[132:133]
	v_pk_fma_f32 v[104:105], v[108:109], v[116:117], v[104:105]
	v_pk_mul_f32 v[108:109], v[20:21], v[192:193]
	s_nop 0
	v_pk_fma_f32 v[108:109], v[16:17], v[190:191], v[108:109] neg_lo:[0,0,1] neg_hi:[0,0,1]
	v_pk_mul_f32 v[16:17], v[16:17], v[192:193]
	s_nop 0
	v_pk_fma_f32 v[16:17], v[20:21], v[190:191], v[16:17]
	v_pk_mul_f32 v[20:21], v[12:13], v[202:203]
	s_nop 0
	v_pk_fma_f32 v[20:21], v[8:9], v[194:195], v[20:21] neg_lo:[0,0,1] neg_hi:[0,0,1]
	v_pk_mul_f32 v[8:9], v[8:9], v[202:203]
	v_pk_add_f32 v[116:117], v[4:5], v[20:21]
	v_pk_fma_f32 v[8:9], v[12:13], v[194:195], v[8:9]
	v_pk_add_f32 v[4:5], v[4:5], v[20:21] neg_lo:[0,1] neg_hi:[0,1]
	v_pk_add_f32 v[12:13], v[0:1], v[8:9]
	v_pk_add_f32 v[0:1], v[0:1], v[8:9] neg_lo:[0,1] neg_hi:[0,1]
	v_pk_add_f32 v[8:9], v[16:17], v[104:105]
	v_pk_add_f32 v[20:21], v[108:109], v[128:129]
	v_pk_add_f32 v[16:17], v[16:17], v[104:105] neg_lo:[0,1] neg_hi:[0,1]
	v_pk_add_f32 v[104:105], v[108:109], v[128:129] neg_lo:[0,1] neg_hi:[0,1]
	v_pk_add_f32 v[108:109], v[112:113], v[22:23]
	v_pk_add_f32 v[22:23], v[112:113], v[22:23] neg_lo:[0,1] neg_hi:[0,1]
	v_pk_add_f32 v[112:113], v[120:121], v[132:133] neg_lo:[0,1] neg_hi:[0,1]
	v_pk_add_f32 v[120:121], v[6:7], v[118:119]
	v_pk_add_f32 v[128:129], v[136:137], v[164:165]
	v_pk_add_f32 v[6:7], v[6:7], v[118:119] neg_lo:[0,1] neg_hi:[0,1]
	v_pk_add_f32 v[118:119], v[136:137], v[164:165] neg_lo:[0,1] neg_hi:[0,1]
	v_pk_add_f32 v[132:133], v[2:3], v[10:11]
	v_pk_add_f32 v[136:137], v[14:15], v[134:135]
	v_pk_add_f32 v[2:3], v[2:3], v[10:11] neg_lo:[0,1] neg_hi:[0,1]
	v_pk_add_f32 v[10:11], v[14:15], v[134:135] neg_lo:[0,1] neg_hi:[0,1]
	v_pk_add_f32 v[14:15], v[18:19], v[106:107]
	v_pk_add_f32 v[134:135], v[110:111], v[200:201]
	v_pk_add_f32 v[18:19], v[18:19], v[106:107] neg_lo:[0,1] neg_hi:[0,1]
	v_pk_add_f32 v[106:107], v[110:111], v[200:201] neg_lo:[0,1] neg_hi:[0,1]
	v_pk_add_f32 v[110:111], v[114:115], v[122:123]
	v_pk_add_f32 v[114:115], v[114:115], v[122:123] neg_lo:[0,1] neg_hi:[0,1]
	v_pk_add_f32 v[122:123], v[126:127], v[204:205] neg_lo:[0,1] neg_hi:[0,1]
	v_pk_add_f32 v[126:127], v[130:131], v[138:139]
	v_pk_add_f32 v[130:131], v[130:131], v[138:139] neg_lo:[0,1] neg_hi:[0,1]
	v_pk_add_f32 v[138:139], v[142:143], v[210:211] neg_lo:[0,1] neg_hi:[0,1]
	v_pk_add_f32 v[142:143], v[12:13], v[8:9]
	v_pk_add_f32 v[164:165], v[116:117], v[20:21]
	v_pk_add_f32 v[8:9], v[12:13], v[8:9] neg_lo:[0,1] neg_hi:[0,1]
	v_pk_add_f32 v[12:13], v[116:117], v[20:21] neg_lo:[0,1] neg_hi:[0,1]
	v_pk_add_f32 v[20:21], v[0:1], v[104:105] neg_lo:[0,1] neg_hi:[0,1]
	v_pk_add_f32 v[116:117], v[4:5], v[16:17]
	v_pk_add_f32 v[0:1], v[0:1], v[104:105]
	v_pk_add_f32 v[4:5], v[4:5], v[16:17] neg_lo:[0,1] neg_hi:[0,1]
	v_pk_add_f32 v[16:17], v[108:109], v[120:121]
	v_pk_add_f32 v[104:105], v[124:125], v[128:129]
	v_pk_add_f32 v[108:109], v[108:109], v[120:121] neg_lo:[0,1] neg_hi:[0,1]
	v_pk_add_f32 v[120:121], v[124:125], v[128:129] neg_lo:[0,1] neg_hi:[0,1]
	v_pk_add_f32 v[124:125], v[22:23], v[118:119] neg_lo:[0,1] neg_hi:[0,1]
	v_pk_add_f32 v[128:129], v[112:113], v[6:7]
	v_pk_add_f32 v[6:7], v[112:113], v[6:7] neg_lo:[0,1] neg_hi:[0,1]
	v_pk_mul_f32 v[124:125], v[124:125], s[82:83] op_sel_hi:[1,0]
	v_pk_add_f32 v[22:23], v[22:23], v[118:119]
	v_pk_add_f32 v[112:113], v[132:133], v[14:15]
	v_pk_add_f32 v[118:119], v[136:137], v[134:135]
	v_pk_add_f32 v[14:15], v[132:133], v[14:15] neg_lo:[0,1] neg_hi:[0,1]
	v_pk_add_f32 v[132:133], v[136:137], v[134:135] neg_lo:[0,1] neg_hi:[0,1]
	v_pk_add_f32 v[134:135], v[2:3], v[106:107] neg_lo:[0,1] neg_hi:[0,1]
	v_pk_add_f32 v[136:137], v[10:11], v[18:19]
	v_pk_add_f32 v[2:3], v[2:3], v[106:107]
	v_pk_add_f32 v[10:11], v[10:11], v[18:19] neg_lo:[0,1] neg_hi:[0,1]
	v_pk_add_f32 v[18:19], v[110:111], v[126:127]
	v_pk_add_f32 v[106:107], v[140:141], v[144:145]
	v_pk_add_f32 v[110:111], v[110:111], v[126:127] neg_lo:[0,1] neg_hi:[0,1]
	v_pk_add_f32 v[126:127], v[140:141], v[144:145] neg_lo:[0,1] neg_hi:[0,1]
	v_pk_add_f32 v[144:145], v[122:123], v[130:131]
	v_pk_add_f32 v[122:123], v[122:123], v[130:131] neg_lo:[0,1] neg_hi:[0,1]
	v_pk_add_f32 v[130:131], v[142:143], v[16:17]
	v_pk_add_f32 v[16:17], v[142:143], v[16:17] neg_lo:[0,1] neg_hi:[0,1]
	v_pk_fma_f32 v[142:143], v[128:129], s[82:83], v[124:125] op_sel_hi:[1,0,1] neg_lo:[1,0,0] neg_hi:[1,0,0]
	v_pk_mul_f32 v[6:7], v[6:7], s[82:83] op_sel_hi:[1,0]
	v_pk_add_f32 v[140:141], v[114:115], v[138:139] neg_lo:[0,1] neg_hi:[0,1]
	v_pk_fma_f32 v[124:125], v[128:129], s[82:83], v[124:125] op_sel_hi:[1,0,1]
	v_pk_add_f32 v[128:129], v[20:21], v[142:143]
	v_pk_add_f32 v[20:21], v[20:21], v[142:143] neg_lo:[0,1] neg_hi:[0,1]
	v_pk_add_f32 v[142:143], v[12:13], v[108:109]
	v_pk_add_f32 v[12:13], v[12:13], v[108:109] neg_lo:[0,1] neg_hi:[0,1]
	v_pk_fma_f32 v[108:109], v[22:23], s[54:55], v[6:7] op_sel_hi:[1,0,1] neg_lo:[0,0,1] neg_hi:[0,0,1]
	v_pk_fma_f32 v[6:7], v[22:23], s[82:83], v[6:7] op_sel_hi:[1,0,1] neg_lo:[0,0,1] neg_hi:[0,0,1]
	v_pk_add_f32 v[114:115], v[114:115], v[138:139]
	v_pk_add_f32 v[138:139], v[164:165], v[104:105]
	v_pk_add_f32 v[104:105], v[164:165], v[104:105] neg_lo:[0,1] neg_hi:[0,1]
	v_pk_add_f32 v[164:165], v[116:117], v[124:125]
	v_pk_add_f32 v[116:117], v[116:117], v[124:125] neg_lo:[0,1] neg_hi:[0,1]
	v_pk_add_f32 v[124:125], v[8:9], v[120:121] neg_lo:[0,1] neg_hi:[0,1]
	v_pk_add_f32 v[8:9], v[8:9], v[120:121]
	v_pk_add_f32 v[120:121], v[4:5], v[6:7]
	v_pk_add_f32 v[4:5], v[4:5], v[6:7] neg_lo:[0,1] neg_hi:[0,1]
	v_pk_add_f32 v[6:7], v[112:113], v[18:19]
	v_pk_add_f32 v[18:19], v[112:113], v[18:19] neg_lo:[0,1] neg_hi:[0,1]
	v_pk_mul_f32 v[112:113], v[140:141], s[82:83] op_sel_hi:[1,0]
	v_pk_add_f32 v[22:23], v[0:1], v[108:109]
	v_pk_add_f32 v[0:1], v[0:1], v[108:109] neg_lo:[0,1] neg_hi:[0,1]
	v_pk_add_f32 v[108:109], v[118:119], v[106:107]
	v_pk_add_f32 v[106:107], v[118:119], v[106:107] neg_lo:[0,1] neg_hi:[0,1]
	v_pk_fma_f32 v[118:119], v[144:145], s[82:83], v[112:113] op_sel_hi:[1,0,1] neg_lo:[1,0,0] neg_hi:[1,0,0]
	v_pk_fma_f32 v[112:113], v[144:145], s[82:83], v[112:113] op_sel_hi:[1,0,1]
	v_pk_mul_f32 v[122:123], v[122:123], s[82:83] op_sel_hi:[1,0]
	v_pk_add_f32 v[140:141], v[134:135], v[118:119]
	v_pk_add_f32 v[144:145], v[136:137], v[112:113]
	v_pk_add_f32 v[118:119], v[134:135], v[118:119] neg_lo:[0,1] neg_hi:[0,1]
	v_pk_add_f32 v[134:135], v[14:15], v[126:127] neg_lo:[0,1] neg_hi:[0,1]
	v_pk_add_f32 v[14:15], v[14:15], v[126:127]
	v_pk_fma_f32 v[126:127], v[114:115], s[54:55], v[122:123] op_sel_hi:[1,0,1] neg_lo:[0,0,1] neg_hi:[0,0,1]
	v_pk_fma_f32 v[114:115], v[114:115], s[82:83], v[122:123] op_sel_hi:[1,0,1] neg_lo:[0,0,1] neg_hi:[0,0,1]
	v_pk_add_f32 v[112:113], v[136:137], v[112:113] neg_lo:[0,1] neg_hi:[0,1]
	v_pk_add_f32 v[136:137], v[132:133], v[110:111]
	v_pk_add_f32 v[110:111], v[132:133], v[110:111] neg_lo:[0,1] neg_hi:[0,1]
	v_pk_add_f32 v[122:123], v[2:3], v[126:127]
	v_pk_add_f32 v[132:133], v[10:11], v[114:115]
	v_pk_add_f32 v[2:3], v[2:3], v[126:127] neg_lo:[0,1] neg_hi:[0,1]
	v_pk_add_f32 v[10:11], v[10:11], v[114:115] neg_lo:[0,1] neg_hi:[0,1]
	v_pk_add_f32 v[114:115], v[130:131], v[6:7]
	v_pk_add_f32 v[126:127], v[138:139], v[108:109]
	v_pk_add_f32 v[6:7], v[130:131], v[6:7] neg_lo:[0,1] neg_hi:[0,1]
	v_pk_add_f32 v[108:109], v[138:139], v[108:109] neg_lo:[0,1] neg_hi:[0,1]
	v_pk_mul_f32 v[130:131], v[144:145], s[80:81] op_sel_hi:[1,0]
	v_pk_mul_f32 v[138:139], v[144:145], s[72:73] op_sel_hi:[1,0]
	v_pk_fma_f32 v[130:131], v[140:141], s[72:73], v[130:131] op_sel_hi:[1,0,1] neg_lo:[0,0,1] neg_hi:[0,0,1]
	v_pk_fma_f32 v[138:139], v[140:141], s[80:81], v[138:139] op_sel_hi:[1,0,1]
	v_pk_mul_f32 v[134:135], v[134:135], s[82:83] op_sel_hi:[1,0]
	v_pk_add_f32 v[140:141], v[128:129], v[130:131]
	v_pk_add_f32 v[144:145], v[164:165], v[138:139]
	v_pk_add_f32 v[128:129], v[128:129], v[130:131] neg_lo:[0,1] neg_hi:[0,1]
	v_pk_add_f32 v[130:131], v[164:165], v[138:139] neg_lo:[0,1] neg_hi:[0,1]
	v_pk_fma_f32 v[138:139], v[136:137], s[82:83], v[134:135] op_sel_hi:[1,0,1] neg_lo:[1,0,0] neg_hi:[1,0,0]
	v_pk_fma_f32 v[134:135], v[136:137], s[82:83], v[134:135] op_sel_hi:[1,0,1]
	v_pk_add_f32 v[136:137], v[124:125], v[138:139]
	v_pk_add_f32 v[124:125], v[124:125], v[138:139] neg_lo:[0,1] neg_hi:[0,1]
	v_pk_mul_f32 v[138:139], v[132:133], s[72:73] op_sel_hi:[1,0]
	v_pk_mul_f32 v[132:133], v[132:133], s[80:81] op_sel_hi:[1,0]
	v_pk_fma_f32 v[138:139], v[122:123], s[80:81], v[138:139] op_sel_hi:[1,0,1] neg_lo:[0,0,1] neg_hi:[0,0,1]
	v_pk_fma_f32 v[122:123], v[122:123], s[72:73], v[132:133] op_sel_hi:[1,0,1]
	v_pk_add_f32 v[164:165], v[142:143], v[134:135]
	v_pk_add_f32 v[134:135], v[142:143], v[134:135] neg_lo:[0,1] neg_hi:[0,1]
	v_pk_add_f32 v[132:133], v[22:23], v[138:139]
	v_pk_add_f32 v[142:143], v[120:121], v[122:123]
	v_pk_add_f32 v[22:23], v[22:23], v[138:139] neg_lo:[0,1] neg_hi:[0,1]
	v_pk_add_f32 v[120:121], v[120:121], v[122:123] neg_lo:[0,1] neg_hi:[0,1]
	v_pk_add_f32 v[122:123], v[16:17], v[106:107] neg_lo:[0,1] neg_hi:[0,1]
	v_pk_add_f32 v[138:139], v[104:105], v[18:19]
	v_pk_add_f32 v[16:17], v[16:17], v[106:107]
	v_pk_add_f32 v[18:19], v[104:105], v[18:19] neg_lo:[0,1] neg_hi:[0,1]
	v_pk_mul_f32 v[104:105], v[112:113], s[72:73] op_sel_hi:[1,0]
	v_pk_mul_f32 v[106:107], v[112:113], s[80:81] op_sel_hi:[1,0]
	v_pk_fma_f32 v[104:105], v[118:119], s[84:85], v[104:105] op_sel_hi:[1,0,1] neg_lo:[0,0,1] neg_hi:[0,0,1]
	v_pk_fma_f32 v[106:107], v[118:119], s[72:73], v[106:107] op_sel_hi:[1,0,1] neg_lo:[0,0,1] neg_hi:[0,0,1]
	v_pk_add_f32 v[112:113], v[20:21], v[104:105]
	v_pk_add_f32 v[118:119], v[116:117], v[106:107]
	v_pk_add_f32 v[20:21], v[20:21], v[104:105] neg_lo:[0,1] neg_hi:[0,1]
	v_pk_add_f32 v[104:105], v[116:117], v[106:107] neg_lo:[0,1] neg_hi:[0,1]
	v_pk_mul_f32 v[106:107], v[110:111], s[82:83] op_sel_hi:[1,0]
	s_nop 0
	v_pk_fma_f32 v[110:111], v[14:15], s[54:55], v[106:107] op_sel_hi:[1,0,1] neg_lo:[0,0,1] neg_hi:[0,0,1]
	v_pk_fma_f32 v[14:15], v[14:15], s[82:83], v[106:107] op_sel_hi:[1,0,1] neg_lo:[0,0,1] neg_hi:[0,0,1]
	v_pk_add_f32 v[106:107], v[8:9], v[110:111]
	v_pk_add_f32 v[116:117], v[12:13], v[14:15]
	v_pk_add_f32 v[12:13], v[12:13], v[14:15] neg_lo:[0,1] neg_hi:[0,1]
	v_pk_mul_f32 v[14:15], v[10:11], s[80:81] op_sel_hi:[1,0]
	v_pk_mul_f32 v[10:11], v[10:11], s[72:73] op_sel_hi:[1,0]
	v_pk_fma_f32 v[14:15], v[2:3], s[52:53], v[14:15] op_sel_hi:[1,0,1] neg_lo:[0,0,1] neg_hi:[0,0,1]
	v_pk_fma_f32 v[2:3], v[2:3], s[80:81], v[10:11] op_sel_hi:[1,0,1] neg_lo:[0,0,1] neg_hi:[0,0,1]
	v_pk_add_f32 v[10:11], v[0:1], v[14:15]
	v_pk_add_f32 v[0:1], v[0:1], v[14:15] neg_lo:[0,1] neg_hi:[0,1]
	v_pk_add_f32 v[8:9], v[8:9], v[110:111] neg_lo:[0,1] neg_hi:[0,1]
	v_pk_add_f32 v[110:111], v[4:5], v[2:3]
	v_pk_add_f32 v[2:3], v[4:5], v[2:3] neg_lo:[0,1] neg_hi:[0,1]
	ds_write2_b64 v162, v[114:115], v[140:141] offset1:34
	ds_write2_b64 v187, v[126:127], v[144:145] offset1:34
	ds_write2_b64 v162, v[136:137], v[132:133] offset0:68 offset1:102
	ds_write2_b64 v187, v[164:165], v[142:143] offset0:68 offset1:102
	ds_write2_b64 v162, v[122:123], v[112:113] offset0:136 offset1:170
	ds_write2_b64 v187, v[138:139], v[118:119] offset0:136 offset1:170
	ds_write2_b64 v162, v[106:107], v[10:11] offset0:204 offset1:238
	ds_write2_b64 v187, v[116:117], v[110:111] offset0:204 offset1:238
	ds_write2_b64 v213, v[6:7], v[128:129] offset0:16 offset1:50
	ds_write2_b64 v212, v[108:109], v[130:131] offset0:16 offset1:50
	ds_write2_b64 v213, v[124:125], v[22:23] offset0:84 offset1:118
	ds_write2_b64 v212, v[134:135], v[120:121] offset0:84 offset1:118
	ds_write2_b64 v213, v[16:17], v[20:21] offset0:152 offset1:186
	ds_write2_b64 v212, v[18:19], v[104:105] offset0:152 offset1:186
	ds_write2_b64 v213, v[8:9], v[0:1] offset0:220 offset1:254
	ds_write2_b64 v212, v[12:13], v[2:3] offset0:220 offset1:254
	v_mov_b32_e32 v0, v163
	s_waitcnt lgkmcnt(0)
	s_barrier
	s_nop 0
	s_nop 0
	v_ashrrev_i32_e32 v2, 31, v0
	v_lshlrev_b32_e32 v1, 1, v0
	v_lshrrev_b32_e32 v2, 23, v2
	v_and_b32_e32 v1, 0x3fe, v1
	v_add_lshl_u32 v0, v0, v2, 5
	v_and_or_b32 v0, v0, s85, v1
	v_ashrrev_i32_e32 v2, 4, v0
	v_and_b32_e32 v2, 0x3ffffc3c, v2
	v_add_lshl_u32 v4, v2, v0, 2
	v_cvt_f32_u32_e32 v0, v1
	v_or_b32_e32 v1, 1, v1
	v_cvt_f32_u32_e32 v1, v1
	v_add_u32_e32 v187, 0, v4
	v_mul_f32_e32 v0, 0x38800000, v0
	v_sin_f32_e64 v120, -v0
	v_mul_f32_e32 v1, 0x38800000, v1
	v_sin_f32_e64 v121, -v1
	v_cos_f32_e32 v118, v0
	v_cos_f32_e32 v119, v1
	v_add_u32_e32 v188, s91, v4
	v_pk_mul_f32 v[0:1], v[120:121], v[120:121]
	ds_read_b64 v[4:5], v187
	ds_read_b64 v[6:7], v188
	ds_read_b64 v[164:165], v188 offset:34816
	ds_read_b64 v[166:167], v187 offset:34816
	v_pk_fma_f32 v[22:23], v[118:119], v[118:119], v[0:1] neg_lo:[0,0,1] neg_hi:[0,0,1]
	v_pk_mul_f32 v[0:1], v[118:119], v[120:121]
	s_nop 0
	v_pk_add_f32 v[104:105], v[0:1], v[0:1]
	s_nop 0
	v_pk_mul_f32 v[0:1], v[120:121], v[104:105]
	s_nop 0
	v_pk_fma_f32 v[134:135], v[118:119], v[22:23], v[0:1] neg_lo:[0,0,1] neg_hi:[0,0,1]
	v_pk_mul_f32 v[0:1], v[120:121], v[22:23]
	s_nop 0
	v_pk_fma_f32 v[144:145], v[118:119], v[104:105], v[0:1]
	v_pk_mul_f32 v[0:1], v[104:105], v[104:105]
	s_nop 0
	v_pk_fma_f32 v[14:15], v[22:23], v[22:23], v[0:1] neg_lo:[0,0,1] neg_hi:[0,0,1]
	v_pk_mul_f32 v[0:1], v[22:23], v[104:105]
	s_nop 0
	v_pk_add_f32 v[16:17], v[0:1], v[0:1]
	s_nop 0
	v_pk_mul_f32 v[0:1], v[120:121], v[16:17]
	s_nop 0
	v_pk_fma_f32 v[126:127], v[118:119], v[14:15], v[0:1] neg_lo:[0,0,1] neg_hi:[0,0,1]
	v_pk_mul_f32 v[0:1], v[120:121], v[14:15]
	s_nop 0
	v_pk_fma_f32 v[128:129], v[118:119], v[16:17], v[0:1]
	v_pk_mul_f32 v[0:1], v[104:105], v[16:17]
	s_nop 0
	v_pk_fma_f32 v[110:111], v[22:23], v[14:15], v[0:1] neg_lo:[0,0,1] neg_hi:[0,0,1]
	v_pk_mul_f32 v[0:1], v[104:105], v[14:15]
	s_nop 0
	v_pk_fma_f32 v[112:113], v[22:23], v[16:17], v[0:1]
	v_pk_mul_f32 v[0:1], v[16:17], v[144:145]
	s_nop 0
	v_pk_fma_f32 v[136:137], v[14:15], v[134:135], v[0:1] neg_lo:[0,0,1] neg_hi:[0,0,1]
	v_pk_mul_f32 v[0:1], v[14:15], v[144:145]
	s_nop 0
	v_pk_fma_f32 v[138:139], v[16:17], v[134:135], v[0:1]
	v_pk_mul_f32 v[0:1], v[16:17], v[16:17]
	s_nop 0
	v_pk_fma_f32 v[10:11], v[14:15], v[14:15], v[0:1] neg_lo:[0,0,1] neg_hi:[0,0,1]
	v_pk_mul_f32 v[0:1], v[14:15], v[16:17]
	v_pk_mul_f32 v[2:3], v[10:11], v[138:139]
	v_pk_add_f32 v[12:13], v[0:1], v[0:1]
	s_nop 0
	v_pk_mul_f32 v[0:1], v[120:121], v[12:13]
	v_pk_fma_f32 v[2:3], v[12:13], v[136:137], v[2:3]
	v_pk_fma_f32 v[122:123], v[118:119], v[10:11], v[0:1] neg_lo:[0,0,1] neg_hi:[0,0,1]
	v_pk_mul_f32 v[0:1], v[120:121], v[10:11]
	s_waitcnt lgkmcnt(1)
	v_pk_mul_f32 v[8:9], v[164:165], v[12:13]
	v_pk_fma_f32 v[124:125], v[118:119], v[12:13], v[0:1]
	v_pk_mul_f32 v[0:1], v[104:105], v[12:13]
	s_waitcnt lgkmcnt(0)
	v_pk_fma_f32 v[8:9], v[166:167], v[10:11], v[8:9]
	v_pk_fma_f32 v[106:107], v[22:23], v[10:11], v[0:1] neg_lo:[0,0,1] neg_hi:[0,0,1]
	v_pk_mul_f32 v[0:1], v[104:105], v[10:11]
	s_nop 0
	v_pk_fma_f32 v[108:109], v[22:23], v[12:13], v[0:1]
	v_pk_mul_f32 v[0:1], v[144:145], v[12:13]
	s_nop 0
	v_pk_fma_f32 v[140:141], v[134:135], v[10:11], v[0:1] neg_lo:[0,0,1] neg_hi:[0,0,1]
	v_pk_mul_f32 v[0:1], v[144:145], v[10:11]
	s_nop 0
	v_pk_fma_f32 v[142:143], v[134:135], v[12:13], v[0:1]
	v_pk_mul_f32 v[0:1], v[16:17], v[12:13]
	s_nop 0
	v_pk_fma_f32 v[18:19], v[14:15], v[10:11], v[0:1] neg_lo:[0,0,1] neg_hi:[0,0,1]
	v_pk_mul_f32 v[0:1], v[16:17], v[10:11]
	s_nop 0
	v_pk_fma_f32 v[20:21], v[14:15], v[12:13], v[0:1]
	v_pk_mul_f32 v[0:1], v[12:13], v[128:129]
	s_nop 0
	v_pk_fma_f32 v[130:131], v[10:11], v[126:127], v[0:1] neg_lo:[0,0,1] neg_hi:[0,0,1]
	v_pk_mul_f32 v[0:1], v[10:11], v[128:129]
	s_nop 0
	v_pk_fma_f32 v[132:133], v[12:13], v[126:127], v[0:1]
	v_pk_mul_f32 v[0:1], v[12:13], v[112:113]
	s_nop 0
	v_pk_fma_f32 v[114:115], v[10:11], v[110:111], v[0:1] neg_lo:[0,0,1] neg_hi:[0,0,1]
	v_pk_mul_f32 v[0:1], v[10:11], v[112:113]
	s_nop 0
	v_pk_fma_f32 v[116:117], v[12:13], v[110:111], v[0:1]
	v_pk_mul_f32 v[0:1], v[12:13], v[138:139]
	v_pk_mul_f32 v[12:13], v[166:167], v[12:13]
	v_pk_fma_f32 v[0:1], v[10:11], v[136:137], v[0:1] neg_lo:[0,0,1] neg_hi:[0,0,1]
	v_pk_fma_f32 v[10:11], v[164:165], v[10:11], v[12:13] neg_lo:[0,0,1] neg_hi:[0,0,1]
	ds_read_b64 v[164:165], v188 offset:17408
	ds_read_b64 v[166:167], v187 offset:17408
	s_waitcnt lgkmcnt(1)
	v_pk_mul_f32 v[12:13], v[164:165], v[16:17]
	s_waitcnt lgkmcnt(0)
	v_pk_mul_f32 v[16:17], v[166:167], v[16:17]
	v_pk_fma_f32 v[12:13], v[166:167], v[14:15], v[12:13]
	v_pk_fma_f32 v[14:15], v[164:165], v[14:15], v[16:17] neg_lo:[0,0,1] neg_hi:[0,0,1]
	ds_read_b64 v[164:165], v188 offset:52224
	ds_read_b64 v[166:167], v187 offset:52224
	s_waitcnt lgkmcnt(1)
	v_pk_mul_f32 v[16:17], v[164:165], v[20:21]
	s_waitcnt lgkmcnt(0)
	v_pk_mul_f32 v[20:21], v[166:167], v[20:21]
	v_pk_fma_f32 v[16:17], v[166:167], v[18:19], v[16:17]
	v_pk_fma_f32 v[18:19], v[164:165], v[18:19], v[20:21] neg_lo:[0,0,1] neg_hi:[0,0,1]
	ds_read_b64 v[164:165], v188 offset:8704
	ds_read_b64 v[166:167], v187 offset:8704
	s_waitcnt lgkmcnt(0)
	v_pk_mul_f32 v[20:21], v[22:23], v[166:167]
	s_nop 0
	v_pk_fma_f32 v[20:21], v[164:165], v[104:105], v[20:21]
	v_pk_mul_f32 v[104:105], v[104:105], v[166:167]
	s_nop 0
	v_pk_fma_f32 v[22:23], v[164:165], v[22:23], v[104:105] neg_lo:[0,0,1] neg_hi:[0,0,1]
	ds_read_b64 v[164:165], v188 offset:43520
	ds_read_b64 v[166:167], v187 offset:43520
	s_waitcnt lgkmcnt(1)
	v_pk_mul_f32 v[104:105], v[164:165], v[108:109]
	s_waitcnt lgkmcnt(0)
	v_pk_mul_f32 v[108:109], v[166:167], v[108:109]
	v_pk_fma_f32 v[104:105], v[166:167], v[106:107], v[104:105]
	v_pk_fma_f32 v[106:107], v[164:165], v[106:107], v[108:109] neg_lo:[0,0,1] neg_hi:[0,0,1]
	ds_read_b64 v[164:165], v188 offset:26112
	ds_read_b64 v[166:167], v187 offset:26112
	s_waitcnt lgkmcnt(0)
	v_pk_mul_f32 v[108:109], v[110:111], v[166:167]
	s_nop 0
	v_pk_fma_f32 v[108:109], v[164:165], v[112:113], v[108:109]
	v_pk_mul_f32 v[112:113], v[112:113], v[166:167]
	s_nop 0
	v_pk_fma_f32 v[110:111], v[164:165], v[110:111], v[112:113] neg_lo:[0,0,1] neg_hi:[0,0,1]
	ds_read_b64 v[164:165], v188 offset:60928
	ds_read_b64 v[166:167], v187 offset:60928
	s_waitcnt lgkmcnt(0)
	v_pk_mul_f32 v[112:113], v[114:115], v[166:167]
	s_nop 0
	v_pk_fma_f32 v[112:113], v[164:165], v[116:117], v[112:113]
	v_pk_mul_f32 v[116:117], v[116:117], v[166:167]
	s_nop 0
	v_pk_fma_f32 v[114:115], v[164:165], v[114:115], v[116:117] neg_lo:[0,0,1] neg_hi:[0,0,1]
	ds_read_b64 v[164:165], v188 offset:4352
	ds_read_b64 v[166:167], v187 offset:4352
	s_waitcnt lgkmcnt(0)
	v_pk_mul_f32 v[116:117], v[118:119], v[166:167]
	s_nop 0
	v_pk_fma_f32 v[116:117], v[120:121], v[164:165], v[116:117]
	v_pk_mul_f32 v[120:121], v[120:121], v[166:167]
	s_nop 0
	v_pk_fma_f32 v[118:119], v[118:119], v[164:165], v[120:121] neg_lo:[0,0,1] neg_hi:[0,0,1]
	ds_read_b64 v[164:165], v188 offset:39168
	ds_read_b64 v[166:167], v187 offset:39168
	s_waitcnt lgkmcnt(0)
	v_pk_mul_f32 v[120:121], v[122:123], v[166:167]
	s_nop 0
	v_pk_fma_f32 v[120:121], v[124:125], v[164:165], v[120:121]
	v_pk_mul_f32 v[124:125], v[124:125], v[166:167]
	s_nop 0
	v_pk_fma_f32 v[122:123], v[122:123], v[164:165], v[124:125] neg_lo:[0,0,1] neg_hi:[0,0,1]
	ds_read_b64 v[164:165], v188 offset:21760
	ds_read_b64 v[166:167], v187 offset:21760
	s_waitcnt lgkmcnt(0)
	v_pk_mul_f32 v[124:125], v[126:127], v[166:167]
	s_nop 0
	v_pk_fma_f32 v[124:125], v[128:129], v[164:165], v[124:125]
	v_pk_mul_f32 v[128:129], v[128:129], v[166:167]
	s_nop 0
	v_pk_fma_f32 v[126:127], v[126:127], v[164:165], v[128:129] neg_lo:[0,0,1] neg_hi:[0,0,1]
	ds_read_b64 v[164:165], v188 offset:56576
	ds_read_b64 v[166:167], v187 offset:56576
	s_waitcnt lgkmcnt(0)
	v_pk_mul_f32 v[128:129], v[130:131], v[166:167]
	s_nop 0
	v_pk_fma_f32 v[128:129], v[132:133], v[164:165], v[128:129]
	v_pk_mul_f32 v[132:133], v[132:133], v[166:167]
	s_nop 0
	v_pk_fma_f32 v[130:131], v[130:131], v[164:165], v[132:133] neg_lo:[0,0,1] neg_hi:[0,0,1]
	ds_read_b64 v[164:165], v188 offset:13056
	ds_read_b64 v[166:167], v187 offset:13056
	s_waitcnt lgkmcnt(0)
	v_pk_mul_f32 v[132:133], v[134:135], v[166:167]
	s_nop 0
	v_pk_fma_f32 v[132:133], v[144:145], v[164:165], v[132:133]
	v_pk_mul_f32 v[144:145], v[144:145], v[166:167]
	s_nop 0
	v_pk_fma_f32 v[134:135], v[134:135], v[164:165], v[144:145] neg_lo:[0,0,1] neg_hi:[0,0,1]
	ds_read_b64 v[164:165], v188 offset:47872
	ds_read_b64 v[166:167], v187 offset:47872
	s_waitcnt lgkmcnt(0)
	v_pk_mul_f32 v[144:145], v[140:141], v[166:167]
	s_nop 0
	v_pk_fma_f32 v[144:145], v[142:143], v[164:165], v[144:145]
	v_pk_mul_f32 v[142:143], v[142:143], v[166:167]
	s_nop 0
	v_pk_fma_f32 v[140:141], v[140:141], v[164:165], v[142:143] neg_lo:[0,0,1] neg_hi:[0,0,1]
	ds_read_b64 v[164:165], v188 offset:30464
	ds_read_b64 v[166:167], v187 offset:30464
	s_waitcnt lgkmcnt(0)
	v_pk_mul_f32 v[142:143], v[136:137], v[166:167]
	s_nop 0
	v_pk_fma_f32 v[142:143], v[138:139], v[164:165], v[142:143]
	v_pk_mul_f32 v[138:139], v[138:139], v[166:167]
	s_nop 0
	v_pk_fma_f32 v[136:137], v[136:137], v[164:165], v[138:139] neg_lo:[0,0,1] neg_hi:[0,0,1]
	ds_read_b64 v[138:139], v188 offset:65280
	ds_read_b64 v[164:165], v187 offset:65280
	s_waitcnt lgkmcnt(0)
	v_pk_mul_f32 v[166:167], v[2:3], v[164:165]
	s_nop 0
	v_pk_fma_f32 v[166:167], v[0:1], v[138:139], v[166:167] neg_lo:[0,0,1] neg_hi:[0,0,1]
	v_pk_mul_f32 v[0:1], v[0:1], v[164:165]
	s_nop 0
	v_pk_fma_f32 v[0:1], v[2:3], v[138:139], v[0:1]
	v_pk_add_f32 v[2:3], v[4:5], v[8:9]
	v_pk_add_f32 v[138:139], v[6:7], v[10:11]
	v_pk_add_f32 v[4:5], v[4:5], v[8:9] neg_lo:[0,1] neg_hi:[0,1]
	v_pk_add_f32 v[6:7], v[6:7], v[10:11] neg_lo:[0,1] neg_hi:[0,1]
	v_pk_add_f32 v[8:9], v[12:13], v[16:17]
	v_pk_add_f32 v[10:11], v[14:15], v[18:19]
	v_pk_add_f32 v[12:13], v[12:13], v[16:17] neg_lo:[0,1] neg_hi:[0,1]
	v_pk_add_f32 v[14:15], v[14:15], v[18:19] neg_lo:[0,1] neg_hi:[0,1]
	v_pk_add_f32 v[16:17], v[20:21], v[104:105]
	v_pk_add_f32 v[18:19], v[22:23], v[106:107]
	v_pk_add_f32 v[20:21], v[20:21], v[104:105] neg_lo:[0,1] neg_hi:[0,1]
	v_pk_add_f32 v[22:23], v[22:23], v[106:107] neg_lo:[0,1] neg_hi:[0,1]
	v_pk_add_f32 v[104:105], v[108:109], v[112:113]
	v_pk_add_f32 v[106:107], v[110:111], v[114:115]
	v_pk_add_f32 v[108:109], v[108:109], v[112:113] neg_lo:[0,1] neg_hi:[0,1]
	v_pk_add_f32 v[110:111], v[110:111], v[114:115] neg_lo:[0,1] neg_hi:[0,1]
	v_pk_add_f32 v[112:113], v[116:117], v[120:121]
	v_pk_add_f32 v[114:115], v[118:119], v[122:123]
	v_pk_add_f32 v[116:117], v[116:117], v[120:121] neg_lo:[0,1] neg_hi:[0,1]
	v_pk_add_f32 v[118:119], v[118:119], v[122:123] neg_lo:[0,1] neg_hi:[0,1]
	v_pk_add_f32 v[120:121], v[124:125], v[128:129]
	v_pk_add_f32 v[122:123], v[126:127], v[130:131]
	v_pk_add_f32 v[124:125], v[124:125], v[128:129] neg_lo:[0,1] neg_hi:[0,1]
	v_pk_add_f32 v[126:127], v[126:127], v[130:131] neg_lo:[0,1] neg_hi:[0,1]
	v_pk_add_f32 v[128:129], v[132:133], v[144:145]
	v_pk_add_f32 v[130:131], v[134:135], v[140:141]
	v_pk_add_f32 v[132:133], v[132:133], v[144:145] neg_lo:[0,1] neg_hi:[0,1]
	v_pk_add_f32 v[134:135], v[134:135], v[140:141] neg_lo:[0,1] neg_hi:[0,1]
	v_pk_add_f32 v[140:141], v[142:143], v[0:1]
	v_pk_add_f32 v[144:145], v[136:137], v[166:167]
	v_pk_add_f32 v[136:137], v[136:137], v[166:167] neg_lo:[0,1] neg_hi:[0,1]
	v_pk_add_f32 v[0:1], v[142:143], v[0:1] neg_lo:[0,1] neg_hi:[0,1]
	v_pk_add_f32 v[142:143], v[2:3], v[8:9]
	v_pk_add_f32 v[164:165], v[138:139], v[10:11]
	v_pk_add_f32 v[2:3], v[2:3], v[8:9] neg_lo:[0,1] neg_hi:[0,1]
	v_pk_add_f32 v[8:9], v[138:139], v[10:11] neg_lo:[0,1] neg_hi:[0,1]
	v_pk_add_f32 v[138:139], v[6:7], v[12:13]
	v_pk_add_f32 v[6:7], v[6:7], v[12:13] neg_lo:[0,1] neg_hi:[0,1]
	v_pk_add_f32 v[12:13], v[16:17], v[104:105]
	v_pk_add_f32 v[16:17], v[16:17], v[104:105] neg_lo:[0,1] neg_hi:[0,1]
	v_pk_add_f32 v[104:105], v[20:21], v[110:111] neg_lo:[0,1] neg_hi:[0,1]
	v_pk_add_f32 v[20:21], v[20:21], v[110:111]
	v_pk_add_f32 v[110:111], v[114:115], v[122:123]
	v_pk_add_f32 v[114:115], v[114:115], v[122:123] neg_lo:[0,1] neg_hi:[0,1]
	v_pk_add_f32 v[122:123], v[118:119], v[124:125]
	v_pk_add_f32 v[118:119], v[118:119], v[124:125] neg_lo:[0,1] neg_hi:[0,1]
	v_pk_add_f32 v[124:125], v[128:129], v[140:141]
	v_pk_add_f32 v[128:129], v[128:129], v[140:141] neg_lo:[0,1] neg_hi:[0,1]
	v_pk_add_f32 v[140:141], v[132:133], v[136:137] neg_lo:[0,1] neg_hi:[0,1]
	v_pk_add_f32 v[10:11], v[4:5], v[14:15] neg_lo:[0,1] neg_hi:[0,1]
	v_pk_add_f32 v[4:5], v[4:5], v[14:15]
	v_pk_add_f32 v[14:15], v[18:19], v[106:107]
	v_pk_add_f32 v[18:19], v[18:19], v[106:107] neg_lo:[0,1] neg_hi:[0,1]
	v_pk_add_f32 v[106:107], v[22:23], v[108:109]
	v_pk_add_f32 v[22:23], v[22:23], v[108:109] neg_lo:[0,1] neg_hi:[0,1]
	v_pk_add_f32 v[108:109], v[112:113], v[120:121]
	v_pk_add_f32 v[112:113], v[112:113], v[120:121] neg_lo:[0,1] neg_hi:[0,1]
	v_pk_add_f32 v[120:121], v[116:117], v[126:127] neg_lo:[0,1] neg_hi:[0,1]
	v_pk_add_f32 v[116:117], v[116:117], v[126:127]
	v_pk_add_f32 v[126:127], v[130:131], v[144:145]
	v_pk_add_f32 v[130:131], v[130:131], v[144:145] neg_lo:[0,1] neg_hi:[0,1]
	v_pk_add_f32 v[144:145], v[134:135], v[0:1]
	v_pk_add_f32 v[0:1], v[134:135], v[0:1] neg_lo:[0,1] neg_hi:[0,1]
	v_pk_mul_f32 v[140:141], v[140:141], s[82:83] op_sel_hi:[1,0]
	v_pk_add_f32 v[132:133], v[132:133], v[136:137]
	v_pk_fma_f32 v[192:193], v[144:145], s[82:83], v[140:141] op_sel_hi:[1,0,1] neg_lo:[1,0,0] neg_hi:[1,0,0]
	v_pk_fma_f32 v[140:141], v[144:145], s[82:83], v[140:141] op_sel_hi:[1,0,1]
	v_pk_mul_f32 v[0:1], v[0:1], s[82:83] op_sel_hi:[1,0]
	v_pk_mul_f32 v[104:105], v[104:105], s[82:83] op_sel_hi:[1,0]
	v_pk_add_f32 v[144:145], v[120:121], v[192:193]
	v_pk_add_f32 v[194:195], v[122:123], v[140:141]
	v_pk_add_f32 v[120:121], v[120:121], v[192:193] neg_lo:[0,1] neg_hi:[0,1]
	v_pk_add_f32 v[192:193], v[114:115], v[128:129]
	v_pk_add_f32 v[114:115], v[114:115], v[128:129] neg_lo:[0,1] neg_hi:[0,1]
	v_pk_fma_f32 v[128:129], v[132:133], s[54:55], v[0:1] op_sel_hi:[1,0,1] neg_lo:[0,0,1] neg_hi:[0,0,1]
	v_pk_fma_f32 v[0:1], v[132:133], s[82:83], v[0:1] op_sel_hi:[1,0,1] neg_lo:[0,0,1] neg_hi:[0,0,1]
	v_pk_fma_f32 v[166:167], v[106:107], s[82:83], v[104:105] op_sel_hi:[1,0,1] neg_lo:[1,0,0] neg_hi:[1,0,0]
	v_pk_fma_f32 v[104:105], v[106:107], s[82:83], v[104:105] op_sel_hi:[1,0,1]
	v_pk_add_f32 v[122:123], v[122:123], v[140:141] neg_lo:[0,1] neg_hi:[0,1]
	v_pk_add_f32 v[140:141], v[112:113], v[130:131] neg_lo:[0,1] neg_hi:[0,1]
	v_pk_add_f32 v[112:113], v[112:113], v[130:131]
	v_pk_add_f32 v[130:131], v[116:117], v[128:129]
	v_pk_add_f32 v[132:133], v[118:119], v[0:1]
	v_pk_add_f32 v[116:117], v[116:117], v[128:129] neg_lo:[0,1] neg_hi:[0,1]
	v_pk_add_f32 v[0:1], v[118:119], v[0:1] neg_lo:[0,1] neg_hi:[0,1]
	v_pk_mul_f32 v[118:119], v[194:195], s[80:81] op_sel_hi:[1,0]
	v_pk_mul_f32 v[128:129], v[194:195], s[72:73] op_sel_hi:[1,0]
	v_pk_add_f32 v[106:107], v[10:11], v[166:167]
	v_pk_add_f32 v[190:191], v[138:139], v[104:105]
	v_pk_fma_f32 v[118:119], v[144:145], s[72:73], v[118:119] op_sel_hi:[1,0,1] neg_lo:[0,0,1] neg_hi:[0,0,1]
	v_pk_fma_f32 v[128:129], v[144:145], s[80:81], v[128:129] op_sel_hi:[1,0,1]
	v_pk_add_f32 v[106:107], v[106:107], v[118:119]
	v_pk_add_f32 v[118:119], v[190:191], v[128:129]
	v_pk_mul_f32 v[128:129], v[140:141], s[82:83] op_sel_hi:[1,0]
	v_pk_add_f32 v[10:11], v[10:11], v[166:167] neg_lo:[0,1] neg_hi:[0,1]
	v_pk_add_f32 v[104:105], v[138:139], v[104:105] neg_lo:[0,1] neg_hi:[0,1]
	v_pk_add_f32 v[138:139], v[2:3], v[18:19] neg_lo:[0,1] neg_hi:[0,1]
	v_pk_add_f32 v[166:167], v[8:9], v[16:17]
	v_pk_add_f32 v[8:9], v[8:9], v[16:17] neg_lo:[0,1] neg_hi:[0,1]
	v_pk_mul_f32 v[16:17], v[22:23], s[82:83] op_sel_hi:[1,0]
	v_pk_fma_f32 v[140:141], v[192:193], s[82:83], v[128:129] op_sel_hi:[1,0,1] neg_lo:[1,0,0] neg_hi:[1,0,0]
	v_pk_add_f32 v[2:3], v[2:3], v[18:19]
	v_pk_fma_f32 v[18:19], v[20:21], s[54:55], v[16:17] op_sel_hi:[1,0,1] neg_lo:[0,0,1] neg_hi:[0,0,1]
	v_pk_fma_f32 v[16:17], v[20:21], s[82:83], v[16:17] op_sel_hi:[1,0,1] neg_lo:[0,0,1] neg_hi:[0,0,1]
	v_pk_add_f32 v[138:139], v[138:139], v[140:141]
	v_pk_mul_f32 v[140:141], v[132:133], s[72:73] op_sel_hi:[1,0]
	v_pk_mul_f32 v[132:133], v[132:133], s[80:81] op_sel_hi:[1,0]
	v_pk_add_f32 v[22:23], v[6:7], v[16:17]
	v_pk_fma_f32 v[140:141], v[130:131], s[80:81], v[140:141] op_sel_hi:[1,0,1] neg_lo:[0,0,1] neg_hi:[0,0,1]
	v_pk_fma_f32 v[130:131], v[130:131], s[72:73], v[132:133] op_sel_hi:[1,0,1]
	v_pk_mul_f32 v[114:115], v[114:115], s[82:83] op_sel_hi:[1,0]
	v_pk_add_f32 v[22:23], v[22:23], v[130:131]
	v_pk_mul_f32 v[130:131], v[122:123], s[72:73] op_sel_hi:[1,0]
	v_pk_mul_f32 v[122:123], v[122:123], s[80:81] op_sel_hi:[1,0]
	v_pk_fma_f32 v[130:131], v[120:121], s[84:85], v[130:131] op_sel_hi:[1,0,1] neg_lo:[0,0,1] neg_hi:[0,0,1]
	v_pk_fma_f32 v[120:121], v[120:121], s[72:73], v[122:123] op_sel_hi:[1,0,1] neg_lo:[0,0,1] neg_hi:[0,0,1]
	v_pk_add_f32 v[6:7], v[6:7], v[16:17] neg_lo:[0,1] neg_hi:[0,1]
	v_pk_add_f32 v[104:105], v[104:105], v[120:121]
	v_pk_fma_f32 v[120:121], v[112:113], s[54:55], v[114:115] op_sel_hi:[1,0,1] neg_lo:[0,0,1] neg_hi:[0,0,1]
	v_pk_fma_f32 v[112:113], v[112:113], s[82:83], v[114:115] op_sel_hi:[1,0,1] neg_lo:[0,0,1] neg_hi:[0,0,1]
	v_pk_add_f32 v[136:137], v[164:165], v[14:15] neg_lo:[0,1] neg_hi:[0,1]
	v_pk_add_f32 v[8:9], v[8:9], v[112:113]
	v_pk_mul_f32 v[112:113], v[0:1], s[80:81] op_sel_hi:[1,0]
	v_pk_mul_f32 v[0:1], v[0:1], s[72:73] op_sel_hi:[1,0]
	v_pk_add_f32 v[134:135], v[142:143], v[12:13] neg_lo:[0,1] neg_hi:[0,1]
	v_pk_fma_f32 v[0:1], v[116:117], s[80:81], v[0:1] op_sel_hi:[1,0,1] neg_lo:[0,0,1] neg_hi:[0,0,1]
	v_pk_add_f32 v[12:13], v[142:143], v[12:13]
	v_pk_add_f32 v[0:1], v[6:7], v[0:1]
	v_pk_add_f32 v[6:7], v[164:165], v[14:15]
	v_pk_add_f32 v[14:15], v[110:111], v[126:127]
	v_pk_add_f32 v[20:21], v[4:5], v[18:19]
	v_pk_add_f32 v[6:7], v[6:7], v[14:15]
	v_pk_add_f32 v[14:15], v[108:109], v[124:125]
	v_pk_add_f32 v[4:5], v[4:5], v[18:19] neg_lo:[0,1] neg_hi:[0,1]
	v_pk_add_f32 v[16:17], v[108:109], v[124:125] neg_lo:[0,1] neg_hi:[0,1]
	v_pk_add_f32 v[18:19], v[110:111], v[126:127] neg_lo:[0,1] neg_hi:[0,1]
	v_pk_fma_f32 v[128:129], v[192:193], s[82:83], v[128:129] op_sel_hi:[1,0,1]
	v_pk_add_f32 v[2:3], v[2:3], v[120:121]
	v_pk_fma_f32 v[112:113], v[116:117], s[52:53], v[112:113] op_sel_hi:[1,0,1] neg_lo:[0,0,1] neg_hi:[0,0,1]
	v_pk_add_f32 v[12:13], v[12:13], v[14:15]
	v_pk_add_f32 v[128:129], v[166:167], v[128:129]
	v_pk_add_f32 v[20:21], v[20:21], v[140:141]
	v_pk_add_f32 v[18:19], v[134:135], v[18:19] neg_lo:[0,1] neg_hi:[0,1]
	v_pk_add_f32 v[16:17], v[136:137], v[16:17]
	v_pk_add_f32 v[10:11], v[10:11], v[130:131]
	v_pk_add_f32 v[4:5], v[4:5], v[112:113]
	ds_write_b64 v187, v[12:13]
	ds_write_b64 v188, v[6:7]
	ds_write_b64 v187, v[106:107] offset:4352
	ds_write_b64 v188, v[118:119] offset:4352
	ds_write_b64 v187, v[138:139] offset:8704
	ds_write_b64 v188, v[128:129] offset:8704
	ds_write_b64 v187, v[20:21] offset:13056
	ds_write_b64 v188, v[22:23] offset:13056
	ds_write_b64 v187, v[18:19] offset:17408
	ds_write_b64 v188, v[16:17] offset:17408
	ds_write_b64 v187, v[10:11] offset:21760
	ds_write_b64 v188, v[104:105] offset:21760
	ds_write_b64 v187, v[2:3] offset:26112
	ds_write_b64 v188, v[8:9] offset:26112
	ds_write_b64 v187, v[4:5] offset:30464
	ds_write_b64 v188, v[0:1] offset:30464
	s_waitcnt lgkmcnt(0)
	s_barrier
	ds_read_b64 v[0:1], v172
	ds_read_b64 v[2:3], v173
	v_lshlrev_b32_e32 v4, 16, v186
	v_and_b32_e32 v5, 0xffff0000, v186
	s_waitcnt lgkmcnt(1)
	v_pk_fma_f32 v[0:1], v[24:25], v[100:101], v[0:1]
	s_nop 0
	v_pk_mul_f32 v[0:1], v[0:1], v[4:5]
	v_lshlrev_b32_e32 v4, 16, v185
	v_and_b32_e32 v5, 0xffff0000, v185
	s_waitcnt lgkmcnt(0)
	v_pk_fma_f32 v[2:3], v[24:25], v[102:103], v[2:3]
	s_nop 0
	v_pk_mul_f32 v[2:3], v[2:3], v[4:5]
	ds_write_b64 v172, v[0:1]
	ds_write_b64 v173, v[2:3]
	v_cvt_pk_bf16_f32 v113, v0, v1
	v_cvt_pk_bf16_f32 v112, v2, v3
	ds_read_b64 v[0:1], v160 offset:4096
	ds_read_b64 v[2:3], v169
	v_lshlrev_b32_e32 v4, 16, v184
	v_and_b32_e32 v5, 0xffff0000, v184
	s_waitcnt lgkmcnt(1)
	v_pk_fma_f32 v[0:1], v[24:25], v[96:97], v[0:1]
	s_nop 0
	v_pk_mul_f32 v[0:1], v[0:1], v[4:5]
	v_lshlrev_b32_e32 v4, 16, v183
	v_and_b32_e32 v5, 0xffff0000, v183
	s_waitcnt lgkmcnt(0)
	v_pk_fma_f32 v[2:3], v[24:25], v[98:99], v[2:3]
	s_nop 0
	v_pk_mul_f32 v[2:3], v[2:3], v[4:5]
	ds_write_b64 v160, v[0:1] offset:4096
	ds_write_b64 v169, v[2:3]
	v_cvt_pk_bf16_f32 v111, v0, v1
	v_cvt_pk_bf16_f32 v110, v2, v3
	ds_read_b64 v[0:1], v158 offset:8192
	ds_read_b64 v[2:3], v159
	v_lshlrev_b32_e32 v4, 16, v182
	v_and_b32_e32 v5, 0xffff0000, v182
	s_waitcnt lgkmcnt(1)
	v_pk_fma_f32 v[0:1], v[24:25], v[92:93], v[0:1]
	s_nop 0
	v_pk_mul_f32 v[0:1], v[0:1], v[4:5]
	v_lshlrev_b32_e32 v4, 16, v181
	v_and_b32_e32 v5, 0xffff0000, v181
	s_waitcnt lgkmcnt(0)
	v_pk_fma_f32 v[2:3], v[24:25], v[94:95], v[2:3]
	s_nop 0
	v_pk_mul_f32 v[2:3], v[2:3], v[4:5]
	ds_write_b64 v158, v[0:1] offset:8192
	ds_write_b64 v159, v[2:3]
	v_cvt_pk_bf16_f32 v109, v0, v1
	v_cvt_pk_bf16_f32 v108, v2, v3
	ds_read_b64 v[0:1], v156 offset:12288
	ds_read_b64 v[2:3], v157
	v_lshlrev_b32_e32 v4, 16, v180
	v_and_b32_e32 v5, 0xffff0000, v180
	s_waitcnt lgkmcnt(1)
	v_pk_fma_f32 v[0:1], v[24:25], v[88:89], v[0:1]
	s_nop 0
	v_pk_mul_f32 v[0:1], v[0:1], v[4:5]
	v_lshlrev_b32_e32 v4, 16, v178
	v_and_b32_e32 v5, 0xffff0000, v178
	s_waitcnt lgkmcnt(0)
	v_pk_fma_f32 v[2:3], v[24:25], v[90:91], v[2:3]
	s_nop 0
	v_pk_mul_f32 v[2:3], v[2:3], v[4:5]
	ds_write_b64 v156, v[0:1] offset:12288
	ds_write_b64 v157, v[2:3]
	v_cvt_pk_bf16_f32 v107, v0, v1
	v_cvt_pk_bf16_f32 v106, v2, v3
	ds_read_b64 v[0:1], v154 offset:16384
	ds_read_b64 v[2:3], v155
	v_lshlrev_b32_e32 v4, 16, v179
	v_and_b32_e32 v5, 0xffff0000, v179
	s_waitcnt lgkmcnt(1)
	v_pk_fma_f32 v[0:1], v[24:25], v[84:85], v[0:1]
	s_nop 0
	v_pk_mul_f32 v[0:1], v[0:1], v[4:5]
	v_lshlrev_b32_e32 v4, 16, v177
	v_and_b32_e32 v5, 0xffff0000, v177
	s_waitcnt lgkmcnt(0)
	v_pk_fma_f32 v[2:3], v[24:25], v[86:87], v[2:3]
	s_nop 0
	v_pk_mul_f32 v[2:3], v[2:3], v[4:5]
	ds_write_b64 v154, v[0:1] offset:16384
	ds_write_b64 v155, v[2:3]
	v_cvt_pk_bf16_f32 v105, v0, v1
	v_cvt_pk_bf16_f32 v104, v2, v3
	ds_read_b64 v[0:1], v152 offset:20480
	ds_read_b64 v[2:3], v153
	v_lshlrev_b32_e32 v4, 16, v176
	v_and_b32_e32 v5, 0xffff0000, v176
	s_waitcnt lgkmcnt(1)
	v_pk_fma_f32 v[0:1], v[24:25], v[80:81], v[0:1]
	s_nop 0
	v_pk_mul_f32 v[0:1], v[0:1], v[4:5]
	v_lshlrev_b32_e32 v4, 16, v175
	v_and_b32_e32 v5, 0xffff0000, v175
	s_waitcnt lgkmcnt(0)
	v_pk_fma_f32 v[2:3], v[24:25], v[82:83], v[2:3]
	s_nop 0
	v_pk_mul_f32 v[2:3], v[2:3], v[4:5]
	ds_write_b64 v152, v[0:1] offset:20480
	ds_write_b64 v153, v[2:3]
	v_cvt_pk_bf16_f32 v103, v0, v1
	v_cvt_pk_bf16_f32 v102, v2, v3
	ds_read_b64 v[0:1], v150 offset:24576
	ds_read_b64 v[2:3], v151
	v_lshlrev_b32_e32 v4, 16, v174
	v_and_b32_e32 v5, 0xffff0000, v174
	s_waitcnt lgkmcnt(1)
	v_pk_fma_f32 v[0:1], v[24:25], v[76:77], v[0:1]
	s_nop 0
	v_pk_mul_f32 v[0:1], v[0:1], v[4:5]
	v_lshlrev_b32_e32 v4, 16, v171
	v_and_b32_e32 v5, 0xffff0000, v171
	s_waitcnt lgkmcnt(0)
	v_pk_fma_f32 v[2:3], v[24:25], v[78:79], v[2:3]
	s_nop 0
	v_pk_mul_f32 v[2:3], v[2:3], v[4:5]
	ds_write_b64 v150, v[0:1] offset:24576
	ds_write_b64 v151, v[2:3]
	v_cvt_pk_bf16_f32 v101, v0, v1
	v_cvt_pk_bf16_f32 v100, v2, v3
	ds_read_b64 v[0:1], v148 offset:28672
	ds_read_b64 v[2:3], v149
	v_lshlrev_b32_e32 v4, 16, v170
	v_and_b32_e32 v5, 0xffff0000, v170
	s_waitcnt lgkmcnt(1)
	v_pk_fma_f32 v[0:1], v[24:25], v[72:73], v[0:1]
	s_nop 0
	v_pk_mul_f32 v[0:1], v[0:1], v[4:5]
	v_lshlrev_b32_e32 v4, 16, v168
	v_and_b32_e32 v5, 0xffff0000, v168
	s_waitcnt lgkmcnt(0)
	v_pk_fma_f32 v[2:3], v[24:25], v[74:75], v[2:3]
	s_nop 0
	v_pk_mul_f32 v[2:3], v[2:3], v[4:5]
	ds_write_b64 v148, v[0:1] offset:28672
	ds_write_b64 v149, v[2:3]
	v_cvt_pk_bf16_f32 v99, v0, v1
	v_lshl_add_u64 v[0:1], s[4:5], 0, v[68:69]
	v_cvt_pk_bf16_f32 v98, v2, v3
	global_load_dword v128, v[0:1], off
	v_lshl_add_u64 v[0:1], s[6:7], 0, v[68:69]
	global_load_dword v129, v[0:1], off
	v_lshl_add_u64 v[0:1], s[4:5], 0, v[70:71]
	global_load_dword v126, v[0:1], off
	v_lshl_add_u64 v[0:1], s[6:7], 0, v[70:71]
	global_load_dword v127, v[0:1], off
	v_lshl_add_u64 v[0:1], s[4:5], 0, v[66:67]
	global_load_dword v123, v[0:1], off
	v_lshl_add_u64 v[0:1], s[6:7], 0, v[66:67]
	global_load_dword v124, v[0:1], off
	v_lshl_add_u64 v[0:1], s[4:5], 0, v[64:65]
	global_load_dword v120, v[0:1], off
	v_lshl_add_u64 v[0:1], s[6:7], 0, v[64:65]
	global_load_dword v125, v[0:1], off
	v_lshl_add_u64 v[0:1], s[4:5], 0, v[62:63]
	global_load_dword v121, v[0:1], off
	v_lshl_add_u64 v[0:1], s[6:7], 0, v[62:63]
	global_load_dword v122, v[0:1], off
	v_lshl_add_u64 v[0:1], s[4:5], 0, v[60:61]
	global_load_dword v118, v[0:1], off
	v_lshl_add_u64 v[0:1], s[6:7], 0, v[60:61]
	global_load_dword v119, v[0:1], off
	v_lshl_add_u64 v[0:1], s[4:5], 0, v[58:59]
	global_load_dword v115, v[0:1], off
	v_lshl_add_u64 v[0:1], s[6:7], 0, v[58:59]
	global_load_dword v116, v[0:1], off
	v_lshl_add_u64 v[0:1], s[4:5], 0, v[56:57]
	global_load_dword v114, v[0:1], off
	v_lshl_add_u64 v[0:1], s[6:7], 0, v[56:57]
	global_load_dword v117, v[0:1], off
	v_mov_b32_e32 v0, v163
	s_waitcnt lgkmcnt(0)
	s_barrier
	s_nop 0
	s_nop 0
	v_ashrrev_i32_e32 v2, 31, v0
	v_lshlrev_b32_e32 v1, 1, v0
	v_lshrrev_b32_e32 v2, 23, v2
	v_and_b32_e32 v1, 0x3fe, v1
	v_add_lshl_u32 v0, v0, v2, 5
	v_and_or_b32 v0, v0, s85, v1
	v_ashrrev_i32_e32 v2, 4, v0
	v_and_b32_e32 v2, 0x3ffffc3c, v2
	v_add_lshl_u32 v88, v2, v0, 2
	v_cvt_f32_u32_e32 v0, v1
	v_or_b32_e32 v1, 1, v1
	v_cvt_f32_u32_e32 v1, v1
	v_add_u32_e32 v162, 0, v88
	v_mul_f32_e32 v2, 0x38800000, v0
	v_add_u32_e32 v168, s91, v88
	v_mul_f32_e32 v3, 0x38800000, v1
	ds_read_b64 v[88:89], v162
	ds_read_b64 v[90:91], v168
	ds_read_b64 v[92:93], v162 offset:4352
	ds_read_b64 v[94:95], v168 offset:4352
	ds_read_b64 v[96:97], v162 offset:8704
	ds_read_b64 v[130:131], v168 offset:8704
	ds_read_b64 v[132:133], v162 offset:13056
	ds_read_b64 v[134:135], v168 offset:13056
	ds_read_b64 v[136:137], v162 offset:17408
	ds_read_b64 v[138:139], v168 offset:17408
	ds_read_b64 v[140:141], v162 offset:21760
	ds_read_b64 v[142:143], v168 offset:21760
	ds_read_b64 v[144:145], v162 offset:26112
	ds_read_b64 v[164:165], v168 offset:26112
	ds_read_b64 v[166:167], v162 offset:30464
	ds_read_b64 v[170:171], v168 offset:30464
	v_sin_f32_e64 v14, -v2
	v_sin_f32_e64 v15, -v3
	s_waitcnt lgkmcnt(12)
	v_pk_mul_f32 v[182:183], v[94:95], s[80:81] op_sel_hi:[1,0]
	v_cos_f32_e32 v0, v2
	v_cos_f32_e32 v1, v3
	v_pk_add_f32 v[178:179], v[92:93], 0 op_sel_hi:[1,0]
	v_pk_fma_f32 v[182:183], v[92:93], s[72:73], v[182:183] op_sel_hi:[1,0,1]
	v_pk_mul_f32 v[92:93], v[92:93], s[80:81] op_sel_hi:[1,0]
	v_pk_add_f32 v[180:181], v[94:95], 0 op_sel_hi:[1,0]
	v_pk_fma_f32 v[92:93], v[94:95], s[72:73], v[92:93] op_sel_hi:[1,0,1] neg_lo:[0,0,1] neg_hi:[0,0,1]
	s_waitcnt lgkmcnt(11)
	v_pk_add_f32 v[94:95], v[96:97], 0 op_sel_hi:[1,0]
	v_pk_mul_f32 v[96:97], v[96:97], s[82:83] op_sel_hi:[1,0]
	s_waitcnt lgkmcnt(8)
	v_pk_mul_f32 v[190:191], v[134:135], s[72:73] op_sel_hi:[1,0]
	v_pk_add_f32 v[184:185], v[130:131], 0 op_sel_hi:[1,0]
	v_pk_fma_f32 v[186:187], v[130:131], s[82:83], v[96:97] op_sel_hi:[1,0,1]
	v_pk_fma_f32 v[96:97], v[130:131], s[82:83], v[96:97] op_sel_hi:[1,0,1] neg_lo:[0,0,1] neg_hi:[0,0,1]
	v_pk_add_f32 v[130:131], v[132:133], 0 op_sel_hi:[1,0]
	v_pk_fma_f32 v[190:191], v[132:133], s[80:81], v[190:191] op_sel_hi:[1,0,1]
	v_pk_mul_f32 v[132:133], v[132:133], s[72:73] op_sel_hi:[1,0]
	s_waitcnt lgkmcnt(5)
	v_pk_mul_f32 v[198:199], v[140:141], s[80:81] op_sel_hi:[1,0]
	s_waitcnt lgkmcnt(1)
	v_pk_mul_f32 v[206:207], v[166:167], s[72:73] op_sel_hi:[1,0]
	v_pk_mul_f32 v[2:3], v[14:15], v[14:15]
	v_pk_add_f32 v[174:175], v[88:89], 0 op_sel_hi:[1,0]
	v_pk_add_f32 v[176:177], v[90:91], 0 op_sel_hi:[1,0]
	v_pk_add_f32 v[188:189], v[134:135], 0 op_sel_hi:[1,0]
	v_pk_fma_f32 v[132:133], v[134:135], s[80:81], v[132:133] op_sel_hi:[1,0,1] neg_lo:[0,0,1] neg_hi:[0,0,1]
	v_pk_add_f32 v[134:135], v[136:137], 0 op_sel_hi:[1,0]
	v_pk_add_f32 v[192:193], v[138:139], 0 op_sel_hi:[1,0]
	v_pk_add_f32 v[194:195], v[140:141], 0 op_sel_hi:[1,0]
	v_pk_add_f32 v[196:197], v[142:143], 0 op_sel_hi:[1,0]
	v_pk_fma_f32 v[198:199], v[142:143], s[72:73], v[198:199] op_sel_hi:[1,0,1] neg_lo:[0,0,1] neg_hi:[0,0,1]
	v_pk_mul_f32 v[142:143], v[142:143], s[80:81] op_sel_hi:[1,0]
	v_pk_add_f32 v[200:201], v[164:165], 0 op_sel_hi:[1,0]
	v_pk_mul_f32 v[164:165], v[164:165], s[54:55] op_sel_hi:[1,0]
	s_waitcnt lgkmcnt(0)
	v_pk_add_f32 v[204:205], v[170:171], 0 op_sel_hi:[1,0]
	v_pk_fma_f32 v[206:207], v[170:171], s[80:81], v[206:207] op_sel_hi:[1,0,1] neg_lo:[0,0,1] neg_hi:[0,0,1]
	v_pk_mul_f32 v[170:171], v[170:171], s[72:73] op_sel_hi:[1,0]
	v_pk_fma_f32 v[58:59], v[0:1], v[0:1], v[2:3] neg_lo:[0,0,1] neg_hi:[0,0,1]
	v_pk_mul_f32 v[2:3], v[0:1], v[14:15]
	v_pk_fma_f32 v[140:141], v[140:141], s[52:53], v[142:143] op_sel_hi:[1,0,1] neg_lo:[0,0,1] neg_hi:[0,0,1]
	v_pk_add_f32 v[142:143], v[144:145], 0 op_sel_hi:[1,0]
	v_pk_fma_f32 v[202:203], v[144:145], s[54:55], v[164:165] op_sel_hi:[1,0,1] neg_lo:[0,0,1] neg_hi:[0,0,1]
	v_pk_fma_f32 v[144:145], v[144:145], s[54:55], v[164:165] op_sel_hi:[1,0,1]
	v_pk_add_f32 v[164:165], v[166:167], 0 op_sel_hi:[1,0]
	v_pk_fma_f32 v[166:167], v[166:167], s[84:85], v[170:171] op_sel_hi:[1,0,1] neg_lo:[0,0,1] neg_hi:[0,0,1]
	v_pk_add_f32 v[170:171], v[174:175], v[134:135]
	v_pk_add_f32 v[208:209], v[176:177], v[192:193]
	v_pk_add_f32 v[134:135], v[174:175], v[134:135] neg_lo:[0,1] neg_hi:[0,1]
	v_pk_add_f32 v[174:175], v[176:177], v[192:193] neg_lo:[0,1] neg_hi:[0,1]
	v_pk_add_f32 v[176:177], v[178:179], v[194:195]
	v_pk_add_f32 v[178:179], v[178:179], v[194:195] neg_lo:[0,1] neg_hi:[0,1]
	v_pk_add_f32 v[64:65], v[2:3], v[2:3]
	v_pk_add_f32 v[192:193], v[180:181], v[196:197]
	v_pk_add_f32 v[180:181], v[180:181], v[196:197] neg_lo:[0,1] neg_hi:[0,1]
	v_pk_mul_f32 v[178:179], v[178:179], s[82:83] op_sel_hi:[1,0]
	v_pk_mul_f32 v[2:3], v[14:15], v[64:65]
	v_pk_fma_f32 v[194:195], v[180:181], s[82:83], v[178:179] op_sel_hi:[1,0,1]
	v_pk_fma_f32 v[178:179], v[180:181], s[82:83], v[178:179] op_sel_hi:[1,0,1] neg_lo:[0,0,1] neg_hi:[0,0,1]
	v_pk_add_f32 v[180:181], v[94:95], v[142:143]
	v_pk_add_f32 v[196:197], v[184:185], v[200:201]
	v_pk_add_f32 v[94:95], v[94:95], v[142:143] neg_lo:[0,1] neg_hi:[0,1]
	v_pk_add_f32 v[142:143], v[184:185], v[200:201] neg_lo:[0,1] neg_hi:[0,1]
	v_pk_add_f32 v[184:185], v[130:131], v[164:165]
	v_pk_add_f32 v[130:131], v[130:131], v[164:165] neg_lo:[0,1] neg_hi:[0,1]
	v_pk_add_f32 v[164:165], v[188:189], v[204:205] neg_lo:[0,1] neg_hi:[0,1]
	v_pk_fma_f32 v[6:7], v[0:1], v[58:59], v[2:3] neg_lo:[0,0,1] neg_hi:[0,0,1]
	v_pk_mul_f32 v[2:3], v[14:15], v[58:59]
	v_pk_add_f32 v[200:201], v[188:189], v[204:205]
	v_pk_mul_f32 v[164:165], v[164:165], s[54:55] op_sel_hi:[1,0]
	v_pk_add_f32 v[204:205], v[90:91], v[136:137] neg_lo:[0,1] neg_hi:[0,1]
	v_pk_add_f32 v[90:91], v[90:91], v[136:137]
	v_pk_add_f32 v[136:137], v[182:183], v[198:199]
	v_pk_add_f32 v[182:183], v[182:183], v[198:199] neg_lo:[0,1] neg_hi:[0,1]
	v_pk_fma_f32 v[12:13], v[0:1], v[64:65], v[2:3]
	v_pk_mul_f32 v[2:3], v[64:65], v[64:65]
	v_pk_fma_f32 v[188:189], v[130:131], s[54:55], v[164:165] op_sel_hi:[1,0,1] neg_lo:[0,0,1] neg_hi:[0,0,1]
	v_pk_fma_f32 v[130:131], v[130:131], s[54:55], v[164:165] op_sel_hi:[1,0,1]
	v_pk_add_f32 v[164:165], v[88:89], v[138:139]
	v_pk_add_f32 v[88:89], v[88:89], v[138:139] neg_lo:[0,1] neg_hi:[0,1]
	v_pk_add_f32 v[138:139], v[92:93], v[140:141]
	v_pk_add_f32 v[92:93], v[92:93], v[140:141] neg_lo:[0,1] neg_hi:[0,1]
	v_pk_mul_f32 v[140:141], v[182:183], s[82:83] op_sel_hi:[1,0]
	v_pk_fma_f32 v[72:73], v[58:59], v[58:59], v[2:3] neg_lo:[0,0,1] neg_hi:[0,0,1]
	v_pk_mul_f32 v[2:3], v[58:59], v[64:65]
	v_pk_fma_f32 v[182:183], v[92:93], s[82:83], v[140:141] op_sel_hi:[1,0,1]
	v_pk_fma_f32 v[92:93], v[92:93], s[82:83], v[140:141] op_sel_hi:[1,0,1] neg_lo:[0,0,1] neg_hi:[0,0,1]
	v_pk_add_f32 v[140:141], v[186:187], v[202:203]
	v_pk_add_f32 v[186:187], v[186:187], v[202:203] neg_lo:[0,1] neg_hi:[0,1]
	v_pk_add_f32 v[202:203], v[132:133], v[166:167]
	v_pk_add_f32 v[132:133], v[132:133], v[166:167] neg_lo:[0,1] neg_hi:[0,1]
	v_pk_add_f32 v[74:75], v[2:3], v[2:3]
	v_pk_add_f32 v[198:199], v[96:97], v[144:145]
	v_pk_add_f32 v[96:97], v[96:97], v[144:145] neg_lo:[0,1] neg_hi:[0,1]
	v_pk_add_f32 v[144:145], v[190:191], v[206:207]
	v_pk_add_f32 v[190:191], v[190:191], v[206:207] neg_lo:[0,1] neg_hi:[0,1]
	v_pk_mul_f32 v[132:133], v[132:133], s[54:55] op_sel_hi:[1,0]
	v_pk_mul_f32 v[2:3], v[14:15], v[74:75]
	v_pk_mul_f32 v[8:9], v[74:75], v[74:75]
	v_pk_mul_f32 v[10:11], v[72:73], v[74:75]
	v_pk_fma_f32 v[166:167], v[190:191], s[54:55], v[132:133] op_sel_hi:[1,0,1] neg_lo:[0,0,1] neg_hi:[0,0,1]
	v_pk_fma_f32 v[132:133], v[190:191], s[54:55], v[132:133] op_sel_hi:[1,0,1]
	v_pk_add_f32 v[190:191], v[170:171], v[180:181]
	v_pk_add_f32 v[206:207], v[208:209], v[196:197]
	v_pk_add_f32 v[170:171], v[170:171], v[180:181] neg_lo:[0,1] neg_hi:[0,1]
	v_pk_add_f32 v[180:181], v[208:209], v[196:197] neg_lo:[0,1] neg_hi:[0,1]
	v_pk_add_f32 v[196:197], v[176:177], v[184:185]
	v_pk_add_f32 v[208:209], v[192:193], v[200:201]
	v_pk_fma_f32 v[16:17], v[0:1], v[72:73], v[2:3] neg_lo:[0,0,1] neg_hi:[0,0,1]
	v_pk_mul_f32 v[2:3], v[14:15], v[72:73]
	v_pk_fma_f32 v[8:9], v[72:73], v[72:73], v[8:9] neg_lo:[0,0,1] neg_hi:[0,0,1]
	v_pk_add_f32 v[10:11], v[10:11], v[10:11]
	v_pk_add_f32 v[176:177], v[176:177], v[184:185] neg_lo:[0,1] neg_hi:[0,1]
	v_pk_add_f32 v[184:185], v[192:193], v[200:201] neg_lo:[0,1] neg_hi:[0,1]
	v_pk_add_f32 v[192:193], v[134:135], v[142:143]
	v_pk_add_f32 v[200:201], v[174:175], v[94:95] neg_lo:[0,1] neg_hi:[0,1]
	v_pk_add_f32 v[134:135], v[134:135], v[142:143] neg_lo:[0,1] neg_hi:[0,1]
	v_pk_add_f32 v[94:95], v[174:175], v[94:95]
	v_pk_add_f32 v[142:143], v[194:195], v[188:189]
	v_pk_add_f32 v[174:175], v[178:179], v[130:131]
	v_pk_add_f32 v[188:189], v[194:195], v[188:189] neg_lo:[0,1] neg_hi:[0,1]
	v_pk_add_f32 v[130:131], v[178:179], v[130:131] neg_lo:[0,1] neg_hi:[0,1]
	v_pk_add_f32 v[178:179], v[164:165], v[140:141]
	v_pk_add_f32 v[194:195], v[204:205], v[198:199]
	v_pk_add_f32 v[140:141], v[164:165], v[140:141] neg_lo:[0,1] neg_hi:[0,1]
	v_pk_add_f32 v[164:165], v[204:205], v[198:199] neg_lo:[0,1] neg_hi:[0,1]
	v_pk_add_f32 v[198:199], v[136:137], v[144:145]
	v_pk_add_f32 v[204:205], v[138:139], v[202:203]
	v_pk_add_f32 v[136:137], v[136:137], v[144:145] neg_lo:[0,1] neg_hi:[0,1]
	v_pk_add_f32 v[138:139], v[138:139], v[202:203] neg_lo:[0,1] neg_hi:[0,1]
	v_pk_add_f32 v[144:145], v[88:89], v[96:97]
	v_pk_add_f32 v[202:203], v[90:91], v[186:187] neg_lo:[0,1] neg_hi:[0,1]
	v_pk_add_f32 v[88:89], v[88:89], v[96:97] neg_lo:[0,1] neg_hi:[0,1]
	v_pk_add_f32 v[90:91], v[90:91], v[186:187]
	v_pk_add_f32 v[96:97], v[182:183], v[166:167]
	v_pk_add_f32 v[186:187], v[92:93], v[132:133]
	v_pk_add_f32 v[166:167], v[182:183], v[166:167] neg_lo:[0,1] neg_hi:[0,1]
	v_pk_add_f32 v[92:93], v[92:93], v[132:133] neg_lo:[0,1] neg_hi:[0,1]
	v_pk_add_f32 v[132:133], v[190:191], v[196:197]
	v_pk_add_f32 v[182:183], v[206:207], v[208:209]
	v_pk_add_f32 v[190:191], v[190:191], v[196:197] neg_lo:[0,1] neg_hi:[0,1]
	v_pk_add_f32 v[196:197], v[206:207], v[208:209] neg_lo:[0,1] neg_hi:[0,1]
	v_pk_fma_f32 v[18:19], v[0:1], v[74:75], v[2:3]
	v_pk_mul_f32 v[2:3], v[64:65], v[74:75]
	ds_write_b64 v162, v[132:133]
	ds_write_b64 v168, v[182:183]
	v_pk_mul_f32 v[132:133], v[8:9], v[196:197]
	v_pk_mul_f32 v[182:183], v[10:11], v[196:197]
	v_pk_fma_f32 v[66:67], v[58:59], v[72:73], v[2:3] neg_lo:[0,0,1] neg_hi:[0,0,1]
	v_pk_mul_f32 v[2:3], v[64:65], v[72:73]
	v_pk_mul_f32 v[4:5], v[72:73], v[12:13]
	v_pk_mul_f32 v[62:63], v[74:75], v[10:11]
	v_pk_add_f32 v[206:207], v[170:171], v[184:185]
	v_pk_add_f32 v[208:209], v[180:181], v[176:177] neg_lo:[0,1] neg_hi:[0,1]
	v_pk_fma_f32 v[132:133], v[10:11], v[190:191], v[132:133]
	v_pk_fma_f32 v[182:183], v[8:9], v[190:191], v[182:183] neg_lo:[0,0,1] neg_hi:[0,0,1]
	v_pk_fma_f32 v[70:71], v[58:59], v[74:75], v[2:3]
	v_pk_mul_f32 v[2:3], v[74:75], v[12:13]
	v_pk_fma_f32 v[4:5], v[74:75], v[6:7], v[4:5]
	v_pk_fma_f32 v[80:81], v[72:73], v[8:9], v[62:63] neg_lo:[0,0,1] neg_hi:[0,0,1]
	v_pk_mul_f32 v[62:63], v[74:75], v[8:9]
	ds_write_b64 v162, v[182:183] offset:34816
	ds_write_b64 v168, v[132:133] offset:34816
	v_pk_mul_f32 v[132:133], v[74:75], v[206:207]
	v_pk_mul_f32 v[74:75], v[74:75], v[208:209]
	v_pk_fma_f32 v[2:3], v[72:73], v[6:7], v[2:3] neg_lo:[0,0,1] neg_hi:[0,0,1]
	v_pk_mul_f32 v[20:21], v[14:15], v[10:11]
	v_pk_fma_f32 v[82:83], v[72:73], v[10:11], v[62:63]
	v_pk_add_f32 v[170:171], v[170:171], v[184:185] neg_lo:[0,1] neg_hi:[0,1]
	v_pk_add_f32 v[176:177], v[180:181], v[176:177]
	v_pk_fma_f32 v[132:133], v[72:73], v[208:209], v[132:133]
	v_pk_fma_f32 v[72:73], v[72:73], v[206:207], v[74:75] neg_lo:[0,0,1] neg_hi:[0,0,1]
	v_pk_fma_f32 v[56:57], v[0:1], v[8:9], v[20:21] neg_lo:[0,0,1] neg_hi:[0,0,1]
	v_pk_mul_f32 v[20:21], v[14:15], v[8:9]
	ds_write_b64 v162, v[72:73] offset:17408
	ds_write_b64 v168, v[132:133] offset:17408
	v_pk_mul_f32 v[72:73], v[82:83], v[170:171]
	v_pk_mul_f32 v[74:75], v[82:83], v[176:177]
	v_pk_fma_f32 v[60:61], v[0:1], v[10:11], v[20:21]
	v_pk_mul_f32 v[20:21], v[64:65], v[10:11]
	v_pk_add_f32 v[180:181], v[192:193], v[142:143]
	v_pk_add_f32 v[184:185], v[200:201], v[174:175]
	v_pk_fma_f32 v[72:73], v[80:81], v[176:177], v[72:73]
	v_pk_fma_f32 v[74:75], v[80:81], v[170:171], v[74:75] neg_lo:[0,0,1] neg_hi:[0,0,1]
	v_pk_fma_f32 v[76:77], v[58:59], v[8:9], v[20:21] neg_lo:[0,0,1] neg_hi:[0,0,1]
	v_pk_mul_f32 v[20:21], v[64:65], v[8:9]
	ds_write_b64 v162, v[74:75] offset:52224
	ds_write_b64 v168, v[72:73] offset:52224
	v_pk_mul_f32 v[72:73], v[64:65], v[180:181]
	v_pk_mul_f32 v[64:65], v[64:65], v[184:185]
	v_pk_fma_f32 v[78:79], v[58:59], v[10:11], v[20:21]
	v_pk_add_f32 v[142:143], v[192:193], v[142:143] neg_lo:[0,1] neg_hi:[0,1]
	v_pk_add_f32 v[174:175], v[200:201], v[174:175] neg_lo:[0,1] neg_hi:[0,1]
	v_pk_fma_f32 v[72:73], v[58:59], v[184:185], v[72:73]
	v_pk_fma_f32 v[58:59], v[58:59], v[180:181], v[64:65] neg_lo:[0,0,1] neg_hi:[0,0,1]
	ds_write_b64 v162, v[58:59] offset:8704
	ds_write_b64 v168, v[72:73] offset:8704
	v_pk_mul_f32 v[58:59], v[78:79], v[142:143]
	v_pk_mul_f32 v[64:65], v[78:79], v[174:175]
	v_pk_add_f32 v[192:193], v[134:135], v[130:131]
	v_pk_add_f32 v[200:201], v[94:95], v[188:189] neg_lo:[0,1] neg_hi:[0,1]
	v_pk_fma_f32 v[58:59], v[76:77], v[174:175], v[58:59]
	v_pk_fma_f32 v[64:65], v[76:77], v[142:143], v[64:65] neg_lo:[0,0,1] neg_hi:[0,0,1]
	v_pk_mul_f32 v[86:87], v[8:9], v[70:71]
	ds_write_b64 v162, v[64:65] offset:43520
	ds_write_b64 v168, v[58:59] offset:43520
	v_pk_mul_f32 v[58:59], v[70:71], v[192:193]
	v_pk_mul_f32 v[64:65], v[70:71], v[200:201]
	v_pk_mul_f32 v[84:85], v[10:11], v[70:71]
	v_pk_fma_f32 v[86:87], v[10:11], v[66:67], v[86:87]
	v_pk_add_f32 v[130:131], v[134:135], v[130:131] neg_lo:[0,1] neg_hi:[0,1]
	v_pk_add_f32 v[94:95], v[94:95], v[188:189]
	v_pk_fma_f32 v[58:59], v[66:67], v[200:201], v[58:59]
	v_pk_fma_f32 v[64:65], v[66:67], v[192:193], v[64:65] neg_lo:[0,0,1] neg_hi:[0,0,1]
	v_pk_fma_f32 v[84:85], v[8:9], v[66:67], v[84:85] neg_lo:[0,0,1] neg_hi:[0,0,1]
	ds_write_b64 v162, v[64:65] offset:26112
	ds_write_b64 v168, v[58:59] offset:26112
	v_pk_mul_f32 v[58:59], v[86:87], v[130:131]
	v_pk_mul_f32 v[64:65], v[86:87], v[94:95]
	v_pk_add_f32 v[134:135], v[178:179], v[198:199]
	v_pk_add_f32 v[188:189], v[194:195], v[204:205]
	v_pk_fma_f32 v[58:59], v[84:85], v[94:95], v[58:59]
	v_pk_fma_f32 v[64:65], v[84:85], v[130:131], v[64:65] neg_lo:[0,0,1] neg_hi:[0,0,1]
	ds_write_b64 v162, v[64:65] offset:60928
	ds_write_b64 v168, v[58:59] offset:60928
	v_pk_mul_f32 v[58:59], v[14:15], v[134:135]
	v_pk_mul_f32 v[14:15], v[14:15], v[188:189]
	v_pk_add_f32 v[178:179], v[178:179], v[198:199] neg_lo:[0,1] neg_hi:[0,1]
	v_pk_add_f32 v[194:195], v[194:195], v[204:205] neg_lo:[0,1] neg_hi:[0,1]
	v_pk_fma_f32 v[58:59], v[0:1], v[188:189], v[58:59]
	v_pk_fma_f32 v[0:1], v[0:1], v[134:135], v[14:15] neg_lo:[0,0,1] neg_hi:[0,0,1]
	ds_write_b64 v162, v[0:1] offset:4352
	ds_write_b64 v168, v[58:59] offset:4352
	v_pk_mul_f32 v[0:1], v[60:61], v[178:179]
	v_pk_mul_f32 v[14:15], v[60:61], v[194:195]
	v_pk_add_f32 v[198:199], v[140:141], v[138:139]
	v_pk_add_f32 v[204:205], v[164:165], v[136:137] neg_lo:[0,1] neg_hi:[0,1]
	v_pk_fma_f32 v[0:1], v[56:57], v[194:195], v[0:1]
	v_pk_fma_f32 v[14:15], v[56:57], v[178:179], v[14:15] neg_lo:[0,0,1] neg_hi:[0,0,1]
	v_pk_mul_f32 v[68:69], v[8:9], v[18:19]
	ds_write_b64 v162, v[14:15] offset:39168
	ds_write_b64 v168, v[0:1] offset:39168
	v_pk_mul_f32 v[0:1], v[18:19], v[198:199]
	v_pk_mul_f32 v[14:15], v[18:19], v[204:205]
	v_pk_mul_f32 v[62:63], v[10:11], v[18:19]
	v_pk_fma_f32 v[68:69], v[10:11], v[16:17], v[68:69]
	v_pk_add_f32 v[138:139], v[140:141], v[138:139] neg_lo:[0,1] neg_hi:[0,1]
	v_pk_add_f32 v[136:137], v[164:165], v[136:137]
	v_pk_fma_f32 v[0:1], v[16:17], v[204:205], v[0:1]
	v_pk_fma_f32 v[14:15], v[16:17], v[198:199], v[14:15] neg_lo:[0,0,1] neg_hi:[0,0,1]
	v_pk_fma_f32 v[62:63], v[8:9], v[16:17], v[62:63] neg_lo:[0,0,1] neg_hi:[0,0,1]
	ds_write_b64 v162, v[14:15] offset:21760
	ds_write_b64 v168, v[0:1] offset:21760
	v_pk_mul_f32 v[0:1], v[68:69], v[138:139]
	v_pk_mul_f32 v[14:15], v[68:69], v[136:137]
	v_pk_add_f32 v[140:141], v[144:145], v[96:97]
	v_pk_add_f32 v[164:165], v[202:203], v[186:187]
	v_pk_fma_f32 v[0:1], v[62:63], v[136:137], v[0:1]
	v_pk_fma_f32 v[14:15], v[62:63], v[138:139], v[14:15] neg_lo:[0,0,1] neg_hi:[0,0,1]
	v_pk_mul_f32 v[20:21], v[12:13], v[10:11]
	v_pk_mul_f32 v[22:23], v[12:13], v[8:9]
	ds_write_b64 v162, v[14:15] offset:56576
	ds_write_b64 v168, v[0:1] offset:56576
	v_pk_mul_f32 v[0:1], v[12:13], v[140:141]
	v_pk_mul_f32 v[12:13], v[12:13], v[164:165]
	v_pk_fma_f32 v[20:21], v[6:7], v[8:9], v[20:21] neg_lo:[0,0,1] neg_hi:[0,0,1]
	v_pk_fma_f32 v[22:23], v[6:7], v[10:11], v[22:23]
	v_pk_add_f32 v[96:97], v[144:145], v[96:97] neg_lo:[0,1] neg_hi:[0,1]
	v_pk_add_f32 v[144:145], v[202:203], v[186:187] neg_lo:[0,1] neg_hi:[0,1]
	v_pk_fma_f32 v[0:1], v[6:7], v[164:165], v[0:1]
	v_pk_fma_f32 v[6:7], v[6:7], v[140:141], v[12:13] neg_lo:[0,0,1] neg_hi:[0,0,1]
	ds_write_b64 v162, v[6:7] offset:13056
	ds_write_b64 v168, v[0:1] offset:13056
	v_pk_mul_f32 v[6:7], v[22:23], v[144:145]
	v_pk_add_f32 v[202:203], v[90:91], v[166:167] neg_lo:[0,1] neg_hi:[0,1]
	v_pk_mul_f32 v[0:1], v[22:23], v[96:97]
	v_pk_fma_f32 v[6:7], v[20:21], v[96:97], v[6:7] neg_lo:[0,0,1] neg_hi:[0,0,1]
	v_pk_add_f32 v[186:187], v[88:89], v[92:93]
	v_pk_fma_f32 v[0:1], v[20:21], v[144:145], v[0:1]
	ds_write_b64 v162, v[6:7] offset:47872
	ds_write_b64 v168, v[0:1] offset:47872
	v_pk_mul_f32 v[6:7], v[4:5], v[202:203]
	v_pk_mul_f32 v[0:1], v[4:5], v[186:187]
	v_pk_fma_f32 v[6:7], v[2:3], v[186:187], v[6:7] neg_lo:[0,0,1] neg_hi:[0,0,1]
	v_pk_fma_f32 v[0:1], v[2:3], v[202:203], v[0:1]
	ds_write_b64 v162, v[6:7] offset:30464
	ds_write_b64 v168, v[0:1] offset:30464
	v_pk_mul_f32 v[6:7], v[10:11], v[4:5]
	v_pk_mul_f32 v[4:5], v[8:9], v[4:5]
	v_pk_fma_f32 v[6:7], v[8:9], v[2:3], v[6:7] neg_lo:[0,0,1] neg_hi:[0,0,1]
	v_pk_add_f32 v[12:13], v[88:89], v[92:93] neg_lo:[0,1] neg_hi:[0,1]
	v_pk_fma_f32 v[2:3], v[10:11], v[2:3], v[4:5]
	v_pk_add_f32 v[0:1], v[90:91], v[166:167]
	v_pk_mul_f32 v[4:5], v[2:3], v[12:13]
	s_nop 0
	v_pk_fma_f32 v[4:5], v[6:7], v[0:1], v[4:5]
	v_pk_mul_f32 v[0:1], v[2:3], v[0:1]
	s_nop 0
	v_pk_fma_f32 v[0:1], v[6:7], v[12:13], v[0:1] neg_lo:[0,0,1] neg_hi:[0,0,1]
	ds_write_b64 v162, v[0:1] offset:65280
	ds_write_b64 v168, v[4:5] offset:65280
	v_mov_b32_e32 v0, v163
	s_waitcnt lgkmcnt(0)
	s_barrier
	s_nop 0
	s_nop 0
	v_ashrrev_i32_e32 v2, 31, v0
	v_lshrrev_b32_e32 v2, 27, v2
	v_lshlrev_b32_e32 v1, 1, v0
	v_add_u32_e32 v0, v0, v2
	v_and_b32_e32 v1, 62, v1
	v_ashrrev_i32_e32 v0, 5, v0
	v_lshl_or_b32 v2, v0, 10, v1
	v_lshlrev_b32_e32 v0, 6, v0
	v_add_lshl_u32 v58, v2, v0, 2
	v_cvt_f32_ubyte0_e32 v0, v1
	v_or_b32_e32 v1, 1, v1
	v_cvt_f32_ubyte0_e32 v1, v1
	v_mul_f32_e32 v2, 0x3a800000, v0
	v_mul_f32_e32 v3, 0x3a800000, v1
	v_sin_f32_e64 v14, -v2
	v_sin_f32_e64 v15, -v3
	v_cos_f32_e32 v0, v2
	v_cos_f32_e32 v1, v3
	v_add_u32_e32 v162, 0, v58
	v_pk_mul_f32 v[2:3], v[14:15], v[14:15]
	v_add_u32_e32 v212, 0x800, v162
	v_pk_fma_f32 v[96:97], v[0:1], v[0:1], v[2:3] neg_lo:[0,0,1] neg_hi:[0,0,1]
	v_pk_mul_f32 v[2:3], v[0:1], v[14:15]
	v_add_u32_e32 v168, s91, v58
	v_pk_add_f32 v[164:165], v[2:3], v[2:3]
	v_add_u32_e32 v213, 0x800, v168
	v_pk_mul_f32 v[2:3], v[14:15], v[164:165]
	s_nop 0
	v_pk_fma_f32 v[6:7], v[0:1], v[96:97], v[2:3] neg_lo:[0,0,1] neg_hi:[0,0,1]
	v_pk_mul_f32 v[2:3], v[14:15], v[96:97]
	s_nop 0
	v_pk_fma_f32 v[12:13], v[0:1], v[164:165], v[2:3]
	v_pk_mul_f32 v[2:3], v[164:165], v[164:165]
	s_nop 0
	v_pk_fma_f32 v[166:167], v[96:97], v[96:97], v[2:3] neg_lo:[0,0,1] neg_hi:[0,0,1]
	v_pk_mul_f32 v[2:3], v[96:97], v[164:165]
	v_pk_mul_f32 v[4:5], v[166:167], v[12:13]
	v_pk_add_f32 v[170:171], v[2:3], v[2:3]
	s_nop 0
	v_pk_mul_f32 v[10:11], v[166:167], v[170:171]
	v_pk_mul_f32 v[2:3], v[14:15], v[170:171]
	v_pk_mul_f32 v[8:9], v[170:171], v[170:171]
	v_pk_add_f32 v[10:11], v[10:11], v[10:11]
	v_pk_fma_f32 v[16:17], v[0:1], v[166:167], v[2:3] neg_lo:[0,0,1] neg_hi:[0,0,1]
	v_pk_mul_f32 v[2:3], v[14:15], v[166:167]
	v_pk_fma_f32 v[8:9], v[166:167], v[166:167], v[8:9] neg_lo:[0,0,1] neg_hi:[0,0,1]
	v_pk_mul_f32 v[56:57], v[170:171], v[10:11]
	v_pk_fma_f32 v[18:19], v[0:1], v[170:171], v[2:3]
	v_pk_mul_f32 v[2:3], v[164:165], v[170:171]
	v_pk_fma_f32 v[194:195], v[166:167], v[8:9], v[56:57] neg_lo:[0,0,1] neg_hi:[0,0,1]
	v_pk_mul_f32 v[56:57], v[170:171], v[8:9]
	v_pk_fma_f32 v[182:183], v[96:97], v[166:167], v[2:3] neg_lo:[0,0,1] neg_hi:[0,0,1]
	v_pk_mul_f32 v[2:3], v[164:165], v[166:167]
	v_pk_fma_f32 v[196:197], v[166:167], v[10:11], v[56:57]
	v_pk_mul_f32 v[56:57], v[10:11], v[18:19]
	v_pk_fma_f32 v[184:185], v[96:97], v[170:171], v[2:3]
	v_pk_fma_f32 v[198:199], v[8:9], v[16:17], v[56:57] neg_lo:[0,0,1] neg_hi:[0,0,1]
	v_pk_mul_f32 v[56:57], v[8:9], v[18:19]
	v_pk_mul_f32 v[2:3], v[170:171], v[12:13]
	v_pk_fma_f32 v[200:201], v[10:11], v[16:17], v[56:57]
	v_pk_mul_f32 v[56:57], v[10:11], v[184:185]
	v_pk_fma_f32 v[4:5], v[170:171], v[6:7], v[4:5]
	v_pk_fma_f32 v[202:203], v[8:9], v[182:183], v[56:57] neg_lo:[0,0,1] neg_hi:[0,0,1]
	v_pk_mul_f32 v[56:57], v[8:9], v[184:185]
	v_pk_fma_f32 v[2:3], v[166:167], v[6:7], v[2:3] neg_lo:[0,0,1] neg_hi:[0,0,1]
	v_pk_fma_f32 v[204:205], v[10:11], v[182:183], v[56:57]
	ds_read2_b64 v[56:59], v162 offset1:34
	ds_read2_b64 v[60:63], v168 offset1:34
	ds_read2_b64 v[64:67], v162 offset0:68 offset1:102
	ds_read2_b64 v[68:71], v168 offset0:68 offset1:102
	ds_read2_b64 v[72:75], v162 offset0:136 offset1:170
	ds_read2_b64 v[76:79], v168 offset0:136 offset1:170
	ds_read2_b64 v[80:83], v162 offset0:204 offset1:238
	ds_read2_b64 v[84:87], v168 offset0:204 offset1:238
	ds_read2_b64 v[88:91], v212 offset0:16 offset1:50
	ds_read2_b64 v[92:95], v213 offset0:16 offset1:50
	ds_read2_b64 v[130:133], v212 offset0:84 offset1:118
	ds_read2_b64 v[134:137], v213 offset0:84 offset1:118
	ds_read2_b64 v[138:141], v212 offset0:152 offset1:186
	ds_read2_b64 v[142:145], v213 offset0:152 offset1:186
	ds_read2_b64 v[174:177], v212 offset0:220 offset1:254
	ds_read2_b64 v[178:181], v213 offset0:220 offset1:254
	s_waitcnt lgkmcnt(6)
	v_pk_add_f32 v[208:209], v[60:61], v[92:93]
	v_pk_add_f32 v[60:61], v[60:61], v[92:93] neg_lo:[0,1] neg_hi:[0,1]
	v_pk_add_f32 v[92:93], v[62:63], v[94:95]
	v_pk_add_f32 v[62:63], v[62:63], v[94:95] neg_lo:[0,1] neg_hi:[0,1]
	v_pk_add_f32 v[206:207], v[56:57], v[88:89]
	v_pk_add_f32 v[56:57], v[56:57], v[88:89] neg_lo:[0,1] neg_hi:[0,1]
	v_pk_add_f32 v[88:89], v[58:59], v[90:91]
	v_pk_add_f32 v[58:59], v[58:59], v[90:91] neg_lo:[0,1] neg_hi:[0,1]
	v_pk_mul_f32 v[90:91], v[62:63], s[80:81] op_sel_hi:[1,0]
	s_waitcnt lgkmcnt(4)
	v_pk_add_f32 v[94:95], v[68:69], v[134:135]
	v_pk_fma_f32 v[90:91], v[58:59], s[72:73], v[90:91] op_sel_hi:[1,0,1]
	v_pk_mul_f32 v[58:59], v[58:59], s[80:81] op_sel_hi:[1,0]
	v_pk_add_f32 v[68:69], v[68:69], v[134:135] neg_lo:[0,1] neg_hi:[0,1]
	v_pk_fma_f32 v[58:59], v[62:63], s[72:73], v[58:59] op_sel_hi:[1,0,1] neg_lo:[0,0,1] neg_hi:[0,0,1]
	v_pk_add_f32 v[62:63], v[64:65], v[130:131]
	v_pk_add_f32 v[64:65], v[64:65], v[130:131] neg_lo:[0,1] neg_hi:[0,1]
	v_pk_add_f32 v[134:135], v[70:71], v[136:137]
	v_pk_mul_f32 v[64:65], v[64:65], s[82:83] op_sel_hi:[1,0]
	v_pk_add_f32 v[70:71], v[70:71], v[136:137] neg_lo:[0,1] neg_hi:[0,1]
	v_pk_fma_f32 v[130:131], v[68:69], s[82:83], v[64:65] op_sel_hi:[1,0,1]
	v_pk_fma_f32 v[64:65], v[68:69], s[82:83], v[64:65] op_sel_hi:[1,0,1] neg_lo:[0,0,1] neg_hi:[0,0,1]
	v_pk_add_f32 v[68:69], v[66:67], v[132:133]
	v_pk_add_f32 v[66:67], v[66:67], v[132:133] neg_lo:[0,1] neg_hi:[0,1]
	v_pk_mul_f32 v[132:133], v[70:71], s[72:73] op_sel_hi:[1,0]
	s_waitcnt lgkmcnt(2)
	v_pk_add_f32 v[136:137], v[76:77], v[142:143]
	v_pk_fma_f32 v[132:133], v[66:67], s[80:81], v[132:133] op_sel_hi:[1,0,1]
	v_pk_mul_f32 v[66:67], v[66:67], s[72:73] op_sel_hi:[1,0]
	v_pk_add_f32 v[76:77], v[76:77], v[142:143] neg_lo:[0,1] neg_hi:[0,1]
	v_pk_fma_f32 v[66:67], v[70:71], s[80:81], v[66:67] op_sel_hi:[1,0,1] neg_lo:[0,0,1] neg_hi:[0,0,1]
	v_pk_add_f32 v[70:71], v[72:73], v[138:139]
	v_pk_add_f32 v[72:73], v[72:73], v[138:139] neg_lo:[0,1] neg_hi:[0,1]
	v_pk_add_f32 v[138:139], v[74:75], v[140:141]
	v_pk_add_f32 v[74:75], v[74:75], v[140:141] neg_lo:[0,1] neg_hi:[0,1]
	v_pk_add_f32 v[142:143], v[78:79], v[144:145]
	v_pk_add_f32 v[78:79], v[78:79], v[144:145] neg_lo:[0,1] neg_hi:[0,1]
	v_pk_mul_f32 v[140:141], v[74:75], s[80:81] op_sel_hi:[1,0]
	s_waitcnt lgkmcnt(0)
	v_pk_add_f32 v[144:145], v[84:85], v[178:179]
	v_pk_fma_f32 v[140:141], v[78:79], s[72:73], v[140:141] op_sel_hi:[1,0,1] neg_lo:[0,0,1] neg_hi:[0,0,1]
	v_pk_mul_f32 v[78:79], v[78:79], s[80:81] op_sel_hi:[1,0]
	v_pk_add_f32 v[84:85], v[84:85], v[178:179] neg_lo:[0,1] neg_hi:[0,1]
	v_pk_fma_f32 v[74:75], v[74:75], s[52:53], v[78:79] op_sel_hi:[1,0,1] neg_lo:[0,0,1] neg_hi:[0,0,1]
	v_pk_add_f32 v[78:79], v[80:81], v[174:175]
	v_pk_add_f32 v[80:81], v[80:81], v[174:175] neg_lo:[0,1] neg_hi:[0,1]
	v_pk_mul_f32 v[84:85], v[84:85], s[54:55] op_sel_hi:[1,0]
	v_pk_add_f32 v[178:179], v[86:87], v[180:181]
	v_pk_fma_f32 v[174:175], v[80:81], s[54:55], v[84:85] op_sel_hi:[1,0,1] neg_lo:[0,0,1] neg_hi:[0,0,1]
	v_pk_fma_f32 v[80:81], v[80:81], s[54:55], v[84:85] op_sel_hi:[1,0,1]
	v_pk_add_f32 v[84:85], v[82:83], v[176:177]
	v_pk_add_f32 v[82:83], v[82:83], v[176:177] neg_lo:[0,1] neg_hi:[0,1]
	v_pk_add_f32 v[86:87], v[86:87], v[180:181] neg_lo:[0,1] neg_hi:[0,1]
	v_pk_mul_f32 v[176:177], v[82:83], s[72:73] op_sel_hi:[1,0]
	v_pk_add_f32 v[180:181], v[208:209], v[136:137]
	v_pk_fma_f32 v[176:177], v[86:87], s[80:81], v[176:177] op_sel_hi:[1,0,1] neg_lo:[0,0,1] neg_hi:[0,0,1]
	v_pk_mul_f32 v[86:87], v[86:87], s[72:73] op_sel_hi:[1,0]
	v_pk_add_f32 v[136:137], v[208:209], v[136:137] neg_lo:[0,1] neg_hi:[0,1]
	v_pk_fma_f32 v[82:83], v[82:83], s[84:85], v[86:87] op_sel_hi:[1,0,1] neg_lo:[0,0,1] neg_hi:[0,0,1]
	v_pk_add_f32 v[86:87], v[206:207], v[70:71]
	v_pk_add_f32 v[70:71], v[206:207], v[70:71] neg_lo:[0,1] neg_hi:[0,1]
	v_pk_add_f32 v[206:207], v[88:89], v[138:139]
	v_pk_add_f32 v[88:89], v[88:89], v[138:139] neg_lo:[0,1] neg_hi:[0,1]
	v_pk_add_f32 v[208:209], v[92:93], v[142:143]
	v_pk_add_f32 v[92:93], v[92:93], v[142:143] neg_lo:[0,1] neg_hi:[0,1]
	v_pk_mul_f32 v[88:89], v[88:89], s[82:83] op_sel_hi:[1,0]
	v_pk_add_f32 v[142:143], v[94:95], v[144:145]
	v_pk_fma_f32 v[138:139], v[92:93], s[82:83], v[88:89] op_sel_hi:[1,0,1]
	v_pk_fma_f32 v[88:89], v[92:93], s[82:83], v[88:89] op_sel_hi:[1,0,1] neg_lo:[0,0,1] neg_hi:[0,0,1]
	v_pk_add_f32 v[92:93], v[62:63], v[78:79]
	v_pk_add_f32 v[62:63], v[62:63], v[78:79] neg_lo:[0,1] neg_hi:[0,1]
	v_pk_add_f32 v[78:79], v[94:95], v[144:145] neg_lo:[0,1] neg_hi:[0,1]
	v_pk_add_f32 v[94:95], v[68:69], v[84:85]
	v_pk_add_f32 v[68:69], v[68:69], v[84:85] neg_lo:[0,1] neg_hi:[0,1]
	v_pk_add_f32 v[84:85], v[134:135], v[178:179] neg_lo:[0,1] neg_hi:[0,1]
	v_pk_add_f32 v[144:145], v[134:135], v[178:179]
	v_pk_mul_f32 v[84:85], v[84:85], s[54:55] op_sel_hi:[1,0]
	v_pk_add_f32 v[178:179], v[60:61], v[72:73] neg_lo:[0,1] neg_hi:[0,1]
	v_pk_add_f32 v[60:61], v[60:61], v[72:73]
	v_pk_add_f32 v[72:73], v[90:91], v[140:141]
	v_pk_add_f32 v[90:91], v[90:91], v[140:141] neg_lo:[0,1] neg_hi:[0,1]
	v_pk_fma_f32 v[134:135], v[68:69], s[54:55], v[84:85] op_sel_hi:[1,0,1] neg_lo:[0,0,1] neg_hi:[0,0,1]
	v_pk_fma_f32 v[68:69], v[68:69], s[54:55], v[84:85] op_sel_hi:[1,0,1]
	v_pk_add_f32 v[84:85], v[56:57], v[76:77]
	v_pk_add_f32 v[56:57], v[56:57], v[76:77] neg_lo:[0,1] neg_hi:[0,1]
	v_pk_add_f32 v[76:77], v[58:59], v[74:75]
	v_pk_add_f32 v[58:59], v[58:59], v[74:75] neg_lo:[0,1] neg_hi:[0,1]
	v_pk_mul_f32 v[74:75], v[90:91], s[82:83] op_sel_hi:[1,0]
	v_pk_add_f32 v[140:141], v[64:65], v[80:81]
	v_pk_fma_f32 v[90:91], v[58:59], s[82:83], v[74:75] op_sel_hi:[1,0,1]
	v_pk_fma_f32 v[58:59], v[58:59], s[82:83], v[74:75] op_sel_hi:[1,0,1] neg_lo:[0,0,1] neg_hi:[0,0,1]
	v_pk_add_f32 v[74:75], v[130:131], v[174:175]
	v_pk_add_f32 v[130:131], v[130:131], v[174:175] neg_lo:[0,1] neg_hi:[0,1]
	v_pk_add_f32 v[174:175], v[66:67], v[82:83]
	v_pk_add_f32 v[66:67], v[66:67], v[82:83] neg_lo:[0,1] neg_hi:[0,1]
	v_pk_add_f32 v[64:65], v[64:65], v[80:81] neg_lo:[0,1] neg_hi:[0,1]
	v_pk_add_f32 v[80:81], v[132:133], v[176:177]
	v_pk_add_f32 v[132:133], v[132:133], v[176:177] neg_lo:[0,1] neg_hi:[0,1]
	v_pk_mul_f32 v[66:67], v[66:67], s[54:55] op_sel_hi:[1,0]
	v_pk_add_f32 v[176:177], v[180:181], v[142:143]
	v_pk_fma_f32 v[82:83], v[132:133], s[54:55], v[66:67] op_sel_hi:[1,0,1] neg_lo:[0,0,1] neg_hi:[0,0,1]
	v_pk_fma_f32 v[66:67], v[132:133], s[54:55], v[66:67] op_sel_hi:[1,0,1]
	v_pk_add_f32 v[132:133], v[86:87], v[92:93]
	v_pk_add_f32 v[86:87], v[86:87], v[92:93] neg_lo:[0,1] neg_hi:[0,1]
	v_pk_add_f32 v[92:93], v[180:181], v[142:143] neg_lo:[0,1] neg_hi:[0,1]
	v_pk_add_f32 v[142:143], v[206:207], v[94:95]
	v_pk_add_f32 v[180:181], v[208:209], v[144:145]
	v_pk_add_f32 v[94:95], v[206:207], v[94:95] neg_lo:[0,1] neg_hi:[0,1]
	v_pk_add_f32 v[144:145], v[208:209], v[144:145] neg_lo:[0,1] neg_hi:[0,1]
	v_pk_add_f32 v[206:207], v[70:71], v[78:79]
	v_pk_add_f32 v[208:209], v[136:137], v[62:63] neg_lo:[0,1] neg_hi:[0,1]
	v_pk_add_f32 v[70:71], v[70:71], v[78:79] neg_lo:[0,1] neg_hi:[0,1]
	v_pk_add_f32 v[62:63], v[136:137], v[62:63]
	v_pk_add_f32 v[78:79], v[138:139], v[134:135]
	v_pk_add_f32 v[136:137], v[88:89], v[68:69]
	v_pk_add_f32 v[134:135], v[138:139], v[134:135] neg_lo:[0,1] neg_hi:[0,1]
	v_pk_add_f32 v[68:69], v[88:89], v[68:69] neg_lo:[0,1] neg_hi:[0,1]
	v_pk_add_f32 v[88:89], v[84:85], v[74:75]
	v_pk_add_f32 v[138:139], v[178:179], v[140:141]
	v_pk_add_f32 v[74:75], v[84:85], v[74:75] neg_lo:[0,1] neg_hi:[0,1]
	v_pk_add_f32 v[84:85], v[178:179], v[140:141] neg_lo:[0,1] neg_hi:[0,1]
	v_pk_add_f32 v[178:179], v[76:77], v[174:175]
	v_pk_add_f32 v[76:77], v[76:77], v[174:175] neg_lo:[0,1] neg_hi:[0,1]
	v_pk_add_f32 v[174:175], v[60:61], v[130:131] neg_lo:[0,1] neg_hi:[0,1]
	v_pk_add_f32 v[60:61], v[60:61], v[130:131]
	v_pk_add_f32 v[130:131], v[58:59], v[66:67]
	v_pk_add_f32 v[58:59], v[58:59], v[66:67] neg_lo:[0,1] neg_hi:[0,1]
	v_pk_add_f32 v[66:67], v[132:133], v[142:143]
	v_pk_add_f32 v[132:133], v[132:133], v[142:143] neg_lo:[0,1] neg_hi:[0,1]
	v_pk_add_f32 v[142:143], v[176:177], v[180:181] neg_lo:[0,1] neg_hi:[0,1]
	v_pk_add_f32 v[140:141], v[72:73], v[80:81]
	v_pk_add_f32 v[72:73], v[72:73], v[80:81] neg_lo:[0,1] neg_hi:[0,1]
	v_pk_add_f32 v[80:81], v[56:57], v[64:65]
	v_pk_add_f32 v[56:57], v[56:57], v[64:65] neg_lo:[0,1] neg_hi:[0,1]
	v_pk_add_f32 v[64:65], v[90:91], v[82:83]
	v_pk_add_f32 v[82:83], v[90:91], v[82:83] neg_lo:[0,1] neg_hi:[0,1]
	v_pk_add_f32 v[90:91], v[176:177], v[180:181]
	v_pk_add_f32 v[176:177], v[86:87], v[144:145]
	v_pk_add_f32 v[180:181], v[92:93], v[94:95] neg_lo:[0,1] neg_hi:[0,1]
	v_pk_mul_f32 v[210:211], v[8:9], v[142:143]
	v_pk_mul_f32 v[142:143], v[10:11], v[142:143]
	v_pk_add_f32 v[86:87], v[86:87], v[144:145] neg_lo:[0,1] neg_hi:[0,1]
	v_pk_fma_f32 v[210:211], v[10:11], v[132:133], v[210:211]
	v_pk_fma_f32 v[132:133], v[8:9], v[132:133], v[142:143] neg_lo:[0,0,1] neg_hi:[0,0,1]
	v_pk_mul_f32 v[142:143], v[170:171], v[176:177]
	v_pk_mul_f32 v[170:171], v[170:171], v[180:181]
	v_pk_mul_f32 v[20:21], v[14:15], v[10:11]
	v_pk_add_f32 v[92:93], v[92:93], v[94:95]
	v_pk_fma_f32 v[142:143], v[166:167], v[180:181], v[142:143]
	v_pk_fma_f32 v[166:167], v[166:167], v[176:177], v[170:171] neg_lo:[0,0,1] neg_hi:[0,0,1]
	v_pk_mul_f32 v[170:171], v[196:197], v[86:87]
	v_pk_fma_f32 v[186:187], v[0:1], v[8:9], v[20:21] neg_lo:[0,0,1] neg_hi:[0,0,1]
	v_pk_mul_f32 v[20:21], v[14:15], v[8:9]
	v_pk_add_f32 v[94:95], v[206:207], v[78:79]
	v_pk_fma_f32 v[170:171], v[194:195], v[92:93], v[170:171]
	v_pk_mul_f32 v[92:93], v[196:197], v[92:93]
	v_pk_fma_f32 v[188:189], v[0:1], v[10:11], v[20:21]
	v_pk_mul_f32 v[20:21], v[164:165], v[10:11]
	v_pk_add_f32 v[144:145], v[208:209], v[136:137]
	v_pk_add_f32 v[78:79], v[206:207], v[78:79] neg_lo:[0,1] neg_hi:[0,1]
	v_pk_add_f32 v[206:207], v[70:71], v[68:69]
	v_pk_add_f32 v[68:69], v[70:71], v[68:69] neg_lo:[0,1] neg_hi:[0,1]
	v_pk_fma_f32 v[86:87], v[194:195], v[86:87], v[92:93] neg_lo:[0,0,1] neg_hi:[0,0,1]
	v_pk_mul_f32 v[92:93], v[164:165], v[94:95]
	v_pk_fma_f32 v[190:191], v[96:97], v[8:9], v[20:21] neg_lo:[0,0,1] neg_hi:[0,0,1]
	v_pk_mul_f32 v[20:21], v[164:165], v[8:9]
	v_pk_add_f32 v[136:137], v[208:209], v[136:137] neg_lo:[0,1] neg_hi:[0,1]
	v_pk_add_f32 v[208:209], v[62:63], v[134:135] neg_lo:[0,1] neg_hi:[0,1]
	v_pk_add_f32 v[62:63], v[62:63], v[134:135]
	v_pk_fma_f32 v[92:93], v[96:97], v[144:145], v[92:93]
	v_pk_mul_f32 v[144:145], v[164:165], v[144:145]
	v_pk_mul_f32 v[164:165], v[204:205], v[68:69]
	v_pk_add_f32 v[70:71], v[88:89], v[140:141]
	v_pk_add_f32 v[134:135], v[138:139], v[178:179]
	v_pk_fma_f32 v[164:165], v[202:203], v[62:63], v[164:165]
	v_pk_mul_f32 v[62:63], v[204:205], v[62:63]
	v_pk_add_f32 v[88:89], v[88:89], v[140:141] neg_lo:[0,1] neg_hi:[0,1]
	v_pk_fma_f32 v[62:63], v[202:203], v[68:69], v[62:63] neg_lo:[0,0,1] neg_hi:[0,0,1]
	v_pk_mul_f32 v[68:69], v[14:15], v[70:71]
	v_pk_mul_f32 v[14:15], v[14:15], v[134:135]
	v_pk_add_f32 v[138:139], v[138:139], v[178:179] neg_lo:[0,1] neg_hi:[0,1]
	v_pk_fma_f32 v[68:69], v[0:1], v[134:135], v[68:69]
	v_pk_fma_f32 v[0:1], v[0:1], v[70:71], v[14:15] neg_lo:[0,0,1] neg_hi:[0,0,1]
	ds_write2_b64 v162, v[66:67], v[0:1] offset1:34
	ds_write2_b64 v168, v[90:91], v[68:69] offset1:34
	v_pk_mul_f32 v[0:1], v[188:189], v[88:89]
	v_pk_mul_f32 v[14:15], v[188:189], v[138:139]
	v_pk_add_f32 v[140:141], v[74:75], v[76:77]
	v_pk_add_f32 v[178:179], v[84:85], v[72:73] neg_lo:[0,1] neg_hi:[0,1]
	v_pk_fma_f32 v[0:1], v[186:187], v[138:139], v[0:1]
	v_pk_fma_f32 v[14:15], v[186:187], v[88:89], v[14:15] neg_lo:[0,0,1] neg_hi:[0,0,1]
	ds_write2_b64 v212, v[132:133], v[14:15] offset0:16 offset1:50
	ds_write2_b64 v213, v[210:211], v[0:1] offset0:16 offset1:50
	v_pk_mul_f32 v[0:1], v[18:19], v[140:141]
	v_pk_mul_f32 v[14:15], v[18:19], v[178:179]
	v_pk_add_f32 v[74:75], v[74:75], v[76:77] neg_lo:[0,1] neg_hi:[0,1]
	v_pk_add_f32 v[72:73], v[84:85], v[72:73]
	v_pk_fma_f32 v[0:1], v[16:17], v[178:179], v[0:1]
	v_pk_fma_f32 v[14:15], v[16:17], v[140:141], v[14:15] neg_lo:[0,0,1] neg_hi:[0,0,1]
	ds_write2_b64 v162, v[166:167], v[14:15] offset0:136 offset1:170
	ds_write2_b64 v168, v[142:143], v[0:1] offset0:136 offset1:170
	v_pk_mul_f32 v[0:1], v[200:201], v[74:75]
	v_pk_mul_f32 v[14:15], v[200:201], v[72:73]
	v_pk_add_f32 v[76:77], v[80:81], v[64:65]
	v_pk_add_f32 v[84:85], v[174:175], v[130:131]
	v_pk_fma_f32 v[0:1], v[198:199], v[72:73], v[0:1]
	v_pk_fma_f32 v[14:15], v[198:199], v[74:75], v[14:15] neg_lo:[0,0,1] neg_hi:[0,0,1]
	v_pk_fma_f32 v[192:193], v[96:97], v[10:11], v[20:21]
	v_pk_mul_f32 v[20:21], v[12:13], v[10:11]
	v_pk_mul_f32 v[22:23], v[12:13], v[8:9]
	ds_write2_b64 v212, v[86:87], v[14:15] offset0:152 offset1:186
	ds_write2_b64 v213, v[170:171], v[0:1] offset0:152 offset1:186
	v_pk_mul_f32 v[0:1], v[12:13], v[76:77]
	v_pk_mul_f32 v[12:13], v[12:13], v[84:85]
	v_pk_fma_f32 v[20:21], v[6:7], v[8:9], v[20:21] neg_lo:[0,0,1] neg_hi:[0,0,1]
	v_pk_fma_f32 v[22:23], v[6:7], v[10:11], v[22:23]
	v_pk_add_f32 v[64:65], v[80:81], v[64:65] neg_lo:[0,1] neg_hi:[0,1]
	v_pk_add_f32 v[80:81], v[174:175], v[130:131] neg_lo:[0,1] neg_hi:[0,1]
	v_pk_fma_f32 v[94:95], v[96:97], v[94:95], v[144:145] neg_lo:[0,0,1] neg_hi:[0,0,1]
	v_pk_mul_f32 v[96:97], v[192:193], v[78:79]
	v_pk_fma_f32 v[0:1], v[6:7], v[84:85], v[0:1]
	v_pk_fma_f32 v[6:7], v[6:7], v[76:77], v[12:13] neg_lo:[0,0,1] neg_hi:[0,0,1]
	v_pk_fma_f32 v[96:97], v[190:191], v[136:137], v[96:97]
	v_pk_mul_f32 v[136:137], v[192:193], v[136:137]
	ds_write2_b64 v162, v[94:95], v[6:7] offset0:68 offset1:102
	ds_write2_b64 v168, v[92:93], v[0:1] offset0:68 offset1:102
	v_pk_mul_f32 v[6:7], v[22:23], v[80:81]
	v_pk_add_f32 v[174:175], v[60:61], v[82:83] neg_lo:[0,1] neg_hi:[0,1]
	v_pk_fma_f32 v[78:79], v[190:191], v[78:79], v[136:137] neg_lo:[0,0,1] neg_hi:[0,0,1]
	v_pk_mul_f32 v[0:1], v[22:23], v[64:65]
	v_pk_fma_f32 v[6:7], v[20:21], v[64:65], v[6:7] neg_lo:[0,0,1] neg_hi:[0,0,1]
	v_pk_add_f32 v[130:131], v[56:57], v[58:59]
	v_pk_mul_f32 v[144:145], v[184:185], v[208:209]
	v_pk_fma_f32 v[0:1], v[20:21], v[80:81], v[0:1]
	ds_write2_b64 v212, v[78:79], v[6:7] offset0:84 offset1:118
	ds_write2_b64 v213, v[96:97], v[0:1] offset0:84 offset1:118
	v_pk_mul_f32 v[6:7], v[4:5], v[174:175]
	v_pk_mul_f32 v[136:137], v[184:185], v[206:207]
	v_pk_fma_f32 v[144:145], v[182:183], v[206:207], v[144:145] neg_lo:[0,0,1] neg_hi:[0,0,1]
	v_pk_mul_f32 v[0:1], v[4:5], v[130:131]
	v_pk_fma_f32 v[6:7], v[2:3], v[130:131], v[6:7] neg_lo:[0,0,1] neg_hi:[0,0,1]
	v_pk_fma_f32 v[136:137], v[182:183], v[208:209], v[136:137]
	v_pk_fma_f32 v[0:1], v[2:3], v[174:175], v[0:1]
	ds_write2_b64 v162, v[144:145], v[6:7] offset0:204 offset1:238
	ds_write2_b64 v168, v[136:137], v[0:1] offset0:204 offset1:238
	v_pk_mul_f32 v[6:7], v[10:11], v[4:5]
	v_pk_mul_f32 v[4:5], v[8:9], v[4:5]
	v_pk_fma_f32 v[6:7], v[8:9], v[2:3], v[6:7] neg_lo:[0,0,1] neg_hi:[0,0,1]
	v_pk_add_f32 v[12:13], v[56:57], v[58:59] neg_lo:[0,1] neg_hi:[0,1]
	v_pk_fma_f32 v[2:3], v[10:11], v[2:3], v[4:5]
	v_pk_add_f32 v[0:1], v[60:61], v[82:83]
	v_pk_mul_f32 v[4:5], v[2:3], v[12:13]
	s_nop 0
	v_pk_fma_f32 v[4:5], v[6:7], v[0:1], v[4:5]
	v_pk_mul_f32 v[0:1], v[2:3], v[0:1]
	s_nop 0
	v_pk_fma_f32 v[0:1], v[6:7], v[12:13], v[0:1] neg_lo:[0,0,1] neg_hi:[0,0,1]
	ds_write2_b64 v212, v[62:63], v[0:1] offset0:220 offset1:254
	ds_write2_b64 v213, v[164:165], v[4:5] offset0:220 offset1:254
	v_mov_b32_e32 v0, v163
	s_waitcnt lgkmcnt(0)
	s_barrier
	v_lshlrev_b32_e32 v219, 5, v163
	global_load_dwordx4 v[220:223], v219, s[94:95] offset:16
	global_load_dwordx4 v[224:227], v219, s[94:95]
	global_load_dwordx4 v[228:231], v219, s[30:31] offset:16
	global_load_dwordx4 v[232:235], v219, s[30:31]
	s_nop 0
	s_nop 0
	v_lshlrev_b32_e32 v1, 1, v0
	v_and_b32_e32 v162, 2, v1
	v_lshrrev_b32_e32 v1, 31, v0
	v_add_u32_e32 v0, v0, v1
	v_ashrrev_i32_e32 v168, 1, v0
	v_lshl_or_b32 v0, v168, 6, v162
	v_lshlrev_b32_e32 v1, 2, v168
	v_add_lshl_u32 v74, v0, v1, 2
	v_add_u32_e32 v190, 0, v74
	v_add_u32_e32 v218, s91, v74
	ds_read2_b64 v[74:77], v190 offset1:2
	ds_read2_b64 v[78:81], v190 offset0:4 offset1:6
	ds_read2_b64 v[82:85], v218 offset1:2
	ds_read2_b64 v[86:89], v218 offset0:4 offset1:6
	ds_read2_b64 v[90:93], v190 offset0:8 offset1:10
	ds_read2_b64 v[94:97], v218 offset0:8 offset1:10
	ds_read2_b64 v[130:133], v190 offset0:12 offset1:14
	ds_read2_b64 v[134:137], v218 offset0:12 offset1:14
	ds_read2_b64 v[138:141], v190 offset0:16 offset1:18
	ds_read2_b64 v[142:145], v218 offset0:16 offset1:18
	ds_read2_b64 v[174:177], v190 offset0:20 offset1:22
	ds_read2_b64 v[178:181], v218 offset0:20 offset1:22
	ds_read2_b64 v[182:185], v190 offset0:24 offset1:26
	ds_read2_b64 v[186:189], v218 offset0:24 offset1:26
	ds_read2_b64 v[190:193], v190 offset0:28 offset1:30
	ds_read2_b64 v[194:197], v218 offset0:28 offset1:30
	s_waitcnt lgkmcnt(6)
	v_pk_add_f32 v[204:205], v[82:83], v[142:143]
	v_pk_add_f32 v[82:83], v[82:83], v[142:143] neg_lo:[0,1] neg_hi:[0,1]
	v_pk_add_f32 v[142:143], v[84:85], v[144:145]
	v_pk_add_f32 v[84:85], v[84:85], v[144:145] neg_lo:[0,1] neg_hi:[0,1]
	v_pk_add_f32 v[202:203], v[74:75], v[138:139]
	v_pk_add_f32 v[74:75], v[74:75], v[138:139] neg_lo:[0,1] neg_hi:[0,1]
	v_pk_add_f32 v[138:139], v[76:77], v[140:141]
	v_pk_add_f32 v[76:77], v[76:77], v[140:141] neg_lo:[0,1] neg_hi:[0,1]
	v_pk_mul_f32 v[140:141], v[84:85], s[80:81] op_sel_hi:[1,0]
	s_waitcnt lgkmcnt(4)
	v_pk_add_f32 v[144:145], v[86:87], v[178:179]
	v_pk_fma_f32 v[140:141], v[76:77], s[72:73], v[140:141] op_sel_hi:[1,0,1]
	v_pk_mul_f32 v[76:77], v[76:77], s[80:81] op_sel_hi:[1,0]
	v_pk_add_f32 v[86:87], v[86:87], v[178:179] neg_lo:[0,1] neg_hi:[0,1]
	v_pk_fma_f32 v[76:77], v[84:85], s[72:73], v[76:77] op_sel_hi:[1,0,1] neg_lo:[0,0,1] neg_hi:[0,0,1]
	v_pk_add_f32 v[84:85], v[78:79], v[174:175]
	v_pk_add_f32 v[78:79], v[78:79], v[174:175] neg_lo:[0,1] neg_hi:[0,1]
	v_pk_add_f32 v[178:179], v[88:89], v[180:181]
	v_pk_mul_f32 v[78:79], v[78:79], s[82:83] op_sel_hi:[1,0]
	v_pk_add_f32 v[88:89], v[88:89], v[180:181] neg_lo:[0,1] neg_hi:[0,1]
	v_pk_fma_f32 v[174:175], v[86:87], s[82:83], v[78:79] op_sel_hi:[1,0,1]
	v_pk_fma_f32 v[78:79], v[86:87], s[82:83], v[78:79] op_sel_hi:[1,0,1] neg_lo:[0,0,1] neg_hi:[0,0,1]
	v_pk_add_f32 v[86:87], v[80:81], v[176:177]
	v_pk_add_f32 v[80:81], v[80:81], v[176:177] neg_lo:[0,1] neg_hi:[0,1]
	v_pk_mul_f32 v[176:177], v[88:89], s[72:73] op_sel_hi:[1,0]
	v_or_b32_e32 v1, 1, v162
	v_pk_fma_f32 v[176:177], v[80:81], s[80:81], v[176:177] op_sel_hi:[1,0,1]
	v_pk_mul_f32 v[80:81], v[80:81], s[72:73] op_sel_hi:[1,0]
	v_cvt_f32_ubyte0_e32 v0, v162
	v_cvt_f32_ubyte0_e32 v1, v1
	v_pk_fma_f32 v[80:81], v[88:89], s[80:81], v[80:81] op_sel_hi:[1,0,1] neg_lo:[0,0,1] neg_hi:[0,0,1]
	s_waitcnt lgkmcnt(3)
	v_pk_add_f32 v[88:89], v[90:91], v[182:183]
	v_pk_add_f32 v[90:91], v[90:91], v[182:183] neg_lo:[0,1] neg_hi:[0,1]
	v_pk_add_f32 v[182:183], v[92:93], v[184:185]
	v_pk_add_f32 v[92:93], v[92:93], v[184:185] neg_lo:[0,1] neg_hi:[0,1]
	v_mul_f32_e32 v0, 0x3c800000, v0
	v_mul_f32_e32 v1, 0x3c800000, v1
	s_waitcnt lgkmcnt(2)
	v_pk_add_f32 v[180:181], v[94:95], v[186:187]
	v_pk_add_f32 v[94:95], v[94:95], v[186:187] neg_lo:[0,1] neg_hi:[0,1]
	v_pk_add_f32 v[186:187], v[96:97], v[188:189]
	v_pk_add_f32 v[96:97], v[96:97], v[188:189] neg_lo:[0,1] neg_hi:[0,1]
	v_pk_mul_f32 v[184:185], v[92:93], s[80:81] op_sel_hi:[1,0]
	v_sin_f32_e64 v164, -v0
	v_sin_f32_e64 v165, -v1
	v_pk_fma_f32 v[184:185], v[96:97], s[72:73], v[184:185] op_sel_hi:[1,0,1] neg_lo:[0,0,1] neg_hi:[0,0,1]
	v_pk_mul_f32 v[96:97], v[96:97], s[80:81] op_sel_hi:[1,0]
	s_waitcnt lgkmcnt(0)
	v_pk_add_f32 v[188:189], v[134:135], v[194:195]
	v_pk_add_f32 v[134:135], v[134:135], v[194:195] neg_lo:[0,1] neg_hi:[0,1]
	v_cos_f32_e32 v72, v0
	v_cos_f32_e32 v73, v1
	v_pk_fma_f32 v[92:93], v[92:93], s[52:53], v[96:97] op_sel_hi:[1,0,1] neg_lo:[0,0,1] neg_hi:[0,0,1]
	v_pk_add_f32 v[96:97], v[130:131], v[190:191]
	v_pk_add_f32 v[130:131], v[130:131], v[190:191] neg_lo:[0,1] neg_hi:[0,1]
	v_pk_mul_f32 v[134:135], v[134:135], s[54:55] op_sel_hi:[1,0]
	v_pk_add_f32 v[194:195], v[136:137], v[196:197]
	v_pk_fma_f32 v[190:191], v[130:131], s[54:55], v[134:135] op_sel_hi:[1,0,1] neg_lo:[0,0,1] neg_hi:[0,0,1]
	v_pk_fma_f32 v[130:131], v[130:131], s[54:55], v[134:135] op_sel_hi:[1,0,1]
	v_pk_add_f32 v[134:135], v[132:133], v[192:193]
	v_pk_add_f32 v[132:133], v[132:133], v[192:193] neg_lo:[0,1] neg_hi:[0,1]
	v_pk_add_f32 v[136:137], v[136:137], v[196:197] neg_lo:[0,1] neg_hi:[0,1]
	v_pk_mul_f32 v[192:193], v[132:133], s[72:73] op_sel_hi:[1,0]
	v_pk_mul_f32 v[0:1], v[164:165], v[164:165]
	v_pk_fma_f32 v[192:193], v[136:137], s[80:81], v[192:193] op_sel_hi:[1,0,1] neg_lo:[0,0,1] neg_hi:[0,0,1]
	v_pk_mul_f32 v[136:137], v[136:137], s[72:73] op_sel_hi:[1,0]
	v_pk_fma_f32 v[166:167], v[72:73], v[72:73], v[0:1] neg_lo:[0,0,1] neg_hi:[0,0,1]
	v_pk_mul_f32 v[0:1], v[72:73], v[164:165]
	v_pk_fma_f32 v[132:133], v[132:133], s[84:85], v[136:137] op_sel_hi:[1,0,1] neg_lo:[0,0,1] neg_hi:[0,0,1]
	v_pk_add_f32 v[136:137], v[202:203], v[88:89]
	v_pk_add_f32 v[88:89], v[202:203], v[88:89] neg_lo:[0,1] neg_hi:[0,1]
	v_pk_add_f32 v[202:203], v[138:139], v[182:183]
	v_pk_add_f32 v[138:139], v[138:139], v[182:183] neg_lo:[0,1] neg_hi:[0,1]
	v_pk_add_f32 v[170:171], v[0:1], v[0:1]
	v_pk_add_f32 v[196:197], v[204:205], v[180:181]
	v_pk_add_f32 v[180:181], v[204:205], v[180:181] neg_lo:[0,1] neg_hi:[0,1]
	v_pk_add_f32 v[204:205], v[142:143], v[186:187]
	v_pk_add_f32 v[142:143], v[142:143], v[186:187] neg_lo:[0,1] neg_hi:[0,1]
	v_pk_mul_f32 v[138:139], v[138:139], s[82:83] op_sel_hi:[1,0]
	v_pk_mul_f32 v[0:1], v[164:165], v[170:171]
	v_pk_fma_f32 v[182:183], v[142:143], s[82:83], v[138:139] op_sel_hi:[1,0,1]
	v_pk_fma_f32 v[138:139], v[142:143], s[82:83], v[138:139] op_sel_hi:[1,0,1] neg_lo:[0,0,1] neg_hi:[0,0,1]
	v_pk_add_f32 v[142:143], v[84:85], v[96:97]
	v_pk_add_f32 v[186:187], v[144:145], v[188:189]
	v_pk_add_f32 v[84:85], v[84:85], v[96:97] neg_lo:[0,1] neg_hi:[0,1]
	v_pk_add_f32 v[96:97], v[144:145], v[188:189] neg_lo:[0,1] neg_hi:[0,1]
	v_pk_add_f32 v[144:145], v[86:87], v[134:135]
	v_pk_add_f32 v[86:87], v[86:87], v[134:135] neg_lo:[0,1] neg_hi:[0,1]
	v_pk_add_f32 v[134:135], v[178:179], v[194:195] neg_lo:[0,1] neg_hi:[0,1]
	v_pk_fma_f32 v[198:199], v[72:73], v[166:167], v[0:1] neg_lo:[0,0,1] neg_hi:[0,0,1]
	v_pk_mul_f32 v[0:1], v[164:165], v[166:167]
	v_pk_add_f32 v[188:189], v[178:179], v[194:195]
	v_pk_mul_f32 v[134:135], v[134:135], s[54:55] op_sel_hi:[1,0]
	v_pk_add_f32 v[194:195], v[82:83], v[90:91] neg_lo:[0,1] neg_hi:[0,1]
	v_pk_add_f32 v[82:83], v[82:83], v[90:91]
	v_pk_add_f32 v[90:91], v[140:141], v[184:185]
	v_pk_add_f32 v[140:141], v[140:141], v[184:185] neg_lo:[0,1] neg_hi:[0,1]
	v_pk_fma_f32 v[200:201], v[72:73], v[170:171], v[0:1]
	v_pk_mul_f32 v[0:1], v[170:171], v[170:171]
	v_pk_fma_f32 v[178:179], v[86:87], s[54:55], v[134:135] op_sel_hi:[1,0,1] neg_lo:[0,0,1] neg_hi:[0,0,1]
	v_pk_fma_f32 v[86:87], v[86:87], s[54:55], v[134:135] op_sel_hi:[1,0,1]
	v_pk_add_f32 v[134:135], v[74:75], v[94:95]
	v_pk_add_f32 v[74:75], v[74:75], v[94:95] neg_lo:[0,1] neg_hi:[0,1]
	v_pk_add_f32 v[94:95], v[76:77], v[92:93]
	v_pk_add_f32 v[76:77], v[76:77], v[92:93] neg_lo:[0,1] neg_hi:[0,1]
	v_pk_mul_f32 v[92:93], v[140:141], s[82:83] op_sel_hi:[1,0]
	v_pk_fma_f32 v[64:65], v[166:167], v[166:167], v[0:1] neg_lo:[0,0,1] neg_hi:[0,0,1]
	v_pk_mul_f32 v[0:1], v[166:167], v[170:171]
	v_pk_fma_f32 v[140:141], v[76:77], s[82:83], v[92:93] op_sel_hi:[1,0,1]
	v_pk_fma_f32 v[76:77], v[76:77], s[82:83], v[92:93] op_sel_hi:[1,0,1] neg_lo:[0,0,1] neg_hi:[0,0,1]
	v_pk_add_f32 v[92:93], v[174:175], v[190:191]
	v_pk_add_f32 v[174:175], v[174:175], v[190:191] neg_lo:[0,1] neg_hi:[0,1]
	v_pk_add_f32 v[190:191], v[80:81], v[132:133]
	v_pk_add_f32 v[80:81], v[80:81], v[132:133] neg_lo:[0,1] neg_hi:[0,1]
	v_pk_add_f32 v[68:69], v[0:1], v[0:1]
	v_pk_add_f32 v[184:185], v[78:79], v[130:131]
	v_pk_add_f32 v[78:79], v[78:79], v[130:131] neg_lo:[0,1] neg_hi:[0,1]
	v_pk_add_f32 v[130:131], v[176:177], v[192:193]
	v_pk_add_f32 v[176:177], v[176:177], v[192:193] neg_lo:[0,1] neg_hi:[0,1]
	v_pk_mul_f32 v[80:81], v[80:81], s[54:55] op_sel_hi:[1,0]
	v_pk_mul_f32 v[8:9], v[64:65], v[68:69]
	v_pk_fma_f32 v[132:133], v[176:177], s[54:55], v[80:81] op_sel_hi:[1,0,1] neg_lo:[0,0,1] neg_hi:[0,0,1]
	v_pk_fma_f32 v[80:81], v[176:177], s[54:55], v[80:81] op_sel_hi:[1,0,1]
	v_pk_add_f32 v[176:177], v[136:137], v[142:143]
	v_pk_add_f32 v[192:193], v[196:197], v[186:187]
	v_pk_add_f32 v[136:137], v[136:137], v[142:143] neg_lo:[0,1] neg_hi:[0,1]
	v_pk_add_f32 v[142:143], v[196:197], v[186:187] neg_lo:[0,1] neg_hi:[0,1]
	v_pk_add_f32 v[186:187], v[202:203], v[144:145]
	v_pk_add_f32 v[196:197], v[204:205], v[188:189]
	v_pk_add_f32 v[144:145], v[202:203], v[144:145] neg_lo:[0,1] neg_hi:[0,1]
	v_pk_add_f32 v[188:189], v[204:205], v[188:189] neg_lo:[0,1] neg_hi:[0,1]
	v_pk_add_f32 v[202:203], v[88:89], v[96:97]
	v_pk_add_f32 v[204:205], v[180:181], v[84:85] neg_lo:[0,1] neg_hi:[0,1]
	v_pk_add_f32 v[88:89], v[88:89], v[96:97] neg_lo:[0,1] neg_hi:[0,1]
	v_pk_add_f32 v[84:85], v[180:181], v[84:85]
	v_pk_add_f32 v[96:97], v[182:183], v[178:179]
	v_pk_add_f32 v[180:181], v[138:139], v[86:87]
	v_pk_add_f32 v[178:179], v[182:183], v[178:179] neg_lo:[0,1] neg_hi:[0,1]
	v_pk_add_f32 v[86:87], v[138:139], v[86:87] neg_lo:[0,1] neg_hi:[0,1]
	v_pk_add_f32 v[138:139], v[134:135], v[92:93]
	v_pk_add_f32 v[182:183], v[194:195], v[184:185]
	v_pk_add_f32 v[92:93], v[134:135], v[92:93] neg_lo:[0,1] neg_hi:[0,1]
	v_pk_add_f32 v[134:135], v[194:195], v[184:185] neg_lo:[0,1] neg_hi:[0,1]
	v_pk_add_f32 v[194:195], v[94:95], v[190:191]
	v_pk_mul_f32 v[4:5], v[68:69], v[68:69]
	v_pk_add_f32 v[8:9], v[8:9], v[8:9]
	v_mul_lo_u32 v168, v168, s49
	v_pk_add_f32 v[184:185], v[90:91], v[130:131]
	v_pk_add_f32 v[212:213], v[182:183], v[194:195] neg_lo:[0,1] neg_hi:[0,1]
	v_pk_add_f32 v[182:183], v[182:183], v[194:195]
	v_pk_mul_f32 v[0:1], v[164:165], v[68:69]
	v_pk_fma_f32 v[4:5], v[64:65], v[64:65], v[4:5] neg_lo:[0,0,1] neg_hi:[0,0,1]
	v_pk_mul_f32 v[12:13], v[164:165], v[8:9]
	v_pk_add_f32 v[90:91], v[90:91], v[130:131] neg_lo:[0,1] neg_hi:[0,1]
	v_pk_add_f32 v[94:95], v[94:95], v[190:191] neg_lo:[0,1] neg_hi:[0,1]
	v_pk_add_f32 v[130:131], v[74:75], v[78:79]
	v_pk_add_f32 v[190:191], v[82:83], v[174:175] neg_lo:[0,1] neg_hi:[0,1]
	v_pk_add_f32 v[74:75], v[74:75], v[78:79] neg_lo:[0,1] neg_hi:[0,1]
	v_pk_add_f32 v[78:79], v[82:83], v[174:175]
	v_pk_add_f32 v[174:175], v[76:77], v[80:81]
	v_pk_add_f32 v[76:77], v[76:77], v[80:81] neg_lo:[0,1] neg_hi:[0,1]
	v_pk_add_f32 v[80:81], v[176:177], v[186:187] neg_lo:[0,1] neg_hi:[0,1]
	v_pk_add_f32 v[210:211], v[138:139], v[184:185] neg_lo:[0,1] neg_hi:[0,1]
	v_or_b32_e32 v162, v168, v162
	v_pk_add_f32 v[138:139], v[138:139], v[184:185]
	v_pk_add_f32 v[176:177], v[176:177], v[186:187]
	v_pk_mul_f32 v[186:187], v[164:165], v[182:183]
	v_pk_fma_f32 v[66:67], v[72:73], v[64:65], v[0:1] neg_lo:[0,0,1] neg_hi:[0,0,1]
	v_pk_mul_f32 v[0:1], v[164:165], v[64:65]
	v_pk_fma_f32 v[60:61], v[72:73], v[4:5], v[12:13] neg_lo:[0,0,1] neg_hi:[0,0,1]
	v_pk_mul_f32 v[12:13], v[164:165], v[4:5]
	v_pk_fma_f32 v[186:187], v[72:73], v[138:139], v[186:187] neg_lo:[0,0,1] neg_hi:[0,0,1]
	v_pk_mul_f32 v[138:139], v[164:165], v[138:139]
	v_lshlrev_b32_e32 v162, 2, v162
	v_pk_fma_f32 v[70:71], v[72:73], v[68:69], v[0:1]
	v_pk_fma_f32 v[62:63], v[72:73], v[8:9], v[12:13]
	v_pk_add_f32 v[184:185], v[192:193], v[196:197]
	v_pk_fma_f32 v[72:73], v[72:73], v[182:183], v[138:139]
	v_mov_b32_e32 v138, v176
	v_mov_b32_e32 v139, v186
	v_add_u32_e32 v164, 0, v162
	v_mov_b32_e32 v186, v177
	v_pk_add_f32 v[206:207], v[136:137], v[188:189]
	v_pk_add_f32 v[136:137], v[136:137], v[188:189] neg_lo:[0,1] neg_hi:[0,1]
	v_pk_add_f32 v[188:189], v[204:205], v[180:181]
	ds_write2_b64 v164, v[138:139], v[186:187] offset1:2
	v_mov_b32_e32 v138, v184
	v_mov_b32_e32 v139, v72
	v_add_u32_e32 v162, s91, v162
	v_mov_b32_e32 v72, v185
	v_pk_mul_f32 v[12:13], v[170:171], v[8:9]
	v_pk_add_f32 v[82:83], v[140:141], v[132:133]
	v_pk_add_f32 v[208:209], v[142:143], v[144:145] neg_lo:[0,1] neg_hi:[0,1]
	v_pk_add_f32 v[142:143], v[142:143], v[144:145]
	v_pk_add_f32 v[144:145], v[202:203], v[96:97]
	v_pk_add_f32 v[216:217], v[134:135], v[90:91] neg_lo:[0,1] neg_hi:[0,1]
	v_pk_add_f32 v[90:91], v[134:135], v[90:91]
	v_pk_add_f32 v[134:135], v[190:191], v[174:175]
	ds_write2_b64 v162, v[138:139], v[72:73] offset1:2
	v_pk_mul_f32 v[138:139], v[170:171], v[188:189]
	v_pk_fma_f32 v[20:21], v[166:167], v[4:5], v[12:13] neg_lo:[0,0,1] neg_hi:[0,0,1]
	v_pk_mul_f32 v[12:13], v[170:171], v[4:5]
	v_pk_add_f32 v[214:215], v[92:93], v[94:95]
	v_pk_add_f32 v[92:93], v[92:93], v[94:95] neg_lo:[0,1] neg_hi:[0,1]
	v_pk_add_f32 v[94:95], v[130:131], v[82:83]
	v_pk_mul_f32 v[72:73], v[170:171], v[144:145]
	v_pk_fma_f32 v[138:139], v[166:167], v[144:145], v[138:139] neg_lo:[0,0,1] neg_hi:[0,0,1]
	v_pk_mul_f32 v[144:145], v[200:201], v[134:135]
	v_pk_mul_f32 v[0:1], v[170:171], v[68:69]
	v_pk_fma_f32 v[56:57], v[166:167], v[8:9], v[12:13]
	v_pk_mul_f32 v[12:13], v[200:201], v[8:9]
	v_pk_fma_f32 v[144:145], v[198:199], v[94:95], v[144:145] neg_lo:[0,0,1] neg_hi:[0,0,1]
	v_pk_mul_f32 v[94:95], v[200:201], v[94:95]
	v_pk_fma_f32 v[6:7], v[166:167], v[64:65], v[0:1] neg_lo:[0,0,1] neg_hi:[0,0,1]
	v_pk_mul_f32 v[0:1], v[170:171], v[64:65]
	v_pk_mul_f32 v[2:3], v[64:65], v[200:201]
	v_pk_fma_f32 v[22:23], v[198:199], v[4:5], v[12:13] neg_lo:[0,0,1] neg_hi:[0,0,1]
	v_pk_mul_f32 v[12:13], v[200:201], v[4:5]
	v_pk_fma_f32 v[72:73], v[166:167], v[188:189], v[72:73]
	v_pk_fma_f32 v[94:95], v[198:199], v[134:135], v[94:95]
	v_mov_b32_e32 v134, v138
	v_mov_b32_e32 v135, v144
	v_mov_b32_e32 v144, v139
	v_pk_fma_f32 v[10:11], v[166:167], v[68:69], v[0:1]
	v_pk_mul_f32 v[0:1], v[68:69], v[200:201]
	v_pk_fma_f32 v[2:3], v[68:69], v[198:199], v[2:3]
	v_pk_fma_f32 v[58:59], v[198:199], v[8:9], v[12:13]
	v_pk_mul_f32 v[12:13], v[68:69], v[8:9]
	v_pk_mul_f32 v[14:15], v[68:69], v[4:5]
	ds_write2_b64 v164, v[134:135], v[144:145] offset0:4 offset1:6
	v_mov_b32_e32 v134, v72
	v_mov_b32_e32 v135, v94
	v_mov_b32_e32 v94, v73
	v_pk_mul_f32 v[72:73], v[68:69], v[206:207]
	v_pk_mul_f32 v[68:69], v[68:69], v[208:209]
	v_pk_fma_f32 v[0:1], v[64:65], v[198:199], v[0:1] neg_lo:[0,0,1] neg_hi:[0,0,1]
	v_pk_fma_f32 v[12:13], v[64:65], v[4:5], v[12:13] neg_lo:[0,0,1] neg_hi:[0,0,1]
	v_pk_fma_f32 v[16:17], v[64:65], v[8:9], v[14:15]
	v_pk_mul_f32 v[14:15], v[8:9], v[70:71]
	v_pk_mul_f32 v[18:19], v[4:5], v[70:71]
	v_pk_fma_f32 v[72:73], v[64:65], v[208:209], v[72:73]
	v_pk_fma_f32 v[64:65], v[64:65], v[206:207], v[68:69] neg_lo:[0,0,1] neg_hi:[0,0,1]
	v_pk_mul_f32 v[68:69], v[70:71], v[216:217]
	v_pk_mul_f32 v[70:71], v[70:71], v[214:215]
	v_pk_fma_f32 v[14:15], v[4:5], v[66:67], v[14:15] neg_lo:[0,0,1] neg_hi:[0,0,1]
	v_pk_fma_f32 v[18:19], v[8:9], v[66:67], v[18:19]
	v_pk_add_f32 v[132:133], v[140:141], v[132:133] neg_lo:[0,1] neg_hi:[0,1]
	v_pk_fma_f32 v[68:69], v[66:67], v[214:215], v[68:69] neg_lo:[0,0,1] neg_hi:[0,0,1]
	v_pk_fma_f32 v[66:67], v[66:67], v[216:217], v[70:71]
	v_pk_add_f32 v[96:97], v[202:203], v[96:97] neg_lo:[0,1] neg_hi:[0,1]
	v_pk_add_f32 v[180:181], v[204:205], v[180:181] neg_lo:[0,1] neg_hi:[0,1]
	v_pk_add_f32 v[202:203], v[88:89], v[86:87]
	v_pk_add_f32 v[204:205], v[84:85], v[178:179] neg_lo:[0,1] neg_hi:[0,1]
	v_pk_add_f32 v[82:83], v[130:131], v[82:83] neg_lo:[0,1] neg_hi:[0,1]
	v_pk_add_f32 v[130:131], v[190:191], v[174:175] neg_lo:[0,1] neg_hi:[0,1]
	v_pk_add_f32 v[174:175], v[74:75], v[76:77]
	v_pk_add_f32 v[190:191], v[78:79], v[132:133] neg_lo:[0,1] neg_hi:[0,1]
	v_mov_b32_e32 v70, v64
	v_mov_b32_e32 v71, v68
	v_mov_b32_e32 v68, v65
	v_mov_b32_e32 v64, v72
	v_mov_b32_e32 v65, v66
	v_mov_b32_e32 v66, v73
	ds_write2_b64 v162, v[134:135], v[94:95] offset0:4 offset1:6
	ds_write2_b64 v164, v[70:71], v[68:69] offset0:8 offset1:10
	ds_write2_b64 v218, v[64:65], v[66:67] offset0:8 offset1:10
	v_pk_mul_f32 v[64:65], v[10:11], v[202:203]
	v_pk_mul_f32 v[66:67], v[10:11], v[204:205]
	v_pk_mul_f32 v[68:69], v[2:3], v[190:191]
	v_pk_mul_f32 v[70:71], v[2:3], v[174:175]
	v_pk_fma_f32 v[64:65], v[6:7], v[204:205], v[64:65]
	v_pk_fma_f32 v[66:67], v[6:7], v[202:203], v[66:67] neg_lo:[0,0,1] neg_hi:[0,0,1]
	v_pk_fma_f32 v[68:69], v[0:1], v[174:175], v[68:69] neg_lo:[0,0,1] neg_hi:[0,0,1]
	v_pk_fma_f32 v[70:71], v[0:1], v[190:191], v[70:71]
	v_pk_add_f32 v[140:141], v[192:193], v[196:197] neg_lo:[0,1] neg_hi:[0,1]
	v_mov_b32_e32 v72, v66
	v_mov_b32_e32 v73, v68
	v_mov_b32_e32 v68, v67
	v_mov_b32_e32 v66, v64
	v_mov_b32_e32 v67, v70
	v_mov_b32_e32 v70, v65
	ds_write2_b64 v164, v[72:73], v[68:69] offset0:12 offset1:14
	ds_write2_b64 v162, v[66:67], v[70:71] offset0:12 offset1:14
	v_pk_mul_f32 v[66:67], v[8:9], v[140:141]
	v_pk_mul_f32 v[68:69], v[62:63], v[212:213]
	v_pk_mul_f32 v[64:65], v[4:5], v[140:141]
	v_pk_fma_f32 v[66:67], v[4:5], v[80:81], v[66:67] neg_lo:[0,0,1] neg_hi:[0,0,1]
	v_pk_fma_f32 v[68:69], v[60:61], v[210:211], v[68:69] neg_lo:[0,0,1] neg_hi:[0,0,1]
	v_pk_mul_f32 v[62:63], v[62:63], v[210:211]
	v_pk_fma_f32 v[64:65], v[8:9], v[80:81], v[64:65]
	v_pk_fma_f32 v[60:61], v[60:61], v[212:213], v[62:63]
	v_mov_b32_e32 v62, v66
	v_mov_b32_e32 v63, v68
	v_mov_b32_e32 v68, v67
	ds_write2_b64 v164, v[62:63], v[68:69] offset0:16 offset1:18
	v_mov_b32_e32 v62, v64
	v_mov_b32_e32 v63, v60
	v_mov_b32_e32 v60, v65
	ds_write2_b64 v218, v[62:63], v[60:61] offset0:16 offset1:18
	v_pk_mul_f32 v[60:61], v[56:57], v[96:97]
	v_pk_mul_f32 v[56:57], v[56:57], v[180:181]
	v_pk_fma_f32 v[60:61], v[20:21], v[180:181], v[60:61]
	v_pk_fma_f32 v[20:21], v[20:21], v[96:97], v[56:57] neg_lo:[0,0,1] neg_hi:[0,0,1]
	v_pk_mul_f32 v[56:57], v[58:59], v[130:131]
	v_pk_mul_f32 v[58:59], v[58:59], v[82:83]
	v_pk_fma_f32 v[56:57], v[22:23], v[82:83], v[56:57] neg_lo:[0,0,1] neg_hi:[0,0,1]
	v_pk_fma_f32 v[22:23], v[22:23], v[130:131], v[58:59]
	v_mov_b32_e32 v58, v20
	v_mov_b32_e32 v59, v56
	v_mov_b32_e32 v56, v21
	v_mov_b32_e32 v20, v60
	v_mov_b32_e32 v21, v22
	v_mov_b32_e32 v22, v61
	ds_write2_b64 v162, v[20:21], v[22:23] offset0:20 offset1:22
	v_pk_mul_f32 v[20:21], v[16:17], v[136:137]
	v_pk_mul_f32 v[16:17], v[16:17], v[142:143]
	v_pk_fma_f32 v[20:21], v[12:13], v[142:143], v[20:21]
	v_pk_fma_f32 v[12:13], v[12:13], v[136:137], v[16:17] neg_lo:[0,0,1] neg_hi:[0,0,1]
	v_pk_mul_f32 v[16:17], v[18:19], v[90:91]
	v_pk_mul_f32 v[18:19], v[18:19], v[92:93]
	v_pk_fma_f32 v[16:17], v[14:15], v[92:93], v[16:17] neg_lo:[0,0,1] neg_hi:[0,0,1]
	v_pk_fma_f32 v[14:15], v[14:15], v[90:91], v[18:19]
	v_mov_b32_e32 v18, v12
	v_mov_b32_e32 v19, v16
	v_mov_b32_e32 v16, v13
	v_mov_b32_e32 v12, v20
	v_mov_b32_e32 v13, v14
	v_mov_b32_e32 v14, v21
	ds_write2_b64 v164, v[58:59], v[56:57] offset0:20 offset1:22
	ds_write2_b64 v164, v[18:19], v[16:17] offset0:24 offset1:26
	ds_write2_b64 v218, v[12:13], v[14:15] offset0:24 offset1:26
	v_pk_mul_f32 v[14:15], v[8:9], v[10:11]
	v_pk_mul_f32 v[10:11], v[4:5], v[10:11]
	v_pk_add_f32 v[12:13], v[84:85], v[178:179]
	v_pk_fma_f32 v[14:15], v[4:5], v[6:7], v[14:15] neg_lo:[0,0,1] neg_hi:[0,0,1]
	v_pk_add_f32 v[16:17], v[88:89], v[86:87] neg_lo:[0,1] neg_hi:[0,1]
	v_pk_fma_f32 v[6:7], v[8:9], v[6:7], v[10:11]
	s_nop 0
	v_pk_mul_f32 v[10:11], v[6:7], v[16:17]
	v_pk_mul_f32 v[6:7], v[6:7], v[12:13]
	v_pk_fma_f32 v[10:11], v[14:15], v[12:13], v[10:11]
	v_pk_fma_f32 v[6:7], v[14:15], v[16:17], v[6:7] neg_lo:[0,0,1] neg_hi:[0,0,1]
	v_pk_mul_f32 v[16:17], v[4:5], v[2:3]
	v_pk_add_f32 v[12:13], v[78:79], v[132:133]
	v_pk_fma_f32 v[16:17], v[8:9], v[0:1], v[16:17]
	v_pk_mul_f32 v[2:3], v[8:9], v[2:3]
	v_pk_add_f32 v[14:15], v[74:75], v[76:77] neg_lo:[0,1] neg_hi:[0,1]
	v_pk_fma_f32 v[0:1], v[4:5], v[0:1], v[2:3] neg_lo:[0,0,1] neg_hi:[0,0,1]
	v_pk_mul_f32 v[2:3], v[16:17], v[12:13]
	v_pk_mul_f32 v[4:5], v[16:17], v[14:15]
	v_pk_fma_f32 v[2:3], v[0:1], v[14:15], v[2:3] neg_lo:[0,0,1] neg_hi:[0,0,1]
	v_pk_fma_f32 v[0:1], v[0:1], v[12:13], v[4:5]
	v_mov_b32_e32 v4, v6
	v_mov_b32_e32 v5, v2
	v_mov_b32_e32 v2, v7
	ds_write2_b64 v164, v[4:5], v[2:3] offset0:28 offset1:30
	v_mov_b32_e32 v2, v10
	v_mov_b32_e32 v3, v0
	v_mov_b32_e32 v0, v11
	ds_write2_b64 v162, v[2:3], v[0:1] offset0:28 offset1:30
	v_mov_b32_e32 v0, v163
	s_waitcnt lgkmcnt(0)
	s_barrier
	v_lshlrev_b32_e32 v236, 5, v163
	v_add_u32_e32 v236, 0x4000, v236
	global_load_dwordx4 v[176:179], v236, s[94:95] offset:16
	global_load_dwordx4 v[180:183], v236, s[94:95]
	global_load_dwordx4 v[184:187], v236, s[30:31] offset:16
	global_load_dwordx4 v[188:191], v236, s[30:31]
	v_add_u32_e32 v236, 0x4000, v236
	global_load_dwordx4 v[192:195], v236, s[94:95] offset:16
	global_load_dwordx4 v[196:199], v236, s[94:95]
	global_load_dwordx4 v[208:211], v236, s[30:31] offset:16
	global_load_dwordx4 v[212:215], v236, s[30:31]
	v_add_u32_e32 v236, 0x4000, v236
	global_load_dwordx4 v[72:75], v236, s[94:95] offset:16
	global_load_dwordx4 v[76:79], v236, s[94:95]
	global_load_dwordx4 v[80:83], v236, s[30:31] offset:16
	global_load_dwordx4 v[84:87], v236, s[30:31]
	s_nop 0
	s_nop 0
	v_lshlrev_b32_e32 v18, 3, v0
	v_ashrrev_i32_e32 v2, 3, v0
	v_and_b32_e32 v1, 56, v18
	v_mul_lo_u32 v2, v2, s49
	v_add_lshl_u32 v10, v2, v1, 2
	v_add_u32_e32 v68, 0, v10
	ds_read_b128 v[2:5], v68
	ds_read_b128 v[6:9], v68 offset:16
	v_add_u32_e32 v69, s91, v10
	ds_read_b128 v[10:13], v69
	ds_read_b128 v[14:17], v69 offset:16
	v_ashrrev_i32_e32 v19, 31, v18
	s_waitcnt lgkmcnt(3)
	v_pk_add_f32 v[20:21], v[2:3], v[4:5]
	v_pk_add_f32 v[2:3], v[2:3], v[4:5] neg_lo:[0,1] neg_hi:[0,1]
	s_waitcnt lgkmcnt(1)
	v_pk_add_f32 v[22:23], v[10:11], v[12:13]
	v_pk_add_f32 v[4:5], v[10:11], v[12:13] neg_lo:[0,1] neg_hi:[0,1]
	v_pk_add_f32 v[10:11], v[6:7], v[8:9]
	v_pk_add_f32 v[6:7], v[6:7], v[8:9] neg_lo:[0,1] neg_hi:[0,1]
	v_pk_add_f32 v[56:57], v[20:21], v[10:11]
	v_pk_add_f32 v[20:21], v[20:21], v[10:11] neg_lo:[0,1] neg_hi:[0,1]
	v_lshlrev_b64 v[10:11], 2, v[18:19]
	s_waitcnt lgkmcnt(0)
	v_pk_add_f32 v[12:13], v[14:15], v[16:17]
	v_pk_add_f32 v[8:9], v[14:15], v[16:17] neg_lo:[0,1] neg_hi:[0,1]
	v_pk_add_f32 v[62:63], v[4:5], v[6:7] neg_lo:[0,1] neg_hi:[0,1]
	v_pk_add_f32 v[66:67], v[6:7], v[4:5]
	v_lshl_add_u64 v[6:7], s[94:95], 0, v[10:11]
	v_lshl_add_u64 v[14:15], s[30:31], 0, v[10:11]
	v_pk_add_f32 v[58:59], v[22:23], v[12:13]
	v_pk_add_f32 v[22:23], v[22:23], v[12:13] neg_lo:[0,1] neg_hi:[0,1]
	v_pk_add_f32 v[60:61], v[2:3], v[8:9]
	v_pk_add_f32 v[64:65], v[2:3], v[8:9] neg_lo:[0,1] neg_hi:[0,1]
	s_waitcnt vmcnt(12)
	v_pk_mul_f32 v[18:19], v[58:59], v[232:233]
	v_pk_mul_f32 v[14:15], v[56:57], v[232:233]
	v_pk_fma_f32 v[18:19], v[56:57], v[224:225], v[18:19] neg_lo:[0,0,1] neg_hi:[0,0,1]
	v_pk_fma_f32 v[6:7], v[224:225], v[58:59], v[14:15]
	v_pk_mul_f32 v[14:15], v[22:23], v[234:235]
	v_pk_mul_f32 v[16:17], v[20:21], v[234:235]
	v_pk_fma_f32 v[14:15], v[20:21], v[226:227], v[14:15] neg_lo:[0,0,1] neg_hi:[0,0,1]
	v_pk_fma_f32 v[8:9], v[226:227], v[22:23], v[16:17]
	v_pk_mul_f32 v[16:17], v[62:63], v[228:229]
	v_pk_mul_f32 v[10:11], v[60:61], v[228:229]
	v_pk_fma_f32 v[16:17], v[60:61], v[220:221], v[16:17] neg_lo:[0,0,1] neg_hi:[0,0,1]
	v_pk_fma_f32 v[2:3], v[62:63], v[220:221], v[10:11]
	v_pk_mul_f32 v[10:11], v[66:67], v[230:231]
	v_pk_mul_f32 v[12:13], v[64:65], v[230:231]
	v_pk_fma_f32 v[10:11], v[64:65], v[222:223], v[10:11] neg_lo:[0,0,1] neg_hi:[0,0,1]
	v_pk_fma_f32 v[4:5], v[66:67], v[222:223], v[12:13]
	v_pk_add_f32 v[12:13], v[18:19], v[14:15]
	v_pk_add_f32 v[20:21], v[6:7], v[8:9]
	v_pk_add_f32 v[22:23], v[6:7], v[8:9] neg_lo:[0,1] neg_hi:[0,1]
	v_pk_add_f32 v[8:9], v[16:17], v[10:11]
	v_pk_add_f32 v[18:19], v[18:19], v[14:15] neg_lo:[0,1] neg_hi:[0,1]
	v_pk_add_f32 v[14:15], v[2:3], v[4:5]
	v_pk_add_f32 v[16:17], v[16:17], v[10:11] neg_lo:[0,1] neg_hi:[0,1]
	v_pk_add_f32 v[56:57], v[2:3], v[4:5] neg_lo:[0,1] neg_hi:[0,1]
	v_pk_add_f32 v[2:3], v[12:13], v[8:9]
	v_pk_add_f32 v[4:5], v[12:13], v[8:9] neg_lo:[0,1] neg_hi:[0,1]
	v_add_u32_e32 v66, 0x200, v0
	v_pk_add_f32 v[6:7], v[20:21], v[14:15]
	v_pk_add_f32 v[8:9], v[20:21], v[14:15] neg_lo:[0,1] neg_hi:[0,1]
	v_pk_add_f32 v[10:11], v[18:19], v[56:57] neg_lo:[0,1] neg_hi:[0,1]
	v_pk_add_f32 v[14:15], v[22:23], v[16:17]
	v_pk_add_f32 v[12:13], v[18:19], v[56:57]
	v_pk_add_f32 v[16:17], v[22:23], v[16:17] neg_lo:[0,1] neg_hi:[0,1]
	ds_write_b128 v68, v[2:5]
	ds_write_b128 v68, v[10:13] offset:16
	ds_write_b128 v69, v[6:9]
	ds_write_b128 v69, v[14:17] offset:16
	v_ashrrev_i32_e32 v2, 3, v66
	v_mul_lo_u32 v2, v2, s49
	v_add_lshl_u32 v10, v2, v1, 2
	v_add_u32_e32 v68, 0, v10
	v_add_u32_e32 v69, s91, v10
	ds_read_b128 v[2:5], v68
	ds_read_b128 v[6:9], v68 offset:16
	ds_read_b128 v[10:13], v69
	ds_read_b128 v[14:17], v69 offset:16
	s_waitcnt lgkmcnt(3)
	v_pk_add_f32 v[18:19], v[2:3], v[4:5]
	s_waitcnt lgkmcnt(1)
	v_pk_add_f32 v[20:21], v[10:11], v[12:13]
	v_pk_add_f32 v[2:3], v[2:3], v[4:5] neg_lo:[0,1] neg_hi:[0,1]
	v_pk_add_f32 v[4:5], v[10:11], v[12:13] neg_lo:[0,1] neg_hi:[0,1]
	v_pk_add_f32 v[10:11], v[6:7], v[8:9]
	v_pk_add_f32 v[6:7], v[6:7], v[8:9] neg_lo:[0,1] neg_hi:[0,1]
	s_waitcnt lgkmcnt(0)
	v_pk_add_f32 v[8:9], v[14:15], v[16:17] neg_lo:[0,1] neg_hi:[0,1]
	v_pk_add_f32 v[22:23], v[18:19], v[10:11]
	v_pk_add_f32 v[58:59], v[2:3], v[8:9]
	v_pk_add_f32 v[62:63], v[2:3], v[8:9] neg_lo:[0,1] neg_hi:[0,1]
	v_lshlrev_b32_e32 v2, 3, v66
	v_ashrrev_i32_e32 v3, 31, v2
	v_pk_add_f32 v[18:19], v[18:19], v[10:11] neg_lo:[0,1] neg_hi:[0,1]
	v_lshlrev_b64 v[10:11], 2, v[2:3]
	v_pk_add_f32 v[12:13], v[14:15], v[16:17]
	v_pk_add_f32 v[60:61], v[4:5], v[6:7] neg_lo:[0,1] neg_hi:[0,1]
	v_pk_add_f32 v[64:65], v[6:7], v[4:5]
	v_lshl_add_u64 v[6:7], s[94:95], 0, v[10:11]
	v_lshl_add_u64 v[14:15], s[30:31], 0, v[10:11]
	v_pk_add_f32 v[56:57], v[20:21], v[12:13]
	v_pk_add_f32 v[20:21], v[20:21], v[12:13] neg_lo:[0,1] neg_hi:[0,1]
	s_waitcnt vmcnt(8)
	v_pk_mul_f32 v[66:67], v[56:57], v[188:189]
	v_pk_mul_f32 v[14:15], v[22:23], v[188:189]
	v_pk_fma_f32 v[66:67], v[22:23], v[180:181], v[66:67] neg_lo:[0,0,1] neg_hi:[0,0,1]
	v_pk_fma_f32 v[6:7], v[180:181], v[56:57], v[14:15]
	v_pk_mul_f32 v[14:15], v[20:21], v[190:191]
	v_pk_mul_f32 v[16:17], v[18:19], v[190:191]
	v_pk_fma_f32 v[14:15], v[18:19], v[182:183], v[14:15] neg_lo:[0,0,1] neg_hi:[0,0,1]
	v_pk_fma_f32 v[8:9], v[182:183], v[20:21], v[16:17]
	v_pk_mul_f32 v[16:17], v[60:61], v[184:185]
	v_pk_mul_f32 v[10:11], v[58:59], v[184:185]
	v_pk_fma_f32 v[16:17], v[58:59], v[176:177], v[16:17] neg_lo:[0,0,1] neg_hi:[0,0,1]
	v_pk_fma_f32 v[2:3], v[60:61], v[176:177], v[10:11]
	v_pk_mul_f32 v[10:11], v[64:65], v[186:187]
	v_pk_mul_f32 v[12:13], v[62:63], v[186:187]
	v_pk_fma_f32 v[10:11], v[62:63], v[178:179], v[10:11] neg_lo:[0,0,1] neg_hi:[0,0,1]
	v_pk_fma_f32 v[4:5], v[64:65], v[178:179], v[12:13]
	v_pk_add_f32 v[12:13], v[66:67], v[14:15]
	v_pk_add_f32 v[18:19], v[6:7], v[8:9]
	v_pk_add_f32 v[22:23], v[6:7], v[8:9] neg_lo:[0,1] neg_hi:[0,1]
	v_pk_add_f32 v[8:9], v[16:17], v[10:11]
	v_pk_add_f32 v[20:21], v[66:67], v[14:15] neg_lo:[0,1] neg_hi:[0,1]
	v_pk_add_f32 v[14:15], v[2:3], v[4:5]
	v_pk_add_f32 v[16:17], v[16:17], v[10:11] neg_lo:[0,1] neg_hi:[0,1]
	v_pk_add_f32 v[56:57], v[2:3], v[4:5] neg_lo:[0,1] neg_hi:[0,1]
	v_pk_add_f32 v[2:3], v[12:13], v[8:9]
	v_pk_add_f32 v[4:5], v[12:13], v[8:9] neg_lo:[0,1] neg_hi:[0,1]
	v_add_u32_e32 v66, 0x400, v0
	v_pk_add_f32 v[6:7], v[18:19], v[14:15]
	v_pk_add_f32 v[8:9], v[18:19], v[14:15] neg_lo:[0,1] neg_hi:[0,1]
	v_pk_add_f32 v[10:11], v[20:21], v[56:57] neg_lo:[0,1] neg_hi:[0,1]
	v_pk_add_f32 v[14:15], v[22:23], v[16:17]
	v_pk_add_f32 v[12:13], v[20:21], v[56:57]
	v_pk_add_f32 v[16:17], v[22:23], v[16:17] neg_lo:[0,1] neg_hi:[0,1]
	ds_write_b128 v68, v[2:5]
	ds_write_b128 v68, v[10:13] offset:16
	ds_write_b128 v69, v[6:9]
	ds_write_b128 v69, v[14:17] offset:16
	v_ashrrev_i32_e32 v2, 3, v66
	v_mul_lo_u32 v2, v2, s49
	v_add_lshl_u32 v10, v2, v1, 2
	v_add_u32_e32 v68, 0, v10
	v_add_u32_e32 v69, s91, v10
	ds_read_b128 v[2:5], v68
	ds_read_b128 v[6:9], v68 offset:16
	ds_read_b128 v[10:13], v69
	ds_read_b128 v[14:17], v69 offset:16
	s_waitcnt lgkmcnt(3)
	v_pk_add_f32 v[18:19], v[2:3], v[4:5]
	s_waitcnt lgkmcnt(1)
	v_pk_add_f32 v[20:21], v[10:11], v[12:13]
	v_pk_add_f32 v[2:3], v[2:3], v[4:5] neg_lo:[0,1] neg_hi:[0,1]
	v_pk_add_f32 v[4:5], v[10:11], v[12:13] neg_lo:[0,1] neg_hi:[0,1]
	v_pk_add_f32 v[10:11], v[6:7], v[8:9]
	v_pk_add_f32 v[6:7], v[6:7], v[8:9] neg_lo:[0,1] neg_hi:[0,1]
	s_waitcnt lgkmcnt(0)
	v_pk_add_f32 v[8:9], v[14:15], v[16:17] neg_lo:[0,1] neg_hi:[0,1]
	v_pk_add_f32 v[22:23], v[18:19], v[10:11]
	v_pk_add_f32 v[58:59], v[2:3], v[8:9]
	v_pk_add_f32 v[62:63], v[2:3], v[8:9] neg_lo:[0,1] neg_hi:[0,1]
	v_lshlrev_b32_e32 v2, 3, v66
	v_ashrrev_i32_e32 v3, 31, v2
	v_pk_add_f32 v[18:19], v[18:19], v[10:11] neg_lo:[0,1] neg_hi:[0,1]
	v_lshlrev_b64 v[10:11], 2, v[2:3]
	v_pk_add_f32 v[12:13], v[14:15], v[16:17]
	v_pk_add_f32 v[60:61], v[4:5], v[6:7] neg_lo:[0,1] neg_hi:[0,1]
	v_pk_add_f32 v[64:65], v[6:7], v[4:5]
	v_lshl_add_u64 v[6:7], s[94:95], 0, v[10:11]
	v_lshl_add_u64 v[14:15], s[30:31], 0, v[10:11]
	v_pk_add_f32 v[56:57], v[20:21], v[12:13]
	v_pk_add_f32 v[20:21], v[20:21], v[12:13] neg_lo:[0,1] neg_hi:[0,1]
	s_waitcnt vmcnt(4)
	v_pk_mul_f32 v[66:67], v[56:57], v[212:213]
	v_pk_mul_f32 v[14:15], v[22:23], v[212:213]
	v_pk_fma_f32 v[66:67], v[22:23], v[196:197], v[66:67] neg_lo:[0,0,1] neg_hi:[0,0,1]
	v_pk_fma_f32 v[6:7], v[196:197], v[56:57], v[14:15]
	v_pk_mul_f32 v[14:15], v[20:21], v[214:215]
	v_pk_mul_f32 v[16:17], v[18:19], v[214:215]
	v_pk_fma_f32 v[14:15], v[18:19], v[198:199], v[14:15] neg_lo:[0,0,1] neg_hi:[0,0,1]
	v_pk_fma_f32 v[8:9], v[198:199], v[20:21], v[16:17]
	v_pk_mul_f32 v[16:17], v[60:61], v[208:209]
	v_pk_mul_f32 v[10:11], v[58:59], v[208:209]
	v_pk_fma_f32 v[16:17], v[58:59], v[192:193], v[16:17] neg_lo:[0,0,1] neg_hi:[0,0,1]
	v_pk_fma_f32 v[2:3], v[60:61], v[192:193], v[10:11]
	v_pk_mul_f32 v[10:11], v[64:65], v[210:211]
	v_pk_mul_f32 v[12:13], v[62:63], v[210:211]
	v_pk_fma_f32 v[10:11], v[62:63], v[194:195], v[10:11] neg_lo:[0,0,1] neg_hi:[0,0,1]
	v_pk_fma_f32 v[4:5], v[64:65], v[194:195], v[12:13]
	v_pk_add_f32 v[12:13], v[66:67], v[14:15]
	v_pk_add_f32 v[20:21], v[66:67], v[14:15] neg_lo:[0,1] neg_hi:[0,1]
	v_add_u32_e32 v66, 0x600, v0
	v_pk_add_f32 v[18:19], v[6:7], v[8:9]
	v_pk_add_f32 v[22:23], v[6:7], v[8:9] neg_lo:[0,1] neg_hi:[0,1]
	v_pk_add_f32 v[8:9], v[16:17], v[10:11]
	v_pk_add_f32 v[14:15], v[2:3], v[4:5]
	v_ashrrev_i32_e32 v0, 3, v66
	v_pk_add_f32 v[16:17], v[16:17], v[10:11] neg_lo:[0,1] neg_hi:[0,1]
	v_pk_add_f32 v[56:57], v[2:3], v[4:5] neg_lo:[0,1] neg_hi:[0,1]
	v_pk_add_f32 v[2:3], v[12:13], v[8:9]
	v_pk_add_f32 v[4:5], v[12:13], v[8:9] neg_lo:[0,1] neg_hi:[0,1]
	v_pk_add_f32 v[8:9], v[18:19], v[14:15] neg_lo:[0,1] neg_hi:[0,1]
	v_mul_lo_u32 v0, v0, s49
	v_pk_add_f32 v[6:7], v[18:19], v[14:15]
	v_pk_add_f32 v[10:11], v[20:21], v[56:57] neg_lo:[0,1] neg_hi:[0,1]
	v_pk_add_f32 v[14:15], v[22:23], v[16:17]
	v_pk_add_f32 v[12:13], v[20:21], v[56:57]
	v_pk_add_f32 v[16:17], v[22:23], v[16:17] neg_lo:[0,1] neg_hi:[0,1]
	ds_write_b128 v68, v[2:5]
	ds_write_b128 v68, v[10:13] offset:16
	ds_write_b128 v69, v[6:9]
	ds_write_b128 v69, v[14:17] offset:16
	v_add_lshl_u32 v8, v0, v1, 2
	v_add_u32_e32 v65, 0, v8
	v_add_u32_e32 v64, s91, v8
	ds_read_b128 v[0:3], v65
	ds_read_b128 v[4:7], v65 offset:16
	ds_read_b128 v[8:11], v64
	ds_read_b128 v[12:15], v64 offset:16
	s_waitcnt lgkmcnt(3)
	v_pk_add_f32 v[16:17], v[0:1], v[2:3]
	s_waitcnt lgkmcnt(1)
	v_pk_add_f32 v[18:19], v[8:9], v[10:11]
	v_pk_add_f32 v[0:1], v[0:1], v[2:3] neg_lo:[0,1] neg_hi:[0,1]
	v_pk_add_f32 v[2:3], v[8:9], v[10:11] neg_lo:[0,1] neg_hi:[0,1]
	v_pk_add_f32 v[8:9], v[4:5], v[6:7]
	v_pk_add_f32 v[4:5], v[4:5], v[6:7] neg_lo:[0,1] neg_hi:[0,1]
	s_waitcnt lgkmcnt(0)
	v_pk_add_f32 v[6:7], v[12:13], v[14:15] neg_lo:[0,1] neg_hi:[0,1]
	v_pk_add_f32 v[60:61], v[16:17], v[8:9]
	v_pk_add_f32 v[56:57], v[16:17], v[8:9] neg_lo:[0,1] neg_hi:[0,1]
	v_pk_add_f32 v[20:21], v[0:1], v[6:7]
	v_pk_add_f32 v[16:17], v[0:1], v[6:7] neg_lo:[0,1] neg_hi:[0,1]
	v_lshlrev_b32_e32 v0, 3, v66
	v_pk_add_f32 v[10:11], v[12:13], v[14:15]
	v_ashrrev_i32_e32 v1, 31, v0
	v_pk_add_f32 v[62:63], v[18:19], v[10:11]
	v_pk_add_f32 v[58:59], v[18:19], v[10:11] neg_lo:[0,1] neg_hi:[0,1]
	v_pk_add_f32 v[22:23], v[2:3], v[4:5] neg_lo:[0,1] neg_hi:[0,1]
	v_pk_add_f32 v[18:19], v[4:5], v[2:3]
	v_lshlrev_b64 v[4:5], 2, v[0:1]
	v_lshl_add_u64 v[6:7], s[94:95], 0, v[4:5]
	v_lshl_add_u64 v[12:13], s[30:31], 0, v[4:5]
	s_waitcnt vmcnt(0)
	v_pk_mul_f32 v[66:67], v[62:63], v[84:85]
	v_pk_mul_f32 v[12:13], v[60:61], v[84:85]
	v_pk_fma_f32 v[66:67], v[60:61], v[76:77], v[66:67] neg_lo:[0,0,1] neg_hi:[0,0,1]
	v_pk_fma_f32 v[8:9], v[76:77], v[62:63], v[12:13]
	v_pk_mul_f32 v[12:13], v[58:59], v[86:87]
	v_pk_mul_f32 v[14:15], v[56:57], v[86:87]
	v_pk_fma_f32 v[12:13], v[56:57], v[78:79], v[12:13] neg_lo:[0,0,1] neg_hi:[0,0,1]
	v_pk_fma_f32 v[10:11], v[78:79], v[58:59], v[14:15]
	v_pk_mul_f32 v[14:15], v[22:23], v[80:81]
	v_pk_mul_f32 v[4:5], v[20:21], v[80:81]
	v_pk_fma_f32 v[14:15], v[20:21], v[72:73], v[14:15] neg_lo:[0,0,1] neg_hi:[0,0,1]
	v_pk_fma_f32 v[0:1], v[22:23], v[72:73], v[4:5]
	v_pk_mul_f32 v[4:5], v[18:19], v[82:83]
	v_pk_mul_f32 v[6:7], v[16:17], v[82:83]
	v_pk_fma_f32 v[4:5], v[16:17], v[74:75], v[4:5] neg_lo:[0,0,1] neg_hi:[0,0,1]
	v_pk_fma_f32 v[2:3], v[18:19], v[74:75], v[6:7]
	v_pk_add_f32 v[6:7], v[66:67], v[12:13]
	v_pk_add_f32 v[16:17], v[8:9], v[10:11]
	v_pk_add_f32 v[20:21], v[8:9], v[10:11] neg_lo:[0,1] neg_hi:[0,1]
	v_pk_add_f32 v[8:9], v[14:15], v[4:5]
	v_pk_add_f32 v[18:19], v[66:67], v[12:13] neg_lo:[0,1] neg_hi:[0,1]
	v_pk_add_f32 v[10:11], v[0:1], v[2:3]
	v_pk_add_f32 v[14:15], v[14:15], v[4:5] neg_lo:[0,1] neg_hi:[0,1]
	v_pk_add_f32 v[22:23], v[0:1], v[2:3] neg_lo:[0,1] neg_hi:[0,1]
	v_pk_add_f32 v[0:1], v[6:7], v[8:9]
	v_pk_add_f32 v[2:3], v[6:7], v[8:9] neg_lo:[0,1] neg_hi:[0,1]
	v_pk_add_f32 v[4:5], v[16:17], v[10:11]
	v_pk_add_f32 v[6:7], v[16:17], v[10:11] neg_lo:[0,1] neg_hi:[0,1]
	v_pk_add_f32 v[8:9], v[18:19], v[22:23] neg_lo:[0,1] neg_hi:[0,1]
	v_pk_add_f32 v[12:13], v[20:21], v[14:15]
	v_pk_add_f32 v[10:11], v[18:19], v[22:23]
	v_pk_add_f32 v[14:15], v[20:21], v[14:15] neg_lo:[0,1] neg_hi:[0,1]
	ds_write_b128 v65, v[0:3]
	ds_write_b128 v65, v[8:11] offset:16
	ds_write_b128 v64, v[4:7]
	ds_write_b128 v64, v[12:15] offset:16
	v_mov_b32_e32 v0, v163
	s_waitcnt lgkmcnt(0)
	s_barrier
	s_nop 0
	s_nop 0
	v_lshlrev_b32_e32 v1, 1, v0
	v_and_b32_e32 v162, 2, v1
	v_lshrrev_b32_e32 v1, 31, v0
	v_add_u32_e32 v0, v0, v1
	v_ashrrev_i32_e32 v168, 1, v0
	v_mul_lo_u32 v0, v168, s49
	v_or_b32_e32 v0, v0, v162
	v_lshlrev_b32_e32 v0, 2, v0
	v_add_u32_e32 v88, 0, v0
	v_add_u32_e32 v92, s91, v0
	ds_read2_b64 v[0:3], v88 offset1:2
	ds_read2_b64 v[8:11], v88 offset0:4 offset1:6
	ds_read2_b64 v[4:7], v92 offset1:2
	ds_read2_b64 v[12:15], v92 offset0:4 offset1:6
	ds_read2_b64 v[16:19], v88 offset0:8 offset1:10
	ds_read2_b64 v[20:23], v92 offset0:8 offset1:10
	ds_read2_b64 v[56:59], v88 offset0:12 offset1:14
	ds_read2_b64 v[60:63], v92 offset0:12 offset1:14
	ds_read2_b64 v[64:67], v88 offset0:16 offset1:18
	ds_read2_b64 v[68:71], v88 offset0:20 offset1:22
	ds_read2_b64 v[72:75], v92 offset0:16 offset1:18
	ds_read2_b64 v[76:79], v92 offset0:20 offset1:22
	ds_read2_b64 v[80:83], v88 offset0:24 offset1:26
	ds_read2_b64 v[84:87], v92 offset0:24 offset1:26
	ds_read2_b64 v[88:91], v88 offset0:28 offset1:30
	ds_read2_b64 v[92:95], v92 offset0:28 offset1:30
	s_mov_b64 s[4:5], 0x800
	s_waitcnt lgkmcnt(3)
	v_mov_b32_e32 v186, v81
	v_mov_b32_e32 v187, v83
	s_waitcnt lgkmcnt(1)
	v_mov_b32_e32 v178, v89
	s_waitcnt lgkmcnt(0)
	v_mov_b32_e32 v97, v95
	v_or_b32_e32 v95, 1, v162
	v_mov_b32_e32 v96, v93
	v_cvt_f32_ubyte0_e32 v93, v162
	v_cvt_f32_ubyte0_e32 v95, v95
	v_mul_f32_e32 v93, 0x3c800000, v93
	v_mul_f32_e32 v95, 0x3c800000, v95
	v_cos_f32_e32 v130, v93
	v_cos_f32_e32 v131, v95
	v_sin_f32_e64 v132, -v93
	v_sin_f32_e64 v133, -v95
	v_mov_b32_e32 v179, v91
	v_mov_b32_e32 v93, v94
	v_mov_b32_e32 v89, v90
	v_pk_mul_f32 v[134:135], v[132:133], v[132:133]
	v_pk_mul_f32 v[136:137], v[130:131], v[132:133]
	v_pk_fma_f32 v[134:135], v[130:131], v[130:131], v[134:135] neg_lo:[0,0,1] neg_hi:[0,0,1]
	v_pk_add_f32 v[136:137], v[136:137], v[136:137]
	v_pk_mul_f32 v[164:165], v[132:133], v[134:135]
	v_pk_mul_f32 v[138:139], v[136:137], v[136:137]
	v_pk_mul_f32 v[140:141], v[134:135], v[136:137]
	v_pk_fma_f32 v[138:139], v[134:135], v[134:135], v[138:139] neg_lo:[0,0,1] neg_hi:[0,0,1]
	v_pk_add_f32 v[140:141], v[140:141], v[140:141]
	v_pk_mul_f32 v[144:145], v[132:133], v[136:137]
	v_pk_fma_f32 v[164:165], v[130:131], v[136:137], v[164:165]
	v_pk_mul_f32 v[142:143], v[140:141], v[140:141]
	v_pk_fma_f32 v[144:145], v[130:131], v[134:135], v[144:145] neg_lo:[0,0,1] neg_hi:[0,0,1]
	v_pk_mul_f32 v[174:175], v[138:139], v[164:165]
	v_pk_fma_f32 v[142:143], v[138:139], v[138:139], v[142:143] neg_lo:[0,0,1] neg_hi:[0,0,1]
	v_pk_mul_f32 v[166:167], v[140:141], v[164:165]
	v_pk_mul_f32 v[170:171], v[138:139], v[140:141]
	v_pk_fma_f32 v[174:175], v[140:141], v[144:145], v[174:175]
	v_pk_fma_f32 v[166:167], v[138:139], v[144:145], v[166:167] neg_lo:[0,0,1] neg_hi:[0,0,1]
	v_pk_add_f32 v[170:171], v[170:171], v[170:171]
	v_pk_mul_f32 v[180:181], v[142:143], v[174:175]
	v_pk_mul_f32 v[176:177], v[170:171], v[174:175]
	v_pk_fma_f32 v[180:181], v[170:171], v[166:167], v[180:181]
	v_pk_fma_f32 v[176:177], v[142:143], v[166:167], v[176:177] neg_lo:[0,0,1] neg_hi:[0,0,1]
	v_pk_mul_f32 v[182:183], v[180:181], v[178:179]
	v_pk_mul_f32 v[94:95], v[136:137], v[140:141]
	v_pk_fma_f32 v[182:183], v[176:177], v[96:97], v[182:183] neg_lo:[0,0,1] neg_hi:[0,0,1]
	v_pk_mul_f32 v[96:97], v[180:181], v[96:97]
	v_pk_fma_f32 v[94:95], v[134:135], v[138:139], v[94:95] neg_lo:[0,0,1] neg_hi:[0,0,1]
	v_pk_fma_f32 v[96:97], v[176:177], v[178:179], v[96:97]
	v_pk_mul_f32 v[176:177], v[136:137], v[138:139]
	v_mov_b32_e32 v81, v82
	v_pk_fma_f32 v[176:177], v[134:135], v[140:141], v[176:177]
	v_pk_mul_f32 v[82:83], v[140:141], v[142:143]
	v_pk_mul_f32 v[90:91], v[142:143], v[176:177]
	v_pk_mul_f32 v[178:179], v[170:171], v[176:177]
	v_pk_fma_f32 v[90:91], v[170:171], v[94:95], v[90:91]
	v_pk_fma_f32 v[178:179], v[142:143], v[94:95], v[178:179] neg_lo:[0,0,1] neg_hi:[0,0,1]
	v_pk_mul_f32 v[180:181], v[90:91], v[88:89]
	v_pk_mul_f32 v[90:91], v[90:91], v[92:93]
	v_pk_fma_f32 v[180:181], v[178:179], v[92:93], v[180:181] neg_lo:[0,0,1] neg_hi:[0,0,1]
	v_pk_fma_f32 v[88:89], v[178:179], v[88:89], v[90:91]
	v_pk_mul_f32 v[178:179], v[132:133], v[138:139]
	v_pk_mul_f32 v[92:93], v[132:133], v[140:141]
	v_pk_fma_f32 v[178:179], v[130:131], v[140:141], v[178:179]
	v_pk_fma_f32 v[92:93], v[130:131], v[138:139], v[92:93] neg_lo:[0,0,1] neg_hi:[0,0,1]
	v_pk_mul_f32 v[188:189], v[142:143], v[178:179]
	v_pk_mul_f32 v[184:185], v[170:171], v[178:179]
	v_pk_fma_f32 v[188:189], v[170:171], v[92:93], v[188:189]
	v_mov_b32_e32 v90, v85
	v_mov_b32_e32 v91, v87
	v_pk_fma_f32 v[184:185], v[142:143], v[92:93], v[184:185] neg_lo:[0,0,1] neg_hi:[0,0,1]
	v_pk_mul_f32 v[190:191], v[188:189], v[186:187]
	v_mov_b32_e32 v85, v86
	v_pk_fma_f32 v[190:191], v[184:185], v[90:91], v[190:191] neg_lo:[0,0,1] neg_hi:[0,0,1]
	v_pk_mul_f32 v[90:91], v[188:189], v[90:91]
	v_pk_mul_f32 v[86:87], v[140:141], v[170:171]
	v_pk_fma_f32 v[82:83], v[138:139], v[170:171], v[82:83]
	v_pk_fma_f32 v[90:91], v[184:185], v[186:187], v[90:91]
	v_pk_fma_f32 v[86:87], v[138:139], v[142:143], v[86:87] neg_lo:[0,0,1] neg_hi:[0,0,1]
	v_pk_mul_f32 v[184:185], v[82:83], v[80:81]
	v_pk_mul_f32 v[82:83], v[82:83], v[84:85]
	v_pk_mul_f32 v[186:187], v[164:165], v[142:143]
	v_pk_fma_f32 v[184:185], v[86:87], v[84:85], v[184:185] neg_lo:[0,0,1] neg_hi:[0,0,1]
	v_pk_fma_f32 v[80:81], v[86:87], v[80:81], v[82:83]
	v_pk_mul_f32 v[84:85], v[164:165], v[170:171]
	v_mov_b32_e32 v86, v69
	v_mov_b32_e32 v87, v71
	v_pk_fma_f32 v[186:187], v[144:145], v[170:171], v[186:187]
	v_mov_b32_e32 v82, v77
	v_mov_b32_e32 v83, v79
	v_pk_fma_f32 v[84:85], v[144:145], v[142:143], v[84:85] neg_lo:[0,0,1] neg_hi:[0,0,1]
	v_pk_mul_f32 v[188:189], v[186:187], v[86:87]
	v_mov_b32_e32 v69, v70
	v_pk_mul_f32 v[70:71], v[136:137], v[142:143]
	v_pk_fma_f32 v[188:189], v[84:85], v[82:83], v[188:189] neg_lo:[0,0,1] neg_hi:[0,0,1]
	v_pk_mul_f32 v[82:83], v[186:187], v[82:83]
	v_mov_b32_e32 v77, v78
	v_pk_mul_f32 v[78:79], v[136:137], v[170:171]
	v_pk_fma_f32 v[70:71], v[134:135], v[170:171], v[70:71]
	v_pk_fma_f32 v[82:83], v[84:85], v[86:87], v[82:83]
	v_pk_fma_f32 v[78:79], v[134:135], v[142:143], v[78:79] neg_lo:[0,0,1] neg_hi:[0,0,1]
	v_pk_mul_f32 v[84:85], v[70:71], v[68:69]
	v_pk_mul_f32 v[70:71], v[70:71], v[76:77]
	v_pk_mul_f32 v[86:87], v[132:133], v[142:143]
	v_pk_fma_f32 v[84:85], v[78:79], v[76:77], v[84:85] neg_lo:[0,0,1] neg_hi:[0,0,1]
	v_pk_fma_f32 v[68:69], v[78:79], v[68:69], v[70:71]
	v_pk_mul_f32 v[76:77], v[132:133], v[170:171]
	v_mov_b32_e32 v78, v65
	v_mov_b32_e32 v79, v67
	v_pk_fma_f32 v[86:87], v[130:131], v[170:171], v[86:87]
	v_mov_b32_e32 v65, v66
	v_mov_b32_e32 v70, v73
	v_mov_b32_e32 v71, v75
	v_pk_fma_f32 v[76:77], v[130:131], v[142:143], v[76:77] neg_lo:[0,0,1] neg_hi:[0,0,1]
	v_pk_mul_f32 v[186:187], v[86:87], v[78:79]
	v_mov_b32_e32 v73, v74
	v_pk_mul_f32 v[66:67], v[170:171], v[64:65]
	v_pk_fma_f32 v[186:187], v[76:77], v[70:71], v[186:187] neg_lo:[0,0,1] neg_hi:[0,0,1]
	v_pk_mul_f32 v[70:71], v[86:87], v[70:71]
	v_pk_fma_f32 v[66:67], v[142:143], v[72:73], v[66:67] neg_lo:[0,0,1] neg_hi:[0,0,1]
	v_pk_mul_f32 v[72:73], v[170:171], v[72:73]
	v_mov_b32_e32 v74, v57
	v_mov_b32_e32 v75, v59
	v_mov_b32_e32 v57, v58
	v_pk_fma_f32 v[70:71], v[76:77], v[78:79], v[70:71]
	v_pk_fma_f32 v[64:65], v[142:143], v[64:65], v[72:73]
	v_mov_b32_e32 v72, v61
	v_mov_b32_e32 v73, v63
	v_pk_mul_f32 v[76:77], v[174:175], v[74:75]
	v_mov_b32_e32 v61, v62
	v_pk_mul_f32 v[58:59], v[176:177], v[56:57]
	v_pk_fma_f32 v[76:77], v[166:167], v[72:73], v[76:77] neg_lo:[0,0,1] neg_hi:[0,0,1]
	v_pk_mul_f32 v[72:73], v[174:175], v[72:73]
	v_pk_fma_f32 v[58:59], v[94:95], v[60:61], v[58:59] neg_lo:[0,0,1] neg_hi:[0,0,1]
	v_pk_mul_f32 v[60:61], v[176:177], v[60:61]
	v_mov_b32_e32 v62, v17
	v_mov_b32_e32 v63, v19
	v_mov_b32_e32 v17, v18
	v_pk_fma_f32 v[72:73], v[166:167], v[74:75], v[72:73]
	v_pk_fma_f32 v[56:57], v[94:95], v[56:57], v[60:61]
	v_mov_b32_e32 v60, v21
	v_mov_b32_e32 v61, v23
	v_pk_mul_f32 v[74:75], v[62:63], v[178:179]
	v_mov_b32_e32 v21, v22
	v_pk_mul_f32 v[18:19], v[16:17], v[140:141]
	v_pk_fma_f32 v[74:75], v[60:61], v[92:93], v[74:75] neg_lo:[0,0,1] neg_hi:[0,0,1]
	v_pk_mul_f32 v[60:61], v[60:61], v[178:179]
	v_pk_fma_f32 v[18:19], v[138:139], v[20:21], v[18:19] neg_lo:[0,0,1] neg_hi:[0,0,1]
	v_pk_mul_f32 v[20:21], v[140:141], v[20:21]
	v_mov_b32_e32 v22, v9
	v_mov_b32_e32 v23, v11
	v_mov_b32_e32 v9, v10
	v_pk_fma_f32 v[60:61], v[62:63], v[92:93], v[60:61]
	v_pk_fma_f32 v[16:17], v[16:17], v[138:139], v[20:21]
	v_mov_b32_e32 v20, v13
	v_mov_b32_e32 v21, v15
	v_pk_mul_f32 v[62:63], v[22:23], v[164:165]
	v_mov_b32_e32 v13, v14
	v_pk_mul_f32 v[10:11], v[8:9], v[136:137]
	v_pk_fma_f32 v[62:63], v[20:21], v[144:145], v[62:63] neg_lo:[0,0,1] neg_hi:[0,0,1]
	v_pk_mul_f32 v[20:21], v[20:21], v[164:165]
	v_pk_fma_f32 v[10:11], v[12:13], v[134:135], v[10:11] neg_lo:[0,0,1] neg_hi:[0,0,1]
	v_pk_mul_f32 v[12:13], v[12:13], v[136:137]
	v_mov_b32_e32 v14, v1
	v_mov_b32_e32 v15, v3
	v_pk_fma_f32 v[20:21], v[22:23], v[144:145], v[20:21]
	v_pk_fma_f32 v[8:9], v[8:9], v[134:135], v[12:13]
	v_mov_b32_e32 v12, v5
	v_mov_b32_e32 v13, v7
	v_pk_mul_f32 v[22:23], v[14:15], v[132:133]
	v_mov_b32_e32 v1, v2
	v_lshl_or_b32 v2, v168, 6, v162
	v_lshlrev_b32_e32 v3, 2, v168
	v_pk_fma_f32 v[22:23], v[12:13], v[130:131], v[22:23] neg_lo:[0,0,1] neg_hi:[0,0,1]
	v_pk_mul_f32 v[12:13], v[12:13], v[132:133]
	v_mov_b32_e32 v5, v6
	v_add_lshl_u32 v2, v2, v3, 2
	v_pk_fma_f32 v[12:13], v[14:15], v[130:131], v[12:13]
	v_add_u32_e32 v132, 0, v2
	v_add_u32_e32 v133, s91, v2
	v_pk_add_f32 v[2:3], v[0:1], v[64:65]
	v_pk_add_f32 v[6:7], v[4:5], v[66:67]
	v_pk_add_f32 v[0:1], v[0:1], v[64:65] neg_lo:[0,1] neg_hi:[0,1]
	v_pk_add_f32 v[4:5], v[4:5], v[66:67] neg_lo:[0,1] neg_hi:[0,1]
	v_pk_add_f32 v[14:15], v[16:17], v[80:81]
	v_pk_add_f32 v[64:65], v[18:19], v[184:185]
	v_pk_add_f32 v[16:17], v[16:17], v[80:81] neg_lo:[0,1] neg_hi:[0,1]
	v_pk_add_f32 v[18:19], v[18:19], v[184:185] neg_lo:[0,1] neg_hi:[0,1]
	v_pk_add_f32 v[66:67], v[8:9], v[68:69]
	v_pk_add_f32 v[78:79], v[10:11], v[84:85]
	v_pk_add_f32 v[8:9], v[8:9], v[68:69] neg_lo:[0,1] neg_hi:[0,1]
	v_pk_add_f32 v[68:69], v[56:57], v[88:89]
	v_pk_add_f32 v[80:81], v[58:59], v[180:181]
	v_pk_add_f32 v[58:59], v[58:59], v[180:181] neg_lo:[0,1] neg_hi:[0,1]
	v_pk_add_f32 v[10:11], v[10:11], v[84:85] neg_lo:[0,1] neg_hi:[0,1]
	v_pk_add_f32 v[56:57], v[56:57], v[88:89] neg_lo:[0,1] neg_hi:[0,1]
	v_pk_add_f32 v[84:85], v[12:13], v[70:71]
	v_pk_add_f32 v[12:13], v[12:13], v[70:71] neg_lo:[0,1] neg_hi:[0,1]
	v_pk_add_f32 v[70:71], v[60:61], v[90:91]
	v_pk_add_f32 v[60:61], v[60:61], v[90:91] neg_lo:[0,1] neg_hi:[0,1]
	v_pk_add_f32 v[90:91], v[20:21], v[82:83]
	v_pk_add_f32 v[20:21], v[20:21], v[82:83] neg_lo:[0,1] neg_hi:[0,1]
	v_pk_add_f32 v[82:83], v[72:73], v[96:97]
	v_pk_add_f32 v[72:73], v[72:73], v[96:97] neg_lo:[0,1] neg_hi:[0,1]
	v_pk_add_f32 v[96:97], v[2:3], v[14:15]
	v_pk_add_f32 v[130:131], v[6:7], v[64:65]
	v_pk_add_f32 v[2:3], v[2:3], v[14:15] neg_lo:[0,1] neg_hi:[0,1]
	v_pk_add_f32 v[6:7], v[6:7], v[64:65] neg_lo:[0,1] neg_hi:[0,1]
	v_pk_add_f32 v[14:15], v[0:1], v[18:19] neg_lo:[0,1] neg_hi:[0,1]
	v_pk_add_f32 v[64:65], v[4:5], v[16:17]
	v_pk_add_f32 v[0:1], v[0:1], v[18:19]
	v_pk_add_f32 v[4:5], v[4:5], v[16:17] neg_lo:[0,1] neg_hi:[0,1]
	v_pk_add_f32 v[16:17], v[66:67], v[68:69]
	v_pk_add_f32 v[18:19], v[78:79], v[80:81]
	v_pk_add_f32 v[66:67], v[66:67], v[68:69] neg_lo:[0,1] neg_hi:[0,1]
	v_pk_add_f32 v[68:69], v[78:79], v[80:81] neg_lo:[0,1] neg_hi:[0,1]
	v_pk_add_f32 v[78:79], v[8:9], v[58:59] neg_lo:[0,1] neg_hi:[0,1]
	v_pk_add_f32 v[86:87], v[22:23], v[186:187]
	v_pk_add_f32 v[22:23], v[22:23], v[186:187] neg_lo:[0,1] neg_hi:[0,1]
	v_pk_add_f32 v[88:89], v[74:75], v[190:191]
	v_pk_add_f32 v[74:75], v[74:75], v[190:191] neg_lo:[0,1] neg_hi:[0,1]
	v_pk_add_f32 v[92:93], v[62:63], v[188:189]
	v_pk_add_f32 v[62:63], v[62:63], v[188:189] neg_lo:[0,1] neg_hi:[0,1]
	v_pk_add_f32 v[94:95], v[76:77], v[182:183]
	v_pk_add_f32 v[80:81], v[10:11], v[56:57]
	v_pk_add_f32 v[10:11], v[10:11], v[56:57] neg_lo:[0,1] neg_hi:[0,1]
	v_pk_mul_f32 v[78:79], v[78:79], s[82:83] op_sel_hi:[1,0]
	v_pk_add_f32 v[76:77], v[76:77], v[182:183] neg_lo:[0,1] neg_hi:[0,1]
	v_pk_add_f32 v[8:9], v[8:9], v[58:59]
	v_pk_add_f32 v[56:57], v[84:85], v[70:71]
	v_pk_add_f32 v[58:59], v[86:87], v[88:89]
	v_pk_add_f32 v[70:71], v[84:85], v[70:71] neg_lo:[0,1] neg_hi:[0,1]
	v_pk_add_f32 v[84:85], v[86:87], v[88:89] neg_lo:[0,1] neg_hi:[0,1]
	v_pk_add_f32 v[86:87], v[12:13], v[74:75] neg_lo:[0,1] neg_hi:[0,1]
	v_pk_add_f32 v[88:89], v[22:23], v[60:61]
	v_pk_add_f32 v[12:13], v[12:13], v[74:75]
	v_pk_add_f32 v[22:23], v[22:23], v[60:61] neg_lo:[0,1] neg_hi:[0,1]
	v_pk_add_f32 v[60:61], v[90:91], v[82:83]
	v_pk_add_f32 v[74:75], v[92:93], v[94:95]
	v_pk_add_f32 v[82:83], v[90:91], v[82:83] neg_lo:[0,1] neg_hi:[0,1]
	v_pk_add_f32 v[90:91], v[92:93], v[94:95] neg_lo:[0,1] neg_hi:[0,1]
	v_pk_add_f32 v[94:95], v[62:63], v[72:73]
	v_pk_add_f32 v[62:63], v[62:63], v[72:73] neg_lo:[0,1] neg_hi:[0,1]
	v_pk_add_f32 v[72:73], v[96:97], v[16:17]
	v_pk_add_f32 v[16:17], v[96:97], v[16:17] neg_lo:[0,1] neg_hi:[0,1]
	v_pk_fma_f32 v[96:97], v[80:81], s[82:83], v[78:79] op_sel_hi:[1,0,1] neg_lo:[1,0,0] neg_hi:[1,0,0]
	v_pk_mul_f32 v[10:11], v[10:11], s[82:83] op_sel_hi:[1,0]
	v_pk_add_f32 v[92:93], v[20:21], v[76:77] neg_lo:[0,1] neg_hi:[0,1]
	v_pk_fma_f32 v[78:79], v[80:81], s[82:83], v[78:79] op_sel_hi:[1,0,1]
	v_pk_add_f32 v[80:81], v[14:15], v[96:97]
	v_pk_add_f32 v[14:15], v[14:15], v[96:97] neg_lo:[0,1] neg_hi:[0,1]
	v_pk_add_f32 v[96:97], v[6:7], v[66:67]
	v_pk_add_f32 v[6:7], v[6:7], v[66:67] neg_lo:[0,1] neg_hi:[0,1]
	v_pk_fma_f32 v[66:67], v[8:9], s[54:55], v[10:11] op_sel_hi:[1,0,1] neg_lo:[0,0,1] neg_hi:[0,0,1]
	v_pk_fma_f32 v[8:9], v[8:9], s[82:83], v[10:11] op_sel_hi:[1,0,1] neg_lo:[0,0,1] neg_hi:[0,0,1]
	v_pk_add_f32 v[20:21], v[20:21], v[76:77]
	v_pk_add_f32 v[76:77], v[130:131], v[18:19]
	v_pk_add_f32 v[18:19], v[130:131], v[18:19] neg_lo:[0,1] neg_hi:[0,1]
	v_pk_add_f32 v[130:131], v[64:65], v[78:79]
	v_pk_add_f32 v[64:65], v[64:65], v[78:79] neg_lo:[0,1] neg_hi:[0,1]
	v_pk_add_f32 v[78:79], v[2:3], v[68:69] neg_lo:[0,1] neg_hi:[0,1]
	v_pk_add_f32 v[2:3], v[2:3], v[68:69]
	v_pk_add_f32 v[68:69], v[4:5], v[8:9]
	v_pk_add_f32 v[4:5], v[4:5], v[8:9] neg_lo:[0,1] neg_hi:[0,1]
	v_pk_add_f32 v[8:9], v[56:57], v[60:61]
	v_pk_add_f32 v[56:57], v[56:57], v[60:61] neg_lo:[0,1] neg_hi:[0,1]
	v_pk_mul_f32 v[60:61], v[92:93], s[82:83] op_sel_hi:[1,0]
	v_pk_add_f32 v[10:11], v[0:1], v[66:67]
	v_pk_add_f32 v[0:1], v[0:1], v[66:67] neg_lo:[0,1] neg_hi:[0,1]
	v_pk_add_f32 v[66:67], v[58:59], v[74:75]
	v_pk_add_f32 v[58:59], v[58:59], v[74:75] neg_lo:[0,1] neg_hi:[0,1]
	v_pk_fma_f32 v[74:75], v[94:95], s[82:83], v[60:61] op_sel_hi:[1,0,1] neg_lo:[1,0,0] neg_hi:[1,0,0]
	v_pk_fma_f32 v[60:61], v[94:95], s[82:83], v[60:61] op_sel_hi:[1,0,1]
	v_pk_mul_f32 v[62:63], v[62:63], s[82:83] op_sel_hi:[1,0]
	v_pk_add_f32 v[94:95], v[88:89], v[60:61]
	v_pk_add_f32 v[60:61], v[88:89], v[60:61] neg_lo:[0,1] neg_hi:[0,1]
	v_pk_add_f32 v[88:89], v[84:85], v[82:83]
	v_pk_add_f32 v[82:83], v[84:85], v[82:83] neg_lo:[0,1] neg_hi:[0,1]
	v_pk_fma_f32 v[84:85], v[20:21], s[54:55], v[62:63] op_sel_hi:[1,0,1] neg_lo:[0,0,1] neg_hi:[0,0,1]
	v_pk_fma_f32 v[20:21], v[20:21], s[82:83], v[62:63] op_sel_hi:[1,0,1] neg_lo:[0,0,1] neg_hi:[0,0,1]
	v_pk_add_f32 v[92:93], v[86:87], v[74:75]
	v_pk_add_f32 v[74:75], v[86:87], v[74:75] neg_lo:[0,1] neg_hi:[0,1]
	v_pk_add_f32 v[86:87], v[70:71], v[90:91] neg_lo:[0,1] neg_hi:[0,1]
	v_pk_add_f32 v[70:71], v[70:71], v[90:91]
	v_pk_add_f32 v[90:91], v[22:23], v[20:21]
	v_pk_add_f32 v[20:21], v[22:23], v[20:21] neg_lo:[0,1] neg_hi:[0,1]
	v_pk_add_f32 v[22:23], v[72:73], v[8:9]
	v_pk_add_f32 v[8:9], v[72:73], v[8:9] neg_lo:[0,1] neg_hi:[0,1]
	v_pk_mul_f32 v[72:73], v[94:95], s[80:81] op_sel_hi:[1,0]
	v_pk_add_f32 v[62:63], v[12:13], v[84:85]
	v_pk_add_f32 v[12:13], v[12:13], v[84:85] neg_lo:[0,1] neg_hi:[0,1]
	v_pk_add_f32 v[84:85], v[76:77], v[66:67]
	v_pk_add_f32 v[66:67], v[76:77], v[66:67] neg_lo:[0,1] neg_hi:[0,1]
	v_pk_fma_f32 v[72:73], v[92:93], s[72:73], v[72:73] op_sel_hi:[1,0,1] neg_lo:[0,0,1] neg_hi:[0,0,1]
	v_pk_mul_f32 v[76:77], v[94:95], s[72:73] op_sel_hi:[1,0]
	s_andn2_b64 vcc, exec, s[2:3]
	v_pk_fma_f32 v[76:77], v[92:93], s[80:81], v[76:77] op_sel_hi:[1,0,1]
	v_pk_add_f32 v[92:93], v[80:81], v[72:73]
	v_pk_add_f32 v[72:73], v[80:81], v[72:73] neg_lo:[0,1] neg_hi:[0,1]
	v_pk_mul_f32 v[80:81], v[86:87], s[82:83] op_sel_hi:[1,0]
	v_pk_add_f32 v[94:95], v[130:131], v[76:77]
	v_pk_fma_f32 v[86:87], v[88:89], s[82:83], v[80:81] op_sel_hi:[1,0,1] neg_lo:[1,0,0] neg_hi:[1,0,0]
	v_pk_fma_f32 v[80:81], v[88:89], s[82:83], v[80:81] op_sel_hi:[1,0,1]
	v_pk_add_f32 v[88:89], v[78:79], v[86:87]
	v_pk_add_f32 v[78:79], v[78:79], v[86:87] neg_lo:[0,1] neg_hi:[0,1]
	v_pk_mul_f32 v[86:87], v[90:91], s[72:73] op_sel_hi:[1,0]
	v_pk_mul_f32 v[90:91], v[90:91], s[80:81] op_sel_hi:[1,0]
	v_pk_fma_f32 v[86:87], v[62:63], s[80:81], v[86:87] op_sel_hi:[1,0,1] neg_lo:[0,0,1] neg_hi:[0,0,1]
	v_pk_fma_f32 v[62:63], v[62:63], s[72:73], v[90:91] op_sel_hi:[1,0,1]
	v_pk_add_f32 v[76:77], v[130:131], v[76:77] neg_lo:[0,1] neg_hi:[0,1]
	v_pk_add_f32 v[130:131], v[96:97], v[80:81]
	v_pk_add_f32 v[80:81], v[96:97], v[80:81] neg_lo:[0,1] neg_hi:[0,1]
	v_pk_add_f32 v[90:91], v[10:11], v[86:87]
	v_pk_add_f32 v[96:97], v[68:69], v[62:63]
	v_pk_add_f32 v[10:11], v[10:11], v[86:87] neg_lo:[0,1] neg_hi:[0,1]
	v_pk_add_f32 v[62:63], v[68:69], v[62:63] neg_lo:[0,1] neg_hi:[0,1]
	v_pk_add_f32 v[68:69], v[16:17], v[58:59] neg_lo:[0,1] neg_hi:[0,1]
	v_pk_add_f32 v[86:87], v[18:19], v[56:57]
	v_pk_add_f32 v[16:17], v[16:17], v[58:59]
	v_pk_add_f32 v[18:19], v[18:19], v[56:57] neg_lo:[0,1] neg_hi:[0,1]
	v_pk_mul_f32 v[56:57], v[60:61], s[72:73] op_sel_hi:[1,0]
	v_pk_mul_f32 v[58:59], v[60:61], s[80:81] op_sel_hi:[1,0]
	v_pk_fma_f32 v[56:57], v[74:75], s[84:85], v[56:57] op_sel_hi:[1,0,1] neg_lo:[0,0,1] neg_hi:[0,0,1]
	v_pk_fma_f32 v[58:59], v[74:75], s[72:73], v[58:59] op_sel_hi:[1,0,1] neg_lo:[0,0,1] neg_hi:[0,0,1]
	v_pk_add_f32 v[60:61], v[14:15], v[56:57]
	v_pk_add_f32 v[74:75], v[64:65], v[58:59]
	v_pk_add_f32 v[14:15], v[14:15], v[56:57] neg_lo:[0,1] neg_hi:[0,1]
	v_pk_add_f32 v[56:57], v[64:65], v[58:59] neg_lo:[0,1] neg_hi:[0,1]
	v_pk_mul_f32 v[58:59], v[82:83], s[82:83] op_sel_hi:[1,0]
	s_mov_b64 s[2:3], 0
	v_pk_fma_f32 v[64:65], v[70:71], s[54:55], v[58:59] op_sel_hi:[1,0,1] neg_lo:[0,0,1] neg_hi:[0,0,1]
	v_pk_fma_f32 v[58:59], v[70:71], s[82:83], v[58:59] op_sel_hi:[1,0,1] neg_lo:[0,0,1] neg_hi:[0,0,1]
	v_pk_add_f32 v[70:71], v[2:3], v[64:65]
	v_pk_add_f32 v[82:83], v[6:7], v[58:59]
	v_pk_add_f32 v[6:7], v[6:7], v[58:59] neg_lo:[0,1] neg_hi:[0,1]
	v_pk_mul_f32 v[58:59], v[20:21], s[80:81] op_sel_hi:[1,0]
	v_pk_mul_f32 v[20:21], v[20:21], s[72:73] op_sel_hi:[1,0]
	v_pk_fma_f32 v[58:59], v[12:13], s[52:53], v[58:59] op_sel_hi:[1,0,1] neg_lo:[0,0,1] neg_hi:[0,0,1]
	v_pk_fma_f32 v[12:13], v[12:13], s[80:81], v[20:21] op_sel_hi:[1,0,1] neg_lo:[0,0,1] neg_hi:[0,0,1]
	v_pk_add_f32 v[20:21], v[0:1], v[58:59]
	v_pk_add_f32 v[0:1], v[0:1], v[58:59] neg_lo:[0,1] neg_hi:[0,1]
	v_pk_add_f32 v[2:3], v[2:3], v[64:65] neg_lo:[0,1] neg_hi:[0,1]
	v_pk_add_f32 v[64:65], v[4:5], v[12:13]
	v_pk_add_f32 v[4:5], v[4:5], v[12:13] neg_lo:[0,1] neg_hi:[0,1]
	ds_write2_b64 v132, v[22:23], v[92:93] offset1:2
	ds_write2_b64 v133, v[84:85], v[94:95] offset1:2
	ds_write2_b64 v132, v[88:89], v[90:91] offset0:4 offset1:6
	ds_write2_b64 v133, v[130:131], v[96:97] offset0:4 offset1:6
	ds_write2_b64 v132, v[68:69], v[60:61] offset0:8 offset1:10
	ds_write2_b64 v133, v[86:87], v[74:75] offset0:8 offset1:10
	ds_write2_b64 v132, v[70:71], v[20:21] offset0:12 offset1:14
	ds_write2_b64 v133, v[82:83], v[64:65] offset0:12 offset1:14
	ds_write2_b64 v132, v[8:9], v[72:73] offset0:16 offset1:18
	ds_write2_b64 v133, v[66:67], v[76:77] offset0:16 offset1:18
	ds_write2_b64 v132, v[78:79], v[10:11] offset0:20 offset1:22
	ds_write2_b64 v133, v[80:81], v[62:63] offset0:20 offset1:22
	ds_write2_b64 v132, v[16:17], v[14:15] offset0:24 offset1:26
	ds_write2_b64 v133, v[18:19], v[56:57] offset0:24 offset1:26
	ds_write2_b64 v132, v[2:3], v[0:1] offset0:28 offset1:30
	ds_write2_b64 v133, v[6:7], v[4:5] offset0:28 offset1:30
	v_mov_b32_e32 v0, v163
	s_waitcnt lgkmcnt(0)
	s_barrier
	s_nop 0
	s_nop 0
	v_lshlrev_b32_e32 v1, 1, v0
	v_and_b32_e32 v97, 62, v1
	v_ashrrev_i32_e32 v1, 31, v0
	v_lshrrev_b32_e32 v1, 27, v1
	v_add_u32_e32 v0, v0, v1
	v_ashrrev_i32_e32 v0, 5, v0
	v_lshl_or_b32 v1, v0, 10, v97
	v_cvt_f32_ubyte0_e32 v96, v97
	v_or_b32_e32 v97, 1, v97
	v_cvt_f32_ubyte0_e32 v97, v97
	v_mul_f32_e32 v130, 0x3a800000, v96
	v_mul_f32_e32 v131, 0x3a800000, v97
	v_cos_f32_e32 v96, v130
	v_cos_f32_e32 v97, v131
	v_sin_f32_e64 v130, -v130
	v_sin_f32_e64 v131, -v131
	v_lshlrev_b32_e32 v0, 6, v0
	v_add_lshl_u32 v0, v1, v0, 2
	v_add_u32_e32 v162, 0, v0
	v_pk_mul_f32 v[132:133], v[130:131], v[130:131]
	v_pk_mul_f32 v[134:135], v[96:97], v[130:131]
	v_add_u32_e32 v168, s91, v0
	v_pk_fma_f32 v[132:133], v[96:97], v[96:97], v[132:133] neg_lo:[0,0,1] neg_hi:[0,0,1]
	v_pk_add_f32 v[134:135], v[134:135], v[134:135]
	v_add_u32_e32 v180, 0x800, v168
	v_add_u32_e32 v181, 0x800, v162
	v_pk_mul_f32 v[136:137], v[134:135], v[134:135]
	v_pk_mul_f32 v[138:139], v[132:133], v[134:135]
	v_pk_mul_f32 v[144:145], v[130:131], v[132:133]
	ds_read2_b64 v[0:3], v162 offset1:34
	ds_read2_b64 v[4:7], v168 offset1:34
	ds_read2_b64 v[8:11], v180 offset0:16 offset1:50
	ds_read2_b64 v[12:15], v181 offset0:16 offset1:50
	ds_read2_b64 v[16:19], v168 offset0:136 offset1:170
	ds_read2_b64 v[20:23], v162 offset0:136 offset1:170
	ds_read2_b64 v[56:59], v180 offset0:152 offset1:186
	ds_read2_b64 v[60:63], v181 offset0:152 offset1:186
	ds_read2_b64 v[64:67], v168 offset0:68 offset1:102
	ds_read2_b64 v[68:71], v162 offset0:68 offset1:102
	ds_read2_b64 v[72:75], v180 offset0:84 offset1:118
	ds_read2_b64 v[76:79], v181 offset0:84 offset1:118
	ds_read2_b64 v[80:83], v168 offset0:204 offset1:238
	ds_read2_b64 v[84:87], v162 offset0:204 offset1:238
	ds_read2_b64 v[88:91], v180 offset0:220 offset1:254
	ds_read2_b64 v[92:95], v181 offset0:220 offset1:254
	v_pk_fma_f32 v[136:137], v[132:133], v[132:133], v[136:137] neg_lo:[0,0,1] neg_hi:[0,0,1]
	v_pk_add_f32 v[138:139], v[138:139], v[138:139]
	v_pk_mul_f32 v[142:143], v[130:131], v[134:135]
	v_pk_fma_f32 v[144:145], v[96:97], v[134:135], v[144:145]
	v_pk_mul_f32 v[140:141], v[138:139], v[138:139]
	v_pk_fma_f32 v[142:143], v[96:97], v[132:133], v[142:143] neg_lo:[0,0,1] neg_hi:[0,0,1]
	v_pk_mul_f32 v[166:167], v[136:137], v[138:139]
	v_pk_mul_f32 v[170:171], v[136:137], v[144:145]
	v_pk_fma_f32 v[140:141], v[136:137], v[136:137], v[140:141] neg_lo:[0,0,1] neg_hi:[0,0,1]
	v_pk_mul_f32 v[164:165], v[138:139], v[144:145]
	v_pk_add_f32 v[166:167], v[166:167], v[166:167]
	v_pk_fma_f32 v[170:171], v[138:139], v[142:143], v[170:171]
	v_pk_fma_f32 v[164:165], v[136:137], v[142:143], v[164:165] neg_lo:[0,0,1] neg_hi:[0,0,1]
	v_pk_mul_f32 v[174:175], v[166:167], v[170:171]
	v_pk_mul_f32 v[176:177], v[140:141], v[170:171]
	v_pk_fma_f32 v[174:175], v[140:141], v[164:165], v[174:175] neg_lo:[0,0,1] neg_hi:[0,0,1]
	v_pk_fma_f32 v[176:177], v[166:167], v[164:165], v[176:177]
	s_waitcnt lgkmcnt(0)
	v_pk_mul_f32 v[178:179], v[176:177], v[94:95]
	v_pk_mul_f32 v[94:95], v[174:175], v[94:95]
	v_pk_fma_f32 v[178:179], v[174:175], v[90:91], v[178:179] neg_lo:[0,0,1] neg_hi:[0,0,1]
	v_pk_fma_f32 v[90:91], v[176:177], v[90:91], v[94:95]
	v_pk_mul_f32 v[94:95], v[170:171], v[86:87]
	v_pk_mul_f32 v[86:87], v[164:165], v[86:87]
	v_pk_fma_f32 v[94:95], v[164:165], v[82:83], v[94:95] neg_lo:[0,0,1] neg_hi:[0,0,1]
	v_pk_fma_f32 v[82:83], v[170:171], v[82:83], v[86:87]
	v_pk_mul_f32 v[86:87], v[144:145], v[166:167]
	v_pk_mul_f32 v[164:165], v[144:145], v[140:141]
	v_pk_fma_f32 v[86:87], v[142:143], v[140:141], v[86:87] neg_lo:[0,0,1] neg_hi:[0,0,1]
	v_pk_fma_f32 v[164:165], v[142:143], v[166:167], v[164:165]
	s_nop 0
	v_pk_mul_f32 v[170:171], v[164:165], v[78:79]
	v_pk_mul_f32 v[78:79], v[86:87], v[78:79]
	v_pk_fma_f32 v[170:171], v[86:87], v[74:75], v[170:171] neg_lo:[0,0,1] neg_hi:[0,0,1]
	v_pk_fma_f32 v[74:75], v[164:165], v[74:75], v[78:79]
	v_pk_mul_f32 v[78:79], v[144:145], v[70:71]
	v_pk_mul_f32 v[70:71], v[142:143], v[70:71]
	v_pk_mul_f32 v[86:87], v[130:131], v[136:137]
	v_pk_fma_f32 v[78:79], v[142:143], v[66:67], v[78:79] neg_lo:[0,0,1] neg_hi:[0,0,1]
	v_pk_fma_f32 v[66:67], v[144:145], v[66:67], v[70:71]
	v_pk_mul_f32 v[70:71], v[130:131], v[138:139]
	v_pk_fma_f32 v[86:87], v[96:97], v[138:139], v[86:87]
	v_pk_fma_f32 v[70:71], v[96:97], v[136:137], v[70:71] neg_lo:[0,0,1] neg_hi:[0,0,1]
	v_pk_mul_f32 v[142:143], v[166:167], v[86:87]
	v_pk_mul_f32 v[144:145], v[140:141], v[86:87]
	v_pk_fma_f32 v[142:143], v[140:141], v[70:71], v[142:143] neg_lo:[0,0,1] neg_hi:[0,0,1]
	v_pk_fma_f32 v[144:145], v[166:167], v[70:71], v[144:145]
	s_nop 0
	v_pk_mul_f32 v[164:165], v[144:145], v[62:63]
	v_pk_mul_f32 v[62:63], v[142:143], v[62:63]
	v_pk_fma_f32 v[164:165], v[142:143], v[58:59], v[164:165] neg_lo:[0,0,1] neg_hi:[0,0,1]
	v_pk_fma_f32 v[58:59], v[144:145], v[58:59], v[62:63]
	v_pk_mul_f32 v[62:63], v[86:87], v[22:23]
	v_pk_mul_f32 v[22:23], v[70:71], v[22:23]
	v_pk_fma_f32 v[62:63], v[70:71], v[18:19], v[62:63] neg_lo:[0,0,1] neg_hi:[0,0,1]
	v_pk_fma_f32 v[18:19], v[86:87], v[18:19], v[22:23]
	v_pk_mul_f32 v[22:23], v[130:131], v[166:167]
	v_pk_mul_f32 v[70:71], v[130:131], v[140:141]
	v_pk_fma_f32 v[22:23], v[96:97], v[140:141], v[22:23] neg_lo:[0,0,1] neg_hi:[0,0,1]
	v_pk_fma_f32 v[70:71], v[96:97], v[166:167], v[70:71]
	s_nop 0
	v_pk_mul_f32 v[86:87], v[70:71], v[14:15]
	v_pk_mul_f32 v[14:15], v[22:23], v[14:15]
	v_pk_fma_f32 v[86:87], v[22:23], v[10:11], v[86:87] neg_lo:[0,0,1] neg_hi:[0,0,1]
	v_pk_fma_f32 v[10:11], v[70:71], v[10:11], v[14:15]
	v_pk_mul_f32 v[14:15], v[130:131], v[2:3]
	v_pk_mul_f32 v[2:3], v[96:97], v[2:3]
	v_pk_mul_f32 v[22:23], v[134:135], v[136:137]
	v_pk_fma_f32 v[14:15], v[96:97], v[6:7], v[14:15] neg_lo:[0,0,1] neg_hi:[0,0,1]
	v_pk_fma_f32 v[2:3], v[130:131], v[6:7], v[2:3]
	v_pk_mul_f32 v[6:7], v[134:135], v[138:139]
	v_pk_fma_f32 v[22:23], v[132:133], v[138:139], v[22:23]
	v_pk_fma_f32 v[6:7], v[132:133], v[136:137], v[6:7] neg_lo:[0,0,1] neg_hi:[0,0,1]
	v_pk_mul_f32 v[96:97], v[140:141], v[22:23]
	v_pk_mul_f32 v[70:71], v[166:167], v[22:23]
	v_pk_fma_f32 v[96:97], v[166:167], v[6:7], v[96:97]
	v_pk_fma_f32 v[70:71], v[140:141], v[6:7], v[70:71] neg_lo:[0,0,1] neg_hi:[0,0,1]
	v_pk_mul_f32 v[130:131], v[96:97], v[92:93]
	s_nop 0
	v_pk_fma_f32 v[130:131], v[88:89], v[70:71], v[130:131] neg_lo:[0,0,1] neg_hi:[0,0,1]
	v_pk_mul_f32 v[70:71], v[70:71], v[92:93]
	v_pk_add_f32 v[92:93], v[78:79], v[170:171]
	v_pk_fma_f32 v[70:71], v[88:89], v[96:97], v[70:71]
	v_pk_mul_f32 v[88:89], v[22:23], v[84:85]
	v_pk_add_f32 v[96:97], v[94:95], v[178:179]
	v_pk_fma_f32 v[88:89], v[80:81], v[6:7], v[88:89] neg_lo:[0,0,1] neg_hi:[0,0,1]
	v_pk_mul_f32 v[6:7], v[6:7], v[84:85]
	s_nop 0
	v_pk_fma_f32 v[6:7], v[80:81], v[22:23], v[6:7]
	v_pk_mul_f32 v[80:81], v[134:135], v[140:141]
	v_pk_mul_f32 v[22:23], v[134:135], v[166:167]
	v_pk_fma_f32 v[80:81], v[132:133], v[166:167], v[80:81]
	v_pk_fma_f32 v[22:23], v[132:133], v[140:141], v[22:23] neg_lo:[0,0,1] neg_hi:[0,0,1]
	v_pk_mul_f32 v[84:85], v[76:77], v[80:81]
	s_nop 0
	v_pk_fma_f32 v[84:85], v[72:73], v[22:23], v[84:85] neg_lo:[0,0,1] neg_hi:[0,0,1]
	v_pk_mul_f32 v[72:73], v[72:73], v[80:81]
	s_nop 0
	v_pk_fma_f32 v[22:23], v[76:77], v[22:23], v[72:73]
	v_pk_mul_f32 v[72:73], v[134:135], v[68:69]
	v_pk_mul_f32 v[68:69], v[132:133], v[68:69]
	v_pk_mul_f32 v[76:77], v[138:139], v[140:141]
	v_pk_fma_f32 v[72:73], v[64:65], v[132:133], v[72:73] neg_lo:[0,0,1] neg_hi:[0,0,1]
	v_pk_fma_f32 v[64:65], v[64:65], v[134:135], v[68:69]
	v_pk_mul_f32 v[68:69], v[138:139], v[166:167]
	v_pk_fma_f32 v[76:77], v[136:137], v[166:167], v[76:77]
	v_pk_fma_f32 v[68:69], v[136:137], v[140:141], v[68:69] neg_lo:[0,0,1] neg_hi:[0,0,1]
	v_pk_mul_f32 v[80:81], v[60:61], v[76:77]
	s_nop 0
	v_pk_fma_f32 v[80:81], v[56:57], v[68:69], v[80:81] neg_lo:[0,0,1] neg_hi:[0,0,1]
	v_pk_mul_f32 v[56:57], v[56:57], v[76:77]
	v_pk_add_f32 v[76:77], v[72:73], v[84:85]
	v_pk_fma_f32 v[56:57], v[60:61], v[68:69], v[56:57]
	v_pk_mul_f32 v[60:61], v[20:21], v[138:139]
	s_nop 0
	v_pk_fma_f32 v[60:61], v[16:17], v[136:137], v[60:61] neg_lo:[0,0,1] neg_hi:[0,0,1]
	v_pk_mul_f32 v[16:17], v[16:17], v[138:139]
	s_nop 0
	v_pk_fma_f32 v[16:17], v[20:21], v[136:137], v[16:17]
	v_pk_mul_f32 v[20:21], v[12:13], v[166:167]
	s_nop 0
	v_pk_fma_f32 v[20:21], v[8:9], v[140:141], v[20:21] neg_lo:[0,0,1] neg_hi:[0,0,1]
	v_pk_mul_f32 v[8:9], v[8:9], v[166:167]
	v_pk_add_f32 v[68:69], v[4:5], v[20:21]
	v_pk_fma_f32 v[8:9], v[12:13], v[140:141], v[8:9]
	v_pk_add_f32 v[4:5], v[4:5], v[20:21] neg_lo:[0,1] neg_hi:[0,1]
	v_pk_add_f32 v[12:13], v[0:1], v[8:9]
	v_pk_add_f32 v[0:1], v[0:1], v[8:9] neg_lo:[0,1] neg_hi:[0,1]
	v_pk_add_f32 v[8:9], v[16:17], v[56:57]
	v_pk_add_f32 v[20:21], v[60:61], v[80:81]
	v_pk_add_f32 v[16:17], v[16:17], v[56:57] neg_lo:[0,1] neg_hi:[0,1]
	v_pk_add_f32 v[56:57], v[60:61], v[80:81] neg_lo:[0,1] neg_hi:[0,1]
	v_pk_add_f32 v[60:61], v[64:65], v[22:23]
	v_pk_add_f32 v[22:23], v[64:65], v[22:23] neg_lo:[0,1] neg_hi:[0,1]
	v_pk_add_f32 v[64:65], v[72:73], v[84:85] neg_lo:[0,1] neg_hi:[0,1]
	v_pk_add_f32 v[72:73], v[6:7], v[70:71]
	v_pk_add_f32 v[80:81], v[88:89], v[130:131]
	v_pk_add_f32 v[6:7], v[6:7], v[70:71] neg_lo:[0,1] neg_hi:[0,1]
	v_pk_add_f32 v[70:71], v[88:89], v[130:131] neg_lo:[0,1] neg_hi:[0,1]
	v_pk_add_f32 v[84:85], v[2:3], v[10:11]
	v_pk_add_f32 v[88:89], v[14:15], v[86:87]
	v_pk_add_f32 v[2:3], v[2:3], v[10:11] neg_lo:[0,1] neg_hi:[0,1]
	v_pk_add_f32 v[10:11], v[14:15], v[86:87] neg_lo:[0,1] neg_hi:[0,1]
	v_pk_add_f32 v[14:15], v[18:19], v[58:59]
	v_pk_add_f32 v[86:87], v[62:63], v[164:165]
	v_pk_add_f32 v[18:19], v[18:19], v[58:59] neg_lo:[0,1] neg_hi:[0,1]
	v_pk_add_f32 v[58:59], v[62:63], v[164:165] neg_lo:[0,1] neg_hi:[0,1]
	v_pk_add_f32 v[62:63], v[66:67], v[74:75]
	v_pk_add_f32 v[66:67], v[66:67], v[74:75] neg_lo:[0,1] neg_hi:[0,1]
	v_pk_add_f32 v[74:75], v[78:79], v[170:171] neg_lo:[0,1] neg_hi:[0,1]
	v_pk_add_f32 v[78:79], v[82:83], v[90:91]
	v_pk_add_f32 v[82:83], v[82:83], v[90:91] neg_lo:[0,1] neg_hi:[0,1]
	v_pk_add_f32 v[90:91], v[94:95], v[178:179] neg_lo:[0,1] neg_hi:[0,1]
	v_pk_add_f32 v[94:95], v[12:13], v[8:9]
	v_pk_add_f32 v[130:131], v[68:69], v[20:21]
	v_pk_add_f32 v[8:9], v[12:13], v[8:9] neg_lo:[0,1] neg_hi:[0,1]
	v_pk_add_f32 v[12:13], v[68:69], v[20:21] neg_lo:[0,1] neg_hi:[0,1]
	v_pk_add_f32 v[20:21], v[0:1], v[56:57] neg_lo:[0,1] neg_hi:[0,1]
	v_pk_add_f32 v[68:69], v[4:5], v[16:17]
	v_pk_add_f32 v[0:1], v[0:1], v[56:57]
	v_pk_add_f32 v[4:5], v[4:5], v[16:17] neg_lo:[0,1] neg_hi:[0,1]
	v_pk_add_f32 v[16:17], v[60:61], v[72:73]
	v_pk_add_f32 v[56:57], v[76:77], v[80:81]
	v_pk_add_f32 v[60:61], v[60:61], v[72:73] neg_lo:[0,1] neg_hi:[0,1]
	v_pk_add_f32 v[72:73], v[76:77], v[80:81] neg_lo:[0,1] neg_hi:[0,1]
	v_pk_add_f32 v[76:77], v[22:23], v[70:71] neg_lo:[0,1] neg_hi:[0,1]
	v_pk_add_f32 v[80:81], v[64:65], v[6:7]
	v_pk_add_f32 v[6:7], v[64:65], v[6:7] neg_lo:[0,1] neg_hi:[0,1]
	v_pk_mul_f32 v[76:77], v[76:77], s[82:83] op_sel_hi:[1,0]
	v_pk_add_f32 v[22:23], v[22:23], v[70:71]
	v_pk_add_f32 v[64:65], v[84:85], v[14:15]
	v_pk_add_f32 v[70:71], v[88:89], v[86:87]
	v_pk_add_f32 v[14:15], v[84:85], v[14:15] neg_lo:[0,1] neg_hi:[0,1]
	v_pk_add_f32 v[84:85], v[88:89], v[86:87] neg_lo:[0,1] neg_hi:[0,1]
	v_pk_add_f32 v[86:87], v[2:3], v[58:59] neg_lo:[0,1] neg_hi:[0,1]
	v_pk_add_f32 v[88:89], v[10:11], v[18:19]
	v_pk_add_f32 v[2:3], v[2:3], v[58:59]
	v_pk_add_f32 v[10:11], v[10:11], v[18:19] neg_lo:[0,1] neg_hi:[0,1]
	v_pk_add_f32 v[18:19], v[62:63], v[78:79]
	v_pk_add_f32 v[58:59], v[92:93], v[96:97]
	v_pk_add_f32 v[62:63], v[62:63], v[78:79] neg_lo:[0,1] neg_hi:[0,1]
	v_pk_add_f32 v[78:79], v[92:93], v[96:97] neg_lo:[0,1] neg_hi:[0,1]
	v_pk_add_f32 v[96:97], v[74:75], v[82:83]
	v_pk_add_f32 v[74:75], v[74:75], v[82:83] neg_lo:[0,1] neg_hi:[0,1]
	v_pk_add_f32 v[82:83], v[94:95], v[16:17]
	v_pk_add_f32 v[16:17], v[94:95], v[16:17] neg_lo:[0,1] neg_hi:[0,1]
	v_pk_fma_f32 v[94:95], v[80:81], s[82:83], v[76:77] op_sel_hi:[1,0,1] neg_lo:[1,0,0] neg_hi:[1,0,0]
	v_pk_mul_f32 v[6:7], v[6:7], s[82:83] op_sel_hi:[1,0]
	v_pk_add_f32 v[92:93], v[66:67], v[90:91] neg_lo:[0,1] neg_hi:[0,1]
	v_pk_fma_f32 v[76:77], v[80:81], s[82:83], v[76:77] op_sel_hi:[1,0,1]
	v_pk_add_f32 v[80:81], v[20:21], v[94:95]
	v_pk_add_f32 v[20:21], v[20:21], v[94:95] neg_lo:[0,1] neg_hi:[0,1]
	v_pk_add_f32 v[94:95], v[12:13], v[60:61]
	v_pk_add_f32 v[12:13], v[12:13], v[60:61] neg_lo:[0,1] neg_hi:[0,1]
	v_pk_fma_f32 v[60:61], v[22:23], s[54:55], v[6:7] op_sel_hi:[1,0,1] neg_lo:[0,0,1] neg_hi:[0,0,1]
	v_pk_fma_f32 v[6:7], v[22:23], s[82:83], v[6:7] op_sel_hi:[1,0,1] neg_lo:[0,0,1] neg_hi:[0,0,1]
	v_pk_add_f32 v[66:67], v[66:67], v[90:91]
	v_pk_add_f32 v[90:91], v[130:131], v[56:57]
	v_pk_add_f32 v[56:57], v[130:131], v[56:57] neg_lo:[0,1] neg_hi:[0,1]
	v_pk_add_f32 v[130:131], v[68:69], v[76:77]
	v_pk_add_f32 v[68:69], v[68:69], v[76:77] neg_lo:[0,1] neg_hi:[0,1]
	v_pk_add_f32 v[76:77], v[8:9], v[72:73] neg_lo:[0,1] neg_hi:[0,1]
	v_pk_add_f32 v[8:9], v[8:9], v[72:73]
	v_pk_add_f32 v[72:73], v[4:5], v[6:7]
	v_pk_add_f32 v[4:5], v[4:5], v[6:7] neg_lo:[0,1] neg_hi:[0,1]
	v_pk_add_f32 v[6:7], v[64:65], v[18:19]
	v_pk_add_f32 v[18:19], v[64:65], v[18:19] neg_lo:[0,1] neg_hi:[0,1]
	v_pk_mul_f32 v[64:65], v[92:93], s[82:83] op_sel_hi:[1,0]
	v_pk_add_f32 v[22:23], v[0:1], v[60:61]
	v_pk_add_f32 v[0:1], v[0:1], v[60:61] neg_lo:[0,1] neg_hi:[0,1]
	v_pk_add_f32 v[60:61], v[70:71], v[58:59]
	v_pk_add_f32 v[58:59], v[70:71], v[58:59] neg_lo:[0,1] neg_hi:[0,1]
	v_pk_fma_f32 v[70:71], v[96:97], s[82:83], v[64:65] op_sel_hi:[1,0,1] neg_lo:[1,0,0] neg_hi:[1,0,0]
	v_pk_fma_f32 v[64:65], v[96:97], s[82:83], v[64:65] op_sel_hi:[1,0,1]
	v_pk_mul_f32 v[74:75], v[74:75], s[82:83] op_sel_hi:[1,0]
	v_pk_add_f32 v[92:93], v[86:87], v[70:71]
	v_pk_add_f32 v[96:97], v[88:89], v[64:65]
	v_pk_add_f32 v[70:71], v[86:87], v[70:71] neg_lo:[0,1] neg_hi:[0,1]
	v_pk_add_f32 v[86:87], v[14:15], v[78:79] neg_lo:[0,1] neg_hi:[0,1]
	v_pk_add_f32 v[14:15], v[14:15], v[78:79]
	v_pk_fma_f32 v[78:79], v[66:67], s[54:55], v[74:75] op_sel_hi:[1,0,1] neg_lo:[0,0,1] neg_hi:[0,0,1]
	v_pk_fma_f32 v[66:67], v[66:67], s[82:83], v[74:75] op_sel_hi:[1,0,1] neg_lo:[0,0,1] neg_hi:[0,0,1]
	v_pk_add_f32 v[64:65], v[88:89], v[64:65] neg_lo:[0,1] neg_hi:[0,1]
	v_pk_add_f32 v[88:89], v[84:85], v[62:63]
	v_pk_add_f32 v[62:63], v[84:85], v[62:63] neg_lo:[0,1] neg_hi:[0,1]
	v_pk_add_f32 v[74:75], v[2:3], v[78:79]
	v_pk_add_f32 v[84:85], v[10:11], v[66:67]
	v_pk_add_f32 v[2:3], v[2:3], v[78:79] neg_lo:[0,1] neg_hi:[0,1]
	v_pk_add_f32 v[10:11], v[10:11], v[66:67] neg_lo:[0,1] neg_hi:[0,1]
	v_pk_add_f32 v[66:67], v[82:83], v[6:7]
	v_pk_add_f32 v[78:79], v[90:91], v[60:61]
	v_pk_add_f32 v[6:7], v[82:83], v[6:7] neg_lo:[0,1] neg_hi:[0,1]
	v_pk_add_f32 v[60:61], v[90:91], v[60:61] neg_lo:[0,1] neg_hi:[0,1]
	v_pk_mul_f32 v[82:83], v[96:97], s[80:81] op_sel_hi:[1,0]
	v_pk_mul_f32 v[90:91], v[96:97], s[72:73] op_sel_hi:[1,0]
	v_pk_fma_f32 v[82:83], v[92:93], s[72:73], v[82:83] op_sel_hi:[1,0,1] neg_lo:[0,0,1] neg_hi:[0,0,1]
	v_pk_fma_f32 v[90:91], v[92:93], s[80:81], v[90:91] op_sel_hi:[1,0,1]
	v_pk_mul_f32 v[86:87], v[86:87], s[82:83] op_sel_hi:[1,0]
	v_pk_add_f32 v[92:93], v[80:81], v[82:83]
	v_pk_add_f32 v[96:97], v[130:131], v[90:91]
	v_pk_add_f32 v[80:81], v[80:81], v[82:83] neg_lo:[0,1] neg_hi:[0,1]
	v_pk_add_f32 v[82:83], v[130:131], v[90:91] neg_lo:[0,1] neg_hi:[0,1]
	v_pk_fma_f32 v[90:91], v[88:89], s[82:83], v[86:87] op_sel_hi:[1,0,1] neg_lo:[1,0,0] neg_hi:[1,0,0]
	v_pk_fma_f32 v[86:87], v[88:89], s[82:83], v[86:87] op_sel_hi:[1,0,1]
	v_pk_add_f32 v[88:89], v[76:77], v[90:91]
	v_pk_add_f32 v[76:77], v[76:77], v[90:91] neg_lo:[0,1] neg_hi:[0,1]
	v_pk_mul_f32 v[90:91], v[84:85], s[72:73] op_sel_hi:[1,0]
	v_pk_mul_f32 v[84:85], v[84:85], s[80:81] op_sel_hi:[1,0]
	v_pk_fma_f32 v[90:91], v[74:75], s[80:81], v[90:91] op_sel_hi:[1,0,1] neg_lo:[0,0,1] neg_hi:[0,0,1]
	v_pk_fma_f32 v[74:75], v[74:75], s[72:73], v[84:85] op_sel_hi:[1,0,1]
	v_pk_add_f32 v[130:131], v[94:95], v[86:87]
	v_pk_add_f32 v[86:87], v[94:95], v[86:87] neg_lo:[0,1] neg_hi:[0,1]
	v_pk_add_f32 v[84:85], v[22:23], v[90:91]
	v_pk_add_f32 v[94:95], v[72:73], v[74:75]
	v_pk_add_f32 v[22:23], v[22:23], v[90:91] neg_lo:[0,1] neg_hi:[0,1]
	v_pk_add_f32 v[72:73], v[72:73], v[74:75] neg_lo:[0,1] neg_hi:[0,1]
	v_pk_add_f32 v[74:75], v[16:17], v[58:59] neg_lo:[0,1] neg_hi:[0,1]
	v_pk_add_f32 v[90:91], v[56:57], v[18:19]
	v_pk_add_f32 v[16:17], v[16:17], v[58:59]
	v_pk_add_f32 v[18:19], v[56:57], v[18:19] neg_lo:[0,1] neg_hi:[0,1]
	v_pk_mul_f32 v[56:57], v[64:65], s[72:73] op_sel_hi:[1,0]
	v_pk_mul_f32 v[58:59], v[64:65], s[80:81] op_sel_hi:[1,0]
	v_pk_fma_f32 v[56:57], v[70:71], s[84:85], v[56:57] op_sel_hi:[1,0,1] neg_lo:[0,0,1] neg_hi:[0,0,1]
	v_pk_fma_f32 v[58:59], v[70:71], s[72:73], v[58:59] op_sel_hi:[1,0,1] neg_lo:[0,0,1] neg_hi:[0,0,1]
	v_pk_add_f32 v[64:65], v[20:21], v[56:57]
	v_pk_add_f32 v[70:71], v[68:69], v[58:59]
	v_pk_add_f32 v[20:21], v[20:21], v[56:57] neg_lo:[0,1] neg_hi:[0,1]
	v_pk_add_f32 v[56:57], v[68:69], v[58:59] neg_lo:[0,1] neg_hi:[0,1]
	v_pk_mul_f32 v[58:59], v[62:63], s[82:83] op_sel_hi:[1,0]
	s_nop 0
	v_pk_fma_f32 v[62:63], v[14:15], s[54:55], v[58:59] op_sel_hi:[1,0,1] neg_lo:[0,0,1] neg_hi:[0,0,1]
	v_pk_fma_f32 v[14:15], v[14:15], s[82:83], v[58:59] op_sel_hi:[1,0,1] neg_lo:[0,0,1] neg_hi:[0,0,1]
	v_pk_add_f32 v[58:59], v[8:9], v[62:63]
	v_pk_add_f32 v[68:69], v[12:13], v[14:15]
	v_pk_add_f32 v[12:13], v[12:13], v[14:15] neg_lo:[0,1] neg_hi:[0,1]
	v_pk_mul_f32 v[14:15], v[10:11], s[80:81] op_sel_hi:[1,0]
	v_pk_mul_f32 v[10:11], v[10:11], s[72:73] op_sel_hi:[1,0]
	v_pk_fma_f32 v[14:15], v[2:3], s[52:53], v[14:15] op_sel_hi:[1,0,1] neg_lo:[0,0,1] neg_hi:[0,0,1]
	v_pk_fma_f32 v[2:3], v[2:3], s[80:81], v[10:11] op_sel_hi:[1,0,1] neg_lo:[0,0,1] neg_hi:[0,0,1]
	v_pk_add_f32 v[10:11], v[0:1], v[14:15]
	v_pk_add_f32 v[0:1], v[0:1], v[14:15] neg_lo:[0,1] neg_hi:[0,1]
	v_pk_add_f32 v[8:9], v[8:9], v[62:63] neg_lo:[0,1] neg_hi:[0,1]
	v_pk_add_f32 v[62:63], v[4:5], v[2:3]
	v_pk_add_f32 v[2:3], v[4:5], v[2:3] neg_lo:[0,1] neg_hi:[0,1]
	ds_write2_b64 v162, v[66:67], v[92:93] offset1:34
	ds_write2_b64 v168, v[78:79], v[96:97] offset1:34
	ds_write2_b64 v162, v[88:89], v[84:85] offset0:68 offset1:102
	ds_write2_b64 v168, v[130:131], v[94:95] offset0:68 offset1:102
	ds_write2_b64 v162, v[74:75], v[64:65] offset0:136 offset1:170
	ds_write2_b64 v168, v[90:91], v[70:71] offset0:136 offset1:170
	ds_write2_b64 v162, v[58:59], v[10:11] offset0:204 offset1:238
	ds_write2_b64 v168, v[68:69], v[62:63] offset0:204 offset1:238
	ds_write2_b64 v181, v[6:7], v[80:81] offset0:16 offset1:50
	ds_write2_b64 v180, v[60:61], v[82:83] offset0:16 offset1:50
	ds_write2_b64 v181, v[76:77], v[22:23] offset0:84 offset1:118
	ds_write2_b64 v180, v[86:87], v[72:73] offset0:84 offset1:118
	ds_write2_b64 v181, v[16:17], v[20:21] offset0:152 offset1:186
	ds_write2_b64 v180, v[18:19], v[56:57] offset0:152 offset1:186
	ds_write2_b64 v181, v[8:9], v[0:1] offset0:220 offset1:254
	ds_write2_b64 v180, v[12:13], v[2:3] offset0:220 offset1:254
	v_mov_b32_e32 v0, v163
	s_waitcnt lgkmcnt(0)
	s_barrier
	s_nop 0
	s_nop 0
	v_ashrrev_i32_e32 v2, 31, v0
	v_lshlrev_b32_e32 v1, 1, v0
	v_lshrrev_b32_e32 v2, 23, v2
	v_and_b32_e32 v1, 0x3fe, v1
	v_add_lshl_u32 v0, v0, v2, 5
	v_and_or_b32 v0, v0, s85, v1
	v_ashrrev_i32_e32 v2, 4, v0
	v_and_b32_e32 v2, 0x3ffffc3c, v2
	v_add_lshl_u32 v4, v2, v0, 2
	v_cvt_f32_u32_e32 v0, v1
	v_or_b32_e32 v1, 1, v1
	v_cvt_f32_u32_e32 v1, v1
	v_add_u32_e32 v130, 0, v4
	v_mul_f32_e32 v0, 0x38800000, v0
	v_sin_f32_e64 v72, -v0
	v_mul_f32_e32 v1, 0x38800000, v1
	v_sin_f32_e64 v73, -v1
	v_cos_f32_e32 v70, v0
	v_cos_f32_e32 v71, v1
	v_add_u32_e32 v131, s91, v4
	v_pk_mul_f32 v[0:1], v[72:73], v[72:73]
	ds_read_b64 v[4:5], v130
	ds_read_b64 v[6:7], v131
	ds_read_b64 v[132:133], v131 offset:34816
	ds_read_b64 v[134:135], v130 offset:34816
	v_pk_fma_f32 v[22:23], v[70:71], v[70:71], v[0:1] neg_lo:[0,0,1] neg_hi:[0,0,1]
	v_pk_mul_f32 v[0:1], v[70:71], v[72:73]
	s_nop 0
	v_pk_add_f32 v[56:57], v[0:1], v[0:1]
	s_nop 0
	v_pk_mul_f32 v[0:1], v[72:73], v[56:57]
	s_nop 0
	v_pk_fma_f32 v[86:87], v[70:71], v[22:23], v[0:1] neg_lo:[0,0,1] neg_hi:[0,0,1]
	v_pk_mul_f32 v[0:1], v[72:73], v[22:23]
	s_nop 0
	v_pk_fma_f32 v[96:97], v[70:71], v[56:57], v[0:1]
	v_pk_mul_f32 v[0:1], v[56:57], v[56:57]
	s_nop 0
	v_pk_fma_f32 v[14:15], v[22:23], v[22:23], v[0:1] neg_lo:[0,0,1] neg_hi:[0,0,1]
	v_pk_mul_f32 v[0:1], v[22:23], v[56:57]
	s_nop 0
	v_pk_add_f32 v[16:17], v[0:1], v[0:1]
	s_nop 0
	v_pk_mul_f32 v[0:1], v[72:73], v[16:17]
	s_nop 0
	v_pk_fma_f32 v[78:79], v[70:71], v[14:15], v[0:1] neg_lo:[0,0,1] neg_hi:[0,0,1]
	v_pk_mul_f32 v[0:1], v[72:73], v[14:15]
	s_nop 0
	v_pk_fma_f32 v[80:81], v[70:71], v[16:17], v[0:1]
	v_pk_mul_f32 v[0:1], v[56:57], v[16:17]
	s_nop 0
	v_pk_fma_f32 v[62:63], v[22:23], v[14:15], v[0:1] neg_lo:[0,0,1] neg_hi:[0,0,1]
	v_pk_mul_f32 v[0:1], v[56:57], v[14:15]
	s_nop 0
	v_pk_fma_f32 v[64:65], v[22:23], v[16:17], v[0:1]
	v_pk_mul_f32 v[0:1], v[16:17], v[96:97]
	s_nop 0
	v_pk_fma_f32 v[88:89], v[14:15], v[86:87], v[0:1] neg_lo:[0,0,1] neg_hi:[0,0,1]
	v_pk_mul_f32 v[0:1], v[14:15], v[96:97]
	s_nop 0
	v_pk_fma_f32 v[90:91], v[16:17], v[86:87], v[0:1]
	v_pk_mul_f32 v[0:1], v[16:17], v[16:17]
	s_nop 0
	v_pk_fma_f32 v[10:11], v[14:15], v[14:15], v[0:1] neg_lo:[0,0,1] neg_hi:[0,0,1]
	v_pk_mul_f32 v[0:1], v[14:15], v[16:17]
	v_pk_mul_f32 v[2:3], v[10:11], v[90:91]
	v_pk_add_f32 v[12:13], v[0:1], v[0:1]
	s_nop 0
	v_pk_mul_f32 v[0:1], v[72:73], v[12:13]
	v_pk_fma_f32 v[2:3], v[12:13], v[88:89], v[2:3]
	v_pk_fma_f32 v[74:75], v[70:71], v[10:11], v[0:1] neg_lo:[0,0,1] neg_hi:[0,0,1]
	v_pk_mul_f32 v[0:1], v[72:73], v[10:11]
	s_waitcnt lgkmcnt(1)
	v_pk_mul_f32 v[8:9], v[132:133], v[12:13]
	v_pk_fma_f32 v[76:77], v[70:71], v[12:13], v[0:1]
	v_pk_mul_f32 v[0:1], v[56:57], v[12:13]
	s_waitcnt lgkmcnt(0)
	v_pk_fma_f32 v[8:9], v[134:135], v[10:11], v[8:9]
	v_pk_fma_f32 v[58:59], v[22:23], v[10:11], v[0:1] neg_lo:[0,0,1] neg_hi:[0,0,1]
	v_pk_mul_f32 v[0:1], v[56:57], v[10:11]
	s_nop 0
	v_pk_fma_f32 v[60:61], v[22:23], v[12:13], v[0:1]
	v_pk_mul_f32 v[0:1], v[96:97], v[12:13]
	s_nop 0
	v_pk_fma_f32 v[92:93], v[86:87], v[10:11], v[0:1] neg_lo:[0,0,1] neg_hi:[0,0,1]
	v_pk_mul_f32 v[0:1], v[96:97], v[10:11]
	s_nop 0
	v_pk_fma_f32 v[94:95], v[86:87], v[12:13], v[0:1]
	v_pk_mul_f32 v[0:1], v[16:17], v[12:13]
	s_nop 0
	v_pk_fma_f32 v[18:19], v[14:15], v[10:11], v[0:1] neg_lo:[0,0,1] neg_hi:[0,0,1]
	v_pk_mul_f32 v[0:1], v[16:17], v[10:11]
	s_nop 0
	v_pk_fma_f32 v[20:21], v[14:15], v[12:13], v[0:1]
	v_pk_mul_f32 v[0:1], v[12:13], v[80:81]
	s_nop 0
	v_pk_fma_f32 v[82:83], v[10:11], v[78:79], v[0:1] neg_lo:[0,0,1] neg_hi:[0,0,1]
	v_pk_mul_f32 v[0:1], v[10:11], v[80:81]
	s_nop 0
	v_pk_fma_f32 v[84:85], v[12:13], v[78:79], v[0:1]
	v_pk_mul_f32 v[0:1], v[12:13], v[64:65]
	s_nop 0
	v_pk_fma_f32 v[66:67], v[10:11], v[62:63], v[0:1] neg_lo:[0,0,1] neg_hi:[0,0,1]
	v_pk_mul_f32 v[0:1], v[10:11], v[64:65]
	s_nop 0
	v_pk_fma_f32 v[68:69], v[12:13], v[62:63], v[0:1]
	v_pk_mul_f32 v[0:1], v[12:13], v[90:91]
	v_pk_mul_f32 v[12:13], v[134:135], v[12:13]
	v_pk_fma_f32 v[0:1], v[10:11], v[88:89], v[0:1] neg_lo:[0,0,1] neg_hi:[0,0,1]
	v_pk_fma_f32 v[10:11], v[132:133], v[10:11], v[12:13] neg_lo:[0,0,1] neg_hi:[0,0,1]
	ds_read_b64 v[132:133], v131 offset:17408
	ds_read_b64 v[134:135], v130 offset:17408
	s_waitcnt lgkmcnt(1)
	v_pk_mul_f32 v[12:13], v[132:133], v[16:17]
	s_waitcnt lgkmcnt(0)
	v_pk_mul_f32 v[16:17], v[134:135], v[16:17]
	v_pk_fma_f32 v[12:13], v[134:135], v[14:15], v[12:13]
	v_pk_fma_f32 v[14:15], v[132:133], v[14:15], v[16:17] neg_lo:[0,0,1] neg_hi:[0,0,1]
	ds_read_b64 v[132:133], v131 offset:52224
	ds_read_b64 v[134:135], v130 offset:52224
	s_waitcnt lgkmcnt(1)
	v_pk_mul_f32 v[16:17], v[132:133], v[20:21]
	s_waitcnt lgkmcnt(0)
	v_pk_mul_f32 v[20:21], v[134:135], v[20:21]
	v_pk_fma_f32 v[16:17], v[134:135], v[18:19], v[16:17]
	v_pk_fma_f32 v[18:19], v[132:133], v[18:19], v[20:21] neg_lo:[0,0,1] neg_hi:[0,0,1]
	ds_read_b64 v[132:133], v131 offset:8704
	ds_read_b64 v[134:135], v130 offset:8704
	s_waitcnt lgkmcnt(0)
	v_pk_mul_f32 v[20:21], v[22:23], v[134:135]
	s_nop 0
	v_pk_fma_f32 v[20:21], v[132:133], v[56:57], v[20:21]
	v_pk_mul_f32 v[56:57], v[56:57], v[134:135]
	s_nop 0
	v_pk_fma_f32 v[22:23], v[132:133], v[22:23], v[56:57] neg_lo:[0,0,1] neg_hi:[0,0,1]
	ds_read_b64 v[132:133], v131 offset:43520
	ds_read_b64 v[134:135], v130 offset:43520
	s_waitcnt lgkmcnt(1)
	v_pk_mul_f32 v[56:57], v[132:133], v[60:61]
	s_waitcnt lgkmcnt(0)
	v_pk_mul_f32 v[60:61], v[134:135], v[60:61]
	v_pk_fma_f32 v[56:57], v[134:135], v[58:59], v[56:57]
	v_pk_fma_f32 v[58:59], v[132:133], v[58:59], v[60:61] neg_lo:[0,0,1] neg_hi:[0,0,1]
	ds_read_b64 v[132:133], v131 offset:26112
	ds_read_b64 v[134:135], v130 offset:26112
	s_waitcnt lgkmcnt(0)
	v_pk_mul_f32 v[60:61], v[62:63], v[134:135]
	s_nop 0
	v_pk_fma_f32 v[60:61], v[132:133], v[64:65], v[60:61]
	v_pk_mul_f32 v[64:65], v[64:65], v[134:135]
	s_nop 0
	v_pk_fma_f32 v[62:63], v[132:133], v[62:63], v[64:65] neg_lo:[0,0,1] neg_hi:[0,0,1]
	ds_read_b64 v[132:133], v131 offset:60928
	ds_read_b64 v[134:135], v130 offset:60928
	s_waitcnt lgkmcnt(0)
	v_pk_mul_f32 v[64:65], v[66:67], v[134:135]
	s_nop 0
	v_pk_fma_f32 v[64:65], v[132:133], v[68:69], v[64:65]
	v_pk_mul_f32 v[68:69], v[68:69], v[134:135]
	s_nop 0
	v_pk_fma_f32 v[66:67], v[132:133], v[66:67], v[68:69] neg_lo:[0,0,1] neg_hi:[0,0,1]
	ds_read_b64 v[132:133], v131 offset:4352
	ds_read_b64 v[134:135], v130 offset:4352
	s_waitcnt lgkmcnt(0)
	v_pk_mul_f32 v[68:69], v[70:71], v[134:135]
	s_nop 0
	v_pk_fma_f32 v[68:69], v[72:73], v[132:133], v[68:69]
	v_pk_mul_f32 v[72:73], v[72:73], v[134:135]
	s_nop 0
	v_pk_fma_f32 v[70:71], v[70:71], v[132:133], v[72:73] neg_lo:[0,0,1] neg_hi:[0,0,1]
	ds_read_b64 v[132:133], v131 offset:39168
	ds_read_b64 v[134:135], v130 offset:39168
	s_waitcnt lgkmcnt(0)
	v_pk_mul_f32 v[72:73], v[74:75], v[134:135]
	s_nop 0
	v_pk_fma_f32 v[72:73], v[76:77], v[132:133], v[72:73]
	v_pk_mul_f32 v[76:77], v[76:77], v[134:135]
	s_nop 0
	v_pk_fma_f32 v[74:75], v[74:75], v[132:133], v[76:77] neg_lo:[0,0,1] neg_hi:[0,0,1]
	ds_read_b64 v[132:133], v131 offset:21760
	ds_read_b64 v[134:135], v130 offset:21760
	s_waitcnt lgkmcnt(0)
	v_pk_mul_f32 v[76:77], v[78:79], v[134:135]
	s_nop 0
	v_pk_fma_f32 v[76:77], v[80:81], v[132:133], v[76:77]
	v_pk_mul_f32 v[80:81], v[80:81], v[134:135]
	s_nop 0
	v_pk_fma_f32 v[78:79], v[78:79], v[132:133], v[80:81] neg_lo:[0,0,1] neg_hi:[0,0,1]
	ds_read_b64 v[132:133], v131 offset:56576
	ds_read_b64 v[134:135], v130 offset:56576
	s_waitcnt lgkmcnt(0)
	v_pk_mul_f32 v[80:81], v[82:83], v[134:135]
	s_nop 0
	v_pk_fma_f32 v[80:81], v[84:85], v[132:133], v[80:81]
	v_pk_mul_f32 v[84:85], v[84:85], v[134:135]
	s_nop 0
	v_pk_fma_f32 v[82:83], v[82:83], v[132:133], v[84:85] neg_lo:[0,0,1] neg_hi:[0,0,1]
	ds_read_b64 v[132:133], v131 offset:13056
	ds_read_b64 v[134:135], v130 offset:13056
	s_waitcnt lgkmcnt(0)
	v_pk_mul_f32 v[84:85], v[86:87], v[134:135]
	s_nop 0
	v_pk_fma_f32 v[84:85], v[96:97], v[132:133], v[84:85]
	v_pk_mul_f32 v[96:97], v[96:97], v[134:135]
	s_nop 0
	v_pk_fma_f32 v[86:87], v[86:87], v[132:133], v[96:97] neg_lo:[0,0,1] neg_hi:[0,0,1]
	ds_read_b64 v[132:133], v131 offset:47872
	ds_read_b64 v[134:135], v130 offset:47872
	s_waitcnt lgkmcnt(0)
	v_pk_mul_f32 v[96:97], v[92:93], v[134:135]
	s_nop 0
	v_pk_fma_f32 v[96:97], v[94:95], v[132:133], v[96:97]
	v_pk_mul_f32 v[94:95], v[94:95], v[134:135]
	s_nop 0
	v_pk_fma_f32 v[92:93], v[92:93], v[132:133], v[94:95] neg_lo:[0,0,1] neg_hi:[0,0,1]
	ds_read_b64 v[132:133], v131 offset:30464
	ds_read_b64 v[134:135], v130 offset:30464
	s_waitcnt lgkmcnt(0)
	v_pk_mul_f32 v[94:95], v[88:89], v[134:135]
	s_nop 0
	v_pk_fma_f32 v[94:95], v[90:91], v[132:133], v[94:95]
	v_pk_mul_f32 v[90:91], v[90:91], v[134:135]
	s_nop 0
	v_pk_fma_f32 v[88:89], v[88:89], v[132:133], v[90:91] neg_lo:[0,0,1] neg_hi:[0,0,1]
	ds_read_b64 v[90:91], v131 offset:65280
	ds_read_b64 v[132:133], v130 offset:65280
	s_waitcnt lgkmcnt(0)
	v_pk_mul_f32 v[134:135], v[2:3], v[132:133]
	s_nop 0
	v_pk_fma_f32 v[134:135], v[0:1], v[90:91], v[134:135] neg_lo:[0,0,1] neg_hi:[0,0,1]
	v_pk_mul_f32 v[0:1], v[0:1], v[132:133]
	s_nop 0
	v_pk_fma_f32 v[0:1], v[2:3], v[90:91], v[0:1]
	v_pk_add_f32 v[2:3], v[4:5], v[8:9]
	v_pk_add_f32 v[90:91], v[6:7], v[10:11]
	v_pk_add_f32 v[4:5], v[4:5], v[8:9] neg_lo:[0,1] neg_hi:[0,1]
	v_pk_add_f32 v[6:7], v[6:7], v[10:11] neg_lo:[0,1] neg_hi:[0,1]
	v_pk_add_f32 v[8:9], v[12:13], v[16:17]
	v_pk_add_f32 v[10:11], v[14:15], v[18:19]
	v_pk_add_f32 v[12:13], v[12:13], v[16:17] neg_lo:[0,1] neg_hi:[0,1]
	v_pk_add_f32 v[14:15], v[14:15], v[18:19] neg_lo:[0,1] neg_hi:[0,1]
	v_pk_add_f32 v[16:17], v[20:21], v[56:57]
	v_pk_add_f32 v[18:19], v[22:23], v[58:59]
	v_pk_add_f32 v[20:21], v[20:21], v[56:57] neg_lo:[0,1] neg_hi:[0,1]
	v_pk_add_f32 v[22:23], v[22:23], v[58:59] neg_lo:[0,1] neg_hi:[0,1]
	v_pk_add_f32 v[56:57], v[60:61], v[64:65]
	v_pk_add_f32 v[58:59], v[62:63], v[66:67]
	v_pk_add_f32 v[60:61], v[60:61], v[64:65] neg_lo:[0,1] neg_hi:[0,1]
	v_pk_add_f32 v[62:63], v[62:63], v[66:67] neg_lo:[0,1] neg_hi:[0,1]
	v_pk_add_f32 v[64:65], v[68:69], v[72:73]
	v_pk_add_f32 v[66:67], v[70:71], v[74:75]
	v_pk_add_f32 v[68:69], v[68:69], v[72:73] neg_lo:[0,1] neg_hi:[0,1]
	v_pk_add_f32 v[70:71], v[70:71], v[74:75] neg_lo:[0,1] neg_hi:[0,1]
	v_pk_add_f32 v[72:73], v[76:77], v[80:81]
	v_pk_add_f32 v[74:75], v[78:79], v[82:83]
	v_pk_add_f32 v[76:77], v[76:77], v[80:81] neg_lo:[0,1] neg_hi:[0,1]
	v_pk_add_f32 v[78:79], v[78:79], v[82:83] neg_lo:[0,1] neg_hi:[0,1]
	v_pk_add_f32 v[80:81], v[84:85], v[96:97]
	v_pk_add_f32 v[82:83], v[86:87], v[92:93]
	v_pk_add_f32 v[84:85], v[84:85], v[96:97] neg_lo:[0,1] neg_hi:[0,1]
	v_pk_add_f32 v[86:87], v[86:87], v[92:93] neg_lo:[0,1] neg_hi:[0,1]
	v_pk_add_f32 v[92:93], v[94:95], v[0:1]
	v_pk_add_f32 v[96:97], v[88:89], v[134:135]
	v_pk_add_f32 v[88:89], v[88:89], v[134:135] neg_lo:[0,1] neg_hi:[0,1]
	v_pk_add_f32 v[0:1], v[94:95], v[0:1] neg_lo:[0,1] neg_hi:[0,1]
	v_pk_add_f32 v[94:95], v[2:3], v[8:9]
	v_pk_add_f32 v[132:133], v[90:91], v[10:11]
	v_pk_add_f32 v[2:3], v[2:3], v[8:9] neg_lo:[0,1] neg_hi:[0,1]
	v_pk_add_f32 v[8:9], v[90:91], v[10:11] neg_lo:[0,1] neg_hi:[0,1]
	v_pk_add_f32 v[90:91], v[6:7], v[12:13]
	v_pk_add_f32 v[6:7], v[6:7], v[12:13] neg_lo:[0,1] neg_hi:[0,1]
	v_pk_add_f32 v[12:13], v[16:17], v[56:57]
	v_pk_add_f32 v[16:17], v[16:17], v[56:57] neg_lo:[0,1] neg_hi:[0,1]
	v_pk_add_f32 v[56:57], v[20:21], v[62:63] neg_lo:[0,1] neg_hi:[0,1]
	v_pk_add_f32 v[20:21], v[20:21], v[62:63]
	v_pk_add_f32 v[62:63], v[66:67], v[74:75]
	v_pk_add_f32 v[66:67], v[66:67], v[74:75] neg_lo:[0,1] neg_hi:[0,1]
	v_pk_add_f32 v[74:75], v[70:71], v[76:77]
	v_pk_add_f32 v[70:71], v[70:71], v[76:77] neg_lo:[0,1] neg_hi:[0,1]
	v_pk_add_f32 v[76:77], v[80:81], v[92:93]
	v_pk_add_f32 v[80:81], v[80:81], v[92:93] neg_lo:[0,1] neg_hi:[0,1]
	v_pk_add_f32 v[92:93], v[84:85], v[88:89] neg_lo:[0,1] neg_hi:[0,1]
	v_pk_add_f32 v[10:11], v[4:5], v[14:15] neg_lo:[0,1] neg_hi:[0,1]
	v_pk_add_f32 v[4:5], v[4:5], v[14:15]
	v_pk_add_f32 v[14:15], v[18:19], v[58:59]
	v_pk_add_f32 v[18:19], v[18:19], v[58:59] neg_lo:[0,1] neg_hi:[0,1]
	v_pk_add_f32 v[58:59], v[22:23], v[60:61]
	v_pk_add_f32 v[22:23], v[22:23], v[60:61] neg_lo:[0,1] neg_hi:[0,1]
	v_pk_add_f32 v[60:61], v[64:65], v[72:73]
	v_pk_add_f32 v[64:65], v[64:65], v[72:73] neg_lo:[0,1] neg_hi:[0,1]
	v_pk_add_f32 v[72:73], v[68:69], v[78:79] neg_lo:[0,1] neg_hi:[0,1]
	v_pk_add_f32 v[68:69], v[68:69], v[78:79]
	v_pk_add_f32 v[78:79], v[82:83], v[96:97]
	v_pk_add_f32 v[82:83], v[82:83], v[96:97] neg_lo:[0,1] neg_hi:[0,1]
	v_pk_add_f32 v[96:97], v[86:87], v[0:1]
	v_pk_add_f32 v[0:1], v[86:87], v[0:1] neg_lo:[0,1] neg_hi:[0,1]
	v_pk_mul_f32 v[92:93], v[92:93], s[82:83] op_sel_hi:[1,0]
	v_pk_add_f32 v[84:85], v[84:85], v[88:89]
	v_pk_fma_f32 v[138:139], v[96:97], s[82:83], v[92:93] op_sel_hi:[1,0,1] neg_lo:[1,0,0] neg_hi:[1,0,0]
	v_pk_fma_f32 v[92:93], v[96:97], s[82:83], v[92:93] op_sel_hi:[1,0,1]
	v_pk_mul_f32 v[0:1], v[0:1], s[82:83] op_sel_hi:[1,0]
	v_pk_mul_f32 v[56:57], v[56:57], s[82:83] op_sel_hi:[1,0]
	v_pk_add_f32 v[96:97], v[72:73], v[138:139]
	v_pk_add_f32 v[140:141], v[74:75], v[92:93]
	v_pk_add_f32 v[72:73], v[72:73], v[138:139] neg_lo:[0,1] neg_hi:[0,1]
	v_pk_add_f32 v[138:139], v[66:67], v[80:81]
	v_pk_add_f32 v[66:67], v[66:67], v[80:81] neg_lo:[0,1] neg_hi:[0,1]
	v_pk_fma_f32 v[80:81], v[84:85], s[54:55], v[0:1] op_sel_hi:[1,0,1] neg_lo:[0,0,1] neg_hi:[0,0,1]
	v_pk_fma_f32 v[0:1], v[84:85], s[82:83], v[0:1] op_sel_hi:[1,0,1] neg_lo:[0,0,1] neg_hi:[0,0,1]
	v_pk_fma_f32 v[134:135], v[58:59], s[82:83], v[56:57] op_sel_hi:[1,0,1] neg_lo:[1,0,0] neg_hi:[1,0,0]
	v_pk_fma_f32 v[56:57], v[58:59], s[82:83], v[56:57] op_sel_hi:[1,0,1]
	v_pk_add_f32 v[74:75], v[74:75], v[92:93] neg_lo:[0,1] neg_hi:[0,1]
	v_pk_add_f32 v[92:93], v[64:65], v[82:83] neg_lo:[0,1] neg_hi:[0,1]
	v_pk_add_f32 v[64:65], v[64:65], v[82:83]
	v_pk_add_f32 v[82:83], v[68:69], v[80:81]
	v_pk_add_f32 v[84:85], v[70:71], v[0:1]
	v_pk_add_f32 v[68:69], v[68:69], v[80:81] neg_lo:[0,1] neg_hi:[0,1]
	v_pk_add_f32 v[0:1], v[70:71], v[0:1] neg_lo:[0,1] neg_hi:[0,1]
	v_pk_mul_f32 v[70:71], v[140:141], s[80:81] op_sel_hi:[1,0]
	v_pk_mul_f32 v[80:81], v[140:141], s[72:73] op_sel_hi:[1,0]
	v_pk_add_f32 v[58:59], v[10:11], v[134:135]
	v_pk_add_f32 v[136:137], v[90:91], v[56:57]
	v_pk_fma_f32 v[70:71], v[96:97], s[72:73], v[70:71] op_sel_hi:[1,0,1] neg_lo:[0,0,1] neg_hi:[0,0,1]
	v_pk_fma_f32 v[80:81], v[96:97], s[80:81], v[80:81] op_sel_hi:[1,0,1]
	v_pk_add_f32 v[58:59], v[58:59], v[70:71]
	v_pk_add_f32 v[70:71], v[136:137], v[80:81]
	v_pk_mul_f32 v[80:81], v[92:93], s[82:83] op_sel_hi:[1,0]
	v_pk_add_f32 v[10:11], v[10:11], v[134:135] neg_lo:[0,1] neg_hi:[0,1]
	v_pk_add_f32 v[56:57], v[90:91], v[56:57] neg_lo:[0,1] neg_hi:[0,1]
	v_pk_add_f32 v[90:91], v[2:3], v[18:19] neg_lo:[0,1] neg_hi:[0,1]
	v_pk_add_f32 v[134:135], v[8:9], v[16:17]
	v_pk_add_f32 v[8:9], v[8:9], v[16:17] neg_lo:[0,1] neg_hi:[0,1]
	v_pk_mul_f32 v[16:17], v[22:23], s[82:83] op_sel_hi:[1,0]
	v_pk_fma_f32 v[92:93], v[138:139], s[82:83], v[80:81] op_sel_hi:[1,0,1] neg_lo:[1,0,0] neg_hi:[1,0,0]
	v_pk_add_f32 v[2:3], v[2:3], v[18:19]
	v_pk_fma_f32 v[18:19], v[20:21], s[54:55], v[16:17] op_sel_hi:[1,0,1] neg_lo:[0,0,1] neg_hi:[0,0,1]
	v_pk_fma_f32 v[16:17], v[20:21], s[82:83], v[16:17] op_sel_hi:[1,0,1] neg_lo:[0,0,1] neg_hi:[0,0,1]
	v_pk_add_f32 v[90:91], v[90:91], v[92:93]
	v_pk_mul_f32 v[92:93], v[84:85], s[72:73] op_sel_hi:[1,0]
	v_pk_mul_f32 v[84:85], v[84:85], s[80:81] op_sel_hi:[1,0]
	v_pk_add_f32 v[22:23], v[6:7], v[16:17]
	v_pk_fma_f32 v[92:93], v[82:83], s[80:81], v[92:93] op_sel_hi:[1,0,1] neg_lo:[0,0,1] neg_hi:[0,0,1]
	v_pk_fma_f32 v[82:83], v[82:83], s[72:73], v[84:85] op_sel_hi:[1,0,1]
	v_pk_mul_f32 v[66:67], v[66:67], s[82:83] op_sel_hi:[1,0]
	v_pk_add_f32 v[22:23], v[22:23], v[82:83]
	v_pk_mul_f32 v[82:83], v[74:75], s[72:73] op_sel_hi:[1,0]
	v_pk_mul_f32 v[74:75], v[74:75], s[80:81] op_sel_hi:[1,0]
	v_pk_fma_f32 v[82:83], v[72:73], s[84:85], v[82:83] op_sel_hi:[1,0,1] neg_lo:[0,0,1] neg_hi:[0,0,1]
	v_pk_fma_f32 v[72:73], v[72:73], s[72:73], v[74:75] op_sel_hi:[1,0,1] neg_lo:[0,0,1] neg_hi:[0,0,1]
	v_pk_add_f32 v[6:7], v[6:7], v[16:17] neg_lo:[0,1] neg_hi:[0,1]
	v_pk_add_f32 v[56:57], v[56:57], v[72:73]
	v_pk_fma_f32 v[72:73], v[64:65], s[54:55], v[66:67] op_sel_hi:[1,0,1] neg_lo:[0,0,1] neg_hi:[0,0,1]
	v_pk_fma_f32 v[64:65], v[64:65], s[82:83], v[66:67] op_sel_hi:[1,0,1] neg_lo:[0,0,1] neg_hi:[0,0,1]
	v_pk_add_f32 v[88:89], v[132:133], v[14:15] neg_lo:[0,1] neg_hi:[0,1]
	v_pk_add_f32 v[8:9], v[8:9], v[64:65]
	v_pk_mul_f32 v[64:65], v[0:1], s[80:81] op_sel_hi:[1,0]
	v_pk_mul_f32 v[0:1], v[0:1], s[72:73] op_sel_hi:[1,0]
	v_pk_add_f32 v[86:87], v[94:95], v[12:13] neg_lo:[0,1] neg_hi:[0,1]
	v_pk_fma_f32 v[0:1], v[68:69], s[80:81], v[0:1] op_sel_hi:[1,0,1] neg_lo:[0,0,1] neg_hi:[0,0,1]
	v_pk_add_f32 v[12:13], v[94:95], v[12:13]
	v_pk_add_f32 v[0:1], v[6:7], v[0:1]
	v_pk_add_f32 v[6:7], v[132:133], v[14:15]
	v_pk_add_f32 v[14:15], v[62:63], v[78:79]
	v_pk_add_f32 v[20:21], v[4:5], v[18:19]
	v_pk_add_f32 v[6:7], v[6:7], v[14:15]
	v_pk_add_f32 v[14:15], v[60:61], v[76:77]
	v_pk_add_f32 v[4:5], v[4:5], v[18:19] neg_lo:[0,1] neg_hi:[0,1]
	v_pk_add_f32 v[16:17], v[60:61], v[76:77] neg_lo:[0,1] neg_hi:[0,1]
	v_pk_add_f32 v[18:19], v[62:63], v[78:79] neg_lo:[0,1] neg_hi:[0,1]
	v_pk_fma_f32 v[80:81], v[138:139], s[82:83], v[80:81] op_sel_hi:[1,0,1]
	v_pk_add_f32 v[2:3], v[2:3], v[72:73]
	v_pk_fma_f32 v[64:65], v[68:69], s[52:53], v[64:65] op_sel_hi:[1,0,1] neg_lo:[0,0,1] neg_hi:[0,0,1]
	v_pk_add_f32 v[12:13], v[12:13], v[14:15]
	v_pk_add_f32 v[80:81], v[134:135], v[80:81]
	v_pk_add_f32 v[20:21], v[20:21], v[92:93]
	v_pk_add_f32 v[18:19], v[86:87], v[18:19] neg_lo:[0,1] neg_hi:[0,1]
	v_pk_add_f32 v[16:17], v[88:89], v[16:17]
	v_pk_add_f32 v[10:11], v[10:11], v[82:83]
	v_pk_add_f32 v[4:5], v[4:5], v[64:65]
	ds_write_b64 v130, v[12:13]
	ds_write_b64 v131, v[6:7]
	ds_write_b64 v130, v[58:59] offset:4352
	ds_write_b64 v131, v[70:71] offset:4352
	ds_write_b64 v130, v[90:91] offset:8704
	ds_write_b64 v131, v[80:81] offset:8704
	ds_write_b64 v130, v[20:21] offset:13056
	ds_write_b64 v131, v[22:23] offset:13056
	ds_write_b64 v130, v[18:19] offset:17408
	ds_write_b64 v131, v[16:17] offset:17408
	ds_write_b64 v130, v[10:11] offset:21760
	ds_write_b64 v131, v[56:57] offset:21760
	ds_write_b64 v130, v[2:3] offset:26112
	ds_write_b64 v131, v[8:9] offset:26112
	ds_write_b64 v130, v[4:5] offset:30464
	ds_write_b64 v131, v[0:1] offset:30464
	s_waitcnt lgkmcnt(0)
	s_barrier
	ds_read_b64 v[0:1], v172
	ds_read_b64 v[2:3], v173
	v_lshlrev_b32_e32 v5, 16, v113
	v_lshlrev_b32_e32 v4, 16, v128
	v_and_b32_e32 v7, 0xffff0000, v113
	s_waitcnt lgkmcnt(1)
	v_fmac_f32_e32 v0, v147, v5
	v_and_b32_e32 v6, 0xffff0000, v128
	v_lshlrev_b32_e32 v9, 16, v112
	v_and_b32_e32 v11, 0xffff0000, v112
	v_fma_f32 v1, v147, v7, v1
	v_mul_f32_e32 v0, v0, v4
	v_lshlrev_b32_e32 v8, 16, v129
	v_and_b32_e32 v10, 0xffff0000, v129
	s_waitcnt lgkmcnt(0)
	v_fma_f32 v3, v147, v11, v3
	v_fmac_f32_e32 v2, v147, v9
	v_mul_f32_e32 v1, v1, v6
	v_cvt_pk_bf16_f32 v0, v0, v1
	v_mul_f32_e32 v3, v3, v10
	v_mul_f32_e32 v2, v2, v8
	global_store_dword v[50:51], v0, off
	v_cvt_pk_bf16_f32 v0, v2, v3
	global_store_dword v[54:55], v0, off
	ds_read_b64 v[0:1], v160 offset:4096
	ds_read_b64 v[2:3], v169
	v_lshlrev_b32_e32 v5, 16, v111
	v_lshlrev_b32_e32 v4, 16, v126
	v_and_b32_e32 v7, 0xffff0000, v111
	s_waitcnt lgkmcnt(1)
	v_fmac_f32_e32 v0, v147, v5
	v_and_b32_e32 v6, 0xffff0000, v126
	v_lshlrev_b32_e32 v9, 16, v110
	v_and_b32_e32 v11, 0xffff0000, v110
	v_fma_f32 v1, v147, v7, v1
	v_mul_f32_e32 v0, v0, v4
	v_lshlrev_b32_e32 v8, 16, v127
	v_and_b32_e32 v10, 0xffff0000, v127
	s_waitcnt lgkmcnt(0)
	v_fma_f32 v3, v147, v11, v3
	v_fmac_f32_e32 v2, v147, v9
	v_mul_f32_e32 v1, v1, v6
	v_cvt_pk_bf16_f32 v0, v0, v1
	v_mul_f32_e32 v3, v3, v10
	v_mul_f32_e32 v2, v2, v8
	global_store_dword v[50:51], v0, off offset:2048
	v_cvt_pk_bf16_f32 v0, v2, v3
	global_store_dword v[52:53], v0, off
	ds_read_b64 v[0:1], v158 offset:8192
	ds_read_b64 v[2:3], v159
	v_lshlrev_b32_e32 v5, 16, v109
	v_lshlrev_b32_e32 v4, 16, v123
	v_and_b32_e32 v7, 0xffff0000, v109
	s_waitcnt lgkmcnt(1)
	v_fmac_f32_e32 v0, v147, v5
	v_and_b32_e32 v6, 0xffff0000, v123
	v_lshlrev_b32_e32 v9, 16, v108
	v_and_b32_e32 v11, 0xffff0000, v108
	v_fma_f32 v1, v147, v7, v1
	v_mul_f32_e32 v0, v0, v4
	v_lshlrev_b32_e32 v8, 16, v124
	v_and_b32_e32 v10, 0xffff0000, v124
	s_waitcnt lgkmcnt(0)
	v_fma_f32 v3, v147, v11, v3
	v_fmac_f32_e32 v2, v147, v9
	v_mul_f32_e32 v1, v1, v6
	v_cvt_pk_bf16_f32 v0, v0, v1
	v_mul_f32_e32 v3, v3, v10
	v_mul_f32_e32 v2, v2, v8
	global_store_dword v[46:47], v0, off
	v_cvt_pk_bf16_f32 v0, v2, v3
	global_store_dword v[48:49], v0, off
	ds_read_b64 v[0:1], v156 offset:12288
	ds_read_b64 v[2:3], v157
	v_lshlrev_b32_e32 v5, 16, v107
	v_lshlrev_b32_e32 v4, 16, v120
	v_and_b32_e32 v7, 0xffff0000, v107
	s_waitcnt lgkmcnt(1)
	v_fmac_f32_e32 v0, v147, v5
	v_and_b32_e32 v6, 0xffff0000, v120
	v_lshlrev_b32_e32 v9, 16, v106
	v_and_b32_e32 v11, 0xffff0000, v106
	v_fma_f32 v1, v147, v7, v1
	v_mul_f32_e32 v0, v0, v4
	v_lshlrev_b32_e32 v8, 16, v125
	v_and_b32_e32 v10, 0xffff0000, v125
	s_waitcnt lgkmcnt(0)
	v_fma_f32 v3, v147, v11, v3
	v_fmac_f32_e32 v2, v147, v9
	v_mul_f32_e32 v1, v1, v6
	v_cvt_pk_bf16_f32 v0, v0, v1
	v_mul_f32_e32 v3, v3, v10
	v_mul_f32_e32 v2, v2, v8
	global_store_dword v[38:39], v0, off
	v_cvt_pk_bf16_f32 v0, v2, v3
	global_store_dword v[40:41], v0, off
	ds_read_b64 v[0:1], v154 offset:16384
	ds_read_b64 v[2:3], v155
	v_lshlrev_b32_e32 v5, 16, v105
	v_lshlrev_b32_e32 v4, 16, v121
	v_and_b32_e32 v7, 0xffff0000, v105
	s_waitcnt lgkmcnt(1)
	v_fmac_f32_e32 v0, v147, v5
	v_and_b32_e32 v6, 0xffff0000, v121
	v_lshlrev_b32_e32 v9, 16, v104
	v_and_b32_e32 v11, 0xffff0000, v104
	v_fma_f32 v1, v147, v7, v1
	v_mul_f32_e32 v0, v0, v4
	v_lshlrev_b32_e32 v8, 16, v122
	v_and_b32_e32 v10, 0xffff0000, v122
	s_waitcnt lgkmcnt(0)
	v_fma_f32 v3, v147, v11, v3
	v_fmac_f32_e32 v2, v147, v9
	v_mul_f32_e32 v1, v1, v6
	v_cvt_pk_bf16_f32 v0, v0, v1
	v_mul_f32_e32 v3, v3, v10
	v_mul_f32_e32 v2, v2, v8
	global_store_dword v[42:43], v0, off
	v_cvt_pk_bf16_f32 v0, v2, v3
	global_store_dword v[44:45], v0, off
	ds_read_b64 v[0:1], v152 offset:20480
	ds_read_b64 v[2:3], v153
	v_lshlrev_b32_e32 v5, 16, v103
	v_lshlrev_b32_e32 v4, 16, v118
	v_and_b32_e32 v7, 0xffff0000, v103
	s_waitcnt lgkmcnt(1)
	v_fmac_f32_e32 v0, v147, v5
	v_and_b32_e32 v6, 0xffff0000, v118
	v_lshlrev_b32_e32 v9, 16, v102
	v_and_b32_e32 v11, 0xffff0000, v102
	v_fma_f32 v1, v147, v7, v1
	v_mul_f32_e32 v0, v0, v4
	v_lshlrev_b32_e32 v8, 16, v119
	v_and_b32_e32 v10, 0xffff0000, v119
	s_waitcnt lgkmcnt(0)
	v_fma_f32 v3, v147, v11, v3
	v_fmac_f32_e32 v2, v147, v9
	v_mul_f32_e32 v1, v1, v6
	v_cvt_pk_bf16_f32 v0, v0, v1
	v_mul_f32_e32 v3, v3, v10
	v_mul_f32_e32 v2, v2, v8
	global_store_dword v[34:35], v0, off
	v_cvt_pk_bf16_f32 v0, v2, v3
	global_store_dword v[36:37], v0, off
	ds_read_b64 v[0:1], v150 offset:24576
	ds_read_b64 v[2:3], v151
	v_lshlrev_b32_e32 v5, 16, v101
	v_lshlrev_b32_e32 v4, 16, v115
	v_and_b32_e32 v7, 0xffff0000, v101
	s_waitcnt lgkmcnt(1)
	v_fmac_f32_e32 v0, v147, v5
	v_and_b32_e32 v6, 0xffff0000, v115
	v_lshlrev_b32_e32 v9, 16, v100
	v_and_b32_e32 v11, 0xffff0000, v100
	v_fma_f32 v1, v147, v7, v1
	v_mul_f32_e32 v0, v0, v4
	v_lshlrev_b32_e32 v8, 16, v116
	v_and_b32_e32 v10, 0xffff0000, v116
	s_waitcnt lgkmcnt(0)
	v_fma_f32 v3, v147, v11, v3
	v_fmac_f32_e32 v2, v147, v9
	v_mul_f32_e32 v1, v1, v6
	v_cvt_pk_bf16_f32 v0, v0, v1
	v_mul_f32_e32 v3, v3, v10
	v_mul_f32_e32 v2, v2, v8
	global_store_dword v[30:31], v0, off
	v_cvt_pk_bf16_f32 v0, v2, v3
	global_store_dword v[32:33], v0, off
	ds_read_b64 v[0:1], v148 offset:28672
	ds_read_b64 v[2:3], v149
	v_lshlrev_b32_e32 v5, 16, v99
	v_lshlrev_b32_e32 v4, 16, v114
	v_and_b32_e32 v7, 0xffff0000, v99
	s_waitcnt lgkmcnt(1)
	v_fmac_f32_e32 v0, v147, v5
	v_and_b32_e32 v6, 0xffff0000, v114
	v_lshlrev_b32_e32 v9, 16, v98
	v_and_b32_e32 v11, 0xffff0000, v98
	v_fma_f32 v1, v147, v7, v1
	v_mul_f32_e32 v0, v0, v4
	v_lshlrev_b32_e32 v8, 16, v117
	v_and_b32_e32 v10, 0xffff0000, v117
	s_waitcnt lgkmcnt(0)
	v_fma_f32 v3, v147, v11, v3
	v_fmac_f32_e32 v2, v147, v9
	v_mul_f32_e32 v1, v1, v6
	v_cvt_pk_bf16_f32 v0, v0, v1
	v_mul_f32_e32 v3, v3, v10
	v_mul_f32_e32 v2, v2, v8
	global_store_dword v[26:27], v0, off
	v_cvt_pk_bf16_f32 v0, v2, v3
	global_store_dword v[28:29], v0, off
	s_barrier
	s_cbranch_vccz .LBB0_236
	v_readlane_b32 s12, v249, 12
	v_readlane_b32 s18, v249, 18
	s_add_i32 s0, s0, s18
	s_cmpk_gt_i32 s0, 0x3ff
	v_mov_b32_e32 v240, 0x358637bd
	v_bfrev_b32_e32 v248, 0.5
	v_readlane_b32 s13, v249, 13
	v_readlane_b32 s14, v249, 14
	v_readlane_b32 s15, v249, 15
	v_readlane_b32 s16, v249, 16
	v_readlane_b32 s17, v249, 17
	v_readlane_b32 s19, v249, 19
	s_cbranch_scc0 .LBB0_197
